# GEMM loops: dropped the already-satisfied s_waitcnt lgkmcnt(0) at the head of each MFMA burst
# baseline (speedup 1.0000x reference)
; #define PG8_STAGE(bufoff, gbase, voff) do { _Pragma("unroll") for (int _i = 0; _i < 2; ++_i) \
;         __builtin_amdgcn_global_load_lds((const unsigned*)((const char*)(gbase) + (voff)[_i]), (LAS unsigned*)(lds + (bufoff) + ldsw + _i * 8192), 16, 0, 0); } while (0)
; #define PG8_LDA(dst, b, h) do { _Pragma("unroll") for (int m = 0; m < 4; ++m) _Pragma("unroll") for (int k = 0; k < 2; ++k) dst[m][k] = *(const LAS bf16x8*)(lds + PG8_SA(b, h) + aoff + m * 2048 + k * 1024); } while (0)
; #define PG8_LDB(dst, b, h) do { _Pragma("unroll") for (int n = 0; n < 2; ++n) _Pragma("unroll") for (int k = 0; k < 2; ++k) dst[n][k] = *(const LAS bf16x8*)(lds + PG8_SB(b, h) + boff + n * 2048 + k * 1024); } while (0)
; #define PG8_MMA(ai, bj, At, Bt) do { __builtin_amdgcn_s_setprio(3); _Pragma("unroll") for (int m = 0; m < 4; ++m) _Pragma("unroll") for (int n = 0; n < 2; ++n) _Pragma("unroll") for (int k = 0; k < 2; ++k) \
;         acc[ai][bj][m][n] = __builtin_amdgcn_mfma_f32_16x16x32_bf16(Bt[n][k], At[m][k], acc[ai][bj][m][n], 0, 0, 0); __builtin_amdgcn_s_setprio(0); } while (0)
; #define PG8_BAR __builtin_amdgcn_s_barrier()
; template <class Epi, bool ALIGN_EPI>
; __device__ __forceinline__ void gemm_phase(LAS unsigned char* lds, const Gemm g, const StaticOrder& S, const Epi& E) {
;     ...
;         const bool has_next = S.next(ui + 1, nxt);
;         const char* nA = has_next ? (const char*)g.A + (size_t)nxt.pm * tstep : cA; const char* nB = has_next ? (const char*)g.Bt + (size_t)nxt.pn * tstep : cB;
;         for (int t = 0; t < nt; t += 2) {
;             const bool last = (t == nt - 2);
;             const char* a1 = cA + (size_t)(t + 1) * kstep;
;             const char* a2 = last ? nA : cA + (size_t)(t + 2) * kstep; const char* b2 = last ? nB : cB + (size_t)(t + 2) * kstep;
;             const char* a3 = a2 + kstep; const char* b3 = b2 + kstep;
;             PG8_LDB(B0, 0, 0); PG8_LDB(B1, 0, 1); PG8_SCHED; PG8_LDA(At, 0, 0); PG8_STAGE(PG8_SA(1, 1), a1 + hstep, voffA);
;             PG8_WAIT_V(8); PG8_WAIT_L(0); PG8_BAR; PG8_MMA(0, 0, At, B0); PG8_MMA(0, 1, At, B1); PG8_BAR; PG8_SCHED;
;             PG8_LDA(At, 0, 1); PG8_STAGE(PG8_SB(0, 0), b2, voffB); PG8_STAGE(PG8_SB(0, 1), b2 + hstep, voffB); PG8_STAGE(PG8_SA(0, 0), a2, voffA);
;             PG8_WAIT_V(8); PG8_WAIT_L(0); PG8_BAR; PG8_MMA(1, 0, At, B0); PG8_MMA(1, 1, At, B1); PG8_BAR; PG8_SCHED;
.LBB0_292:
	s_ashr_i32 s69, s68, 31
	s_lshl_b64 s[8:9], s[68:69], 19
	s_add_u32 s70, s34, s8
	s_addc_u32 s71, s35, s9
	s_and_b64 s[8:9], s[0:1], exec
	s_cselect_b32 s5, s71, s81
	s_cselect_b32 s69, s70, s80
	s_ashr_i32 s67, s66, 31
	s_lshl_b64 s[8:9], s[66:67], 19
	s_add_u32 s72, s26, s8
	s_addc_u32 s73, s27, s9
	s_and_b64 s[8:9], s[0:1], exec
	s_cselect_b32 s67, s73, s83
	s_cselect_b32 s79, s72, s82
	s_add_u32 s80, s80, 0x40080
	s_addc_u32 s81, s81, 0
	s_add_u32 vcc_lo, s82, 0x100
	s_addc_u32 vcc_hi, s83, 0
	s_mov_b32 s8, -2
	ds_read_b128 v[148:151], v192
	ds_read_b128 v[152:155], v192 offset:1024
	ds_read_b128 v[156:159], v192 offset:2048
	ds_read_b128 v[160:163], v192 offset:3072
	ds_read_b128 v[164:167], v193
	ds_read_b128 v[168:171], v193 offset:1024
	ds_read_b128 v[172:175], v193 offset:2048
	ds_read_b128 v[176:179], v193 offset:3072
	s_add_u32 s9, s80, 0xfffc0080
	s_addc_u32 s50, s81, -1
	s_cmp_eq_u32 s8, 12
	s_cselect_b32 s85, s5, s50
	s_cselect_b32 s84, s69, s9
	s_cselect_b32 s83, s67, vcc_hi
	s_cselect_b32 s82, s79, vcc_lo
	v_lshl_add_u64 v[224:225], s[80:81], 0, v[140:141]
	s_add_i32 m0, s76, 0xc000
	ds_read_b128 v[180:183], v194
	ds_read_b128 v[196:199], v194 offset:1024
	ds_read_b128 v[200:203], v194 offset:2048
	ds_read_b128 v[204:207], v194 offset:3072
	ds_read_b128 v[208:211], v194 offset:4096
	ds_read_b128 v[212:215], v194 offset:5120
	ds_read_b128 v[216:219], v194 offset:6144
	ds_read_b128 v[220:223], v194 offset:7168
	global_load_lds_dwordx4 v[224:225], off
	v_lshl_add_u64 v[224:225], s[80:81], 0, v[142:143]
	s_add_i32 m0, s76, 0xe000
	s_nop 0
	global_load_lds_dwordx4 v[224:225], off
	s_waitcnt vmcnt(8)
	s_waitcnt lgkmcnt(0)
	s_barrier
	s_setprio 3
	v_mfma_f32_16x16x32_bf16 v[118:121], v[148:151], v[180:183], 0
	v_mfma_f32_16x16x32_bf16 v[114:117], v[156:159], v[180:183], 0
	v_mfma_f32_16x16x32_bf16 v[102:105], v[148:151], v[200:203], 0
	v_mfma_f32_16x16x32_bf16 v[98:101], v[156:159], v[200:203], 0
	v_mfma_f32_16x16x32_bf16 v[86:89], v[148:151], v[208:211], 0
	v_mfma_f32_16x16x32_bf16 v[82:85], v[156:159], v[208:211], 0
	v_mfma_f32_16x16x32_bf16 v[70:73], v[148:151], v[216:219], 0
	v_mfma_f32_16x16x32_bf16 v[66:69], v[156:159], v[216:219], 0
	v_mfma_f32_16x16x32_bf16 v[118:121], v[152:155], v[196:199], v[118:121]
	v_mfma_f32_16x16x32_bf16 v[114:117], v[160:163], v[196:199], v[114:117]
	v_mfma_f32_16x16x32_bf16 v[102:105], v[152:155], v[204:207], v[102:105]
	v_mfma_f32_16x16x32_bf16 v[98:101], v[160:163], v[204:207], v[98:101]
	v_mfma_f32_16x16x32_bf16 v[86:89], v[152:155], v[212:215], v[86:89]
	v_mfma_f32_16x16x32_bf16 v[82:85], v[160:163], v[212:215], v[82:85]
	v_mfma_f32_16x16x32_bf16 v[70:73], v[152:155], v[220:223], v[70:73]
	v_mfma_f32_16x16x32_bf16 v[66:69], v[160:163], v[220:223], v[66:69]
	v_mfma_f32_16x16x32_bf16 v[126:129], v[164:167], v[180:183], 0
	v_mfma_f32_16x16x32_bf16 v[122:125], v[172:175], v[180:183], 0
	v_mfma_f32_16x16x32_bf16 v[110:113], v[164:167], v[200:203], 0
	v_mfma_f32_16x16x32_bf16 v[106:109], v[172:175], v[200:203], 0
	v_mfma_f32_16x16x32_bf16 v[94:97], v[164:167], v[208:211], 0
	v_mfma_f32_16x16x32_bf16 v[90:93], v[172:175], v[208:211], 0
	v_mfma_f32_16x16x32_bf16 v[78:81], v[164:167], v[216:219], 0
	v_mfma_f32_16x16x32_bf16 v[74:77], v[172:175], v[216:219], 0
	v_mfma_f32_16x16x32_bf16 v[126:129], v[168:171], v[196:199], v[126:129]
	v_mfma_f32_16x16x32_bf16 v[122:125], v[176:179], v[196:199], v[122:125]
	v_mfma_f32_16x16x32_bf16 v[110:113], v[168:171], v[204:207], v[110:113]
	v_mfma_f32_16x16x32_bf16 v[106:109], v[176:179], v[204:207], v[106:109]
	v_mfma_f32_16x16x32_bf16 v[94:97], v[168:171], v[212:215], v[94:97]
	v_mfma_f32_16x16x32_bf16 v[90:93], v[176:179], v[212:215], v[90:93]
	v_mfma_f32_16x16x32_bf16 v[78:81], v[168:171], v[220:223], v[78:81]
	v_mfma_f32_16x16x32_bf16 v[74:77], v[176:179], v[220:223], v[74:77]
	s_setprio 0
	s_barrier
	s_add_i32 s9, s95, s33
	v_lshl_add_u64 v[224:225], s[82:83], 0, v[132:133]
	s_mov_b32 m0, s9
	ds_read_b128 v[180:183], v194 offset:16384
	ds_read_b128 v[196:199], v194 offset:17408
	ds_read_b128 v[200:203], v194 offset:18432
	ds_read_b128 v[204:207], v194 offset:19456
	ds_read_b128 v[208:211], v194 offset:20480
	ds_read_b128 v[212:215], v194 offset:21504
	ds_read_b128 v[216:219], v194 offset:22528
	ds_read_b128 v[220:223], v194 offset:23552
	global_load_lds_dwordx4 v[224:225], off
	s_add_i32 m0, s9, 0x2000
	s_add_u32 s50, s82, 0x40000
	v_lshl_add_u64 v[226:227], s[82:83], 0, v[136:137]
	s_addc_u32 s51, s83, 0
	s_add_i32 s9, s96, s33
	global_load_lds_dwordx4 v[226:227], off
	v_lshl_add_u64 v[228:229], s[50:51], 0, v[132:133]
	s_mov_b32 m0, s9
	v_lshl_add_u64 v[230:231], s[84:85], 0, v[134:135]
	global_load_lds_dwordx4 v[228:229], off
	v_lshl_add_u64 v[228:229], s[50:51], 0, v[136:137]
	s_add_i32 m0, s9, 0x2000
	s_nop 0
	global_load_lds_dwordx4 v[228:229], off
	v_lshl_add_u64 v[228:229], s[84:85], 0, v[130:131]
	s_mov_b32 m0, s76
	s_nop 0
	global_load_lds_dwordx4 v[228:229], off
	s_mov_b32 m0, s77
	s_nop 0
	global_load_lds_dwordx4 v[230:231], off
	s_waitcnt vmcnt(8)
	s_waitcnt lgkmcnt(0)
	s_barrier
; #define PG8_STAGE(bufoff, gbase, voff) do { _Pragma("unroll") for (int _i = 0; _i < 2; ++_i) \
;         __builtin_amdgcn_global_load_lds((const unsigned*)((const char*)(gbase) + (voff)[_i]), (LAS unsigned*)(lds + (bufoff) + ldsw + _i * 8192), 16, 0, 0); } while (0)
; #define PG8_LDA(dst, b, h) do { _Pragma("unroll") for (int m = 0; m < 4; ++m) _Pragma("unroll") for (int k = 0; k < 2; ++k) dst[m][k] = *(const LAS bf16x8*)(lds + PG8_SA(b, h) + aoff + m * 2048 + k * 1024); } while (0)
; #define PG8_LDB(dst, b, h) do { _Pragma("unroll") for (int n = 0; n < 2; ++n) _Pragma("unroll") for (int k = 0; k < 2; ++k) dst[n][k] = *(const LAS bf16x8*)(lds + PG8_SB(b, h) + boff + n * 2048 + k * 1024); } while (0)
; #define PG8_MMA(ai, bj, At, Bt) do { __builtin_amdgcn_s_setprio(3); _Pragma("unroll") for (int m = 0; m < 4; ++m) _Pragma("unroll") for (int n = 0; n < 2; ++n) _Pragma("unroll") for (int k = 0; k < 2; ++k) \
;         acc[ai][bj][m][n] = __builtin_amdgcn_mfma_f32_16x16x32_bf16(Bt[n][k], At[m][k], acc[ai][bj][m][n], 0, 0, 0); __builtin_amdgcn_s_setprio(0); } while (0)
; #define PG8_WAIT_V(n) asm volatile("s_waitcnt vmcnt(" #n ")" ::: "memory")
; #define PG8_WAIT_L(n) asm volatile("s_waitcnt lgkmcnt(" #n ")" ::: "memory")
; #define PG8_BAR __builtin_amdgcn_s_barrier()
; #define PG8_SCHED __builtin_amdgcn_sched_barrier(0)
; template <class Epi, bool ALIGN_EPI>
; __device__ __forceinline__ void gemm_phase(LAS unsigned char* lds, const Gemm g, const StaticOrder& S, const Epi& E) {
;     ...
;             PG8_WAIT_V(8); PG8_WAIT_L(0); PG8_BAR; PG8_MMA(1, 0, At, B0); PG8_MMA(1, 1, At, B1); PG8_BAR; PG8_SCHED;
;             PG8_LDB(B0, 1, 0); PG8_LDB(B1, 1, 1); PG8_SCHED; PG8_LDA(At, 1, 0); PG8_STAGE(PG8_SA(0, 1), a2 + hstep, voffA);
;             PG8_WAIT_V(8); PG8_WAIT_L(0); PG8_BAR; PG8_MMA(0, 0, At, B0); PG8_MMA(0, 1, At, B1); PG8_BAR; PG8_SCHED;
	s_setprio 3
	v_mfma_f32_16x16x32_bf16 v[54:57], v[148:151], v[180:183], 0
	v_mfma_f32_16x16x32_bf16 v[50:53], v[156:159], v[180:183], 0
	v_mfma_f32_16x16x32_bf16 v[38:41], v[148:151], v[200:203], 0
	v_mfma_f32_16x16x32_bf16 v[34:37], v[156:159], v[200:203], 0
	v_mfma_f32_16x16x32_bf16 v[22:25], v[148:151], v[208:211], 0
	v_mfma_f32_16x16x32_bf16 v[18:21], v[156:159], v[208:211], 0
	v_mfma_f32_16x16x32_bf16 v[6:9], v[148:151], v[216:219], 0
	v_mfma_f32_16x16x32_bf16 v[2:5], v[156:159], v[216:219], 0
	v_mfma_f32_16x16x32_bf16 v[54:57], v[152:155], v[196:199], v[54:57]
	v_mfma_f32_16x16x32_bf16 v[50:53], v[160:163], v[196:199], v[50:53]
	v_mfma_f32_16x16x32_bf16 v[38:41], v[152:155], v[204:207], v[38:41]
	v_mfma_f32_16x16x32_bf16 v[34:37], v[160:163], v[204:207], v[34:37]
	v_mfma_f32_16x16x32_bf16 v[22:25], v[152:155], v[212:215], v[22:25]
	v_mfma_f32_16x16x32_bf16 v[18:21], v[160:163], v[212:215], v[18:21]
	v_mfma_f32_16x16x32_bf16 v[6:9], v[152:155], v[220:223], v[6:9]
	v_mfma_f32_16x16x32_bf16 v[2:5], v[160:163], v[220:223], v[2:5]
	v_mfma_f32_16x16x32_bf16 v[62:65], v[164:167], v[180:183], 0
	v_mfma_f32_16x16x32_bf16 v[58:61], v[172:175], v[180:183], 0
	v_mfma_f32_16x16x32_bf16 v[46:49], v[164:167], v[200:203], 0
	v_mfma_f32_16x16x32_bf16 v[42:45], v[172:175], v[200:203], 0
	v_mfma_f32_16x16x32_bf16 v[30:33], v[164:167], v[208:211], 0
	v_mfma_f32_16x16x32_bf16 v[26:29], v[172:175], v[208:211], 0
	v_mfma_f32_16x16x32_bf16 v[14:17], v[164:167], v[216:219], 0
	v_mfma_f32_16x16x32_bf16 v[10:13], v[172:175], v[216:219], 0
	v_mfma_f32_16x16x32_bf16 v[62:65], v[168:171], v[196:199], v[62:65]
	v_mfma_f32_16x16x32_bf16 v[58:61], v[176:179], v[196:199], v[58:61]
	v_mfma_f32_16x16x32_bf16 v[46:49], v[168:171], v[204:207], v[46:49]
	v_mfma_f32_16x16x32_bf16 v[42:45], v[176:179], v[204:207], v[42:45]
	v_mfma_f32_16x16x32_bf16 v[30:33], v[168:171], v[212:215], v[30:33]
	v_mfma_f32_16x16x32_bf16 v[26:29], v[176:179], v[212:215], v[26:29]
	v_mfma_f32_16x16x32_bf16 v[14:17], v[168:171], v[220:223], v[14:17]
	v_mfma_f32_16x16x32_bf16 v[10:13], v[176:179], v[220:223], v[10:13]
	s_setprio 0
	s_barrier
	s_add_i32 s9, 0, 0x18000
	v_add_u32_e32 v138, s9, v189
	s_add_i32 s89, 0, 0x1c000
	ds_read_b128 v[148:151], v138
	ds_read_b128 v[152:155], v138 offset:1024
	ds_read_b128 v[156:159], v138 offset:2048
	ds_read_b128 v[160:163], v138 offset:3072
	v_add_u32_e32 v138, s89, v189
	ds_read_b128 v[164:167], v138
	ds_read_b128 v[168:171], v138 offset:1024
	ds_read_b128 v[172:175], v138 offset:2048
	ds_read_b128 v[176:179], v138 offset:3072
	s_add_u32 s50, s84, 0x40000
	s_addc_u32 s51, s85, 0
	s_mov_b32 m0, s86
	v_lshl_add_u64 v[232:233], s[50:51], 0, v[130:131]
	ds_read_b128 v[180:183], v194 offset:32768
	ds_read_b128 v[196:199], v194 offset:33792
	ds_read_b128 v[200:203], v194 offset:34816
	ds_read_b128 v[204:207], v194 offset:35840
	ds_read_b128 v[208:211], v194 offset:36864
	ds_read_b128 v[212:215], v194 offset:37888
	ds_read_b128 v[216:219], v194 offset:38912
	ds_read_b128 v[220:223], v194 offset:39936
	global_load_lds_dwordx4 v[232:233], off
	v_lshl_add_u64 v[232:233], s[50:51], 0, v[134:135]
	s_mov_b32 m0, s87
	s_nop 0
	global_load_lds_dwordx4 v[232:233], off
	s_waitcnt vmcnt(8)
	s_waitcnt lgkmcnt(0)
	s_barrier
	s_setprio 3
	v_mfma_f32_16x16x32_bf16 v[118:121], v[148:151], v[180:183], v[118:121]
	v_mfma_f32_16x16x32_bf16 v[114:117], v[156:159], v[180:183], v[114:117]
	v_mfma_f32_16x16x32_bf16 v[102:105], v[148:151], v[200:203], v[102:105]
	v_mfma_f32_16x16x32_bf16 v[98:101], v[156:159], v[200:203], v[98:101]
	v_mfma_f32_16x16x32_bf16 v[86:89], v[148:151], v[208:211], v[86:89]
	v_mfma_f32_16x16x32_bf16 v[82:85], v[156:159], v[208:211], v[82:85]
	v_mfma_f32_16x16x32_bf16 v[70:73], v[148:151], v[216:219], v[70:73]
	v_mfma_f32_16x16x32_bf16 v[66:69], v[156:159], v[216:219], v[66:69]
	v_mfma_f32_16x16x32_bf16 v[118:121], v[152:155], v[196:199], v[118:121]
	v_mfma_f32_16x16x32_bf16 v[114:117], v[160:163], v[196:199], v[114:117]
	v_mfma_f32_16x16x32_bf16 v[102:105], v[152:155], v[204:207], v[102:105]
	v_mfma_f32_16x16x32_bf16 v[98:101], v[160:163], v[204:207], v[98:101]
	v_mfma_f32_16x16x32_bf16 v[86:89], v[152:155], v[212:215], v[86:89]
	v_mfma_f32_16x16x32_bf16 v[82:85], v[160:163], v[212:215], v[82:85]
	v_mfma_f32_16x16x32_bf16 v[70:73], v[152:155], v[220:223], v[70:73]
	v_mfma_f32_16x16x32_bf16 v[66:69], v[160:163], v[220:223], v[66:69]
	v_mfma_f32_16x16x32_bf16 v[126:129], v[164:167], v[180:183], v[126:129]
	v_mfma_f32_16x16x32_bf16 v[122:125], v[172:175], v[180:183], v[122:125]
	v_mfma_f32_16x16x32_bf16 v[110:113], v[164:167], v[200:203], v[110:113]
	v_mfma_f32_16x16x32_bf16 v[106:109], v[172:175], v[200:203], v[106:109]
	v_mfma_f32_16x16x32_bf16 v[94:97], v[164:167], v[208:211], v[94:97]
	v_mfma_f32_16x16x32_bf16 v[90:93], v[172:175], v[208:211], v[90:93]
	v_mfma_f32_16x16x32_bf16 v[78:81], v[164:167], v[216:219], v[78:81]
	v_mfma_f32_16x16x32_bf16 v[74:77], v[172:175], v[216:219], v[74:77]
	v_mfma_f32_16x16x32_bf16 v[126:129], v[168:171], v[196:199], v[126:129]
	v_mfma_f32_16x16x32_bf16 v[122:125], v[176:179], v[196:199], v[122:125]
	v_mfma_f32_16x16x32_bf16 v[110:113], v[168:171], v[204:207], v[110:113]
	v_mfma_f32_16x16x32_bf16 v[106:109], v[176:179], v[204:207], v[106:109]
	v_mfma_f32_16x16x32_bf16 v[94:97], v[168:171], v[212:215], v[94:97]
	v_mfma_f32_16x16x32_bf16 v[90:93], v[176:179], v[212:215], v[90:93]
	v_mfma_f32_16x16x32_bf16 v[78:81], v[168:171], v[220:223], v[78:81]
	v_mfma_f32_16x16x32_bf16 v[74:77], v[176:179], v[220:223], v[74:77]
	s_setprio 0
	s_barrier
; #define PG8_STAGE(bufoff, gbase, voff) do { _Pragma("unroll") for (int _i = 0; _i < 2; ++_i) \
;         __builtin_amdgcn_global_load_lds((const unsigned*)((const char*)(gbase) + (voff)[_i]), (LAS unsigned*)(lds + (bufoff) + ldsw + _i * 8192), 16, 0, 0); } while (0)
; #define PG8_LDA(dst, b, h) do { _Pragma("unroll") for (int m = 0; m < 4; ++m) _Pragma("unroll") for (int k = 0; k < 2; ++k) dst[m][k] = *(const LAS bf16x8*)(lds + PG8_SA(b, h) + aoff + m * 2048 + k * 1024); } while (0)
; #define PG8_LDB(dst, b, h) do { _Pragma("unroll") for (int n = 0; n < 2; ++n) _Pragma("unroll") for (int k = 0; k < 2; ++k) dst[n][k] = *(const LAS bf16x8*)(lds + PG8_SB(b, h) + boff + n * 2048 + k * 1024); } while (0)
; #define PG8_MMA(ai, bj, At, Bt) do { __builtin_amdgcn_s_setprio(3); _Pragma("unroll") for (int m = 0; m < 4; ++m) _Pragma("unroll") for (int n = 0; n < 2; ++n) _Pragma("unroll") for (int k = 0; k < 2; ++k) \
;         acc[ai][bj][m][n] = __builtin_amdgcn_mfma_f32_16x16x32_bf16(Bt[n][k], At[m][k], acc[ai][bj][m][n], 0, 0, 0); __builtin_amdgcn_s_setprio(0); } while (0)
; #define PG8_WAIT_V(n) asm volatile("s_waitcnt vmcnt(" #n ")" ::: "memory")
; #define PG8_WAIT_L(n) asm volatile("s_waitcnt lgkmcnt(" #n ")" ::: "memory")
; #define PG8_BAR __builtin_amdgcn_s_barrier()
; #define PG8_SCHED __builtin_amdgcn_sched_barrier(0)
; template <class Epi, bool ALIGN_EPI>
; __device__ __forceinline__ void gemm_phase(LAS unsigned char* lds, const Gemm g, const StaticOrder& S, const Epi& E) {
;     ...
;             PG8_LDB(B0, 0, 0); PG8_LDB(B1, 0, 1); PG8_SCHED; PG8_LDA(At, 0, 0); PG8_STAGE(PG8_SA(1, 1), a1 + hstep, voffA);
;             PG8_WAIT_V(8); PG8_WAIT_L(0); PG8_BAR; PG8_MMA(0, 0, At, B0); PG8_MMA(0, 1, At, B1); PG8_BAR; PG8_SCHED;
;     ...
;             PG8_LDA(At, 1, 1); PG8_STAGE(PG8_SB(1, 0), b3, voffB); PG8_STAGE(PG8_SB(1, 1), b3 + hstep, voffB); PG8_STAGE(PG8_SA(1, 0), a3, voffA);
;             PG8_WAIT_V(8); PG8_WAIT_L(0); PG8_BAR; PG8_MMA(1, 0, At, B0); PG8_MMA(1, 1, At, B1); PG8_BAR; PG8_SCHED;
	s_add_i32 s9, s9, s33
	v_lshl_add_u64 v[224:225], v[224:225], 0, s[62:63]
	s_mov_b32 m0, s9
	ds_read_b128 v[180:183], v194 offset:49152
	ds_read_b128 v[196:199], v194 offset:50176
	ds_read_b128 v[200:203], v194 offset:51200
	ds_read_b128 v[204:207], v194 offset:52224
	ds_read_b128 v[208:211], v194 offset:53248
	ds_read_b128 v[212:215], v194 offset:54272
	ds_read_b128 v[216:219], v194 offset:55296
	ds_read_b128 v[220:223], v194 offset:56320
	global_load_lds_dwordx4 v[224:225], off
	s_add_i32 m0, s9, 0x2000
	s_add_u32 s50, s82, 0x40080
	v_lshl_add_u64 v[224:225], v[226:227], 0, s[62:63]
	s_addc_u32 s51, s83, 0
	s_add_i32 s9, s89, s33
	global_load_lds_dwordx4 v[224:225], off
	v_lshl_add_u64 v[224:225], s[50:51], 0, v[132:133]
	s_mov_b32 m0, s9
	s_nop 0
	global_load_lds_dwordx4 v[224:225], off
	v_lshl_add_u64 v[224:225], s[50:51], 0, v[136:137]
	s_add_i32 m0, s9, 0x2000
	s_nop 0
	global_load_lds_dwordx4 v[224:225], off
	v_lshl_add_u64 v[224:225], v[228:229], 0, s[62:63]
	s_mov_b32 m0, s93
	s_nop 0
	global_load_lds_dwordx4 v[224:225], off
	v_lshl_add_u64 v[224:225], v[230:231], 0, s[62:63]
	s_mov_b32 m0, s94
	s_nop 0
	global_load_lds_dwordx4 v[224:225], off
	s_waitcnt vmcnt(8)
	s_waitcnt lgkmcnt(0)
	s_barrier
	s_setprio 3
	v_mfma_f32_16x16x32_bf16 v[54:57], v[148:151], v[180:183], v[54:57]
	v_mfma_f32_16x16x32_bf16 v[50:53], v[156:159], v[180:183], v[50:53]
	v_mfma_f32_16x16x32_bf16 v[38:41], v[148:151], v[200:203], v[38:41]
	v_mfma_f32_16x16x32_bf16 v[34:37], v[156:159], v[200:203], v[34:37]
	v_mfma_f32_16x16x32_bf16 v[22:25], v[148:151], v[208:211], v[22:25]
	v_mfma_f32_16x16x32_bf16 v[18:21], v[156:159], v[208:211], v[18:21]
	v_mfma_f32_16x16x32_bf16 v[6:9], v[148:151], v[216:219], v[6:9]
	v_mfma_f32_16x16x32_bf16 v[2:5], v[156:159], v[216:219], v[2:5]
	v_mfma_f32_16x16x32_bf16 v[54:57], v[152:155], v[196:199], v[54:57]
	v_mfma_f32_16x16x32_bf16 v[50:53], v[160:163], v[196:199], v[50:53]
	v_mfma_f32_16x16x32_bf16 v[38:41], v[152:155], v[204:207], v[38:41]
	v_mfma_f32_16x16x32_bf16 v[34:37], v[160:163], v[204:207], v[34:37]
	v_mfma_f32_16x16x32_bf16 v[22:25], v[152:155], v[212:215], v[22:25]
	v_mfma_f32_16x16x32_bf16 v[18:21], v[160:163], v[212:215], v[18:21]
	v_mfma_f32_16x16x32_bf16 v[6:9], v[152:155], v[220:223], v[6:9]
	v_mfma_f32_16x16x32_bf16 v[2:5], v[160:163], v[220:223], v[2:5]
	v_mfma_f32_16x16x32_bf16 v[62:65], v[164:167], v[180:183], v[62:65]
	v_mfma_f32_16x16x32_bf16 v[58:61], v[172:175], v[180:183], v[58:61]
	v_mfma_f32_16x16x32_bf16 v[46:49], v[164:167], v[200:203], v[46:49]
	v_mfma_f32_16x16x32_bf16 v[42:45], v[172:175], v[200:203], v[42:45]
	v_mfma_f32_16x16x32_bf16 v[30:33], v[164:167], v[208:211], v[30:33]
	v_mfma_f32_16x16x32_bf16 v[26:29], v[172:175], v[208:211], v[26:29]
	v_mfma_f32_16x16x32_bf16 v[14:17], v[164:167], v[216:219], v[14:17]
	v_mfma_f32_16x16x32_bf16 v[10:13], v[172:175], v[216:219], v[10:13]
	v_mfma_f32_16x16x32_bf16 v[62:65], v[168:171], v[196:199], v[62:65]
	v_mfma_f32_16x16x32_bf16 v[58:61], v[176:179], v[196:199], v[58:61]
	v_mfma_f32_16x16x32_bf16 v[46:49], v[168:171], v[204:207], v[46:49]
	v_mfma_f32_16x16x32_bf16 v[42:45], v[176:179], v[204:207], v[42:45]
	v_mfma_f32_16x16x32_bf16 v[30:33], v[168:171], v[212:215], v[30:33]
	v_mfma_f32_16x16x32_bf16 v[26:29], v[176:179], v[212:215], v[26:29]
	v_mfma_f32_16x16x32_bf16 v[14:17], v[168:171], v[220:223], v[14:17]
	v_mfma_f32_16x16x32_bf16 v[10:13], v[176:179], v[220:223], v[10:13]
	s_setprio 0
	s_barrier
	s_add_i32 s8, s8, 2
	s_add_u32 s80, s80, 0x100
	s_addc_u32 s81, s81, 0
	s_add_u32 vcc_lo, vcc_lo, 0x100
	s_addc_u32 vcc_hi, vcc_hi, 0
.LBB0_293:
	ds_read_b128 v[148:151], v192
	ds_read_b128 v[152:155], v192 offset:1024
	ds_read_b128 v[156:159], v192 offset:2048
	ds_read_b128 v[160:163], v192 offset:3072
	ds_read_b128 v[164:167], v193
	ds_read_b128 v[168:171], v193 offset:1024
	ds_read_b128 v[172:175], v193 offset:2048
	ds_read_b128 v[176:179], v193 offset:3072
	s_add_u32 s9, s80, 0xfffc0080
	s_addc_u32 s50, s81, -1
	s_cmp_eq_u32 s8, 12
	s_cselect_b32 s85, s5, s50
	s_cselect_b32 s84, s69, s9
	s_cselect_b32 s83, s67, vcc_hi
	s_cselect_b32 s82, s79, vcc_lo
	v_lshl_add_u64 v[224:225], s[80:81], 0, v[140:141]
	s_add_i32 m0, s76, 0xc000
	ds_read_b128 v[180:183], v194
	ds_read_b128 v[196:199], v194 offset:1024
	ds_read_b128 v[200:203], v194 offset:2048
	ds_read_b128 v[204:207], v194 offset:3072
	ds_read_b128 v[208:211], v194 offset:4096
	ds_read_b128 v[212:215], v194 offset:5120
	ds_read_b128 v[216:219], v194 offset:6144
	ds_read_b128 v[220:223], v194 offset:7168
	global_load_lds_dwordx4 v[224:225], off
	v_lshl_add_u64 v[224:225], s[80:81], 0, v[142:143]
	s_add_i32 m0, s76, 0xe000
	s_nop 0
	global_load_lds_dwordx4 v[224:225], off
	s_waitcnt vmcnt(8)
	s_waitcnt lgkmcnt(0)
	s_barrier
; #define PG8_STAGE(bufoff, gbase, voff) do { _Pragma("unroll") for (int _i = 0; _i < 2; ++_i) \
;         __builtin_amdgcn_global_load_lds((const unsigned*)((const char*)(gbase) + (voff)[_i]), (LAS unsigned*)(lds + (bufoff) + ldsw + _i * 8192), 16, 0, 0); } while (0)
; #define PG8_LDA(dst, b, h) do { _Pragma("unroll") for (int m = 0; m < 4; ++m) _Pragma("unroll") for (int k = 0; k < 2; ++k) dst[m][k] = *(const LAS bf16x8*)(lds + PG8_SA(b, h) + aoff + m * 2048 + k * 1024); } while (0)
; #define PG8_MMA(ai, bj, At, Bt) do { __builtin_amdgcn_s_setprio(3); _Pragma("unroll") for (int m = 0; m < 4; ++m) _Pragma("unroll") for (int n = 0; n < 2; ++n) _Pragma("unroll") for (int k = 0; k < 2; ++k) \
;         acc[ai][bj][m][n] = __builtin_amdgcn_mfma_f32_16x16x32_bf16(Bt[n][k], At[m][k], acc[ai][bj][m][n], 0, 0, 0); __builtin_amdgcn_s_setprio(0); } while (0)
; #define PG8_WAIT_V(n) asm volatile("s_waitcnt vmcnt(" #n ")" ::: "memory")
; #define PG8_WAIT_L(n) asm volatile("s_waitcnt lgkmcnt(" #n ")" ::: "memory")
; #define PG8_BAR __builtin_amdgcn_s_barrier()
; #define PG8_SCHED __builtin_amdgcn_sched_barrier(0)
; template <class Epi, bool ALIGN_EPI>
; __device__ __forceinline__ void gemm_phase(LAS unsigned char* lds, const Gemm g, const StaticOrder& S, const Epi& E) {
;     ...
;             PG8_WAIT_V(8); PG8_WAIT_L(0); PG8_BAR; PG8_MMA(0, 0, At, B0); PG8_MMA(0, 1, At, B1); PG8_BAR; PG8_SCHED;
;             PG8_LDA(At, 0, 1); PG8_STAGE(PG8_SB(0, 0), b2, voffB); PG8_STAGE(PG8_SB(0, 1), b2 + hstep, voffB); PG8_STAGE(PG8_SA(0, 0), a2, voffA);
;             PG8_WAIT_V(8); PG8_WAIT_L(0); PG8_BAR; PG8_MMA(1, 0, At, B0); PG8_MMA(1, 1, At, B1); PG8_BAR; PG8_SCHED;
	s_setprio 3
	v_mfma_f32_16x16x32_bf16 v[118:121], v[148:151], v[180:183], v[118:121]
	v_mfma_f32_16x16x32_bf16 v[114:117], v[156:159], v[180:183], v[114:117]
	v_mfma_f32_16x16x32_bf16 v[102:105], v[148:151], v[200:203], v[102:105]
	v_mfma_f32_16x16x32_bf16 v[98:101], v[156:159], v[200:203], v[98:101]
	v_mfma_f32_16x16x32_bf16 v[86:89], v[148:151], v[208:211], v[86:89]
	v_mfma_f32_16x16x32_bf16 v[82:85], v[156:159], v[208:211], v[82:85]
	v_mfma_f32_16x16x32_bf16 v[70:73], v[148:151], v[216:219], v[70:73]
	v_mfma_f32_16x16x32_bf16 v[66:69], v[156:159], v[216:219], v[66:69]
	v_mfma_f32_16x16x32_bf16 v[118:121], v[152:155], v[196:199], v[118:121]
	v_mfma_f32_16x16x32_bf16 v[114:117], v[160:163], v[196:199], v[114:117]
	v_mfma_f32_16x16x32_bf16 v[102:105], v[152:155], v[204:207], v[102:105]
	v_mfma_f32_16x16x32_bf16 v[98:101], v[160:163], v[204:207], v[98:101]
	v_mfma_f32_16x16x32_bf16 v[86:89], v[152:155], v[212:215], v[86:89]
	v_mfma_f32_16x16x32_bf16 v[82:85], v[160:163], v[212:215], v[82:85]
	v_mfma_f32_16x16x32_bf16 v[70:73], v[152:155], v[220:223], v[70:73]
	v_mfma_f32_16x16x32_bf16 v[66:69], v[160:163], v[220:223], v[66:69]
	v_mfma_f32_16x16x32_bf16 v[126:129], v[164:167], v[180:183], v[126:129]
	v_mfma_f32_16x16x32_bf16 v[122:125], v[172:175], v[180:183], v[122:125]
	v_mfma_f32_16x16x32_bf16 v[110:113], v[164:167], v[200:203], v[110:113]
	v_mfma_f32_16x16x32_bf16 v[106:109], v[172:175], v[200:203], v[106:109]
	v_mfma_f32_16x16x32_bf16 v[94:97], v[164:167], v[208:211], v[94:97]
	v_mfma_f32_16x16x32_bf16 v[90:93], v[172:175], v[208:211], v[90:93]
	v_mfma_f32_16x16x32_bf16 v[78:81], v[164:167], v[216:219], v[78:81]
	v_mfma_f32_16x16x32_bf16 v[74:77], v[172:175], v[216:219], v[74:77]
	v_mfma_f32_16x16x32_bf16 v[126:129], v[168:171], v[196:199], v[126:129]
	v_mfma_f32_16x16x32_bf16 v[122:125], v[176:179], v[196:199], v[122:125]
	v_mfma_f32_16x16x32_bf16 v[110:113], v[168:171], v[204:207], v[110:113]
	v_mfma_f32_16x16x32_bf16 v[106:109], v[176:179], v[204:207], v[106:109]
	v_mfma_f32_16x16x32_bf16 v[94:97], v[168:171], v[212:215], v[94:97]
	v_mfma_f32_16x16x32_bf16 v[90:93], v[176:179], v[212:215], v[90:93]
	v_mfma_f32_16x16x32_bf16 v[78:81], v[168:171], v[220:223], v[78:81]
	v_mfma_f32_16x16x32_bf16 v[74:77], v[176:179], v[220:223], v[74:77]
	s_setprio 0
	s_barrier
	s_add_i32 s9, s95, s33
	v_lshl_add_u64 v[224:225], s[82:83], 0, v[132:133]
	s_mov_b32 m0, s9
	ds_read_b128 v[180:183], v194 offset:16384
	ds_read_b128 v[196:199], v194 offset:17408
	ds_read_b128 v[200:203], v194 offset:18432
	ds_read_b128 v[204:207], v194 offset:19456
	ds_read_b128 v[208:211], v194 offset:20480
	ds_read_b128 v[212:215], v194 offset:21504
	ds_read_b128 v[216:219], v194 offset:22528
	ds_read_b128 v[220:223], v194 offset:23552
	global_load_lds_dwordx4 v[224:225], off
	s_add_i32 m0, s9, 0x2000
	s_add_u32 s50, s82, 0x40000
	v_lshl_add_u64 v[226:227], s[82:83], 0, v[136:137]
	s_addc_u32 s51, s83, 0
	s_add_i32 s9, s96, s33
	global_load_lds_dwordx4 v[226:227], off
	v_lshl_add_u64 v[228:229], s[50:51], 0, v[132:133]
	s_mov_b32 m0, s9
	v_lshl_add_u64 v[230:231], s[84:85], 0, v[134:135]
	global_load_lds_dwordx4 v[228:229], off
	v_lshl_add_u64 v[228:229], s[50:51], 0, v[136:137]
	s_add_i32 m0, s9, 0x2000
	s_nop 0
	global_load_lds_dwordx4 v[228:229], off
	v_lshl_add_u64 v[228:229], s[84:85], 0, v[130:131]
	s_mov_b32 m0, s76
	s_nop 0
	global_load_lds_dwordx4 v[228:229], off
	s_mov_b32 m0, s77
	s_nop 0
	global_load_lds_dwordx4 v[230:231], off
	s_waitcnt vmcnt(8)
	s_waitcnt lgkmcnt(0)
	s_barrier
	s_setprio 3
	v_mfma_f32_16x16x32_bf16 v[54:57], v[148:151], v[180:183], v[54:57]
	v_mfma_f32_16x16x32_bf16 v[50:53], v[156:159], v[180:183], v[50:53]
	v_mfma_f32_16x16x32_bf16 v[38:41], v[148:151], v[200:203], v[38:41]
	v_mfma_f32_16x16x32_bf16 v[34:37], v[156:159], v[200:203], v[34:37]
	v_mfma_f32_16x16x32_bf16 v[22:25], v[148:151], v[208:211], v[22:25]
	v_mfma_f32_16x16x32_bf16 v[18:21], v[156:159], v[208:211], v[18:21]
	v_mfma_f32_16x16x32_bf16 v[6:9], v[148:151], v[216:219], v[6:9]
	v_mfma_f32_16x16x32_bf16 v[2:5], v[156:159], v[216:219], v[2:5]
	v_mfma_f32_16x16x32_bf16 v[54:57], v[152:155], v[196:199], v[54:57]
	v_mfma_f32_16x16x32_bf16 v[50:53], v[160:163], v[196:199], v[50:53]
	v_mfma_f32_16x16x32_bf16 v[38:41], v[152:155], v[204:207], v[38:41]
	v_mfma_f32_16x16x32_bf16 v[34:37], v[160:163], v[204:207], v[34:37]
	v_mfma_f32_16x16x32_bf16 v[22:25], v[152:155], v[212:215], v[22:25]
	v_mfma_f32_16x16x32_bf16 v[18:21], v[160:163], v[212:215], v[18:21]
	v_mfma_f32_16x16x32_bf16 v[6:9], v[152:155], v[220:223], v[6:9]
	v_mfma_f32_16x16x32_bf16 v[2:5], v[160:163], v[220:223], v[2:5]
	v_mfma_f32_16x16x32_bf16 v[62:65], v[164:167], v[180:183], v[62:65]
	v_mfma_f32_16x16x32_bf16 v[58:61], v[172:175], v[180:183], v[58:61]
	v_mfma_f32_16x16x32_bf16 v[46:49], v[164:167], v[200:203], v[46:49]
	v_mfma_f32_16x16x32_bf16 v[42:45], v[172:175], v[200:203], v[42:45]
	v_mfma_f32_16x16x32_bf16 v[30:33], v[164:167], v[208:211], v[30:33]
	v_mfma_f32_16x16x32_bf16 v[26:29], v[172:175], v[208:211], v[26:29]
	v_mfma_f32_16x16x32_bf16 v[14:17], v[164:167], v[216:219], v[14:17]
	v_mfma_f32_16x16x32_bf16 v[10:13], v[172:175], v[216:219], v[10:13]
	v_mfma_f32_16x16x32_bf16 v[62:65], v[168:171], v[196:199], v[62:65]
	v_mfma_f32_16x16x32_bf16 v[58:61], v[176:179], v[196:199], v[58:61]
	v_mfma_f32_16x16x32_bf16 v[46:49], v[168:171], v[204:207], v[46:49]
	v_mfma_f32_16x16x32_bf16 v[42:45], v[176:179], v[204:207], v[42:45]
	v_mfma_f32_16x16x32_bf16 v[30:33], v[168:171], v[212:215], v[30:33]
	v_mfma_f32_16x16x32_bf16 v[26:29], v[176:179], v[212:215], v[26:29]
	v_mfma_f32_16x16x32_bf16 v[14:17], v[168:171], v[220:223], v[14:17]
	v_mfma_f32_16x16x32_bf16 v[10:13], v[176:179], v[220:223], v[10:13]
	s_setprio 0
	s_barrier
; #define PG8_STAGE(bufoff, gbase, voff) do { _Pragma("unroll") for (int _i = 0; _i < 2; ++_i) \
;         __builtin_amdgcn_global_load_lds((const unsigned*)((const char*)(gbase) + (voff)[_i]), (LAS unsigned*)(lds + (bufoff) + ldsw + _i * 8192), 16, 0, 0); } while (0)
; #define PG8_LDA(dst, b, h) do { _Pragma("unroll") for (int m = 0; m < 4; ++m) _Pragma("unroll") for (int k = 0; k < 2; ++k) dst[m][k] = *(const LAS bf16x8*)(lds + PG8_SA(b, h) + aoff + m * 2048 + k * 1024); } while (0)
; #define PG8_LDB(dst, b, h) do { _Pragma("unroll") for (int n = 0; n < 2; ++n) _Pragma("unroll") for (int k = 0; k < 2; ++k) dst[n][k] = *(const LAS bf16x8*)(lds + PG8_SB(b, h) + boff + n * 2048 + k * 1024); } while (0)
; #define PG8_MMA(ai, bj, At, Bt) do { __builtin_amdgcn_s_setprio(3); _Pragma("unroll") for (int m = 0; m < 4; ++m) _Pragma("unroll") for (int n = 0; n < 2; ++n) _Pragma("unroll") for (int k = 0; k < 2; ++k) \
;         acc[ai][bj][m][n] = __builtin_amdgcn_mfma_f32_16x16x32_bf16(Bt[n][k], At[m][k], acc[ai][bj][m][n], 0, 0, 0); __builtin_amdgcn_s_setprio(0); } while (0)
; #define PG8_WAIT_V(n) asm volatile("s_waitcnt vmcnt(" #n ")" ::: "memory")
; #define PG8_WAIT_L(n) asm volatile("s_waitcnt lgkmcnt(" #n ")" ::: "memory")
; #define PG8_BAR __builtin_amdgcn_s_barrier()
; #define PG8_SCHED __builtin_amdgcn_sched_barrier(0)
; template <class Epi, bool ALIGN_EPI>
; __device__ __forceinline__ void gemm_phase(LAS unsigned char* lds, const Gemm g, const StaticOrder& S, const Epi& E) {
;     ...
;             PG8_LDB(B0, 1, 0); PG8_LDB(B1, 1, 1); PG8_SCHED; PG8_LDA(At, 1, 0); PG8_STAGE(PG8_SA(0, 1), a2 + hstep, voffA);
;             PG8_WAIT_V(8); PG8_WAIT_L(0); PG8_BAR; PG8_MMA(0, 0, At, B0); PG8_MMA(0, 1, At, B1); PG8_BAR; PG8_SCHED;
	s_add_i32 s9, 0, 0x18000
	v_add_u32_e32 v138, s9, v189
	s_add_i32 s89, 0, 0x1c000
	ds_read_b128 v[148:151], v138
	ds_read_b128 v[152:155], v138 offset:1024
	ds_read_b128 v[156:159], v138 offset:2048
	ds_read_b128 v[160:163], v138 offset:3072
	v_add_u32_e32 v138, s89, v189
	ds_read_b128 v[164:167], v138
	ds_read_b128 v[168:171], v138 offset:1024
	ds_read_b128 v[172:175], v138 offset:2048
	ds_read_b128 v[176:179], v138 offset:3072
	s_add_u32 s50, s84, 0x40000
	s_addc_u32 s51, s85, 0
	s_mov_b32 m0, s86
	v_lshl_add_u64 v[232:233], s[50:51], 0, v[130:131]
	ds_read_b128 v[180:183], v194 offset:32768
	ds_read_b128 v[196:199], v194 offset:33792
	ds_read_b128 v[200:203], v194 offset:34816
	ds_read_b128 v[204:207], v194 offset:35840
	ds_read_b128 v[208:211], v194 offset:36864
	ds_read_b128 v[212:215], v194 offset:37888
	ds_read_b128 v[216:219], v194 offset:38912
	ds_read_b128 v[220:223], v194 offset:39936
	global_load_lds_dwordx4 v[232:233], off
	v_lshl_add_u64 v[232:233], s[50:51], 0, v[134:135]
	s_mov_b32 m0, s87
	s_nop 0
	global_load_lds_dwordx4 v[232:233], off
	s_waitcnt vmcnt(8)
	s_waitcnt lgkmcnt(0)
	s_barrier
	s_setprio 3
	v_mfma_f32_16x16x32_bf16 v[118:121], v[148:151], v[180:183], v[118:121]
	v_mfma_f32_16x16x32_bf16 v[114:117], v[156:159], v[180:183], v[114:117]
	v_mfma_f32_16x16x32_bf16 v[102:105], v[148:151], v[200:203], v[102:105]
	v_mfma_f32_16x16x32_bf16 v[98:101], v[156:159], v[200:203], v[98:101]
	v_mfma_f32_16x16x32_bf16 v[86:89], v[148:151], v[208:211], v[86:89]
	v_mfma_f32_16x16x32_bf16 v[82:85], v[156:159], v[208:211], v[82:85]
	v_mfma_f32_16x16x32_bf16 v[70:73], v[148:151], v[216:219], v[70:73]
	v_mfma_f32_16x16x32_bf16 v[66:69], v[156:159], v[216:219], v[66:69]
	v_mfma_f32_16x16x32_bf16 v[118:121], v[152:155], v[196:199], v[118:121]
	v_mfma_f32_16x16x32_bf16 v[114:117], v[160:163], v[196:199], v[114:117]
	v_mfma_f32_16x16x32_bf16 v[102:105], v[152:155], v[204:207], v[102:105]
	v_mfma_f32_16x16x32_bf16 v[98:101], v[160:163], v[204:207], v[98:101]
	v_mfma_f32_16x16x32_bf16 v[86:89], v[152:155], v[212:215], v[86:89]
	v_mfma_f32_16x16x32_bf16 v[82:85], v[160:163], v[212:215], v[82:85]
	v_mfma_f32_16x16x32_bf16 v[70:73], v[152:155], v[220:223], v[70:73]
	v_mfma_f32_16x16x32_bf16 v[66:69], v[160:163], v[220:223], v[66:69]
	v_mfma_f32_16x16x32_bf16 v[126:129], v[164:167], v[180:183], v[126:129]
	v_mfma_f32_16x16x32_bf16 v[122:125], v[172:175], v[180:183], v[122:125]
	v_mfma_f32_16x16x32_bf16 v[110:113], v[164:167], v[200:203], v[110:113]
	v_mfma_f32_16x16x32_bf16 v[106:109], v[172:175], v[200:203], v[106:109]
	v_mfma_f32_16x16x32_bf16 v[94:97], v[164:167], v[208:211], v[94:97]
	v_mfma_f32_16x16x32_bf16 v[90:93], v[172:175], v[208:211], v[90:93]
	v_mfma_f32_16x16x32_bf16 v[78:81], v[164:167], v[216:219], v[78:81]
	v_mfma_f32_16x16x32_bf16 v[74:77], v[172:175], v[216:219], v[74:77]
	v_mfma_f32_16x16x32_bf16 v[126:129], v[168:171], v[196:199], v[126:129]
	v_mfma_f32_16x16x32_bf16 v[122:125], v[176:179], v[196:199], v[122:125]
	v_mfma_f32_16x16x32_bf16 v[110:113], v[168:171], v[204:207], v[110:113]
	v_mfma_f32_16x16x32_bf16 v[106:109], v[176:179], v[204:207], v[106:109]
	v_mfma_f32_16x16x32_bf16 v[94:97], v[168:171], v[212:215], v[94:97]
	v_mfma_f32_16x16x32_bf16 v[90:93], v[176:179], v[212:215], v[90:93]
	v_mfma_f32_16x16x32_bf16 v[78:81], v[168:171], v[220:223], v[78:81]
	v_mfma_f32_16x16x32_bf16 v[74:77], v[176:179], v[220:223], v[74:77]
	s_setprio 0
	s_barrier
; #define PG8_STAGE(bufoff, gbase, voff) do { _Pragma("unroll") for (int _i = 0; _i < 2; ++_i) \
;         __builtin_amdgcn_global_load_lds((const unsigned*)((const char*)(gbase) + (voff)[_i]), (LAS unsigned*)(lds + (bufoff) + ldsw + _i * 8192), 16, 0, 0); } while (0)
; #define PG8_LDA(dst, b, h) do { _Pragma("unroll") for (int m = 0; m < 4; ++m) _Pragma("unroll") for (int k = 0; k < 2; ++k) dst[m][k] = *(const LAS bf16x8*)(lds + PG8_SA(b, h) + aoff + m * 2048 + k * 1024); } while (0)
; #define PG8_MMA(ai, bj, At, Bt) do { __builtin_amdgcn_s_setprio(3); _Pragma("unroll") for (int m = 0; m < 4; ++m) _Pragma("unroll") for (int n = 0; n < 2; ++n) _Pragma("unroll") for (int k = 0; k < 2; ++k) \
;         acc[ai][bj][m][n] = __builtin_amdgcn_mfma_f32_16x16x32_bf16(Bt[n][k], At[m][k], acc[ai][bj][m][n], 0, 0, 0); __builtin_amdgcn_s_setprio(0); } while (0)
; #define PG8_WAIT_V(n) asm volatile("s_waitcnt vmcnt(" #n ")" ::: "memory")
; #define PG8_WAIT_L(n) asm volatile("s_waitcnt lgkmcnt(" #n ")" ::: "memory")
; #define PG8_BAR __builtin_amdgcn_s_barrier()
; #define PG8_SCHED __builtin_amdgcn_sched_barrier(0)
; template <class Epi, bool ALIGN_EPI>
; __device__ __forceinline__ void gemm_phase(LAS unsigned char* lds, const Gemm g, const StaticOrder& S, const Epi& E) {
;     ...
;             PG8_LDA(At, 1, 1); PG8_STAGE(PG8_SB(1, 0), b3, voffB); PG8_STAGE(PG8_SB(1, 1), b3 + hstep, voffB); PG8_STAGE(PG8_SA(1, 0), a3, voffA);
;             PG8_WAIT_V(8); PG8_WAIT_L(0); PG8_BAR; PG8_MMA(1, 0, At, B0); PG8_MMA(1, 1, At, B1); PG8_BAR; PG8_SCHED;
;         }
;         if constexpr (ALIGN_EPI) { if (wr == 0) PG8_BAR; }
	s_add_i32 s9, s9, s33
	v_lshl_add_u64 v[224:225], v[224:225], 0, s[62:63]
	s_mov_b32 m0, s9
	ds_read_b128 v[180:183], v194 offset:49152
	ds_read_b128 v[196:199], v194 offset:50176
	ds_read_b128 v[200:203], v194 offset:51200
	ds_read_b128 v[204:207], v194 offset:52224
	ds_read_b128 v[208:211], v194 offset:53248
	ds_read_b128 v[212:215], v194 offset:54272
	ds_read_b128 v[216:219], v194 offset:55296
	ds_read_b128 v[220:223], v194 offset:56320
	global_load_lds_dwordx4 v[224:225], off
	s_add_i32 m0, s9, 0x2000
	s_add_u32 s50, s82, 0x40080
	v_lshl_add_u64 v[224:225], v[226:227], 0, s[62:63]
	s_addc_u32 s51, s83, 0
	s_add_i32 s9, s89, s33
	global_load_lds_dwordx4 v[224:225], off
	v_lshl_add_u64 v[224:225], s[50:51], 0, v[132:133]
	s_mov_b32 m0, s9
	s_nop 0
	global_load_lds_dwordx4 v[224:225], off
	v_lshl_add_u64 v[224:225], s[50:51], 0, v[136:137]
	s_add_i32 m0, s9, 0x2000
	s_nop 0
	global_load_lds_dwordx4 v[224:225], off
	v_lshl_add_u64 v[224:225], v[228:229], 0, s[62:63]
	s_mov_b32 m0, s93
	s_nop 0
	global_load_lds_dwordx4 v[224:225], off
	v_lshl_add_u64 v[224:225], v[230:231], 0, s[62:63]
	s_mov_b32 m0, s94
	s_nop 0
	global_load_lds_dwordx4 v[224:225], off
	s_waitcnt vmcnt(8)
	s_waitcnt lgkmcnt(0)
	s_barrier
	s_setprio 3
	v_mfma_f32_16x16x32_bf16 v[54:57], v[148:151], v[180:183], v[54:57]
	v_mfma_f32_16x16x32_bf16 v[50:53], v[156:159], v[180:183], v[50:53]
	v_mfma_f32_16x16x32_bf16 v[38:41], v[148:151], v[200:203], v[38:41]
	v_mfma_f32_16x16x32_bf16 v[34:37], v[156:159], v[200:203], v[34:37]
	v_mfma_f32_16x16x32_bf16 v[22:25], v[148:151], v[208:211], v[22:25]
	v_mfma_f32_16x16x32_bf16 v[18:21], v[156:159], v[208:211], v[18:21]
	v_mfma_f32_16x16x32_bf16 v[6:9], v[148:151], v[216:219], v[6:9]
	v_mfma_f32_16x16x32_bf16 v[2:5], v[156:159], v[216:219], v[2:5]
	v_mfma_f32_16x16x32_bf16 v[54:57], v[152:155], v[196:199], v[54:57]
	v_mfma_f32_16x16x32_bf16 v[50:53], v[160:163], v[196:199], v[50:53]
	v_mfma_f32_16x16x32_bf16 v[38:41], v[152:155], v[204:207], v[38:41]
	v_mfma_f32_16x16x32_bf16 v[34:37], v[160:163], v[204:207], v[34:37]
	v_mfma_f32_16x16x32_bf16 v[22:25], v[152:155], v[212:215], v[22:25]
	v_mfma_f32_16x16x32_bf16 v[18:21], v[160:163], v[212:215], v[18:21]
	v_mfma_f32_16x16x32_bf16 v[6:9], v[152:155], v[220:223], v[6:9]
	v_mfma_f32_16x16x32_bf16 v[2:5], v[160:163], v[220:223], v[2:5]
	v_mfma_f32_16x16x32_bf16 v[62:65], v[164:167], v[180:183], v[62:65]
	v_mfma_f32_16x16x32_bf16 v[58:61], v[172:175], v[180:183], v[58:61]
	v_mfma_f32_16x16x32_bf16 v[46:49], v[164:167], v[200:203], v[46:49]
	v_mfma_f32_16x16x32_bf16 v[42:45], v[172:175], v[200:203], v[42:45]
	v_mfma_f32_16x16x32_bf16 v[30:33], v[164:167], v[208:211], v[30:33]
	v_mfma_f32_16x16x32_bf16 v[26:29], v[172:175], v[208:211], v[26:29]
	v_mfma_f32_16x16x32_bf16 v[14:17], v[164:167], v[216:219], v[14:17]
	v_mfma_f32_16x16x32_bf16 v[10:13], v[172:175], v[216:219], v[10:13]
	v_mfma_f32_16x16x32_bf16 v[62:65], v[168:171], v[196:199], v[62:65]
	v_mfma_f32_16x16x32_bf16 v[58:61], v[176:179], v[196:199], v[58:61]
	v_mfma_f32_16x16x32_bf16 v[46:49], v[168:171], v[204:207], v[46:49]
	v_mfma_f32_16x16x32_bf16 v[42:45], v[176:179], v[204:207], v[42:45]
	v_mfma_f32_16x16x32_bf16 v[30:33], v[168:171], v[212:215], v[30:33]
	v_mfma_f32_16x16x32_bf16 v[26:29], v[176:179], v[212:215], v[26:29]
	v_mfma_f32_16x16x32_bf16 v[14:17], v[168:171], v[220:223], v[14:17]
	v_mfma_f32_16x16x32_bf16 v[10:13], v[176:179], v[220:223], v[10:13]
	s_setprio 0
	s_barrier
	s_add_i32 s8, s8, 2
	s_add_u32 s80, s80, 0x100
	s_addc_u32 s81, s81, 0
	s_add_u32 vcc_lo, vcc_lo, 0x100
	s_addc_u32 vcc_hi, vcc_hi, 0
	s_cmp_gt_u32 s8, 13
	s_cbranch_scc0 .LBB0_293
	s_and_b64 vcc, exec, s[64:65]
	s_cbranch_vccz .LBB0_296
	s_barrier

; #define PG8_STAGE(bufoff, gbase, voff) do { _Pragma("unroll") for (int _i = 0; _i < 2; ++_i) \
;         __builtin_amdgcn_global_load_lds((const unsigned*)((const char*)(gbase) + (voff)[_i]), (LAS unsigned*)(lds + (bufoff) + ldsw + _i * 8192), 16, 0, 0); } while (0)
; #define PG8_LDA(dst, b, h) do { _Pragma("unroll") for (int m = 0; m < 4; ++m) _Pragma("unroll") for (int k = 0; k < 2; ++k) dst[m][k] = *(const LAS bf16x8*)(lds + PG8_SA(b, h) + aoff + m * 2048 + k * 1024); } while (0)
; #define PG8_LDB(dst, b, h) do { _Pragma("unroll") for (int n = 0; n < 2; ++n) _Pragma("unroll") for (int k = 0; k < 2; ++k) dst[n][k] = *(const LAS bf16x8*)(lds + PG8_SB(b, h) + boff + n * 2048 + k * 1024); } while (0)
; #define PG8_MMA(ai, bj, At, Bt) do { __builtin_amdgcn_s_setprio(3); _Pragma("unroll") for (int m = 0; m < 4; ++m) _Pragma("unroll") for (int n = 0; n < 2; ++n) _Pragma("unroll") for (int k = 0; k < 2; ++k) \
;         acc[ai][bj][m][n] = __builtin_amdgcn_mfma_f32_16x16x32_bf16(Bt[n][k], At[m][k], acc[ai][bj][m][n], 0, 0, 0); __builtin_amdgcn_s_setprio(0); } while (0)
; #define PG8_BAR __builtin_amdgcn_s_barrier()
; template <class Epi, bool ALIGN_EPI>
; __device__ __forceinline__ void gemm_phase(LAS unsigned char* lds, const Gemm g, const StaticOrder& S, const Epi& E) {
;     ...
;         const bool has_next = S.next(ui + 1, nxt);
;         const char* nA = has_next ? (const char*)g.A + (size_t)nxt.pm * tstep : cA; const char* nB = has_next ? (const char*)g.Bt + (size_t)nxt.pn * tstep : cB;
;         for (int t = 0; t < nt; t += 2) {
;             const bool last = (t == nt - 2);
;             const char* a1 = cA + (size_t)(t + 1) * kstep;
;             const char* a2 = last ? nA : cA + (size_t)(t + 2) * kstep; const char* b2 = last ? nB : cB + (size_t)(t + 2) * kstep;
;             const char* a3 = a2 + kstep; const char* b3 = b2 + kstep;
;             PG8_LDB(B0, 0, 0); PG8_LDB(B1, 0, 1); PG8_SCHED; PG8_LDA(At, 0, 0); PG8_STAGE(PG8_SA(1, 1), a1 + hstep, voffA);
;             PG8_WAIT_V(8); PG8_WAIT_L(0); PG8_BAR; PG8_MMA(0, 0, At, B0); PG8_MMA(0, 1, At, B1); PG8_BAR; PG8_SCHED;
;             PG8_LDA(At, 0, 1); PG8_STAGE(PG8_SB(0, 0), b2, voffB); PG8_STAGE(PG8_SB(0, 1), b2 + hstep, voffB); PG8_STAGE(PG8_SA(0, 0), a2, voffA);
;             PG8_WAIT_V(8); PG8_WAIT_L(0); PG8_BAR; PG8_MMA(1, 0, At, B0); PG8_MMA(1, 1, At, B1); PG8_BAR; PG8_SCHED;
.LBB0_519:
	s_ashr_i32 s55, s54, 31
	s_lshl_b64 s[56:57], s[54:55], 19
	s_add_u32 s56, s26, s56
	s_addc_u32 s57, s27, s57
	s_and_b64 s[58:59], s[4:5], exec
	s_cselect_b32 s55, s57, s65
	s_cselect_b32 s61, s56, s64
	s_ashr_i32 s53, s52, 31
	s_lshl_b64 s[58:59], s[52:53], 19
	s_add_u32 s58, s10, s58
	s_addc_u32 s59, s11, s59
	s_and_b64 s[68:69], s[4:5], exec
	s_cselect_b32 s53, s59, s67
	s_cselect_b32 s82, s58, s66
	s_add_u32 s64, s64, 0x40080
	s_addc_u32 s65, s65, 0
	s_add_u32 s83, s66, 0x100
	s_addc_u32 s84, s67, 0
	s_mov_b32 s85, -2
	s_waitcnt lgkmcnt(0)
	ds_read_b128 v[130:133], v214
	ds_read_b128 v[134:137], v214 offset:1024
	ds_read_b128 v[138:141], v214 offset:2048
	ds_read_b128 v[142:145], v214 offset:3072
	ds_read_b128 v[146:149], v215
	ds_read_b128 v[150:153], v215 offset:1024
	ds_read_b128 v[154:157], v215 offset:2048
	ds_read_b128 v[158:161], v215 offset:3072
	s_add_u32 s66, s64, 0xfffc0080
	s_addc_u32 s67, s65, -1
	s_cmp_eq_u32 s85, 12
	s_cselect_b32 s69, s55, s67
	s_cselect_b32 s68, s61, s66
	s_cselect_b32 s67, s53, s84
	s_cselect_b32 s66, s82, s83
	v_lshl_add_u64 v[222:223], s[64:65], 0, v[186:187]
	s_add_i32 m0, s63, 0xc000
	ds_read_b128 v[162:165], v216
	ds_read_b128 v[166:169], v216 offset:1024
	ds_read_b128 v[170:173], v216 offset:2048
	ds_read_b128 v[174:177], v216 offset:3072
	ds_read_b128 v[194:197], v216 offset:4096
	ds_read_b128 v[198:201], v216 offset:5120
	ds_read_b128 v[202:205], v216 offset:6144
	ds_read_b128 v[218:221], v216 offset:7168
	global_load_lds_dwordx4 v[222:223], off
	v_lshl_add_u64 v[222:223], s[64:65], 0, v[188:189]
	s_add_i32 m0, s63, 0xe000
	s_nop 0
	global_load_lds_dwordx4 v[222:223], off
	s_waitcnt vmcnt(8)
	s_waitcnt lgkmcnt(0)
	s_barrier
	s_setprio 3
	v_mfma_f32_16x16x32_bf16 v[126:129], v[130:133], v[162:165], 0
	v_mfma_f32_16x16x32_bf16 v[122:125], v[138:141], v[162:165], 0
	v_mfma_f32_16x16x32_bf16 v[110:113], v[130:133], v[170:173], 0
	v_mfma_f32_16x16x32_bf16 v[106:109], v[138:141], v[170:173], 0
	v_mfma_f32_16x16x32_bf16 v[94:97], v[130:133], v[194:197], 0
	v_mfma_f32_16x16x32_bf16 v[90:93], v[138:141], v[194:197], 0
	v_mfma_f32_16x16x32_bf16 v[78:81], v[130:133], v[202:205], 0
	v_mfma_f32_16x16x32_bf16 v[74:77], v[138:141], v[202:205], 0
	v_mfma_f32_16x16x32_bf16 v[126:129], v[134:137], v[166:169], v[126:129]
	v_mfma_f32_16x16x32_bf16 v[122:125], v[142:145], v[166:169], v[122:125]
	v_mfma_f32_16x16x32_bf16 v[110:113], v[134:137], v[174:177], v[110:113]
	v_mfma_f32_16x16x32_bf16 v[106:109], v[142:145], v[174:177], v[106:109]
	v_mfma_f32_16x16x32_bf16 v[94:97], v[134:137], v[198:201], v[94:97]
	v_mfma_f32_16x16x32_bf16 v[90:93], v[142:145], v[198:201], v[90:93]
	v_mfma_f32_16x16x32_bf16 v[78:81], v[134:137], v[218:221], v[78:81]
	v_mfma_f32_16x16x32_bf16 v[74:77], v[142:145], v[218:221], v[74:77]
	v_mfma_f32_16x16x32_bf16 v[118:121], v[146:149], v[162:165], 0
	v_mfma_f32_16x16x32_bf16 v[114:117], v[154:157], v[162:165], 0
	v_mfma_f32_16x16x32_bf16 v[102:105], v[146:149], v[170:173], 0
	v_mfma_f32_16x16x32_bf16 v[98:101], v[154:157], v[170:173], 0
	v_mfma_f32_16x16x32_bf16 v[86:89], v[146:149], v[194:197], 0
	v_mfma_f32_16x16x32_bf16 v[82:85], v[154:157], v[194:197], 0
	v_mfma_f32_16x16x32_bf16 v[70:73], v[146:149], v[202:205], 0
	v_mfma_f32_16x16x32_bf16 v[66:69], v[154:157], v[202:205], 0
	v_mfma_f32_16x16x32_bf16 v[118:121], v[150:153], v[166:169], v[118:121]
	v_mfma_f32_16x16x32_bf16 v[114:117], v[158:161], v[166:169], v[114:117]
	v_mfma_f32_16x16x32_bf16 v[102:105], v[150:153], v[174:177], v[102:105]
	v_mfma_f32_16x16x32_bf16 v[98:101], v[158:161], v[174:177], v[98:101]
	v_mfma_f32_16x16x32_bf16 v[86:89], v[150:153], v[198:201], v[86:89]
	v_mfma_f32_16x16x32_bf16 v[82:85], v[158:161], v[198:201], v[82:85]
	v_mfma_f32_16x16x32_bf16 v[70:73], v[150:153], v[218:221], v[70:73]
	v_mfma_f32_16x16x32_bf16 v[66:69], v[158:161], v[218:221], v[66:69]
	s_setprio 0
	s_barrier
	s_add_i32 s86, s80, s33
	v_lshl_add_u64 v[222:223], s[66:67], 0, v[180:181]
	s_mov_b32 m0, s86
	ds_read_b128 v[162:165], v216 offset:16384
	ds_read_b128 v[166:169], v216 offset:17408
	ds_read_b128 v[170:173], v216 offset:18432
	ds_read_b128 v[174:177], v216 offset:19456
	ds_read_b128 v[194:197], v216 offset:20480
	ds_read_b128 v[198:201], v216 offset:21504
	ds_read_b128 v[202:205], v216 offset:22528
	ds_read_b128 v[218:221], v216 offset:23552
	global_load_lds_dwordx4 v[222:223], off
	s_add_i32 m0, s86, 0x2000
	s_add_u32 s86, s66, 0x40000
	v_lshl_add_u64 v[224:225], s[66:67], 0, v[184:185]
	s_addc_u32 s87, s67, 0
	s_add_i32 s88, s81, s33
	global_load_lds_dwordx4 v[224:225], off
	v_lshl_add_u64 v[226:227], s[86:87], 0, v[180:181]
	s_mov_b32 m0, s88
	v_lshl_add_u64 v[228:229], s[68:69], 0, v[182:183]
	global_load_lds_dwordx4 v[226:227], off
	v_lshl_add_u64 v[226:227], s[86:87], 0, v[184:185]
	s_add_i32 m0, s88, 0x2000
	s_nop 0
	global_load_lds_dwordx4 v[226:227], off
	v_lshl_add_u64 v[226:227], s[68:69], 0, v[178:179]
	s_mov_b32 m0, s63
	s_nop 0
	global_load_lds_dwordx4 v[226:227], off
	s_mov_b32 m0, s70
	s_nop 0
	global_load_lds_dwordx4 v[228:229], off
	s_waitcnt vmcnt(8)
	s_waitcnt lgkmcnt(0)
	s_barrier
; #define PG8_STAGE(bufoff, gbase, voff) do { _Pragma("unroll") for (int _i = 0; _i < 2; ++_i) \
;         __builtin_amdgcn_global_load_lds((const unsigned*)((const char*)(gbase) + (voff)[_i]), (LAS unsigned*)(lds + (bufoff) + ldsw + _i * 8192), 16, 0, 0); } while (0)
; #define PG8_LDA(dst, b, h) do { _Pragma("unroll") for (int m = 0; m < 4; ++m) _Pragma("unroll") for (int k = 0; k < 2; ++k) dst[m][k] = *(const LAS bf16x8*)(lds + PG8_SA(b, h) + aoff + m * 2048 + k * 1024); } while (0)
; #define PG8_LDB(dst, b, h) do { _Pragma("unroll") for (int n = 0; n < 2; ++n) _Pragma("unroll") for (int k = 0; k < 2; ++k) dst[n][k] = *(const LAS bf16x8*)(lds + PG8_SB(b, h) + boff + n * 2048 + k * 1024); } while (0)
; #define PG8_MMA(ai, bj, At, Bt) do { __builtin_amdgcn_s_setprio(3); _Pragma("unroll") for (int m = 0; m < 4; ++m) _Pragma("unroll") for (int n = 0; n < 2; ++n) _Pragma("unroll") for (int k = 0; k < 2; ++k) \
;         acc[ai][bj][m][n] = __builtin_amdgcn_mfma_f32_16x16x32_bf16(Bt[n][k], At[m][k], acc[ai][bj][m][n], 0, 0, 0); __builtin_amdgcn_s_setprio(0); } while (0)
; #define PG8_WAIT_V(n) asm volatile("s_waitcnt vmcnt(" #n ")" ::: "memory")
; #define PG8_WAIT_L(n) asm volatile("s_waitcnt lgkmcnt(" #n ")" ::: "memory")
; #define PG8_BAR __builtin_amdgcn_s_barrier()
; #define PG8_SCHED __builtin_amdgcn_sched_barrier(0)
; template <class Epi, bool ALIGN_EPI>
; __device__ __forceinline__ void gemm_phase(LAS unsigned char* lds, const Gemm g, const StaticOrder& S, const Epi& E) {
;     ...
;             PG8_WAIT_V(8); PG8_WAIT_L(0); PG8_BAR; PG8_MMA(1, 0, At, B0); PG8_MMA(1, 1, At, B1); PG8_BAR; PG8_SCHED;
;             PG8_LDB(B0, 1, 0); PG8_LDB(B1, 1, 1); PG8_SCHED; PG8_LDA(At, 1, 0); PG8_STAGE(PG8_SA(0, 1), a2 + hstep, voffA);
;             PG8_WAIT_V(8); PG8_WAIT_L(0); PG8_BAR; PG8_MMA(0, 0, At, B0); PG8_MMA(0, 1, At, B1); PG8_BAR; PG8_SCHED;
	s_setprio 3
	v_mfma_f32_16x16x32_bf16 v[62:65], v[130:133], v[162:165], 0
	v_mfma_f32_16x16x32_bf16 v[58:61], v[138:141], v[162:165], 0
	v_mfma_f32_16x16x32_bf16 v[46:49], v[130:133], v[170:173], 0
	v_mfma_f32_16x16x32_bf16 v[42:45], v[138:141], v[170:173], 0
	v_mfma_f32_16x16x32_bf16 v[30:33], v[130:133], v[194:197], 0
	v_mfma_f32_16x16x32_bf16 v[26:29], v[138:141], v[194:197], 0
	v_mfma_f32_16x16x32_bf16 v[14:17], v[130:133], v[202:205], 0
	v_mfma_f32_16x16x32_bf16 v[10:13], v[138:141], v[202:205], 0
	v_mfma_f32_16x16x32_bf16 v[62:65], v[134:137], v[166:169], v[62:65]
	v_mfma_f32_16x16x32_bf16 v[58:61], v[142:145], v[166:169], v[58:61]
	v_mfma_f32_16x16x32_bf16 v[46:49], v[134:137], v[174:177], v[46:49]
	v_mfma_f32_16x16x32_bf16 v[42:45], v[142:145], v[174:177], v[42:45]
	v_mfma_f32_16x16x32_bf16 v[30:33], v[134:137], v[198:201], v[30:33]
	v_mfma_f32_16x16x32_bf16 v[26:29], v[142:145], v[198:201], v[26:29]
	v_mfma_f32_16x16x32_bf16 v[14:17], v[134:137], v[218:221], v[14:17]
	v_mfma_f32_16x16x32_bf16 v[10:13], v[142:145], v[218:221], v[10:13]
	v_mfma_f32_16x16x32_bf16 v[54:57], v[146:149], v[162:165], 0
	v_mfma_f32_16x16x32_bf16 v[50:53], v[154:157], v[162:165], 0
	v_mfma_f32_16x16x32_bf16 v[38:41], v[146:149], v[170:173], 0
	v_mfma_f32_16x16x32_bf16 v[34:37], v[154:157], v[170:173], 0
	v_mfma_f32_16x16x32_bf16 v[22:25], v[146:149], v[194:197], 0
	v_mfma_f32_16x16x32_bf16 v[18:21], v[154:157], v[194:197], 0
	v_mfma_f32_16x16x32_bf16 v[6:9], v[146:149], v[202:205], 0
	v_mfma_f32_16x16x32_bf16 v[2:5], v[154:157], v[202:205], 0
	v_mfma_f32_16x16x32_bf16 v[54:57], v[150:153], v[166:169], v[54:57]
	v_mfma_f32_16x16x32_bf16 v[50:53], v[158:161], v[166:169], v[50:53]
	v_mfma_f32_16x16x32_bf16 v[38:41], v[150:153], v[174:177], v[38:41]
	v_mfma_f32_16x16x32_bf16 v[34:37], v[158:161], v[174:177], v[34:37]
	v_mfma_f32_16x16x32_bf16 v[22:25], v[150:153], v[198:201], v[22:25]
	v_mfma_f32_16x16x32_bf16 v[18:21], v[158:161], v[198:201], v[18:21]
	v_mfma_f32_16x16x32_bf16 v[6:9], v[150:153], v[218:221], v[6:9]
	v_mfma_f32_16x16x32_bf16 v[2:5], v[158:161], v[218:221], v[2:5]
	s_setprio 0
	s_barrier
	s_add_i32 s86, 0, 0x18000
	s_add_i32 s87, 0, 0x1c000
	v_add_u32_e32 v142, s86, v212
	v_add_u32_e32 v158, s87, v212
	ds_read_b128 v[130:133], v142
	ds_read_b128 v[134:137], v142 offset:1024
	ds_read_b128 v[138:141], v142 offset:2048
	ds_read_b128 v[142:145], v142 offset:3072
	ds_read_b128 v[146:149], v158
	ds_read_b128 v[150:153], v158 offset:1024
	ds_read_b128 v[154:157], v158 offset:2048
	ds_read_b128 v[158:161], v158 offset:3072
	s_add_u32 s68, s68, 0x40000
	s_addc_u32 s69, s69, 0
	s_mov_b32 m0, s71
	v_lshl_add_u64 v[230:231], s[68:69], 0, v[178:179]
	ds_read_b128 v[162:165], v216 offset:32768
	ds_read_b128 v[166:169], v216 offset:33792
	ds_read_b128 v[170:173], v216 offset:34816
	ds_read_b128 v[174:177], v216 offset:35840
	ds_read_b128 v[194:197], v216 offset:36864
	ds_read_b128 v[198:201], v216 offset:37888
	ds_read_b128 v[202:205], v216 offset:38912
	ds_read_b128 v[218:221], v216 offset:39936
	global_load_lds_dwordx4 v[230:231], off
	v_lshl_add_u64 v[230:231], s[68:69], 0, v[182:183]
	s_mov_b32 m0, s72
	s_nop 0
	global_load_lds_dwordx4 v[230:231], off
	s_waitcnt vmcnt(8)
	s_waitcnt lgkmcnt(0)
	s_barrier
	s_setprio 3
	v_mfma_f32_16x16x32_bf16 v[126:129], v[130:133], v[162:165], v[126:129]
	v_mfma_f32_16x16x32_bf16 v[122:125], v[138:141], v[162:165], v[122:125]
	v_mfma_f32_16x16x32_bf16 v[110:113], v[130:133], v[170:173], v[110:113]
	v_mfma_f32_16x16x32_bf16 v[106:109], v[138:141], v[170:173], v[106:109]
	v_mfma_f32_16x16x32_bf16 v[94:97], v[130:133], v[194:197], v[94:97]
	v_mfma_f32_16x16x32_bf16 v[90:93], v[138:141], v[194:197], v[90:93]
	v_mfma_f32_16x16x32_bf16 v[78:81], v[130:133], v[202:205], v[78:81]
	v_mfma_f32_16x16x32_bf16 v[74:77], v[138:141], v[202:205], v[74:77]
	v_mfma_f32_16x16x32_bf16 v[126:129], v[134:137], v[166:169], v[126:129]
	v_mfma_f32_16x16x32_bf16 v[122:125], v[142:145], v[166:169], v[122:125]
	v_mfma_f32_16x16x32_bf16 v[110:113], v[134:137], v[174:177], v[110:113]
	v_mfma_f32_16x16x32_bf16 v[106:109], v[142:145], v[174:177], v[106:109]
	v_mfma_f32_16x16x32_bf16 v[94:97], v[134:137], v[198:201], v[94:97]
	v_mfma_f32_16x16x32_bf16 v[90:93], v[142:145], v[198:201], v[90:93]
	v_mfma_f32_16x16x32_bf16 v[78:81], v[134:137], v[218:221], v[78:81]
	v_mfma_f32_16x16x32_bf16 v[74:77], v[142:145], v[218:221], v[74:77]
	v_mfma_f32_16x16x32_bf16 v[118:121], v[146:149], v[162:165], v[118:121]
	v_mfma_f32_16x16x32_bf16 v[114:117], v[154:157], v[162:165], v[114:117]
	v_mfma_f32_16x16x32_bf16 v[102:105], v[146:149], v[170:173], v[102:105]
	v_mfma_f32_16x16x32_bf16 v[98:101], v[154:157], v[170:173], v[98:101]
	v_mfma_f32_16x16x32_bf16 v[86:89], v[146:149], v[194:197], v[86:89]
	v_mfma_f32_16x16x32_bf16 v[82:85], v[154:157], v[194:197], v[82:85]
	v_mfma_f32_16x16x32_bf16 v[70:73], v[146:149], v[202:205], v[70:73]
	v_mfma_f32_16x16x32_bf16 v[66:69], v[154:157], v[202:205], v[66:69]
	v_mfma_f32_16x16x32_bf16 v[118:121], v[150:153], v[166:169], v[118:121]
	v_mfma_f32_16x16x32_bf16 v[114:117], v[158:161], v[166:169], v[114:117]
	v_mfma_f32_16x16x32_bf16 v[102:105], v[150:153], v[174:177], v[102:105]
	v_mfma_f32_16x16x32_bf16 v[98:101], v[158:161], v[174:177], v[98:101]
	v_mfma_f32_16x16x32_bf16 v[86:89], v[150:153], v[198:201], v[86:89]
	v_mfma_f32_16x16x32_bf16 v[82:85], v[158:161], v[198:201], v[82:85]
	v_mfma_f32_16x16x32_bf16 v[70:73], v[150:153], v[218:221], v[70:73]
	v_mfma_f32_16x16x32_bf16 v[66:69], v[158:161], v[218:221], v[66:69]
	s_setprio 0
	s_barrier
; #define PG8_STAGE(bufoff, gbase, voff) do { _Pragma("unroll") for (int _i = 0; _i < 2; ++_i) \
;         __builtin_amdgcn_global_load_lds((const unsigned*)((const char*)(gbase) + (voff)[_i]), (LAS unsigned*)(lds + (bufoff) + ldsw + _i * 8192), 16, 0, 0); } while (0)
; #define PG8_LDA(dst, b, h) do { _Pragma("unroll") for (int m = 0; m < 4; ++m) _Pragma("unroll") for (int k = 0; k < 2; ++k) dst[m][k] = *(const LAS bf16x8*)(lds + PG8_SA(b, h) + aoff + m * 2048 + k * 1024); } while (0)
; #define PG8_LDB(dst, b, h) do { _Pragma("unroll") for (int n = 0; n < 2; ++n) _Pragma("unroll") for (int k = 0; k < 2; ++k) dst[n][k] = *(const LAS bf16x8*)(lds + PG8_SB(b, h) + boff + n * 2048 + k * 1024); } while (0)
; #define PG8_MMA(ai, bj, At, Bt) do { __builtin_amdgcn_s_setprio(3); _Pragma("unroll") for (int m = 0; m < 4; ++m) _Pragma("unroll") for (int n = 0; n < 2; ++n) _Pragma("unroll") for (int k = 0; k < 2; ++k) \
;         acc[ai][bj][m][n] = __builtin_amdgcn_mfma_f32_16x16x32_bf16(Bt[n][k], At[m][k], acc[ai][bj][m][n], 0, 0, 0); __builtin_amdgcn_s_setprio(0); } while (0)
; #define PG8_WAIT_V(n) asm volatile("s_waitcnt vmcnt(" #n ")" ::: "memory")
; #define PG8_WAIT_L(n) asm volatile("s_waitcnt lgkmcnt(" #n ")" ::: "memory")
; #define PG8_BAR __builtin_amdgcn_s_barrier()
; #define PG8_SCHED __builtin_amdgcn_sched_barrier(0)
; template <class Epi, bool ALIGN_EPI>
; __device__ __forceinline__ void gemm_phase(LAS unsigned char* lds, const Gemm g, const StaticOrder& S, const Epi& E) {
;     ...
;             PG8_LDB(B0, 0, 0); PG8_LDB(B1, 0, 1); PG8_SCHED; PG8_LDA(At, 0, 0); PG8_STAGE(PG8_SA(1, 1), a1 + hstep, voffA);
;             PG8_WAIT_V(8); PG8_WAIT_L(0); PG8_BAR; PG8_MMA(0, 0, At, B0); PG8_MMA(0, 1, At, B1); PG8_BAR; PG8_SCHED;
;     ...
;             PG8_LDA(At, 1, 1); PG8_STAGE(PG8_SB(1, 0), b3, voffB); PG8_STAGE(PG8_SB(1, 1), b3 + hstep, voffB); PG8_STAGE(PG8_SA(1, 0), a3, voffA);
;             PG8_WAIT_V(8); PG8_WAIT_L(0); PG8_BAR; PG8_MMA(1, 0, At, B0); PG8_MMA(1, 1, At, B1); PG8_BAR; PG8_SCHED;
	s_add_i32 s68, s86, s33
	v_lshl_add_u64 v[222:223], v[222:223], 0, s[18:19]
	s_mov_b32 m0, s68
	ds_read_b128 v[162:165], v216 offset:49152
	ds_read_b128 v[166:169], v216 offset:50176
	ds_read_b128 v[170:173], v216 offset:51200
	ds_read_b128 v[174:177], v216 offset:52224
	ds_read_b128 v[194:197], v216 offset:53248
	ds_read_b128 v[198:201], v216 offset:54272
	ds_read_b128 v[202:205], v216 offset:55296
	ds_read_b128 v[218:221], v216 offset:56320
	global_load_lds_dwordx4 v[222:223], off
	s_add_i32 m0, s68, 0x2000
	s_add_u32 s66, s66, 0x40080
	v_lshl_add_u64 v[222:223], v[224:225], 0, s[18:19]
	s_addc_u32 s67, s67, 0
	s_add_i32 s68, s87, s33
	global_load_lds_dwordx4 v[222:223], off
	v_lshl_add_u64 v[222:223], s[66:67], 0, v[180:181]
	s_mov_b32 m0, s68
	s_nop 0
	global_load_lds_dwordx4 v[222:223], off
	v_lshl_add_u64 v[222:223], s[66:67], 0, v[184:185]
	s_add_i32 m0, s68, 0x2000
	s_nop 0
	global_load_lds_dwordx4 v[222:223], off
	v_lshl_add_u64 v[222:223], v[226:227], 0, s[18:19]
	s_mov_b32 m0, s78
	s_nop 0
	global_load_lds_dwordx4 v[222:223], off
	v_lshl_add_u64 v[222:223], v[228:229], 0, s[18:19]
	s_mov_b32 m0, s79
	s_nop 0
	global_load_lds_dwordx4 v[222:223], off
	s_waitcnt vmcnt(8)
	s_waitcnt lgkmcnt(0)
	s_barrier
	s_setprio 3
	v_mfma_f32_16x16x32_bf16 v[62:65], v[130:133], v[162:165], v[62:65]
	v_mfma_f32_16x16x32_bf16 v[58:61], v[138:141], v[162:165], v[58:61]
	v_mfma_f32_16x16x32_bf16 v[46:49], v[130:133], v[170:173], v[46:49]
	v_mfma_f32_16x16x32_bf16 v[42:45], v[138:141], v[170:173], v[42:45]
	v_mfma_f32_16x16x32_bf16 v[30:33], v[130:133], v[194:197], v[30:33]
	v_mfma_f32_16x16x32_bf16 v[26:29], v[138:141], v[194:197], v[26:29]
	v_mfma_f32_16x16x32_bf16 v[14:17], v[130:133], v[202:205], v[14:17]
	v_mfma_f32_16x16x32_bf16 v[10:13], v[138:141], v[202:205], v[10:13]
	v_mfma_f32_16x16x32_bf16 v[62:65], v[134:137], v[166:169], v[62:65]
	v_mfma_f32_16x16x32_bf16 v[58:61], v[142:145], v[166:169], v[58:61]
	v_mfma_f32_16x16x32_bf16 v[46:49], v[134:137], v[174:177], v[46:49]
	v_mfma_f32_16x16x32_bf16 v[42:45], v[142:145], v[174:177], v[42:45]
	v_mfma_f32_16x16x32_bf16 v[30:33], v[134:137], v[198:201], v[30:33]
	v_mfma_f32_16x16x32_bf16 v[26:29], v[142:145], v[198:201], v[26:29]
	v_mfma_f32_16x16x32_bf16 v[14:17], v[134:137], v[218:221], v[14:17]
	v_mfma_f32_16x16x32_bf16 v[10:13], v[142:145], v[218:221], v[10:13]
	v_mfma_f32_16x16x32_bf16 v[54:57], v[146:149], v[162:165], v[54:57]
	v_mfma_f32_16x16x32_bf16 v[50:53], v[154:157], v[162:165], v[50:53]
	v_mfma_f32_16x16x32_bf16 v[38:41], v[146:149], v[170:173], v[38:41]
	v_mfma_f32_16x16x32_bf16 v[34:37], v[154:157], v[170:173], v[34:37]
	v_mfma_f32_16x16x32_bf16 v[22:25], v[146:149], v[194:197], v[22:25]
	v_mfma_f32_16x16x32_bf16 v[18:21], v[154:157], v[194:197], v[18:21]
	v_mfma_f32_16x16x32_bf16 v[6:9], v[146:149], v[202:205], v[6:9]
	v_mfma_f32_16x16x32_bf16 v[2:5], v[154:157], v[202:205], v[2:5]
	v_mfma_f32_16x16x32_bf16 v[54:57], v[150:153], v[166:169], v[54:57]
	v_mfma_f32_16x16x32_bf16 v[50:53], v[158:161], v[166:169], v[50:53]
	v_mfma_f32_16x16x32_bf16 v[38:41], v[150:153], v[174:177], v[38:41]
	v_mfma_f32_16x16x32_bf16 v[34:37], v[158:161], v[174:177], v[34:37]
	v_mfma_f32_16x16x32_bf16 v[22:25], v[150:153], v[198:201], v[22:25]
	v_mfma_f32_16x16x32_bf16 v[18:21], v[158:161], v[198:201], v[18:21]
	v_mfma_f32_16x16x32_bf16 v[6:9], v[150:153], v[218:221], v[6:9]
	v_mfma_f32_16x16x32_bf16 v[2:5], v[158:161], v[218:221], v[2:5]
	s_setprio 0
	s_barrier
	s_add_i32 s85, s85, 2
	s_add_u32 s64, s64, 0x100
	s_addc_u32 s65, s65, 0
	s_add_u32 s83, s83, 0x100
	s_addc_u32 s84, s84, 0
.LBB0_520:
	ds_read_b128 v[130:133], v214
	ds_read_b128 v[134:137], v214 offset:1024
	ds_read_b128 v[138:141], v214 offset:2048
	ds_read_b128 v[142:145], v214 offset:3072
	ds_read_b128 v[146:149], v215
	ds_read_b128 v[150:153], v215 offset:1024
	ds_read_b128 v[154:157], v215 offset:2048
	ds_read_b128 v[158:161], v215 offset:3072
	s_add_u32 s66, s64, 0xfffc0080
	s_addc_u32 s67, s65, -1
	s_cmp_eq_u32 s85, 12
	s_cselect_b32 s69, s55, s67
	s_cselect_b32 s68, s61, s66
	s_cselect_b32 s67, s53, s84
	s_cselect_b32 s66, s82, s83
	v_lshl_add_u64 v[222:223], s[64:65], 0, v[186:187]
	s_add_i32 m0, s63, 0xc000
	ds_read_b128 v[162:165], v216
	ds_read_b128 v[166:169], v216 offset:1024
	ds_read_b128 v[170:173], v216 offset:2048
	ds_read_b128 v[174:177], v216 offset:3072
	ds_read_b128 v[194:197], v216 offset:4096
	ds_read_b128 v[198:201], v216 offset:5120
	ds_read_b128 v[202:205], v216 offset:6144
	ds_read_b128 v[218:221], v216 offset:7168
	global_load_lds_dwordx4 v[222:223], off
	v_lshl_add_u64 v[222:223], s[64:65], 0, v[188:189]
	s_add_i32 m0, s63, 0xe000
	s_nop 0
	global_load_lds_dwordx4 v[222:223], off
	s_waitcnt vmcnt(8)
	s_waitcnt lgkmcnt(0)
	s_barrier
; #define PG8_STAGE(bufoff, gbase, voff) do { _Pragma("unroll") for (int _i = 0; _i < 2; ++_i) \
;         __builtin_amdgcn_global_load_lds((const unsigned*)((const char*)(gbase) + (voff)[_i]), (LAS unsigned*)(lds + (bufoff) + ldsw + _i * 8192), 16, 0, 0); } while (0)
; #define PG8_LDA(dst, b, h) do { _Pragma("unroll") for (int m = 0; m < 4; ++m) _Pragma("unroll") for (int k = 0; k < 2; ++k) dst[m][k] = *(const LAS bf16x8*)(lds + PG8_SA(b, h) + aoff + m * 2048 + k * 1024); } while (0)
; #define PG8_MMA(ai, bj, At, Bt) do { __builtin_amdgcn_s_setprio(3); _Pragma("unroll") for (int m = 0; m < 4; ++m) _Pragma("unroll") for (int n = 0; n < 2; ++n) _Pragma("unroll") for (int k = 0; k < 2; ++k) \
;         acc[ai][bj][m][n] = __builtin_amdgcn_mfma_f32_16x16x32_bf16(Bt[n][k], At[m][k], acc[ai][bj][m][n], 0, 0, 0); __builtin_amdgcn_s_setprio(0); } while (0)
; #define PG8_WAIT_V(n) asm volatile("s_waitcnt vmcnt(" #n ")" ::: "memory")
; #define PG8_WAIT_L(n) asm volatile("s_waitcnt lgkmcnt(" #n ")" ::: "memory")
; #define PG8_BAR __builtin_amdgcn_s_barrier()
; #define PG8_SCHED __builtin_amdgcn_sched_barrier(0)
; template <class Epi, bool ALIGN_EPI>
; __device__ __forceinline__ void gemm_phase(LAS unsigned char* lds, const Gemm g, const StaticOrder& S, const Epi& E) {
;     ...
;             PG8_WAIT_V(8); PG8_WAIT_L(0); PG8_BAR; PG8_MMA(0, 0, At, B0); PG8_MMA(0, 1, At, B1); PG8_BAR; PG8_SCHED;
;             PG8_LDA(At, 0, 1); PG8_STAGE(PG8_SB(0, 0), b2, voffB); PG8_STAGE(PG8_SB(0, 1), b2 + hstep, voffB); PG8_STAGE(PG8_SA(0, 0), a2, voffA);
;             PG8_WAIT_V(8); PG8_WAIT_L(0); PG8_BAR; PG8_MMA(1, 0, At, B0); PG8_MMA(1, 1, At, B1); PG8_BAR; PG8_SCHED;
	s_setprio 3
	v_mfma_f32_16x16x32_bf16 v[126:129], v[130:133], v[162:165], v[126:129]
	v_mfma_f32_16x16x32_bf16 v[122:125], v[138:141], v[162:165], v[122:125]
	v_mfma_f32_16x16x32_bf16 v[110:113], v[130:133], v[170:173], v[110:113]
	v_mfma_f32_16x16x32_bf16 v[106:109], v[138:141], v[170:173], v[106:109]
	v_mfma_f32_16x16x32_bf16 v[94:97], v[130:133], v[194:197], v[94:97]
	v_mfma_f32_16x16x32_bf16 v[90:93], v[138:141], v[194:197], v[90:93]
	v_mfma_f32_16x16x32_bf16 v[78:81], v[130:133], v[202:205], v[78:81]
	v_mfma_f32_16x16x32_bf16 v[74:77], v[138:141], v[202:205], v[74:77]
	v_mfma_f32_16x16x32_bf16 v[126:129], v[134:137], v[166:169], v[126:129]
	v_mfma_f32_16x16x32_bf16 v[122:125], v[142:145], v[166:169], v[122:125]
	v_mfma_f32_16x16x32_bf16 v[110:113], v[134:137], v[174:177], v[110:113]
	v_mfma_f32_16x16x32_bf16 v[106:109], v[142:145], v[174:177], v[106:109]
	v_mfma_f32_16x16x32_bf16 v[94:97], v[134:137], v[198:201], v[94:97]
	v_mfma_f32_16x16x32_bf16 v[90:93], v[142:145], v[198:201], v[90:93]
	v_mfma_f32_16x16x32_bf16 v[78:81], v[134:137], v[218:221], v[78:81]
	v_mfma_f32_16x16x32_bf16 v[74:77], v[142:145], v[218:221], v[74:77]
	v_mfma_f32_16x16x32_bf16 v[118:121], v[146:149], v[162:165], v[118:121]
	v_mfma_f32_16x16x32_bf16 v[114:117], v[154:157], v[162:165], v[114:117]
	v_mfma_f32_16x16x32_bf16 v[102:105], v[146:149], v[170:173], v[102:105]
	v_mfma_f32_16x16x32_bf16 v[98:101], v[154:157], v[170:173], v[98:101]
	v_mfma_f32_16x16x32_bf16 v[86:89], v[146:149], v[194:197], v[86:89]
	v_mfma_f32_16x16x32_bf16 v[82:85], v[154:157], v[194:197], v[82:85]
	v_mfma_f32_16x16x32_bf16 v[70:73], v[146:149], v[202:205], v[70:73]
	v_mfma_f32_16x16x32_bf16 v[66:69], v[154:157], v[202:205], v[66:69]
	v_mfma_f32_16x16x32_bf16 v[118:121], v[150:153], v[166:169], v[118:121]
	v_mfma_f32_16x16x32_bf16 v[114:117], v[158:161], v[166:169], v[114:117]
	v_mfma_f32_16x16x32_bf16 v[102:105], v[150:153], v[174:177], v[102:105]
	v_mfma_f32_16x16x32_bf16 v[98:101], v[158:161], v[174:177], v[98:101]
	v_mfma_f32_16x16x32_bf16 v[86:89], v[150:153], v[198:201], v[86:89]
	v_mfma_f32_16x16x32_bf16 v[82:85], v[158:161], v[198:201], v[82:85]
	v_mfma_f32_16x16x32_bf16 v[70:73], v[150:153], v[218:221], v[70:73]
	v_mfma_f32_16x16x32_bf16 v[66:69], v[158:161], v[218:221], v[66:69]
	s_setprio 0
	s_barrier
	s_add_i32 s86, s80, s33
	v_lshl_add_u64 v[222:223], s[66:67], 0, v[180:181]
	s_mov_b32 m0, s86
	ds_read_b128 v[162:165], v216 offset:16384
	ds_read_b128 v[166:169], v216 offset:17408
	ds_read_b128 v[170:173], v216 offset:18432
	ds_read_b128 v[174:177], v216 offset:19456
	ds_read_b128 v[194:197], v216 offset:20480
	ds_read_b128 v[198:201], v216 offset:21504
	ds_read_b128 v[202:205], v216 offset:22528
	ds_read_b128 v[218:221], v216 offset:23552
	global_load_lds_dwordx4 v[222:223], off
	s_add_i32 m0, s86, 0x2000
	s_add_u32 s86, s66, 0x40000
	v_lshl_add_u64 v[224:225], s[66:67], 0, v[184:185]
	s_addc_u32 s87, s67, 0
	s_add_i32 s88, s81, s33
	global_load_lds_dwordx4 v[224:225], off
	v_lshl_add_u64 v[226:227], s[86:87], 0, v[180:181]
	s_mov_b32 m0, s88
	v_lshl_add_u64 v[228:229], s[68:69], 0, v[182:183]
	global_load_lds_dwordx4 v[226:227], off
	v_lshl_add_u64 v[226:227], s[86:87], 0, v[184:185]
	s_add_i32 m0, s88, 0x2000
	s_nop 0
	global_load_lds_dwordx4 v[226:227], off
	v_lshl_add_u64 v[226:227], s[68:69], 0, v[178:179]
	s_mov_b32 m0, s63
	s_nop 0
	global_load_lds_dwordx4 v[226:227], off
	s_mov_b32 m0, s70
	s_nop 0
	global_load_lds_dwordx4 v[228:229], off
	s_waitcnt vmcnt(8)
	s_waitcnt lgkmcnt(0)
	s_barrier
	s_setprio 3
	v_mfma_f32_16x16x32_bf16 v[62:65], v[130:133], v[162:165], v[62:65]
	v_mfma_f32_16x16x32_bf16 v[58:61], v[138:141], v[162:165], v[58:61]
	v_mfma_f32_16x16x32_bf16 v[46:49], v[130:133], v[170:173], v[46:49]
	v_mfma_f32_16x16x32_bf16 v[42:45], v[138:141], v[170:173], v[42:45]
	v_mfma_f32_16x16x32_bf16 v[30:33], v[130:133], v[194:197], v[30:33]
	v_mfma_f32_16x16x32_bf16 v[26:29], v[138:141], v[194:197], v[26:29]
	v_mfma_f32_16x16x32_bf16 v[14:17], v[130:133], v[202:205], v[14:17]
	v_mfma_f32_16x16x32_bf16 v[10:13], v[138:141], v[202:205], v[10:13]
	v_mfma_f32_16x16x32_bf16 v[62:65], v[134:137], v[166:169], v[62:65]
	v_mfma_f32_16x16x32_bf16 v[58:61], v[142:145], v[166:169], v[58:61]
	v_mfma_f32_16x16x32_bf16 v[46:49], v[134:137], v[174:177], v[46:49]
	v_mfma_f32_16x16x32_bf16 v[42:45], v[142:145], v[174:177], v[42:45]
	v_mfma_f32_16x16x32_bf16 v[30:33], v[134:137], v[198:201], v[30:33]
	v_mfma_f32_16x16x32_bf16 v[26:29], v[142:145], v[198:201], v[26:29]
	v_mfma_f32_16x16x32_bf16 v[14:17], v[134:137], v[218:221], v[14:17]
	v_mfma_f32_16x16x32_bf16 v[10:13], v[142:145], v[218:221], v[10:13]
	v_mfma_f32_16x16x32_bf16 v[54:57], v[146:149], v[162:165], v[54:57]
	v_mfma_f32_16x16x32_bf16 v[50:53], v[154:157], v[162:165], v[50:53]
	v_mfma_f32_16x16x32_bf16 v[38:41], v[146:149], v[170:173], v[38:41]
	v_mfma_f32_16x16x32_bf16 v[34:37], v[154:157], v[170:173], v[34:37]
	v_mfma_f32_16x16x32_bf16 v[22:25], v[146:149], v[194:197], v[22:25]
	v_mfma_f32_16x16x32_bf16 v[18:21], v[154:157], v[194:197], v[18:21]
	v_mfma_f32_16x16x32_bf16 v[6:9], v[146:149], v[202:205], v[6:9]
	v_mfma_f32_16x16x32_bf16 v[2:5], v[154:157], v[202:205], v[2:5]
	v_mfma_f32_16x16x32_bf16 v[54:57], v[150:153], v[166:169], v[54:57]
	v_mfma_f32_16x16x32_bf16 v[50:53], v[158:161], v[166:169], v[50:53]
	v_mfma_f32_16x16x32_bf16 v[38:41], v[150:153], v[174:177], v[38:41]
	v_mfma_f32_16x16x32_bf16 v[34:37], v[158:161], v[174:177], v[34:37]
	v_mfma_f32_16x16x32_bf16 v[22:25], v[150:153], v[198:201], v[22:25]
	v_mfma_f32_16x16x32_bf16 v[18:21], v[158:161], v[198:201], v[18:21]
	v_mfma_f32_16x16x32_bf16 v[6:9], v[150:153], v[218:221], v[6:9]
	v_mfma_f32_16x16x32_bf16 v[2:5], v[158:161], v[218:221], v[2:5]
	s_setprio 0
	s_barrier
; #define PG8_STAGE(bufoff, gbase, voff) do { _Pragma("unroll") for (int _i = 0; _i < 2; ++_i) \
;         __builtin_amdgcn_global_load_lds((const unsigned*)((const char*)(gbase) + (voff)[_i]), (LAS unsigned*)(lds + (bufoff) + ldsw + _i * 8192), 16, 0, 0); } while (0)
; #define PG8_LDA(dst, b, h) do { _Pragma("unroll") for (int m = 0; m < 4; ++m) _Pragma("unroll") for (int k = 0; k < 2; ++k) dst[m][k] = *(const LAS bf16x8*)(lds + PG8_SA(b, h) + aoff + m * 2048 + k * 1024); } while (0)
; #define PG8_LDB(dst, b, h) do { _Pragma("unroll") for (int n = 0; n < 2; ++n) _Pragma("unroll") for (int k = 0; k < 2; ++k) dst[n][k] = *(const LAS bf16x8*)(lds + PG8_SB(b, h) + boff + n * 2048 + k * 1024); } while (0)
; #define PG8_MMA(ai, bj, At, Bt) do { __builtin_amdgcn_s_setprio(3); _Pragma("unroll") for (int m = 0; m < 4; ++m) _Pragma("unroll") for (int n = 0; n < 2; ++n) _Pragma("unroll") for (int k = 0; k < 2; ++k) \
;         acc[ai][bj][m][n] = __builtin_amdgcn_mfma_f32_16x16x32_bf16(Bt[n][k], At[m][k], acc[ai][bj][m][n], 0, 0, 0); __builtin_amdgcn_s_setprio(0); } while (0)
; #define PG8_WAIT_V(n) asm volatile("s_waitcnt vmcnt(" #n ")" ::: "memory")
; #define PG8_WAIT_L(n) asm volatile("s_waitcnt lgkmcnt(" #n ")" ::: "memory")
; #define PG8_BAR __builtin_amdgcn_s_barrier()
; #define PG8_SCHED __builtin_amdgcn_sched_barrier(0)
; template <class Epi, bool ALIGN_EPI>
; __device__ __forceinline__ void gemm_phase(LAS unsigned char* lds, const Gemm g, const StaticOrder& S, const Epi& E) {
;     ...
;             PG8_LDB(B0, 1, 0); PG8_LDB(B1, 1, 1); PG8_SCHED; PG8_LDA(At, 1, 0); PG8_STAGE(PG8_SA(0, 1), a2 + hstep, voffA);
;             PG8_WAIT_V(8); PG8_WAIT_L(0); PG8_BAR; PG8_MMA(0, 0, At, B0); PG8_MMA(0, 1, At, B1); PG8_BAR; PG8_SCHED;
	s_add_i32 s86, 0, 0x18000
	s_add_i32 s87, 0, 0x1c000
	v_add_u32_e32 v142, s86, v212
	v_add_u32_e32 v158, s87, v212
	ds_read_b128 v[130:133], v142
	ds_read_b128 v[134:137], v142 offset:1024
	ds_read_b128 v[138:141], v142 offset:2048
	ds_read_b128 v[142:145], v142 offset:3072
	ds_read_b128 v[146:149], v158
	ds_read_b128 v[150:153], v158 offset:1024
	ds_read_b128 v[154:157], v158 offset:2048
	ds_read_b128 v[158:161], v158 offset:3072
	s_add_u32 s68, s68, 0x40000
	s_addc_u32 s69, s69, 0
	s_mov_b32 m0, s71
	v_lshl_add_u64 v[230:231], s[68:69], 0, v[178:179]
	ds_read_b128 v[162:165], v216 offset:32768
	ds_read_b128 v[166:169], v216 offset:33792
	ds_read_b128 v[170:173], v216 offset:34816
	ds_read_b128 v[174:177], v216 offset:35840
	ds_read_b128 v[194:197], v216 offset:36864
	ds_read_b128 v[198:201], v216 offset:37888
	ds_read_b128 v[202:205], v216 offset:38912
	ds_read_b128 v[218:221], v216 offset:39936
	global_load_lds_dwordx4 v[230:231], off
	v_lshl_add_u64 v[230:231], s[68:69], 0, v[182:183]
	s_mov_b32 m0, s72
	s_nop 0
	global_load_lds_dwordx4 v[230:231], off
	s_waitcnt vmcnt(8)
	s_waitcnt lgkmcnt(0)
	s_barrier
	s_setprio 3
	v_mfma_f32_16x16x32_bf16 v[126:129], v[130:133], v[162:165], v[126:129]
	v_mfma_f32_16x16x32_bf16 v[122:125], v[138:141], v[162:165], v[122:125]
	v_mfma_f32_16x16x32_bf16 v[110:113], v[130:133], v[170:173], v[110:113]
	v_mfma_f32_16x16x32_bf16 v[106:109], v[138:141], v[170:173], v[106:109]
	v_mfma_f32_16x16x32_bf16 v[94:97], v[130:133], v[194:197], v[94:97]
	v_mfma_f32_16x16x32_bf16 v[90:93], v[138:141], v[194:197], v[90:93]
	v_mfma_f32_16x16x32_bf16 v[78:81], v[130:133], v[202:205], v[78:81]
	v_mfma_f32_16x16x32_bf16 v[74:77], v[138:141], v[202:205], v[74:77]
	v_mfma_f32_16x16x32_bf16 v[126:129], v[134:137], v[166:169], v[126:129]
	v_mfma_f32_16x16x32_bf16 v[122:125], v[142:145], v[166:169], v[122:125]
	v_mfma_f32_16x16x32_bf16 v[110:113], v[134:137], v[174:177], v[110:113]
	v_mfma_f32_16x16x32_bf16 v[106:109], v[142:145], v[174:177], v[106:109]
	v_mfma_f32_16x16x32_bf16 v[94:97], v[134:137], v[198:201], v[94:97]
	v_mfma_f32_16x16x32_bf16 v[90:93], v[142:145], v[198:201], v[90:93]
	v_mfma_f32_16x16x32_bf16 v[78:81], v[134:137], v[218:221], v[78:81]
	v_mfma_f32_16x16x32_bf16 v[74:77], v[142:145], v[218:221], v[74:77]
	v_mfma_f32_16x16x32_bf16 v[118:121], v[146:149], v[162:165], v[118:121]
	v_mfma_f32_16x16x32_bf16 v[114:117], v[154:157], v[162:165], v[114:117]
	v_mfma_f32_16x16x32_bf16 v[102:105], v[146:149], v[170:173], v[102:105]
	v_mfma_f32_16x16x32_bf16 v[98:101], v[154:157], v[170:173], v[98:101]
	v_mfma_f32_16x16x32_bf16 v[86:89], v[146:149], v[194:197], v[86:89]
	v_mfma_f32_16x16x32_bf16 v[82:85], v[154:157], v[194:197], v[82:85]
	v_mfma_f32_16x16x32_bf16 v[70:73], v[146:149], v[202:205], v[70:73]
	v_mfma_f32_16x16x32_bf16 v[66:69], v[154:157], v[202:205], v[66:69]
	v_mfma_f32_16x16x32_bf16 v[118:121], v[150:153], v[166:169], v[118:121]
	v_mfma_f32_16x16x32_bf16 v[114:117], v[158:161], v[166:169], v[114:117]
	v_mfma_f32_16x16x32_bf16 v[102:105], v[150:153], v[174:177], v[102:105]
	v_mfma_f32_16x16x32_bf16 v[98:101], v[158:161], v[174:177], v[98:101]
	v_mfma_f32_16x16x32_bf16 v[86:89], v[150:153], v[198:201], v[86:89]
	v_mfma_f32_16x16x32_bf16 v[82:85], v[158:161], v[198:201], v[82:85]
	v_mfma_f32_16x16x32_bf16 v[70:73], v[150:153], v[218:221], v[70:73]
	v_mfma_f32_16x16x32_bf16 v[66:69], v[158:161], v[218:221], v[66:69]
	s_setprio 0
	s_barrier
; #define PG8_STAGE(bufoff, gbase, voff) do { _Pragma("unroll") for (int _i = 0; _i < 2; ++_i) \
;         __builtin_amdgcn_global_load_lds((const unsigned*)((const char*)(gbase) + (voff)[_i]), (LAS unsigned*)(lds + (bufoff) + ldsw + _i * 8192), 16, 0, 0); } while (0)
; #define PG8_LDA(dst, b, h) do { _Pragma("unroll") for (int m = 0; m < 4; ++m) _Pragma("unroll") for (int k = 0; k < 2; ++k) dst[m][k] = *(const LAS bf16x8*)(lds + PG8_SA(b, h) + aoff + m * 2048 + k * 1024); } while (0)
; #define PG8_MMA(ai, bj, At, Bt) do { __builtin_amdgcn_s_setprio(3); _Pragma("unroll") for (int m = 0; m < 4; ++m) _Pragma("unroll") for (int n = 0; n < 2; ++n) _Pragma("unroll") for (int k = 0; k < 2; ++k) \
;         acc[ai][bj][m][n] = __builtin_amdgcn_mfma_f32_16x16x32_bf16(Bt[n][k], At[m][k], acc[ai][bj][m][n], 0, 0, 0); __builtin_amdgcn_s_setprio(0); } while (0)
; #define PG8_WAIT_V(n) asm volatile("s_waitcnt vmcnt(" #n ")" ::: "memory")
; #define PG8_WAIT_L(n) asm volatile("s_waitcnt lgkmcnt(" #n ")" ::: "memory")
; #define PG8_BAR __builtin_amdgcn_s_barrier()
; #define PG8_SCHED __builtin_amdgcn_sched_barrier(0)
; template <class Epi, bool ALIGN_EPI>
; __device__ __forceinline__ void gemm_phase(LAS unsigned char* lds, const Gemm g, const StaticOrder& S, const Epi& E) {
;     ...
;             PG8_LDA(At, 1, 1); PG8_STAGE(PG8_SB(1, 0), b3, voffB); PG8_STAGE(PG8_SB(1, 1), b3 + hstep, voffB); PG8_STAGE(PG8_SA(1, 0), a3, voffA);
;             PG8_WAIT_V(8); PG8_WAIT_L(0); PG8_BAR; PG8_MMA(1, 0, At, B0); PG8_MMA(1, 1, At, B1); PG8_BAR; PG8_SCHED;
;         }
;         if constexpr (ALIGN_EPI) { if (wr == 0) PG8_BAR; }
	s_add_i32 s68, s86, s33
	v_lshl_add_u64 v[222:223], v[222:223], 0, s[18:19]
	s_mov_b32 m0, s68
	ds_read_b128 v[162:165], v216 offset:49152
	ds_read_b128 v[166:169], v216 offset:50176
	ds_read_b128 v[170:173], v216 offset:51200
	ds_read_b128 v[174:177], v216 offset:52224
	ds_read_b128 v[194:197], v216 offset:53248
	ds_read_b128 v[198:201], v216 offset:54272
	ds_read_b128 v[202:205], v216 offset:55296
	ds_read_b128 v[218:221], v216 offset:56320
	global_load_lds_dwordx4 v[222:223], off
	s_add_i32 m0, s68, 0x2000
	s_add_u32 s66, s66, 0x40080
	v_lshl_add_u64 v[222:223], v[224:225], 0, s[18:19]
	s_addc_u32 s67, s67, 0
	s_add_i32 s68, s87, s33
	global_load_lds_dwordx4 v[222:223], off
	v_lshl_add_u64 v[222:223], s[66:67], 0, v[180:181]
	s_mov_b32 m0, s68
	s_nop 0
	global_load_lds_dwordx4 v[222:223], off
	v_lshl_add_u64 v[222:223], s[66:67], 0, v[184:185]
	s_add_i32 m0, s68, 0x2000
	s_nop 0
	global_load_lds_dwordx4 v[222:223], off
	v_lshl_add_u64 v[222:223], v[226:227], 0, s[18:19]
	s_mov_b32 m0, s78
	s_nop 0
	global_load_lds_dwordx4 v[222:223], off
	v_lshl_add_u64 v[222:223], v[228:229], 0, s[18:19]
	s_mov_b32 m0, s79
	s_nop 0
	global_load_lds_dwordx4 v[222:223], off
	s_waitcnt vmcnt(8)
	s_waitcnt lgkmcnt(0)
	s_barrier
	s_setprio 3
	v_mfma_f32_16x16x32_bf16 v[62:65], v[130:133], v[162:165], v[62:65]
	v_mfma_f32_16x16x32_bf16 v[58:61], v[138:141], v[162:165], v[58:61]
	v_mfma_f32_16x16x32_bf16 v[46:49], v[130:133], v[170:173], v[46:49]
	v_mfma_f32_16x16x32_bf16 v[42:45], v[138:141], v[170:173], v[42:45]
	v_mfma_f32_16x16x32_bf16 v[30:33], v[130:133], v[194:197], v[30:33]
	v_mfma_f32_16x16x32_bf16 v[26:29], v[138:141], v[194:197], v[26:29]
	v_mfma_f32_16x16x32_bf16 v[14:17], v[130:133], v[202:205], v[14:17]
	v_mfma_f32_16x16x32_bf16 v[10:13], v[138:141], v[202:205], v[10:13]
	v_mfma_f32_16x16x32_bf16 v[62:65], v[134:137], v[166:169], v[62:65]
	v_mfma_f32_16x16x32_bf16 v[58:61], v[142:145], v[166:169], v[58:61]
	v_mfma_f32_16x16x32_bf16 v[46:49], v[134:137], v[174:177], v[46:49]
	v_mfma_f32_16x16x32_bf16 v[42:45], v[142:145], v[174:177], v[42:45]
	v_mfma_f32_16x16x32_bf16 v[30:33], v[134:137], v[198:201], v[30:33]
	v_mfma_f32_16x16x32_bf16 v[26:29], v[142:145], v[198:201], v[26:29]
	v_mfma_f32_16x16x32_bf16 v[14:17], v[134:137], v[218:221], v[14:17]
	v_mfma_f32_16x16x32_bf16 v[10:13], v[142:145], v[218:221], v[10:13]
	v_mfma_f32_16x16x32_bf16 v[54:57], v[146:149], v[162:165], v[54:57]
	v_mfma_f32_16x16x32_bf16 v[50:53], v[154:157], v[162:165], v[50:53]
	v_mfma_f32_16x16x32_bf16 v[38:41], v[146:149], v[170:173], v[38:41]
	v_mfma_f32_16x16x32_bf16 v[34:37], v[154:157], v[170:173], v[34:37]
	v_mfma_f32_16x16x32_bf16 v[22:25], v[146:149], v[194:197], v[22:25]
	v_mfma_f32_16x16x32_bf16 v[18:21], v[154:157], v[194:197], v[18:21]
	v_mfma_f32_16x16x32_bf16 v[6:9], v[146:149], v[202:205], v[6:9]
	v_mfma_f32_16x16x32_bf16 v[2:5], v[154:157], v[202:205], v[2:5]
	v_mfma_f32_16x16x32_bf16 v[54:57], v[150:153], v[166:169], v[54:57]
	v_mfma_f32_16x16x32_bf16 v[50:53], v[158:161], v[166:169], v[50:53]
	v_mfma_f32_16x16x32_bf16 v[38:41], v[150:153], v[174:177], v[38:41]
	v_mfma_f32_16x16x32_bf16 v[34:37], v[158:161], v[174:177], v[34:37]
	v_mfma_f32_16x16x32_bf16 v[22:25], v[150:153], v[198:201], v[22:25]
	v_mfma_f32_16x16x32_bf16 v[18:21], v[158:161], v[198:201], v[18:21]
	v_mfma_f32_16x16x32_bf16 v[6:9], v[150:153], v[218:221], v[6:9]
	v_mfma_f32_16x16x32_bf16 v[2:5], v[158:161], v[218:221], v[2:5]
	s_setprio 0
	s_barrier
	s_add_i32 s85, s85, 2
	s_add_u32 s64, s64, 0x100
	s_addc_u32 s65, s65, 0
	s_add_u32 s83, s83, 0x100
	s_addc_u32 s84, s84, 0
	s_cmp_gt_u32 s85, 13
	s_cbranch_scc0 .LBB0_520
	s_and_b64 vcc, exec, s[50:51]
	s_cbranch_vccz .LBB0_523
	s_barrier

; #define PG8_STAGE(bufoff, gbase, voff) do { _Pragma("unroll") for (int _i = 0; _i < 2; ++_i) \
;         __builtin_amdgcn_global_load_lds((const unsigned*)((const char*)(gbase) + (voff)[_i]), (LAS unsigned*)(lds + (bufoff) + ldsw + _i * 8192), 16, 0, 0); } while (0)
; #define PG8_LDA(dst, b, h) do { _Pragma("unroll") for (int m = 0; m < 4; ++m) _Pragma("unroll") for (int k = 0; k < 2; ++k) dst[m][k] = *(const LAS bf16x8*)(lds + PG8_SA(b, h) + aoff + m * 2048 + k * 1024); } while (0)
; #define PG8_LDB(dst, b, h) do { _Pragma("unroll") for (int n = 0; n < 2; ++n) _Pragma("unroll") for (int k = 0; k < 2; ++k) dst[n][k] = *(const LAS bf16x8*)(lds + PG8_SB(b, h) + boff + n * 2048 + k * 1024); } while (0)
; #define PG8_MMA(ai, bj, At, Bt) do { __builtin_amdgcn_s_setprio(3); _Pragma("unroll") for (int m = 0; m < 4; ++m) _Pragma("unroll") for (int n = 0; n < 2; ++n) _Pragma("unroll") for (int k = 0; k < 2; ++k) \
;         acc[ai][bj][m][n] = __builtin_amdgcn_mfma_f32_16x16x32_bf16(Bt[n][k], At[m][k], acc[ai][bj][m][n], 0, 0, 0); __builtin_amdgcn_s_setprio(0); } while (0)
; #define PG8_BAR __builtin_amdgcn_s_barrier()
; template <class Epi, bool ALIGN_EPI>
; __device__ __forceinline__ void gemm_phase(LAS unsigned char* lds, const Gemm g, const StaticOrder& S, const Epi& E) {
;     ...
;         const bool has_next = S.next(ui + 1, nxt);
;         const char* nA = has_next ? (const char*)g.A + (size_t)nxt.pm * tstep : cA; const char* nB = has_next ? (const char*)g.Bt + (size_t)nxt.pn * tstep : cB;
;         for (int t = 0; t < nt; t += 2) {
;             const bool last = (t == nt - 2);
;             const char* a1 = cA + (size_t)(t + 1) * kstep;
;             const char* a2 = last ? nA : cA + (size_t)(t + 2) * kstep; const char* b2 = last ? nB : cB + (size_t)(t + 2) * kstep;
;             const char* a3 = a2 + kstep; const char* b3 = b2 + kstep;
;             PG8_LDB(B0, 0, 0); PG8_LDB(B1, 0, 1); PG8_SCHED; PG8_LDA(At, 0, 0); PG8_STAGE(PG8_SA(1, 1), a1 + hstep, voffA);
;             PG8_WAIT_V(8); PG8_WAIT_L(0); PG8_BAR; PG8_MMA(0, 0, At, B0); PG8_MMA(0, 1, At, B1); PG8_BAR; PG8_SCHED;
;             PG8_LDA(At, 0, 1); PG8_STAGE(PG8_SB(0, 0), b2, voffB); PG8_STAGE(PG8_SB(0, 1), b2 + hstep, voffB); PG8_STAGE(PG8_SA(0, 0), a2, voffA);
;             PG8_WAIT_V(8); PG8_WAIT_L(0); PG8_BAR; PG8_MMA(1, 0, At, B0); PG8_MMA(1, 1, At, B1); PG8_BAR; PG8_SCHED;
.LBB0_608:
	s_ashr_i32 s63, s62, 31
	s_lshl_b64 s[10:11], s[62:63], 19
	s_add_u32 s64, s34, s10
	s_addc_u32 s65, s35, s11
	s_and_b64 s[10:11], s[0:1], exec
	s_cselect_b32 s12, s65, s7
	s_cselect_b32 s13, s64, s6
	s_ashr_i32 s61, s60, 31
	s_lshl_b64 s[10:11], s[60:61], 19
	s_add_u32 s66, s52, s10
	s_addc_u32 s67, s53, s11
	s_and_b64 s[10:11], s[0:1], exec
	s_cselect_b32 s14, s67, s9
	s_cselect_b32 s15, s66, s8
	s_add_u32 s6, s6, 0x40080
	s_addc_u32 s7, s7, 0
	s_add_u32 s16, s8, 0x100
	s_addc_u32 s17, s9, 0
	s_mov_b32 s61, -2
	ds_read_b128 v[146:149], v168
	ds_read_b128 v[150:153], v168 offset:1024
	ds_read_b128 v[154:157], v168 offset:2048
	ds_read_b128 v[158:161], v168 offset:3072
	ds_read_b128 v[172:175], v169
	ds_read_b128 v[176:179], v169 offset:1024
	ds_read_b128 v[180:183], v169 offset:2048
	ds_read_b128 v[184:187], v169 offset:3072
	s_add_u32 s8, s6, 0xfffc0080
	s_addc_u32 s9, s7, -1
	s_cmp_eq_u32 s61, 12
	s_cselect_b32 s11, s12, s9
	s_cselect_b32 s10, s13, s8
	s_cselect_b32 s9, s14, s17
	s_cselect_b32 s8, s15, s16
	v_lshl_add_u64 v[220:221], s[6:7], 0, v[138:139]
	s_add_i32 m0, s70, 0xc000
	ds_read_b128 v[188:191], v170
	ds_read_b128 v[192:195], v170 offset:1024
	ds_read_b128 v[196:199], v170 offset:2048
	ds_read_b128 v[200:203], v170 offset:3072
	ds_read_b128 v[204:207], v170 offset:4096
	ds_read_b128 v[208:211], v170 offset:5120
	ds_read_b128 v[212:215], v170 offset:6144
	ds_read_b128 v[216:219], v170 offset:7168
	global_load_lds_dwordx4 v[220:221], off
	v_lshl_add_u64 v[220:221], s[6:7], 0, v[140:141]
	s_add_i32 m0, s70, 0xe000
	s_nop 0
	global_load_lds_dwordx4 v[220:221], off
	s_waitcnt vmcnt(8)
	s_waitcnt lgkmcnt(0)
	s_barrier
	s_setprio 3
	v_mfma_f32_16x16x32_bf16 v[126:129], v[146:149], v[188:191], 0
	v_mfma_f32_16x16x32_bf16 v[118:121], v[154:157], v[188:191], 0
	v_mfma_f32_16x16x32_bf16 v[110:113], v[146:149], v[196:199], 0
	v_mfma_f32_16x16x32_bf16 v[102:105], v[154:157], v[196:199], 0
	v_mfma_f32_16x16x32_bf16 v[94:97], v[146:149], v[204:207], 0
	v_mfma_f32_16x16x32_bf16 v[86:89], v[154:157], v[204:207], 0
	v_mfma_f32_16x16x32_bf16 v[78:81], v[146:149], v[212:215], 0
	v_mfma_f32_16x16x32_bf16 v[70:73], v[154:157], v[212:215], 0
	v_mfma_f32_16x16x32_bf16 v[126:129], v[150:153], v[192:195], v[126:129]
	v_mfma_f32_16x16x32_bf16 v[118:121], v[158:161], v[192:195], v[118:121]
	v_mfma_f32_16x16x32_bf16 v[110:113], v[150:153], v[200:203], v[110:113]
	v_mfma_f32_16x16x32_bf16 v[102:105], v[158:161], v[200:203], v[102:105]
	v_mfma_f32_16x16x32_bf16 v[94:97], v[150:153], v[208:211], v[94:97]
	v_mfma_f32_16x16x32_bf16 v[86:89], v[158:161], v[208:211], v[86:89]
	v_mfma_f32_16x16x32_bf16 v[78:81], v[150:153], v[216:219], v[78:81]
	v_mfma_f32_16x16x32_bf16 v[70:73], v[158:161], v[216:219], v[70:73]
	v_mfma_f32_16x16x32_bf16 v[122:125], v[172:175], v[188:191], 0
	v_mfma_f32_16x16x32_bf16 v[114:117], v[180:183], v[188:191], 0
	v_mfma_f32_16x16x32_bf16 v[106:109], v[172:175], v[196:199], 0
	v_mfma_f32_16x16x32_bf16 v[98:101], v[180:183], v[196:199], 0
	v_mfma_f32_16x16x32_bf16 v[90:93], v[172:175], v[204:207], 0
	v_mfma_f32_16x16x32_bf16 v[82:85], v[180:183], v[204:207], 0
	v_mfma_f32_16x16x32_bf16 v[74:77], v[172:175], v[212:215], 0
	v_mfma_f32_16x16x32_bf16 v[66:69], v[180:183], v[212:215], 0
	v_mfma_f32_16x16x32_bf16 v[122:125], v[176:179], v[192:195], v[122:125]
	v_mfma_f32_16x16x32_bf16 v[114:117], v[184:187], v[192:195], v[114:117]
	v_mfma_f32_16x16x32_bf16 v[106:109], v[176:179], v[200:203], v[106:109]
	v_mfma_f32_16x16x32_bf16 v[98:101], v[184:187], v[200:203], v[98:101]
	v_mfma_f32_16x16x32_bf16 v[90:93], v[176:179], v[208:211], v[90:93]
	v_mfma_f32_16x16x32_bf16 v[82:85], v[184:187], v[208:211], v[82:85]
	v_mfma_f32_16x16x32_bf16 v[74:77], v[176:179], v[216:219], v[74:77]
	v_mfma_f32_16x16x32_bf16 v[66:69], v[184:187], v[216:219], v[66:69]
	s_setprio 0
	s_barrier
	s_add_i32 s63, s80, s33
	v_lshl_add_u64 v[220:221], s[8:9], 0, v[132:133]
	s_mov_b32 m0, s63
	ds_read_b128 v[188:191], v170 offset:16384
	ds_read_b128 v[192:195], v170 offset:17408
	ds_read_b128 v[196:199], v170 offset:18432
	ds_read_b128 v[200:203], v170 offset:19456
	ds_read_b128 v[204:207], v170 offset:20480
	ds_read_b128 v[208:211], v170 offset:21504
	ds_read_b128 v[212:215], v170 offset:22528
	ds_read_b128 v[216:219], v170 offset:23552
	global_load_lds_dwordx4 v[220:221], off
	s_add_i32 m0, s63, 0x2000
	s_add_u32 s84, s8, 0x40000
	v_lshl_add_u64 v[222:223], s[8:9], 0, v[136:137]
	s_addc_u32 s85, s9, 0
	s_add_i32 s63, s81, s33
	global_load_lds_dwordx4 v[222:223], off
	v_lshl_add_u64 v[224:225], s[84:85], 0, v[132:133]
	s_mov_b32 m0, s63
	v_lshl_add_u64 v[226:227], s[10:11], 0, v[134:135]
	global_load_lds_dwordx4 v[224:225], off
	v_lshl_add_u64 v[224:225], s[84:85], 0, v[136:137]
	s_add_i32 m0, s63, 0x2000
	s_nop 0
	global_load_lds_dwordx4 v[224:225], off
	v_lshl_add_u64 v[224:225], s[10:11], 0, v[130:131]
	s_mov_b32 m0, s70
	s_nop 0
	global_load_lds_dwordx4 v[224:225], off
	s_mov_b32 m0, s71
	s_nop 0
	global_load_lds_dwordx4 v[226:227], off
	s_waitcnt vmcnt(8)
	s_waitcnt lgkmcnt(0)
	s_barrier
; #define PG8_STAGE(bufoff, gbase, voff) do { _Pragma("unroll") for (int _i = 0; _i < 2; ++_i) \
;         __builtin_amdgcn_global_load_lds((const unsigned*)((const char*)(gbase) + (voff)[_i]), (LAS unsigned*)(lds + (bufoff) + ldsw + _i * 8192), 16, 0, 0); } while (0)
; #define PG8_LDA(dst, b, h) do { _Pragma("unroll") for (int m = 0; m < 4; ++m) _Pragma("unroll") for (int k = 0; k < 2; ++k) dst[m][k] = *(const LAS bf16x8*)(lds + PG8_SA(b, h) + aoff + m * 2048 + k * 1024); } while (0)
; #define PG8_LDB(dst, b, h) do { _Pragma("unroll") for (int n = 0; n < 2; ++n) _Pragma("unroll") for (int k = 0; k < 2; ++k) dst[n][k] = *(const LAS bf16x8*)(lds + PG8_SB(b, h) + boff + n * 2048 + k * 1024); } while (0)
; #define PG8_MMA(ai, bj, At, Bt) do { __builtin_amdgcn_s_setprio(3); _Pragma("unroll") for (int m = 0; m < 4; ++m) _Pragma("unroll") for (int n = 0; n < 2; ++n) _Pragma("unroll") for (int k = 0; k < 2; ++k) \
;         acc[ai][bj][m][n] = __builtin_amdgcn_mfma_f32_16x16x32_bf16(Bt[n][k], At[m][k], acc[ai][bj][m][n], 0, 0, 0); __builtin_amdgcn_s_setprio(0); } while (0)
; #define PG8_WAIT_V(n) asm volatile("s_waitcnt vmcnt(" #n ")" ::: "memory")
; #define PG8_WAIT_L(n) asm volatile("s_waitcnt lgkmcnt(" #n ")" ::: "memory")
; #define PG8_BAR __builtin_amdgcn_s_barrier()
; #define PG8_SCHED __builtin_amdgcn_sched_barrier(0)
; template <class Epi, bool ALIGN_EPI>
; __device__ __forceinline__ void gemm_phase(LAS unsigned char* lds, const Gemm g, const StaticOrder& S, const Epi& E) {
;     ...
;             PG8_WAIT_V(8); PG8_WAIT_L(0); PG8_BAR; PG8_MMA(1, 0, At, B0); PG8_MMA(1, 1, At, B1); PG8_BAR; PG8_SCHED;
;             PG8_LDB(B0, 1, 0); PG8_LDB(B1, 1, 1); PG8_SCHED; PG8_LDA(At, 1, 0); PG8_STAGE(PG8_SA(0, 1), a2 + hstep, voffA);
;             PG8_WAIT_V(8); PG8_WAIT_L(0); PG8_BAR; PG8_MMA(0, 0, At, B0); PG8_MMA(0, 1, At, B1); PG8_BAR; PG8_SCHED;
	s_setprio 3
	v_mfma_f32_16x16x32_bf16 v[62:65], v[146:149], v[188:191], 0
	v_mfma_f32_16x16x32_bf16 v[54:57], v[154:157], v[188:191], 0
	v_mfma_f32_16x16x32_bf16 v[46:49], v[146:149], v[196:199], 0
	v_mfma_f32_16x16x32_bf16 v[38:41], v[154:157], v[196:199], 0
	v_mfma_f32_16x16x32_bf16 v[30:33], v[146:149], v[204:207], 0
	v_mfma_f32_16x16x32_bf16 v[22:25], v[154:157], v[204:207], 0
	v_mfma_f32_16x16x32_bf16 v[14:17], v[146:149], v[212:215], 0
	v_mfma_f32_16x16x32_bf16 v[6:9], v[154:157], v[212:215], 0
	v_mfma_f32_16x16x32_bf16 v[62:65], v[150:153], v[192:195], v[62:65]
	v_mfma_f32_16x16x32_bf16 v[54:57], v[158:161], v[192:195], v[54:57]
	v_mfma_f32_16x16x32_bf16 v[46:49], v[150:153], v[200:203], v[46:49]
	v_mfma_f32_16x16x32_bf16 v[38:41], v[158:161], v[200:203], v[38:41]
	v_mfma_f32_16x16x32_bf16 v[30:33], v[150:153], v[208:211], v[30:33]
	v_mfma_f32_16x16x32_bf16 v[22:25], v[158:161], v[208:211], v[22:25]
	v_mfma_f32_16x16x32_bf16 v[14:17], v[150:153], v[216:219], v[14:17]
	v_mfma_f32_16x16x32_bf16 v[6:9], v[158:161], v[216:219], v[6:9]
	v_mfma_f32_16x16x32_bf16 v[58:61], v[172:175], v[188:191], 0
	v_mfma_f32_16x16x32_bf16 v[50:53], v[180:183], v[188:191], 0
	v_mfma_f32_16x16x32_bf16 v[42:45], v[172:175], v[196:199], 0
	v_mfma_f32_16x16x32_bf16 v[34:37], v[180:183], v[196:199], 0
	v_mfma_f32_16x16x32_bf16 v[26:29], v[172:175], v[204:207], 0
	v_mfma_f32_16x16x32_bf16 v[18:21], v[180:183], v[204:207], 0
	v_mfma_f32_16x16x32_bf16 v[10:13], v[172:175], v[212:215], 0
	v_mfma_f32_16x16x32_bf16 v[2:5], v[180:183], v[212:215], 0
	v_mfma_f32_16x16x32_bf16 v[58:61], v[176:179], v[192:195], v[58:61]
	v_mfma_f32_16x16x32_bf16 v[50:53], v[184:187], v[192:195], v[50:53]
	v_mfma_f32_16x16x32_bf16 v[42:45], v[176:179], v[200:203], v[42:45]
	v_mfma_f32_16x16x32_bf16 v[34:37], v[184:187], v[200:203], v[34:37]
	v_mfma_f32_16x16x32_bf16 v[26:29], v[176:179], v[208:211], v[26:29]
	v_mfma_f32_16x16x32_bf16 v[18:21], v[184:187], v[208:211], v[18:21]
	v_mfma_f32_16x16x32_bf16 v[10:13], v[176:179], v[216:219], v[10:13]
	v_mfma_f32_16x16x32_bf16 v[2:5], v[184:187], v[216:219], v[2:5]
	s_setprio 0
	s_barrier
	s_add_i32 s63, 0, 0x18000
	s_add_i32 s84, 0, 0x1c000
	v_add_u32_e32 v158, s63, v166
	v_add_u32_e32 v184, s84, v166
	ds_read_b128 v[146:149], v158
	ds_read_b128 v[150:153], v158 offset:1024
	ds_read_b128 v[154:157], v158 offset:2048
	ds_read_b128 v[158:161], v158 offset:3072
	ds_read_b128 v[172:175], v184
	ds_read_b128 v[176:179], v184 offset:1024
	ds_read_b128 v[180:183], v184 offset:2048
	ds_read_b128 v[184:187], v184 offset:3072
	s_add_u32 s10, s10, 0x40000
	s_addc_u32 s11, s11, 0
	s_mov_b32 m0, s72
	v_lshl_add_u64 v[228:229], s[10:11], 0, v[130:131]
	ds_read_b128 v[188:191], v170 offset:32768
	ds_read_b128 v[192:195], v170 offset:33792
	ds_read_b128 v[196:199], v170 offset:34816
	ds_read_b128 v[200:203], v170 offset:35840
	ds_read_b128 v[204:207], v170 offset:36864
	ds_read_b128 v[208:211], v170 offset:37888
	ds_read_b128 v[212:215], v170 offset:38912
	ds_read_b128 v[216:219], v170 offset:39936
	global_load_lds_dwordx4 v[228:229], off
	v_lshl_add_u64 v[228:229], s[10:11], 0, v[134:135]
	s_mov_b32 m0, s73
	s_nop 0
	global_load_lds_dwordx4 v[228:229], off
	s_waitcnt vmcnt(8)
	s_waitcnt lgkmcnt(0)
	s_barrier
	s_setprio 3
	v_mfma_f32_16x16x32_bf16 v[126:129], v[146:149], v[188:191], v[126:129]
	v_mfma_f32_16x16x32_bf16 v[118:121], v[154:157], v[188:191], v[118:121]
	v_mfma_f32_16x16x32_bf16 v[110:113], v[146:149], v[196:199], v[110:113]
	v_mfma_f32_16x16x32_bf16 v[102:105], v[154:157], v[196:199], v[102:105]
	v_mfma_f32_16x16x32_bf16 v[94:97], v[146:149], v[204:207], v[94:97]
	v_mfma_f32_16x16x32_bf16 v[86:89], v[154:157], v[204:207], v[86:89]
	v_mfma_f32_16x16x32_bf16 v[78:81], v[146:149], v[212:215], v[78:81]
	v_mfma_f32_16x16x32_bf16 v[70:73], v[154:157], v[212:215], v[70:73]
	v_mfma_f32_16x16x32_bf16 v[126:129], v[150:153], v[192:195], v[126:129]
	v_mfma_f32_16x16x32_bf16 v[118:121], v[158:161], v[192:195], v[118:121]
	v_mfma_f32_16x16x32_bf16 v[110:113], v[150:153], v[200:203], v[110:113]
	v_mfma_f32_16x16x32_bf16 v[102:105], v[158:161], v[200:203], v[102:105]
	v_mfma_f32_16x16x32_bf16 v[94:97], v[150:153], v[208:211], v[94:97]
	v_mfma_f32_16x16x32_bf16 v[86:89], v[158:161], v[208:211], v[86:89]
	v_mfma_f32_16x16x32_bf16 v[78:81], v[150:153], v[216:219], v[78:81]
	v_mfma_f32_16x16x32_bf16 v[70:73], v[158:161], v[216:219], v[70:73]
	v_mfma_f32_16x16x32_bf16 v[122:125], v[172:175], v[188:191], v[122:125]
	v_mfma_f32_16x16x32_bf16 v[114:117], v[180:183], v[188:191], v[114:117]
	v_mfma_f32_16x16x32_bf16 v[106:109], v[172:175], v[196:199], v[106:109]
	v_mfma_f32_16x16x32_bf16 v[98:101], v[180:183], v[196:199], v[98:101]
	v_mfma_f32_16x16x32_bf16 v[90:93], v[172:175], v[204:207], v[90:93]
	v_mfma_f32_16x16x32_bf16 v[82:85], v[180:183], v[204:207], v[82:85]
	v_mfma_f32_16x16x32_bf16 v[74:77], v[172:175], v[212:215], v[74:77]
	v_mfma_f32_16x16x32_bf16 v[66:69], v[180:183], v[212:215], v[66:69]
	v_mfma_f32_16x16x32_bf16 v[122:125], v[176:179], v[192:195], v[122:125]
	v_mfma_f32_16x16x32_bf16 v[114:117], v[184:187], v[192:195], v[114:117]
	v_mfma_f32_16x16x32_bf16 v[106:109], v[176:179], v[200:203], v[106:109]
	v_mfma_f32_16x16x32_bf16 v[98:101], v[184:187], v[200:203], v[98:101]
	v_mfma_f32_16x16x32_bf16 v[90:93], v[176:179], v[208:211], v[90:93]
	v_mfma_f32_16x16x32_bf16 v[82:85], v[184:187], v[208:211], v[82:85]
	v_mfma_f32_16x16x32_bf16 v[74:77], v[176:179], v[216:219], v[74:77]
	v_mfma_f32_16x16x32_bf16 v[66:69], v[184:187], v[216:219], v[66:69]
	s_setprio 0
	s_barrier
; #define PG8_STAGE(bufoff, gbase, voff) do { _Pragma("unroll") for (int _i = 0; _i < 2; ++_i) \
;         __builtin_amdgcn_global_load_lds((const unsigned*)((const char*)(gbase) + (voff)[_i]), (LAS unsigned*)(lds + (bufoff) + ldsw + _i * 8192), 16, 0, 0); } while (0)
; #define PG8_LDA(dst, b, h) do { _Pragma("unroll") for (int m = 0; m < 4; ++m) _Pragma("unroll") for (int k = 0; k < 2; ++k) dst[m][k] = *(const LAS bf16x8*)(lds + PG8_SA(b, h) + aoff + m * 2048 + k * 1024); } while (0)
; #define PG8_LDB(dst, b, h) do { _Pragma("unroll") for (int n = 0; n < 2; ++n) _Pragma("unroll") for (int k = 0; k < 2; ++k) dst[n][k] = *(const LAS bf16x8*)(lds + PG8_SB(b, h) + boff + n * 2048 + k * 1024); } while (0)
; #define PG8_MMA(ai, bj, At, Bt) do { __builtin_amdgcn_s_setprio(3); _Pragma("unroll") for (int m = 0; m < 4; ++m) _Pragma("unroll") for (int n = 0; n < 2; ++n) _Pragma("unroll") for (int k = 0; k < 2; ++k) \
;         acc[ai][bj][m][n] = __builtin_amdgcn_mfma_f32_16x16x32_bf16(Bt[n][k], At[m][k], acc[ai][bj][m][n], 0, 0, 0); __builtin_amdgcn_s_setprio(0); } while (0)
; #define PG8_WAIT_V(n) asm volatile("s_waitcnt vmcnt(" #n ")" ::: "memory")
; #define PG8_BAR __builtin_amdgcn_s_barrier()
; template <class Epi, bool ALIGN_EPI>
; __device__ __forceinline__ void gemm_phase(LAS unsigned char* lds, const Gemm g, const StaticOrder& S, const Epi& E) {
;     ...
;             PG8_LDB(B0, 0, 0); PG8_LDB(B1, 0, 1); PG8_SCHED; PG8_LDA(At, 0, 0); PG8_STAGE(PG8_SA(1, 1), a1 + hstep, voffA);
;             PG8_WAIT_V(8); PG8_WAIT_L(0); PG8_BAR; PG8_MMA(0, 0, At, B0); PG8_MMA(0, 1, At, B1); PG8_BAR; PG8_SCHED;
;             PG8_LDA(At, 0, 1); PG8_STAGE(PG8_SB(0, 0), b2, voffB); PG8_STAGE(PG8_SB(0, 1), b2 + hstep, voffB); PG8_STAGE(PG8_SA(0, 0), a2, voffA);
;             PG8_WAIT_V(8); PG8_WAIT_L(0); PG8_BAR; PG8_MMA(1, 0, At, B0); PG8_MMA(1, 1, At, B1); PG8_BAR; PG8_SCHED;
;             PG8_LDB(B0, 1, 0); PG8_LDB(B1, 1, 1); PG8_SCHED; PG8_LDA(At, 1, 0); PG8_STAGE(PG8_SA(0, 1), a2 + hstep, voffA);
;             PG8_WAIT_V(8); PG8_WAIT_L(0); PG8_BAR; PG8_MMA(0, 0, At, B0); PG8_MMA(0, 1, At, B1); PG8_BAR; PG8_SCHED;
;             PG8_LDA(At, 1, 1); PG8_STAGE(PG8_SB(1, 0), b3, voffB); PG8_STAGE(PG8_SB(1, 1), b3 + hstep, voffB); PG8_STAGE(PG8_SA(1, 0), a3, voffA);
;             PG8_WAIT_V(8); PG8_WAIT_L(0); PG8_BAR; PG8_MMA(1, 0, At, B0); PG8_MMA(1, 1, At, B1); PG8_BAR; PG8_SCHED;
	s_add_i32 s10, s63, s33
	v_lshl_add_u64 v[220:221], v[220:221], 0, s[56:57]
	s_mov_b32 m0, s10
	ds_read_b128 v[188:191], v170 offset:49152
	ds_read_b128 v[192:195], v170 offset:50176
	ds_read_b128 v[196:199], v170 offset:51200
	ds_read_b128 v[200:203], v170 offset:52224
	ds_read_b128 v[204:207], v170 offset:53248
	ds_read_b128 v[208:211], v170 offset:54272
	ds_read_b128 v[212:215], v170 offset:55296
	ds_read_b128 v[216:219], v170 offset:56320
	global_load_lds_dwordx4 v[220:221], off
	s_add_i32 m0, s10, 0x2000
	s_add_u32 s8, s8, 0x40080
	v_lshl_add_u64 v[220:221], v[222:223], 0, s[56:57]
	s_addc_u32 s9, s9, 0
	s_add_i32 s10, s84, s33
	global_load_lds_dwordx4 v[220:221], off
	v_lshl_add_u64 v[220:221], s[8:9], 0, v[132:133]
	s_mov_b32 m0, s10
	s_nop 0
	global_load_lds_dwordx4 v[220:221], off
	v_lshl_add_u64 v[220:221], s[8:9], 0, v[136:137]
	s_add_i32 m0, s10, 0x2000
	s_nop 0
	global_load_lds_dwordx4 v[220:221], off
	v_lshl_add_u64 v[220:221], v[224:225], 0, s[56:57]
	s_mov_b32 m0, s78
	s_nop 0
	global_load_lds_dwordx4 v[220:221], off
	v_lshl_add_u64 v[220:221], v[226:227], 0, s[56:57]
	s_mov_b32 m0, s79
	s_nop 0
	global_load_lds_dwordx4 v[220:221], off
	s_waitcnt vmcnt(8)
	s_waitcnt lgkmcnt(0)
	s_barrier
	s_setprio 3
	v_mfma_f32_16x16x32_bf16 v[62:65], v[146:149], v[188:191], v[62:65]
	v_mfma_f32_16x16x32_bf16 v[54:57], v[154:157], v[188:191], v[54:57]
	v_mfma_f32_16x16x32_bf16 v[46:49], v[146:149], v[196:199], v[46:49]
	v_mfma_f32_16x16x32_bf16 v[38:41], v[154:157], v[196:199], v[38:41]
	v_mfma_f32_16x16x32_bf16 v[30:33], v[146:149], v[204:207], v[30:33]
	v_mfma_f32_16x16x32_bf16 v[22:25], v[154:157], v[204:207], v[22:25]
	v_mfma_f32_16x16x32_bf16 v[14:17], v[146:149], v[212:215], v[14:17]
	v_mfma_f32_16x16x32_bf16 v[6:9], v[154:157], v[212:215], v[6:9]
	v_mfma_f32_16x16x32_bf16 v[62:65], v[150:153], v[192:195], v[62:65]
	v_mfma_f32_16x16x32_bf16 v[54:57], v[158:161], v[192:195], v[54:57]
	v_mfma_f32_16x16x32_bf16 v[46:49], v[150:153], v[200:203], v[46:49]
	v_mfma_f32_16x16x32_bf16 v[38:41], v[158:161], v[200:203], v[38:41]
	v_mfma_f32_16x16x32_bf16 v[30:33], v[150:153], v[208:211], v[30:33]
	v_mfma_f32_16x16x32_bf16 v[22:25], v[158:161], v[208:211], v[22:25]
	v_mfma_f32_16x16x32_bf16 v[14:17], v[150:153], v[216:219], v[14:17]
	v_mfma_f32_16x16x32_bf16 v[6:9], v[158:161], v[216:219], v[6:9]
	v_mfma_f32_16x16x32_bf16 v[58:61], v[172:175], v[188:191], v[58:61]
	v_mfma_f32_16x16x32_bf16 v[50:53], v[180:183], v[188:191], v[50:53]
	v_mfma_f32_16x16x32_bf16 v[42:45], v[172:175], v[196:199], v[42:45]
	v_mfma_f32_16x16x32_bf16 v[34:37], v[180:183], v[196:199], v[34:37]
	v_mfma_f32_16x16x32_bf16 v[26:29], v[172:175], v[204:207], v[26:29]
	v_mfma_f32_16x16x32_bf16 v[18:21], v[180:183], v[204:207], v[18:21]
	v_mfma_f32_16x16x32_bf16 v[10:13], v[172:175], v[212:215], v[10:13]
	v_mfma_f32_16x16x32_bf16 v[2:5], v[180:183], v[212:215], v[2:5]
	v_mfma_f32_16x16x32_bf16 v[58:61], v[176:179], v[192:195], v[58:61]
	v_mfma_f32_16x16x32_bf16 v[50:53], v[184:187], v[192:195], v[50:53]
	v_mfma_f32_16x16x32_bf16 v[42:45], v[176:179], v[200:203], v[42:45]
	v_mfma_f32_16x16x32_bf16 v[34:37], v[184:187], v[200:203], v[34:37]
	v_mfma_f32_16x16x32_bf16 v[26:29], v[176:179], v[208:211], v[26:29]
	v_mfma_f32_16x16x32_bf16 v[18:21], v[184:187], v[208:211], v[18:21]
	v_mfma_f32_16x16x32_bf16 v[10:13], v[176:179], v[216:219], v[10:13]
	v_mfma_f32_16x16x32_bf16 v[2:5], v[184:187], v[216:219], v[2:5]
	s_setprio 0
	s_barrier
	s_add_i32 s61, s61, 2
	s_add_u32 s6, s6, 0x100
	s_addc_u32 s7, s7, 0
	s_add_u32 s16, s16, 0x100
	s_addc_u32 s17, s17, 0
.LBB0_609:
	ds_read_b128 v[146:149], v168
	ds_read_b128 v[150:153], v168 offset:1024
	ds_read_b128 v[154:157], v168 offset:2048
	ds_read_b128 v[158:161], v168 offset:3072
	ds_read_b128 v[172:175], v169
	ds_read_b128 v[176:179], v169 offset:1024
	ds_read_b128 v[180:183], v169 offset:2048
	ds_read_b128 v[184:187], v169 offset:3072
	s_add_u32 s8, s6, 0xfffc0080
	s_addc_u32 s9, s7, -1
	s_cmp_eq_u32 s61, 12
	s_cselect_b32 s11, s12, s9
	s_cselect_b32 s10, s13, s8
	s_cselect_b32 s9, s14, s17
	s_cselect_b32 s8, s15, s16
	v_lshl_add_u64 v[220:221], s[6:7], 0, v[138:139]
	s_add_i32 m0, s70, 0xc000
	ds_read_b128 v[188:191], v170
	ds_read_b128 v[192:195], v170 offset:1024
	ds_read_b128 v[196:199], v170 offset:2048
	ds_read_b128 v[200:203], v170 offset:3072
	ds_read_b128 v[204:207], v170 offset:4096
	ds_read_b128 v[208:211], v170 offset:5120
	ds_read_b128 v[212:215], v170 offset:6144
	ds_read_b128 v[216:219], v170 offset:7168
	global_load_lds_dwordx4 v[220:221], off
	v_lshl_add_u64 v[220:221], s[6:7], 0, v[140:141]
	s_add_i32 m0, s70, 0xe000
	s_nop 0
	global_load_lds_dwordx4 v[220:221], off
	s_waitcnt vmcnt(8)
	s_waitcnt lgkmcnt(0)
	s_barrier
; #define PG8_STAGE(bufoff, gbase, voff) do { _Pragma("unroll") for (int _i = 0; _i < 2; ++_i) \
;         __builtin_amdgcn_global_load_lds((const unsigned*)((const char*)(gbase) + (voff)[_i]), (LAS unsigned*)(lds + (bufoff) + ldsw + _i * 8192), 16, 0, 0); } while (0)
; #define PG8_LDA(dst, b, h) do { _Pragma("unroll") for (int m = 0; m < 4; ++m) _Pragma("unroll") for (int k = 0; k < 2; ++k) dst[m][k] = *(const LAS bf16x8*)(lds + PG8_SA(b, h) + aoff + m * 2048 + k * 1024); } while (0)
; #define PG8_MMA(ai, bj, At, Bt) do { __builtin_amdgcn_s_setprio(3); _Pragma("unroll") for (int m = 0; m < 4; ++m) _Pragma("unroll") for (int n = 0; n < 2; ++n) _Pragma("unroll") for (int k = 0; k < 2; ++k) \
;         acc[ai][bj][m][n] = __builtin_amdgcn_mfma_f32_16x16x32_bf16(Bt[n][k], At[m][k], acc[ai][bj][m][n], 0, 0, 0); __builtin_amdgcn_s_setprio(0); } while (0)
; #define PG8_WAIT_V(n) asm volatile("s_waitcnt vmcnt(" #n ")" ::: "memory")
; #define PG8_WAIT_L(n) asm volatile("s_waitcnt lgkmcnt(" #n ")" ::: "memory")
; #define PG8_BAR __builtin_amdgcn_s_barrier()
; #define PG8_SCHED __builtin_amdgcn_sched_barrier(0)
; template <class Epi, bool ALIGN_EPI>
; __device__ __forceinline__ void gemm_phase(LAS unsigned char* lds, const Gemm g, const StaticOrder& S, const Epi& E) {
;     ...
;             PG8_WAIT_V(8); PG8_WAIT_L(0); PG8_BAR; PG8_MMA(0, 0, At, B0); PG8_MMA(0, 1, At, B1); PG8_BAR; PG8_SCHED;
;             PG8_LDA(At, 0, 1); PG8_STAGE(PG8_SB(0, 0), b2, voffB); PG8_STAGE(PG8_SB(0, 1), b2 + hstep, voffB); PG8_STAGE(PG8_SA(0, 0), a2, voffA);
;             PG8_WAIT_V(8); PG8_WAIT_L(0); PG8_BAR; PG8_MMA(1, 0, At, B0); PG8_MMA(1, 1, At, B1); PG8_BAR; PG8_SCHED;
	s_setprio 3
	v_mfma_f32_16x16x32_bf16 v[126:129], v[146:149], v[188:191], v[126:129]
	v_mfma_f32_16x16x32_bf16 v[118:121], v[154:157], v[188:191], v[118:121]
	v_mfma_f32_16x16x32_bf16 v[110:113], v[146:149], v[196:199], v[110:113]
	v_mfma_f32_16x16x32_bf16 v[102:105], v[154:157], v[196:199], v[102:105]
	v_mfma_f32_16x16x32_bf16 v[94:97], v[146:149], v[204:207], v[94:97]
	v_mfma_f32_16x16x32_bf16 v[86:89], v[154:157], v[204:207], v[86:89]
	v_mfma_f32_16x16x32_bf16 v[78:81], v[146:149], v[212:215], v[78:81]
	v_mfma_f32_16x16x32_bf16 v[70:73], v[154:157], v[212:215], v[70:73]
	v_mfma_f32_16x16x32_bf16 v[126:129], v[150:153], v[192:195], v[126:129]
	v_mfma_f32_16x16x32_bf16 v[118:121], v[158:161], v[192:195], v[118:121]
	v_mfma_f32_16x16x32_bf16 v[110:113], v[150:153], v[200:203], v[110:113]
	v_mfma_f32_16x16x32_bf16 v[102:105], v[158:161], v[200:203], v[102:105]
	v_mfma_f32_16x16x32_bf16 v[94:97], v[150:153], v[208:211], v[94:97]
	v_mfma_f32_16x16x32_bf16 v[86:89], v[158:161], v[208:211], v[86:89]
	v_mfma_f32_16x16x32_bf16 v[78:81], v[150:153], v[216:219], v[78:81]
	v_mfma_f32_16x16x32_bf16 v[70:73], v[158:161], v[216:219], v[70:73]
	v_mfma_f32_16x16x32_bf16 v[122:125], v[172:175], v[188:191], v[122:125]
	v_mfma_f32_16x16x32_bf16 v[114:117], v[180:183], v[188:191], v[114:117]
	v_mfma_f32_16x16x32_bf16 v[106:109], v[172:175], v[196:199], v[106:109]
	v_mfma_f32_16x16x32_bf16 v[98:101], v[180:183], v[196:199], v[98:101]
	v_mfma_f32_16x16x32_bf16 v[90:93], v[172:175], v[204:207], v[90:93]
	v_mfma_f32_16x16x32_bf16 v[82:85], v[180:183], v[204:207], v[82:85]
	v_mfma_f32_16x16x32_bf16 v[74:77], v[172:175], v[212:215], v[74:77]
	v_mfma_f32_16x16x32_bf16 v[66:69], v[180:183], v[212:215], v[66:69]
	v_mfma_f32_16x16x32_bf16 v[122:125], v[176:179], v[192:195], v[122:125]
	v_mfma_f32_16x16x32_bf16 v[114:117], v[184:187], v[192:195], v[114:117]
	v_mfma_f32_16x16x32_bf16 v[106:109], v[176:179], v[200:203], v[106:109]
	v_mfma_f32_16x16x32_bf16 v[98:101], v[184:187], v[200:203], v[98:101]
	v_mfma_f32_16x16x32_bf16 v[90:93], v[176:179], v[208:211], v[90:93]
	v_mfma_f32_16x16x32_bf16 v[82:85], v[184:187], v[208:211], v[82:85]
	v_mfma_f32_16x16x32_bf16 v[74:77], v[176:179], v[216:219], v[74:77]
	v_mfma_f32_16x16x32_bf16 v[66:69], v[184:187], v[216:219], v[66:69]
	s_setprio 0
	s_barrier
	s_add_i32 s63, s80, s33
	v_lshl_add_u64 v[220:221], s[8:9], 0, v[132:133]
	s_mov_b32 m0, s63
	ds_read_b128 v[188:191], v170 offset:16384
	ds_read_b128 v[192:195], v170 offset:17408
	ds_read_b128 v[196:199], v170 offset:18432
	ds_read_b128 v[200:203], v170 offset:19456
	ds_read_b128 v[204:207], v170 offset:20480
	ds_read_b128 v[208:211], v170 offset:21504
	ds_read_b128 v[212:215], v170 offset:22528
	ds_read_b128 v[216:219], v170 offset:23552
	global_load_lds_dwordx4 v[220:221], off
	s_add_i32 m0, s63, 0x2000
	s_add_u32 s84, s8, 0x40000
	v_lshl_add_u64 v[222:223], s[8:9], 0, v[136:137]
	s_addc_u32 s85, s9, 0
	s_add_i32 s63, s81, s33
	global_load_lds_dwordx4 v[222:223], off
	v_lshl_add_u64 v[224:225], s[84:85], 0, v[132:133]
	s_mov_b32 m0, s63
	v_lshl_add_u64 v[226:227], s[10:11], 0, v[134:135]
	global_load_lds_dwordx4 v[224:225], off
	v_lshl_add_u64 v[224:225], s[84:85], 0, v[136:137]
	s_add_i32 m0, s63, 0x2000
	s_nop 0
	global_load_lds_dwordx4 v[224:225], off
	v_lshl_add_u64 v[224:225], s[10:11], 0, v[130:131]
	s_mov_b32 m0, s70
	s_nop 0
	global_load_lds_dwordx4 v[224:225], off
	s_mov_b32 m0, s71
	s_nop 0
	global_load_lds_dwordx4 v[226:227], off
	s_waitcnt vmcnt(8)
	s_waitcnt lgkmcnt(0)
	s_barrier
	s_setprio 3
	v_mfma_f32_16x16x32_bf16 v[62:65], v[146:149], v[188:191], v[62:65]
	v_mfma_f32_16x16x32_bf16 v[54:57], v[154:157], v[188:191], v[54:57]
	v_mfma_f32_16x16x32_bf16 v[46:49], v[146:149], v[196:199], v[46:49]
	v_mfma_f32_16x16x32_bf16 v[38:41], v[154:157], v[196:199], v[38:41]
	v_mfma_f32_16x16x32_bf16 v[30:33], v[146:149], v[204:207], v[30:33]
	v_mfma_f32_16x16x32_bf16 v[22:25], v[154:157], v[204:207], v[22:25]
	v_mfma_f32_16x16x32_bf16 v[14:17], v[146:149], v[212:215], v[14:17]
	v_mfma_f32_16x16x32_bf16 v[6:9], v[154:157], v[212:215], v[6:9]
	v_mfma_f32_16x16x32_bf16 v[62:65], v[150:153], v[192:195], v[62:65]
	v_mfma_f32_16x16x32_bf16 v[54:57], v[158:161], v[192:195], v[54:57]
	v_mfma_f32_16x16x32_bf16 v[46:49], v[150:153], v[200:203], v[46:49]
	v_mfma_f32_16x16x32_bf16 v[38:41], v[158:161], v[200:203], v[38:41]
	v_mfma_f32_16x16x32_bf16 v[30:33], v[150:153], v[208:211], v[30:33]
	v_mfma_f32_16x16x32_bf16 v[22:25], v[158:161], v[208:211], v[22:25]
	v_mfma_f32_16x16x32_bf16 v[14:17], v[150:153], v[216:219], v[14:17]
	v_mfma_f32_16x16x32_bf16 v[6:9], v[158:161], v[216:219], v[6:9]
	v_mfma_f32_16x16x32_bf16 v[58:61], v[172:175], v[188:191], v[58:61]
	v_mfma_f32_16x16x32_bf16 v[50:53], v[180:183], v[188:191], v[50:53]
	v_mfma_f32_16x16x32_bf16 v[42:45], v[172:175], v[196:199], v[42:45]
	v_mfma_f32_16x16x32_bf16 v[34:37], v[180:183], v[196:199], v[34:37]
	v_mfma_f32_16x16x32_bf16 v[26:29], v[172:175], v[204:207], v[26:29]
	v_mfma_f32_16x16x32_bf16 v[18:21], v[180:183], v[204:207], v[18:21]
	v_mfma_f32_16x16x32_bf16 v[10:13], v[172:175], v[212:215], v[10:13]
	v_mfma_f32_16x16x32_bf16 v[2:5], v[180:183], v[212:215], v[2:5]
	v_mfma_f32_16x16x32_bf16 v[58:61], v[176:179], v[192:195], v[58:61]
	v_mfma_f32_16x16x32_bf16 v[50:53], v[184:187], v[192:195], v[50:53]
	v_mfma_f32_16x16x32_bf16 v[42:45], v[176:179], v[200:203], v[42:45]
	v_mfma_f32_16x16x32_bf16 v[34:37], v[184:187], v[200:203], v[34:37]
	v_mfma_f32_16x16x32_bf16 v[26:29], v[176:179], v[208:211], v[26:29]
	v_mfma_f32_16x16x32_bf16 v[18:21], v[184:187], v[208:211], v[18:21]
	v_mfma_f32_16x16x32_bf16 v[10:13], v[176:179], v[216:219], v[10:13]
	v_mfma_f32_16x16x32_bf16 v[2:5], v[184:187], v[216:219], v[2:5]
	s_setprio 0
	s_barrier
; #define PG8_STAGE(bufoff, gbase, voff) do { _Pragma("unroll") for (int _i = 0; _i < 2; ++_i) \
;         __builtin_amdgcn_global_load_lds((const unsigned*)((const char*)(gbase) + (voff)[_i]), (LAS unsigned*)(lds + (bufoff) + ldsw + _i * 8192), 16, 0, 0); } while (0)
; #define PG8_LDA(dst, b, h) do { _Pragma("unroll") for (int m = 0; m < 4; ++m) _Pragma("unroll") for (int k = 0; k < 2; ++k) dst[m][k] = *(const LAS bf16x8*)(lds + PG8_SA(b, h) + aoff + m * 2048 + k * 1024); } while (0)
; #define PG8_LDB(dst, b, h) do { _Pragma("unroll") for (int n = 0; n < 2; ++n) _Pragma("unroll") for (int k = 0; k < 2; ++k) dst[n][k] = *(const LAS bf16x8*)(lds + PG8_SB(b, h) + boff + n * 2048 + k * 1024); } while (0)
; #define PG8_MMA(ai, bj, At, Bt) do { __builtin_amdgcn_s_setprio(3); _Pragma("unroll") for (int m = 0; m < 4; ++m) _Pragma("unroll") for (int n = 0; n < 2; ++n) _Pragma("unroll") for (int k = 0; k < 2; ++k) \
;         acc[ai][bj][m][n] = __builtin_amdgcn_mfma_f32_16x16x32_bf16(Bt[n][k], At[m][k], acc[ai][bj][m][n], 0, 0, 0); __builtin_amdgcn_s_setprio(0); } while (0)
; #define PG8_WAIT_V(n) asm volatile("s_waitcnt vmcnt(" #n ")" ::: "memory")
; #define PG8_WAIT_L(n) asm volatile("s_waitcnt lgkmcnt(" #n ")" ::: "memory")
; #define PG8_BAR __builtin_amdgcn_s_barrier()
; #define PG8_SCHED __builtin_amdgcn_sched_barrier(0)
; template <class Epi, bool ALIGN_EPI>
; __device__ __forceinline__ void gemm_phase(LAS unsigned char* lds, const Gemm g, const StaticOrder& S, const Epi& E) {
;     ...
;             PG8_LDB(B0, 1, 0); PG8_LDB(B1, 1, 1); PG8_SCHED; PG8_LDA(At, 1, 0); PG8_STAGE(PG8_SA(0, 1), a2 + hstep, voffA);
;             PG8_WAIT_V(8); PG8_WAIT_L(0); PG8_BAR; PG8_MMA(0, 0, At, B0); PG8_MMA(0, 1, At, B1); PG8_BAR; PG8_SCHED;
	s_add_i32 s63, 0, 0x18000
	s_add_i32 s84, 0, 0x1c000
	v_add_u32_e32 v158, s63, v166
	v_add_u32_e32 v184, s84, v166
	ds_read_b128 v[146:149], v158
	ds_read_b128 v[150:153], v158 offset:1024
	ds_read_b128 v[154:157], v158 offset:2048
	ds_read_b128 v[158:161], v158 offset:3072
	ds_read_b128 v[172:175], v184
	ds_read_b128 v[176:179], v184 offset:1024
	ds_read_b128 v[180:183], v184 offset:2048
	ds_read_b128 v[184:187], v184 offset:3072
	s_add_u32 s10, s10, 0x40000
	s_addc_u32 s11, s11, 0
	s_mov_b32 m0, s72
	v_lshl_add_u64 v[228:229], s[10:11], 0, v[130:131]
	ds_read_b128 v[188:191], v170 offset:32768
	ds_read_b128 v[192:195], v170 offset:33792
	ds_read_b128 v[196:199], v170 offset:34816
	ds_read_b128 v[200:203], v170 offset:35840
	ds_read_b128 v[204:207], v170 offset:36864
	ds_read_b128 v[208:211], v170 offset:37888
	ds_read_b128 v[212:215], v170 offset:38912
	ds_read_b128 v[216:219], v170 offset:39936
	global_load_lds_dwordx4 v[228:229], off
	v_lshl_add_u64 v[228:229], s[10:11], 0, v[134:135]
	s_mov_b32 m0, s73
	s_nop 0
	global_load_lds_dwordx4 v[228:229], off
	s_waitcnt vmcnt(8)
	s_waitcnt lgkmcnt(0)
	s_barrier
	s_setprio 3
	v_mfma_f32_16x16x32_bf16 v[126:129], v[146:149], v[188:191], v[126:129]
	v_mfma_f32_16x16x32_bf16 v[118:121], v[154:157], v[188:191], v[118:121]
	v_mfma_f32_16x16x32_bf16 v[110:113], v[146:149], v[196:199], v[110:113]
	v_mfma_f32_16x16x32_bf16 v[102:105], v[154:157], v[196:199], v[102:105]
	v_mfma_f32_16x16x32_bf16 v[94:97], v[146:149], v[204:207], v[94:97]
	v_mfma_f32_16x16x32_bf16 v[86:89], v[154:157], v[204:207], v[86:89]
	v_mfma_f32_16x16x32_bf16 v[78:81], v[146:149], v[212:215], v[78:81]
	v_mfma_f32_16x16x32_bf16 v[70:73], v[154:157], v[212:215], v[70:73]
	v_mfma_f32_16x16x32_bf16 v[126:129], v[150:153], v[192:195], v[126:129]
	v_mfma_f32_16x16x32_bf16 v[118:121], v[158:161], v[192:195], v[118:121]
	v_mfma_f32_16x16x32_bf16 v[110:113], v[150:153], v[200:203], v[110:113]
	v_mfma_f32_16x16x32_bf16 v[102:105], v[158:161], v[200:203], v[102:105]
	v_mfma_f32_16x16x32_bf16 v[94:97], v[150:153], v[208:211], v[94:97]
	v_mfma_f32_16x16x32_bf16 v[86:89], v[158:161], v[208:211], v[86:89]
	v_mfma_f32_16x16x32_bf16 v[78:81], v[150:153], v[216:219], v[78:81]
	v_mfma_f32_16x16x32_bf16 v[70:73], v[158:161], v[216:219], v[70:73]
	v_mfma_f32_16x16x32_bf16 v[122:125], v[172:175], v[188:191], v[122:125]
	v_mfma_f32_16x16x32_bf16 v[114:117], v[180:183], v[188:191], v[114:117]
	v_mfma_f32_16x16x32_bf16 v[106:109], v[172:175], v[196:199], v[106:109]
	v_mfma_f32_16x16x32_bf16 v[98:101], v[180:183], v[196:199], v[98:101]
	v_mfma_f32_16x16x32_bf16 v[90:93], v[172:175], v[204:207], v[90:93]
	v_mfma_f32_16x16x32_bf16 v[82:85], v[180:183], v[204:207], v[82:85]
	v_mfma_f32_16x16x32_bf16 v[74:77], v[172:175], v[212:215], v[74:77]
	v_mfma_f32_16x16x32_bf16 v[66:69], v[180:183], v[212:215], v[66:69]
	v_mfma_f32_16x16x32_bf16 v[122:125], v[176:179], v[192:195], v[122:125]
	v_mfma_f32_16x16x32_bf16 v[114:117], v[184:187], v[192:195], v[114:117]
	v_mfma_f32_16x16x32_bf16 v[106:109], v[176:179], v[200:203], v[106:109]
	v_mfma_f32_16x16x32_bf16 v[98:101], v[184:187], v[200:203], v[98:101]
	v_mfma_f32_16x16x32_bf16 v[90:93], v[176:179], v[208:211], v[90:93]
	v_mfma_f32_16x16x32_bf16 v[82:85], v[184:187], v[208:211], v[82:85]
	v_mfma_f32_16x16x32_bf16 v[74:77], v[176:179], v[216:219], v[74:77]
	v_mfma_f32_16x16x32_bf16 v[66:69], v[184:187], v[216:219], v[66:69]
	s_setprio 0
	s_barrier
; #define PG8_STAGE(bufoff, gbase, voff) do { _Pragma("unroll") for (int _i = 0; _i < 2; ++_i) \
;         __builtin_amdgcn_global_load_lds((const unsigned*)((const char*)(gbase) + (voff)[_i]), (LAS unsigned*)(lds + (bufoff) + ldsw + _i * 8192), 16, 0, 0); } while (0)
; #define PG8_LDA(dst, b, h) do { _Pragma("unroll") for (int m = 0; m < 4; ++m) _Pragma("unroll") for (int k = 0; k < 2; ++k) dst[m][k] = *(const LAS bf16x8*)(lds + PG8_SA(b, h) + aoff + m * 2048 + k * 1024); } while (0)
; #define PG8_MMA(ai, bj, At, Bt) do { __builtin_amdgcn_s_setprio(3); _Pragma("unroll") for (int m = 0; m < 4; ++m) _Pragma("unroll") for (int n = 0; n < 2; ++n) _Pragma("unroll") for (int k = 0; k < 2; ++k) \
;         acc[ai][bj][m][n] = __builtin_amdgcn_mfma_f32_16x16x32_bf16(Bt[n][k], At[m][k], acc[ai][bj][m][n], 0, 0, 0); __builtin_amdgcn_s_setprio(0); } while (0)
; #define PG8_WAIT_V(n) asm volatile("s_waitcnt vmcnt(" #n ")" ::: "memory")
; #define PG8_WAIT_L(n) asm volatile("s_waitcnt lgkmcnt(" #n ")" ::: "memory")
; #define PG8_BAR __builtin_amdgcn_s_barrier()
; #define PG8_SCHED __builtin_amdgcn_sched_barrier(0)
; template <class Epi, bool ALIGN_EPI>
; __device__ __forceinline__ void gemm_phase(LAS unsigned char* lds, const Gemm g, const StaticOrder& S, const Epi& E) {
;     ...
;             PG8_LDA(At, 1, 1); PG8_STAGE(PG8_SB(1, 0), b3, voffB); PG8_STAGE(PG8_SB(1, 1), b3 + hstep, voffB); PG8_STAGE(PG8_SA(1, 0), a3, voffA);
;             PG8_WAIT_V(8); PG8_WAIT_L(0); PG8_BAR; PG8_MMA(1, 0, At, B0); PG8_MMA(1, 1, At, B1); PG8_BAR; PG8_SCHED;
;         }
;         if constexpr (ALIGN_EPI) { if (wr == 0) PG8_BAR; }
	s_add_i32 s10, s63, s33
	v_lshl_add_u64 v[220:221], v[220:221], 0, s[56:57]
	s_mov_b32 m0, s10
	ds_read_b128 v[188:191], v170 offset:49152
	ds_read_b128 v[192:195], v170 offset:50176
	ds_read_b128 v[196:199], v170 offset:51200
	ds_read_b128 v[200:203], v170 offset:52224
	ds_read_b128 v[204:207], v170 offset:53248
	ds_read_b128 v[208:211], v170 offset:54272
	ds_read_b128 v[212:215], v170 offset:55296
	ds_read_b128 v[216:219], v170 offset:56320
	global_load_lds_dwordx4 v[220:221], off
	s_add_i32 m0, s10, 0x2000
	s_add_u32 s8, s8, 0x40080
	v_lshl_add_u64 v[220:221], v[222:223], 0, s[56:57]
	s_addc_u32 s9, s9, 0
	s_add_i32 s10, s84, s33
	global_load_lds_dwordx4 v[220:221], off
	v_lshl_add_u64 v[220:221], s[8:9], 0, v[132:133]
	s_mov_b32 m0, s10
	s_nop 0
	global_load_lds_dwordx4 v[220:221], off
	v_lshl_add_u64 v[220:221], s[8:9], 0, v[136:137]
	s_add_i32 m0, s10, 0x2000
	s_nop 0
	global_load_lds_dwordx4 v[220:221], off
	v_lshl_add_u64 v[220:221], v[224:225], 0, s[56:57]
	s_mov_b32 m0, s78
	s_nop 0
	global_load_lds_dwordx4 v[220:221], off
	v_lshl_add_u64 v[220:221], v[226:227], 0, s[56:57]
	s_mov_b32 m0, s79
	s_nop 0
	global_load_lds_dwordx4 v[220:221], off
	s_waitcnt vmcnt(8)
	s_waitcnt lgkmcnt(0)
	s_barrier
	s_setprio 3
	v_mfma_f32_16x16x32_bf16 v[62:65], v[146:149], v[188:191], v[62:65]
	v_mfma_f32_16x16x32_bf16 v[54:57], v[154:157], v[188:191], v[54:57]
	v_mfma_f32_16x16x32_bf16 v[46:49], v[146:149], v[196:199], v[46:49]
	v_mfma_f32_16x16x32_bf16 v[38:41], v[154:157], v[196:199], v[38:41]
	v_mfma_f32_16x16x32_bf16 v[30:33], v[146:149], v[204:207], v[30:33]
	v_mfma_f32_16x16x32_bf16 v[22:25], v[154:157], v[204:207], v[22:25]
	v_mfma_f32_16x16x32_bf16 v[14:17], v[146:149], v[212:215], v[14:17]
	v_mfma_f32_16x16x32_bf16 v[6:9], v[154:157], v[212:215], v[6:9]
	v_mfma_f32_16x16x32_bf16 v[62:65], v[150:153], v[192:195], v[62:65]
	v_mfma_f32_16x16x32_bf16 v[54:57], v[158:161], v[192:195], v[54:57]
	v_mfma_f32_16x16x32_bf16 v[46:49], v[150:153], v[200:203], v[46:49]
	v_mfma_f32_16x16x32_bf16 v[38:41], v[158:161], v[200:203], v[38:41]
	v_mfma_f32_16x16x32_bf16 v[30:33], v[150:153], v[208:211], v[30:33]
	v_mfma_f32_16x16x32_bf16 v[22:25], v[158:161], v[208:211], v[22:25]
	v_mfma_f32_16x16x32_bf16 v[14:17], v[150:153], v[216:219], v[14:17]
	v_mfma_f32_16x16x32_bf16 v[6:9], v[158:161], v[216:219], v[6:9]
	v_mfma_f32_16x16x32_bf16 v[58:61], v[172:175], v[188:191], v[58:61]
	v_mfma_f32_16x16x32_bf16 v[50:53], v[180:183], v[188:191], v[50:53]
	v_mfma_f32_16x16x32_bf16 v[42:45], v[172:175], v[196:199], v[42:45]
	v_mfma_f32_16x16x32_bf16 v[34:37], v[180:183], v[196:199], v[34:37]
	v_mfma_f32_16x16x32_bf16 v[26:29], v[172:175], v[204:207], v[26:29]
	v_mfma_f32_16x16x32_bf16 v[18:21], v[180:183], v[204:207], v[18:21]
	v_mfma_f32_16x16x32_bf16 v[10:13], v[172:175], v[212:215], v[10:13]
	v_mfma_f32_16x16x32_bf16 v[2:5], v[180:183], v[212:215], v[2:5]
	v_mfma_f32_16x16x32_bf16 v[58:61], v[176:179], v[192:195], v[58:61]
	v_mfma_f32_16x16x32_bf16 v[50:53], v[184:187], v[192:195], v[50:53]
	v_mfma_f32_16x16x32_bf16 v[42:45], v[176:179], v[200:203], v[42:45]
	v_mfma_f32_16x16x32_bf16 v[34:37], v[184:187], v[200:203], v[34:37]
	v_mfma_f32_16x16x32_bf16 v[26:29], v[176:179], v[208:211], v[26:29]
	v_mfma_f32_16x16x32_bf16 v[18:21], v[184:187], v[208:211], v[18:21]
	v_mfma_f32_16x16x32_bf16 v[10:13], v[176:179], v[216:219], v[10:13]
	v_mfma_f32_16x16x32_bf16 v[2:5], v[184:187], v[216:219], v[2:5]
	s_setprio 0
	s_barrier
	s_add_i32 s61, s61, 2
	s_add_u32 s6, s6, 0x100
	s_addc_u32 s7, s7, 0
	s_add_u32 s16, s16, 0x100
	s_addc_u32 s17, s17, 0
	s_cmp_gt_u32 s61, 13
	s_cbranch_scc0 .LBB0_609
	s_and_b64 vcc, exec, s[58:59]
	s_cbranch_vccz .LBB0_612
	s_barrier

; #define PG8_STAGE(bufoff, gbase, voff) do { _Pragma("unroll") for (int _i = 0; _i < 2; ++_i) \
;         __builtin_amdgcn_global_load_lds((const unsigned*)((const char*)(gbase) + (voff)[_i]), (LAS unsigned*)(lds + (bufoff) + ldsw + _i * 8192), 16, 0, 0); } while (0)
; #define PG8_LDA(dst, b, h) do { _Pragma("unroll") for (int m = 0; m < 4; ++m) _Pragma("unroll") for (int k = 0; k < 2; ++k) dst[m][k] = *(const LAS bf16x8*)(lds + PG8_SA(b, h) + aoff + m * 2048 + k * 1024); } while (0)
; #define PG8_LDB(dst, b, h) do { _Pragma("unroll") for (int n = 0; n < 2; ++n) _Pragma("unroll") for (int k = 0; k < 2; ++k) dst[n][k] = *(const LAS bf16x8*)(lds + PG8_SB(b, h) + boff + n * 2048 + k * 1024); } while (0)
; #define PG8_MMA(ai, bj, At, Bt) do { __builtin_amdgcn_s_setprio(3); _Pragma("unroll") for (int m = 0; m < 4; ++m) _Pragma("unroll") for (int n = 0; n < 2; ++n) _Pragma("unroll") for (int k = 0; k < 2; ++k) \
;         acc[ai][bj][m][n] = __builtin_amdgcn_mfma_f32_16x16x32_bf16(Bt[n][k], At[m][k], acc[ai][bj][m][n], 0, 0, 0); __builtin_amdgcn_s_setprio(0); } while (0)
; #define PG8_WAIT_V(n) asm volatile("s_waitcnt vmcnt(" #n ")" ::: "memory")
; #define PG8_WAIT_L(n) asm volatile("s_waitcnt lgkmcnt(" #n ")" ::: "memory")
; #define PG8_BAR __builtin_amdgcn_s_barrier()
; #define PG8_SCHED __builtin_amdgcn_sched_barrier(0)
; template <class Epi, bool ALIGN_EPI>
; __device__ __forceinline__ void gemm_phase(LAS unsigned char* lds, const Gemm g, const StaticOrder& S, const Epi& E) {
;     ...
;             const char* a1 = cA + (size_t)(t + 1) * kstep;
;             const char* a2 = last ? nA : cA + (size_t)(t + 2) * kstep; const char* b2 = last ? nB : cB + (size_t)(t + 2) * kstep;
;             const char* a3 = a2 + kstep; const char* b3 = b2 + kstep;
;             PG8_LDB(B0, 0, 0); PG8_LDB(B1, 0, 1); PG8_SCHED; PG8_LDA(At, 0, 0); PG8_STAGE(PG8_SA(1, 1), a1 + hstep, voffA);
;             PG8_WAIT_V(8); PG8_WAIT_L(0); PG8_BAR; PG8_MMA(0, 0, At, B0); PG8_MMA(0, 1, At, B1); PG8_BAR; PG8_SCHED;
;             PG8_LDA(At, 0, 1); PG8_STAGE(PG8_SB(0, 0), b2, voffB); PG8_STAGE(PG8_SB(0, 1), b2 + hstep, voffB); PG8_STAGE(PG8_SA(0, 0), a2, voffA);
.LBB0_695:
	s_add_u32 s50, s50, 0xb0080
	s_addc_u32 s51, s51, 0
	s_add_u32 s73, s52, 0x100
	s_addc_u32 s76, s53, 0
	s_mov_b32 s77, -2
	s_waitcnt lgkmcnt(0)
	ds_read_b128 v[130:133], v196
	ds_read_b128 v[134:137], v196 offset:1024
	ds_read_b128 v[138:141], v196 offset:2048
	ds_read_b128 v[142:145], v196 offset:3072
	ds_read_b128 v[146:149], v197
	ds_read_b128 v[150:153], v197 offset:1024
	ds_read_b128 v[170:173], v197 offset:2048
	ds_read_b128 v[174:177], v197 offset:3072
	s_add_u32 s52, s50, 0xfff50080
	s_addc_u32 s53, s51, -1
	s_cmp_eq_u32 s77, 40
	s_cselect_b32 s55, s5, s53
	s_cselect_b32 s54, s4, s52
	s_cselect_b32 s53, s19, s76
	s_cselect_b32 s52, s18, s73
	v_lshl_add_u64 v[186:187], s[50:51], 0, v[162:163]
	s_add_i32 m0, s58, 0xc000
	ds_read_b128 v[178:181], v198
	ds_read_b128 v[182:185], v198 offset:1024
	ds_read_b128 v[200:203], v198 offset:2048
	ds_read_b128 v[204:207], v198 offset:3072
	ds_read_b128 v[208:211], v198 offset:4096
	ds_read_b128 v[212:215], v198 offset:5120
	ds_read_b128 v[216:219], v198 offset:6144
	ds_read_b128 v[220:223], v198 offset:7168
	global_load_lds_dwordx4 v[186:187], off
	v_lshl_add_u64 v[186:187], s[50:51], 0, v[164:165]
	s_add_i32 m0, s58, 0xe000
	s_nop 0
	global_load_lds_dwordx4 v[186:187], off
	s_waitcnt vmcnt(8)
	s_waitcnt lgkmcnt(0)
	s_barrier
	s_setprio 3
	v_mfma_f32_16x16x32_bf16 v[126:129], v[130:133], v[178:181], 0
	v_mfma_f32_16x16x32_bf16 v[122:125], v[138:141], v[178:181], 0
	v_mfma_f32_16x16x32_bf16 v[110:113], v[130:133], v[200:203], 0
	v_mfma_f32_16x16x32_bf16 v[106:109], v[138:141], v[200:203], 0
	v_mfma_f32_16x16x32_bf16 v[94:97], v[130:133], v[208:211], 0
	v_mfma_f32_16x16x32_bf16 v[90:93], v[138:141], v[208:211], 0
	v_mfma_f32_16x16x32_bf16 v[78:81], v[130:133], v[216:219], 0
	v_mfma_f32_16x16x32_bf16 v[74:77], v[138:141], v[216:219], 0
	v_mfma_f32_16x16x32_bf16 v[126:129], v[134:137], v[182:185], v[126:129]
	v_mfma_f32_16x16x32_bf16 v[122:125], v[142:145], v[182:185], v[122:125]
	v_mfma_f32_16x16x32_bf16 v[110:113], v[134:137], v[204:207], v[110:113]
	v_mfma_f32_16x16x32_bf16 v[106:109], v[142:145], v[204:207], v[106:109]
	v_mfma_f32_16x16x32_bf16 v[94:97], v[134:137], v[212:215], v[94:97]
	v_mfma_f32_16x16x32_bf16 v[90:93], v[142:145], v[212:215], v[90:93]
	v_mfma_f32_16x16x32_bf16 v[78:81], v[134:137], v[220:223], v[78:81]
	v_mfma_f32_16x16x32_bf16 v[74:77], v[142:145], v[220:223], v[74:77]
	v_mfma_f32_16x16x32_bf16 v[118:121], v[146:149], v[178:181], 0
	v_mfma_f32_16x16x32_bf16 v[114:117], v[170:173], v[178:181], 0
	v_mfma_f32_16x16x32_bf16 v[102:105], v[146:149], v[200:203], 0
	v_mfma_f32_16x16x32_bf16 v[98:101], v[170:173], v[200:203], 0
	v_mfma_f32_16x16x32_bf16 v[86:89], v[146:149], v[208:211], 0
	v_mfma_f32_16x16x32_bf16 v[82:85], v[170:173], v[208:211], 0
	v_mfma_f32_16x16x32_bf16 v[70:73], v[146:149], v[216:219], 0
	v_mfma_f32_16x16x32_bf16 v[66:69], v[170:173], v[216:219], 0
	v_mfma_f32_16x16x32_bf16 v[118:121], v[150:153], v[182:185], v[118:121]
	v_mfma_f32_16x16x32_bf16 v[114:117], v[174:177], v[182:185], v[114:117]
	v_mfma_f32_16x16x32_bf16 v[102:105], v[150:153], v[204:207], v[102:105]
	v_mfma_f32_16x16x32_bf16 v[98:101], v[174:177], v[204:207], v[98:101]
	v_mfma_f32_16x16x32_bf16 v[86:89], v[150:153], v[212:215], v[86:89]
	v_mfma_f32_16x16x32_bf16 v[82:85], v[174:177], v[212:215], v[82:85]
	v_mfma_f32_16x16x32_bf16 v[70:73], v[150:153], v[220:223], v[70:73]
	v_mfma_f32_16x16x32_bf16 v[66:69], v[174:177], v[220:223], v[66:69]
	s_setprio 0
	s_barrier
	s_add_i32 s78, s67, s57
	v_lshl_add_u64 v[186:187], s[52:53], 0, v[156:157]
	s_mov_b32 m0, s78
	ds_read_b128 v[178:181], v198 offset:16384
	ds_read_b128 v[182:185], v198 offset:17408
	ds_read_b128 v[200:203], v198 offset:18432
	ds_read_b128 v[204:207], v198 offset:19456
	ds_read_b128 v[208:211], v198 offset:20480
	ds_read_b128 v[212:215], v198 offset:21504
	ds_read_b128 v[216:219], v198 offset:22528
	ds_read_b128 v[220:223], v198 offset:23552
	global_load_lds_dwordx4 v[186:187], off
	s_add_i32 m0, s78, 0x2000
	s_add_u32 s78, s52, 0xb0000
	v_lshl_add_u64 v[224:225], s[52:53], 0, v[160:161]
	s_addc_u32 s79, s53, 0
	s_add_i32 s80, s68, s57
	global_load_lds_dwordx4 v[224:225], off
	v_lshl_add_u64 v[226:227], s[78:79], 0, v[156:157]
	s_mov_b32 m0, s80
	v_lshl_add_u64 v[228:229], s[54:55], 0, v[158:159]
	global_load_lds_dwordx4 v[226:227], off
	v_lshl_add_u64 v[226:227], s[78:79], 0, v[160:161]
	s_add_i32 m0, s80, 0x2000
	s_nop 0
	global_load_lds_dwordx4 v[226:227], off
	v_lshl_add_u64 v[226:227], s[54:55], 0, v[154:155]
	s_mov_b32 m0, s58
	s_nop 0
	global_load_lds_dwordx4 v[226:227], off
	s_mov_b32 m0, s59
	s_nop 0
	global_load_lds_dwordx4 v[228:229], off
	s_waitcnt vmcnt(8)
	s_waitcnt lgkmcnt(0)
	s_barrier
; #define PG8_STAGE(bufoff, gbase, voff) do { _Pragma("unroll") for (int _i = 0; _i < 2; ++_i) \
;         __builtin_amdgcn_global_load_lds((const unsigned*)((const char*)(gbase) + (voff)[_i]), (LAS unsigned*)(lds + (bufoff) + ldsw + _i * 8192), 16, 0, 0); } while (0)
; #define PG8_LDA(dst, b, h) do { _Pragma("unroll") for (int m = 0; m < 4; ++m) _Pragma("unroll") for (int k = 0; k < 2; ++k) dst[m][k] = *(const LAS bf16x8*)(lds + PG8_SA(b, h) + aoff + m * 2048 + k * 1024); } while (0)
; #define PG8_LDB(dst, b, h) do { _Pragma("unroll") for (int n = 0; n < 2; ++n) _Pragma("unroll") for (int k = 0; k < 2; ++k) dst[n][k] = *(const LAS bf16x8*)(lds + PG8_SB(b, h) + boff + n * 2048 + k * 1024); } while (0)
; #define PG8_MMA(ai, bj, At, Bt) do { __builtin_amdgcn_s_setprio(3); _Pragma("unroll") for (int m = 0; m < 4; ++m) _Pragma("unroll") for (int n = 0; n < 2; ++n) _Pragma("unroll") for (int k = 0; k < 2; ++k) \
;         acc[ai][bj][m][n] = __builtin_amdgcn_mfma_f32_16x16x32_bf16(Bt[n][k], At[m][k], acc[ai][bj][m][n], 0, 0, 0); __builtin_amdgcn_s_setprio(0); } while (0)
; #define PG8_WAIT_V(n) asm volatile("s_waitcnt vmcnt(" #n ")" ::: "memory")
; #define PG8_WAIT_L(n) asm volatile("s_waitcnt lgkmcnt(" #n ")" ::: "memory")
; #define PG8_BAR __builtin_amdgcn_s_barrier()
; #define PG8_SCHED __builtin_amdgcn_sched_barrier(0)
; template <class Epi, bool ALIGN_EPI>
; __device__ __forceinline__ void gemm_phase(LAS unsigned char* lds, const Gemm g, const StaticOrder& S, const Epi& E) {
;     ...
;             PG8_WAIT_V(8); PG8_WAIT_L(0); PG8_BAR; PG8_MMA(1, 0, At, B0); PG8_MMA(1, 1, At, B1); PG8_BAR; PG8_SCHED;
;             PG8_LDB(B0, 1, 0); PG8_LDB(B1, 1, 1); PG8_SCHED; PG8_LDA(At, 1, 0); PG8_STAGE(PG8_SA(0, 1), a2 + hstep, voffA);
;             PG8_WAIT_V(8); PG8_WAIT_L(0); PG8_BAR; PG8_MMA(0, 0, At, B0); PG8_MMA(0, 1, At, B1); PG8_BAR; PG8_SCHED;
	s_setprio 3
	v_mfma_f32_16x16x32_bf16 v[62:65], v[130:133], v[178:181], 0
	v_mfma_f32_16x16x32_bf16 v[58:61], v[138:141], v[178:181], 0
	v_mfma_f32_16x16x32_bf16 v[46:49], v[130:133], v[200:203], 0
	v_mfma_f32_16x16x32_bf16 v[42:45], v[138:141], v[200:203], 0
	v_mfma_f32_16x16x32_bf16 v[30:33], v[130:133], v[208:211], 0
	v_mfma_f32_16x16x32_bf16 v[26:29], v[138:141], v[208:211], 0
	v_mfma_f32_16x16x32_bf16 v[14:17], v[130:133], v[216:219], 0
	v_mfma_f32_16x16x32_bf16 v[10:13], v[138:141], v[216:219], 0
	v_mfma_f32_16x16x32_bf16 v[62:65], v[134:137], v[182:185], v[62:65]
	v_mfma_f32_16x16x32_bf16 v[58:61], v[142:145], v[182:185], v[58:61]
	v_mfma_f32_16x16x32_bf16 v[46:49], v[134:137], v[204:207], v[46:49]
	v_mfma_f32_16x16x32_bf16 v[42:45], v[142:145], v[204:207], v[42:45]
	v_mfma_f32_16x16x32_bf16 v[30:33], v[134:137], v[212:215], v[30:33]
	v_mfma_f32_16x16x32_bf16 v[26:29], v[142:145], v[212:215], v[26:29]
	v_mfma_f32_16x16x32_bf16 v[14:17], v[134:137], v[220:223], v[14:17]
	v_mfma_f32_16x16x32_bf16 v[10:13], v[142:145], v[220:223], v[10:13]
	v_mfma_f32_16x16x32_bf16 v[54:57], v[146:149], v[178:181], 0
	v_mfma_f32_16x16x32_bf16 v[50:53], v[170:173], v[178:181], 0
	v_mfma_f32_16x16x32_bf16 v[38:41], v[146:149], v[200:203], 0
	v_mfma_f32_16x16x32_bf16 v[34:37], v[170:173], v[200:203], 0
	v_mfma_f32_16x16x32_bf16 v[22:25], v[146:149], v[208:211], 0
	v_mfma_f32_16x16x32_bf16 v[18:21], v[170:173], v[208:211], 0
	v_mfma_f32_16x16x32_bf16 v[6:9], v[146:149], v[216:219], 0
	v_mfma_f32_16x16x32_bf16 v[2:5], v[170:173], v[216:219], 0
	v_mfma_f32_16x16x32_bf16 v[54:57], v[150:153], v[182:185], v[54:57]
	v_mfma_f32_16x16x32_bf16 v[50:53], v[174:177], v[182:185], v[50:53]
	v_mfma_f32_16x16x32_bf16 v[38:41], v[150:153], v[204:207], v[38:41]
	v_mfma_f32_16x16x32_bf16 v[34:37], v[174:177], v[204:207], v[34:37]
	v_mfma_f32_16x16x32_bf16 v[22:25], v[150:153], v[212:215], v[22:25]
	v_mfma_f32_16x16x32_bf16 v[18:21], v[174:177], v[212:215], v[18:21]
	v_mfma_f32_16x16x32_bf16 v[6:9], v[150:153], v[220:223], v[6:9]
	v_mfma_f32_16x16x32_bf16 v[2:5], v[174:177], v[220:223], v[2:5]
	s_setprio 0
	s_barrier
	s_add_i32 s78, 0, 0x18000
	s_add_i32 s79, 0, 0x1c000
	v_add_u32_e32 v142, s78, v194
	v_add_u32_e32 v174, s79, v194
	ds_read_b128 v[130:133], v142
	ds_read_b128 v[134:137], v142 offset:1024
	ds_read_b128 v[138:141], v142 offset:2048
	ds_read_b128 v[142:145], v142 offset:3072
	ds_read_b128 v[146:149], v174
	ds_read_b128 v[150:153], v174 offset:1024
	ds_read_b128 v[170:173], v174 offset:2048
	ds_read_b128 v[174:177], v174 offset:3072
	s_add_u32 s54, s54, 0xb0000
	s_addc_u32 s55, s55, 0
	s_mov_b32 m0, s60
	v_lshl_add_u64 v[230:231], s[54:55], 0, v[154:155]
	ds_read_b128 v[178:181], v198 offset:32768
	ds_read_b128 v[182:185], v198 offset:33792
	ds_read_b128 v[200:203], v198 offset:34816
	ds_read_b128 v[204:207], v198 offset:35840
	ds_read_b128 v[208:211], v198 offset:36864
	ds_read_b128 v[212:215], v198 offset:37888
	ds_read_b128 v[216:219], v198 offset:38912
	ds_read_b128 v[220:223], v198 offset:39936
	global_load_lds_dwordx4 v[230:231], off
	v_lshl_add_u64 v[230:231], s[54:55], 0, v[158:159]
	s_mov_b32 m0, s61
	s_nop 0
	global_load_lds_dwordx4 v[230:231], off
	s_waitcnt vmcnt(8)
	s_waitcnt lgkmcnt(0)
	s_barrier
	s_setprio 3
	v_mfma_f32_16x16x32_bf16 v[126:129], v[130:133], v[178:181], v[126:129]
	v_mfma_f32_16x16x32_bf16 v[122:125], v[138:141], v[178:181], v[122:125]
	v_mfma_f32_16x16x32_bf16 v[110:113], v[130:133], v[200:203], v[110:113]
	v_mfma_f32_16x16x32_bf16 v[106:109], v[138:141], v[200:203], v[106:109]
	v_mfma_f32_16x16x32_bf16 v[94:97], v[130:133], v[208:211], v[94:97]
	v_mfma_f32_16x16x32_bf16 v[90:93], v[138:141], v[208:211], v[90:93]
	v_mfma_f32_16x16x32_bf16 v[78:81], v[130:133], v[216:219], v[78:81]
	v_mfma_f32_16x16x32_bf16 v[74:77], v[138:141], v[216:219], v[74:77]
	v_mfma_f32_16x16x32_bf16 v[126:129], v[134:137], v[182:185], v[126:129]
	v_mfma_f32_16x16x32_bf16 v[122:125], v[142:145], v[182:185], v[122:125]
	v_mfma_f32_16x16x32_bf16 v[110:113], v[134:137], v[204:207], v[110:113]
	v_mfma_f32_16x16x32_bf16 v[106:109], v[142:145], v[204:207], v[106:109]
	v_mfma_f32_16x16x32_bf16 v[94:97], v[134:137], v[212:215], v[94:97]
	v_mfma_f32_16x16x32_bf16 v[90:93], v[142:145], v[212:215], v[90:93]
	v_mfma_f32_16x16x32_bf16 v[78:81], v[134:137], v[220:223], v[78:81]
	v_mfma_f32_16x16x32_bf16 v[74:77], v[142:145], v[220:223], v[74:77]
	v_mfma_f32_16x16x32_bf16 v[118:121], v[146:149], v[178:181], v[118:121]
	v_mfma_f32_16x16x32_bf16 v[114:117], v[170:173], v[178:181], v[114:117]
	v_mfma_f32_16x16x32_bf16 v[102:105], v[146:149], v[200:203], v[102:105]
	v_mfma_f32_16x16x32_bf16 v[98:101], v[170:173], v[200:203], v[98:101]
	v_mfma_f32_16x16x32_bf16 v[86:89], v[146:149], v[208:211], v[86:89]
	v_mfma_f32_16x16x32_bf16 v[82:85], v[170:173], v[208:211], v[82:85]
	v_mfma_f32_16x16x32_bf16 v[70:73], v[146:149], v[216:219], v[70:73]
	v_mfma_f32_16x16x32_bf16 v[66:69], v[170:173], v[216:219], v[66:69]
	v_mfma_f32_16x16x32_bf16 v[118:121], v[150:153], v[182:185], v[118:121]
	v_mfma_f32_16x16x32_bf16 v[114:117], v[174:177], v[182:185], v[114:117]
	v_mfma_f32_16x16x32_bf16 v[102:105], v[150:153], v[204:207], v[102:105]
	v_mfma_f32_16x16x32_bf16 v[98:101], v[174:177], v[204:207], v[98:101]
	v_mfma_f32_16x16x32_bf16 v[86:89], v[150:153], v[212:215], v[86:89]
	v_mfma_f32_16x16x32_bf16 v[82:85], v[174:177], v[212:215], v[82:85]
	v_mfma_f32_16x16x32_bf16 v[70:73], v[150:153], v[220:223], v[70:73]
	v_mfma_f32_16x16x32_bf16 v[66:69], v[174:177], v[220:223], v[66:69]
	s_setprio 0
	s_barrier
; #define PG8_STAGE(bufoff, gbase, voff) do { _Pragma("unroll") for (int _i = 0; _i < 2; ++_i) \
;         __builtin_amdgcn_global_load_lds((const unsigned*)((const char*)(gbase) + (voff)[_i]), (LAS unsigned*)(lds + (bufoff) + ldsw + _i * 8192), 16, 0, 0); } while (0)
; #define PG8_LDA(dst, b, h) do { _Pragma("unroll") for (int m = 0; m < 4; ++m) _Pragma("unroll") for (int k = 0; k < 2; ++k) dst[m][k] = *(const LAS bf16x8*)(lds + PG8_SA(b, h) + aoff + m * 2048 + k * 1024); } while (0)
; #define PG8_LDB(dst, b, h) do { _Pragma("unroll") for (int n = 0; n < 2; ++n) _Pragma("unroll") for (int k = 0; k < 2; ++k) dst[n][k] = *(const LAS bf16x8*)(lds + PG8_SB(b, h) + boff + n * 2048 + k * 1024); } while (0)
; #define PG8_MMA(ai, bj, At, Bt) do { __builtin_amdgcn_s_setprio(3); _Pragma("unroll") for (int m = 0; m < 4; ++m) _Pragma("unroll") for (int n = 0; n < 2; ++n) _Pragma("unroll") for (int k = 0; k < 2; ++k) \
;         acc[ai][bj][m][n] = __builtin_amdgcn_mfma_f32_16x16x32_bf16(Bt[n][k], At[m][k], acc[ai][bj][m][n], 0, 0, 0); __builtin_amdgcn_s_setprio(0); } while (0)
; #define PG8_WAIT_V(n) asm volatile("s_waitcnt vmcnt(" #n ")" ::: "memory")
; #define PG8_BAR __builtin_amdgcn_s_barrier()
; template <class Epi, bool ALIGN_EPI>
; __device__ __forceinline__ void gemm_phase(LAS unsigned char* lds, const Gemm g, const StaticOrder& S, const Epi& E) {
;     ...
;             PG8_LDB(B0, 0, 0); PG8_LDB(B1, 0, 1); PG8_SCHED; PG8_LDA(At, 0, 0); PG8_STAGE(PG8_SA(1, 1), a1 + hstep, voffA);
;             PG8_WAIT_V(8); PG8_WAIT_L(0); PG8_BAR; PG8_MMA(0, 0, At, B0); PG8_MMA(0, 1, At, B1); PG8_BAR; PG8_SCHED;
;             PG8_LDA(At, 0, 1); PG8_STAGE(PG8_SB(0, 0), b2, voffB); PG8_STAGE(PG8_SB(0, 1), b2 + hstep, voffB); PG8_STAGE(PG8_SA(0, 0), a2, voffA);
;             PG8_WAIT_V(8); PG8_WAIT_L(0); PG8_BAR; PG8_MMA(1, 0, At, B0); PG8_MMA(1, 1, At, B1); PG8_BAR; PG8_SCHED;
;             PG8_LDB(B0, 1, 0); PG8_LDB(B1, 1, 1); PG8_SCHED; PG8_LDA(At, 1, 0); PG8_STAGE(PG8_SA(0, 1), a2 + hstep, voffA);
;             PG8_WAIT_V(8); PG8_WAIT_L(0); PG8_BAR; PG8_MMA(0, 0, At, B0); PG8_MMA(0, 1, At, B1); PG8_BAR; PG8_SCHED;
;             PG8_LDA(At, 1, 1); PG8_STAGE(PG8_SB(1, 0), b3, voffB); PG8_STAGE(PG8_SB(1, 1), b3 + hstep, voffB); PG8_STAGE(PG8_SA(1, 0), a3, voffA);
;             PG8_WAIT_V(8); PG8_WAIT_L(0); PG8_BAR; PG8_MMA(1, 0, At, B0); PG8_MMA(1, 1, At, B1); PG8_BAR; PG8_SCHED;
	s_add_i32 s54, s78, s57
	v_lshl_add_u64 v[186:187], v[186:187], 0, s[14:15]
	s_mov_b32 m0, s54
	ds_read_b128 v[178:181], v198 offset:49152
	ds_read_b128 v[182:185], v198 offset:50176
	ds_read_b128 v[200:203], v198 offset:51200
	ds_read_b128 v[204:207], v198 offset:52224
	ds_read_b128 v[208:211], v198 offset:53248
	ds_read_b128 v[212:215], v198 offset:54272
	ds_read_b128 v[216:219], v198 offset:55296
	ds_read_b128 v[220:223], v198 offset:56320
	global_load_lds_dwordx4 v[186:187], off
	s_add_i32 m0, s54, 0x2000
	s_add_u32 s52, s52, 0xb0080
	v_lshl_add_u64 v[186:187], v[224:225], 0, s[14:15]
	s_addc_u32 s53, s53, 0
	s_add_i32 s54, s79, s57
	global_load_lds_dwordx4 v[186:187], off
	v_lshl_add_u64 v[186:187], s[52:53], 0, v[156:157]
	s_mov_b32 m0, s54
	s_nop 0
	global_load_lds_dwordx4 v[186:187], off
	v_lshl_add_u64 v[186:187], s[52:53], 0, v[160:161]
	s_add_i32 m0, s54, 0x2000
	s_nop 0
	global_load_lds_dwordx4 v[186:187], off
	v_lshl_add_u64 v[186:187], v[226:227], 0, s[14:15]
	s_mov_b32 m0, s63
	s_nop 0
	global_load_lds_dwordx4 v[186:187], off
	v_lshl_add_u64 v[186:187], v[228:229], 0, s[14:15]
	s_mov_b32 m0, s64
	s_nop 0
	global_load_lds_dwordx4 v[186:187], off
	s_waitcnt vmcnt(8)
	s_waitcnt lgkmcnt(0)
	s_barrier
	s_setprio 3
	v_mfma_f32_16x16x32_bf16 v[62:65], v[130:133], v[178:181], v[62:65]
	v_mfma_f32_16x16x32_bf16 v[58:61], v[138:141], v[178:181], v[58:61]
	v_mfma_f32_16x16x32_bf16 v[46:49], v[130:133], v[200:203], v[46:49]
	v_mfma_f32_16x16x32_bf16 v[42:45], v[138:141], v[200:203], v[42:45]
	v_mfma_f32_16x16x32_bf16 v[30:33], v[130:133], v[208:211], v[30:33]
	v_mfma_f32_16x16x32_bf16 v[26:29], v[138:141], v[208:211], v[26:29]
	v_mfma_f32_16x16x32_bf16 v[14:17], v[130:133], v[216:219], v[14:17]
	v_mfma_f32_16x16x32_bf16 v[10:13], v[138:141], v[216:219], v[10:13]
	v_mfma_f32_16x16x32_bf16 v[62:65], v[134:137], v[182:185], v[62:65]
	v_mfma_f32_16x16x32_bf16 v[58:61], v[142:145], v[182:185], v[58:61]
	v_mfma_f32_16x16x32_bf16 v[46:49], v[134:137], v[204:207], v[46:49]
	v_mfma_f32_16x16x32_bf16 v[42:45], v[142:145], v[204:207], v[42:45]
	v_mfma_f32_16x16x32_bf16 v[30:33], v[134:137], v[212:215], v[30:33]
	v_mfma_f32_16x16x32_bf16 v[26:29], v[142:145], v[212:215], v[26:29]
	v_mfma_f32_16x16x32_bf16 v[14:17], v[134:137], v[220:223], v[14:17]
	v_mfma_f32_16x16x32_bf16 v[10:13], v[142:145], v[220:223], v[10:13]
	v_mfma_f32_16x16x32_bf16 v[54:57], v[146:149], v[178:181], v[54:57]
	v_mfma_f32_16x16x32_bf16 v[50:53], v[170:173], v[178:181], v[50:53]
	v_mfma_f32_16x16x32_bf16 v[38:41], v[146:149], v[200:203], v[38:41]
	v_mfma_f32_16x16x32_bf16 v[34:37], v[170:173], v[200:203], v[34:37]
	v_mfma_f32_16x16x32_bf16 v[22:25], v[146:149], v[208:211], v[22:25]
	v_mfma_f32_16x16x32_bf16 v[18:21], v[170:173], v[208:211], v[18:21]
	v_mfma_f32_16x16x32_bf16 v[6:9], v[146:149], v[216:219], v[6:9]
	v_mfma_f32_16x16x32_bf16 v[2:5], v[170:173], v[216:219], v[2:5]
	v_mfma_f32_16x16x32_bf16 v[54:57], v[150:153], v[182:185], v[54:57]
	v_mfma_f32_16x16x32_bf16 v[50:53], v[174:177], v[182:185], v[50:53]
	v_mfma_f32_16x16x32_bf16 v[38:41], v[150:153], v[204:207], v[38:41]
	v_mfma_f32_16x16x32_bf16 v[34:37], v[174:177], v[204:207], v[34:37]
	v_mfma_f32_16x16x32_bf16 v[22:25], v[150:153], v[212:215], v[22:25]
	v_mfma_f32_16x16x32_bf16 v[18:21], v[174:177], v[212:215], v[18:21]
	v_mfma_f32_16x16x32_bf16 v[6:9], v[150:153], v[220:223], v[6:9]
	v_mfma_f32_16x16x32_bf16 v[2:5], v[174:177], v[220:223], v[2:5]
	s_setprio 0
	s_barrier
	s_add_i32 s77, s77, 2
	s_add_u32 s50, s50, 0x100
	s_addc_u32 s51, s51, 0
	s_add_u32 s73, s73, 0x100
	s_addc_u32 s76, s76, 0
.LBB0_696:
	ds_read_b128 v[130:133], v196
	ds_read_b128 v[134:137], v196 offset:1024
	ds_read_b128 v[138:141], v196 offset:2048
	ds_read_b128 v[142:145], v196 offset:3072
	ds_read_b128 v[146:149], v197
	ds_read_b128 v[150:153], v197 offset:1024
	ds_read_b128 v[170:173], v197 offset:2048
	ds_read_b128 v[174:177], v197 offset:3072
	s_add_u32 s52, s50, 0xfff50080
	s_addc_u32 s53, s51, -1
	s_cmp_eq_u32 s77, 40
	s_cselect_b32 s55, s5, s53
	s_cselect_b32 s54, s4, s52
	s_cselect_b32 s53, s19, s76
	s_cselect_b32 s52, s18, s73
	v_lshl_add_u64 v[186:187], s[50:51], 0, v[162:163]
	s_add_i32 m0, s58, 0xc000
	ds_read_b128 v[178:181], v198
	ds_read_b128 v[182:185], v198 offset:1024
	ds_read_b128 v[200:203], v198 offset:2048
	ds_read_b128 v[204:207], v198 offset:3072
	ds_read_b128 v[208:211], v198 offset:4096
	ds_read_b128 v[212:215], v198 offset:5120
	ds_read_b128 v[216:219], v198 offset:6144
	ds_read_b128 v[220:223], v198 offset:7168
	global_load_lds_dwordx4 v[186:187], off
	v_lshl_add_u64 v[186:187], s[50:51], 0, v[164:165]
	s_add_i32 m0, s58, 0xe000
	s_nop 0
	global_load_lds_dwordx4 v[186:187], off
	s_waitcnt vmcnt(8)
	s_waitcnt lgkmcnt(0)
	s_barrier
; #define PG8_STAGE(bufoff, gbase, voff) do { _Pragma("unroll") for (int _i = 0; _i < 2; ++_i) \
;         __builtin_amdgcn_global_load_lds((const unsigned*)((const char*)(gbase) + (voff)[_i]), (LAS unsigned*)(lds + (bufoff) + ldsw + _i * 8192), 16, 0, 0); } while (0)
; #define PG8_LDA(dst, b, h) do { _Pragma("unroll") for (int m = 0; m < 4; ++m) _Pragma("unroll") for (int k = 0; k < 2; ++k) dst[m][k] = *(const LAS bf16x8*)(lds + PG8_SA(b, h) + aoff + m * 2048 + k * 1024); } while (0)
; #define PG8_MMA(ai, bj, At, Bt) do { __builtin_amdgcn_s_setprio(3); _Pragma("unroll") for (int m = 0; m < 4; ++m) _Pragma("unroll") for (int n = 0; n < 2; ++n) _Pragma("unroll") for (int k = 0; k < 2; ++k) \
;         acc[ai][bj][m][n] = __builtin_amdgcn_mfma_f32_16x16x32_bf16(Bt[n][k], At[m][k], acc[ai][bj][m][n], 0, 0, 0); __builtin_amdgcn_s_setprio(0); } while (0)
; #define PG8_WAIT_V(n) asm volatile("s_waitcnt vmcnt(" #n ")" ::: "memory")
; #define PG8_WAIT_L(n) asm volatile("s_waitcnt lgkmcnt(" #n ")" ::: "memory")
; #define PG8_BAR __builtin_amdgcn_s_barrier()
; #define PG8_SCHED __builtin_amdgcn_sched_barrier(0)
; template <class Epi, bool ALIGN_EPI>
; __device__ __forceinline__ void gemm_phase(LAS unsigned char* lds, const Gemm g, const StaticOrder& S, const Epi& E) {
;     ...
;             PG8_WAIT_V(8); PG8_WAIT_L(0); PG8_BAR; PG8_MMA(0, 0, At, B0); PG8_MMA(0, 1, At, B1); PG8_BAR; PG8_SCHED;
;             PG8_LDA(At, 0, 1); PG8_STAGE(PG8_SB(0, 0), b2, voffB); PG8_STAGE(PG8_SB(0, 1), b2 + hstep, voffB); PG8_STAGE(PG8_SA(0, 0), a2, voffA);
;             PG8_WAIT_V(8); PG8_WAIT_L(0); PG8_BAR; PG8_MMA(1, 0, At, B0); PG8_MMA(1, 1, At, B1); PG8_BAR; PG8_SCHED;
	s_setprio 3
	v_mfma_f32_16x16x32_bf16 v[126:129], v[130:133], v[178:181], v[126:129]
	v_mfma_f32_16x16x32_bf16 v[122:125], v[138:141], v[178:181], v[122:125]
	v_mfma_f32_16x16x32_bf16 v[110:113], v[130:133], v[200:203], v[110:113]
	v_mfma_f32_16x16x32_bf16 v[106:109], v[138:141], v[200:203], v[106:109]
	v_mfma_f32_16x16x32_bf16 v[94:97], v[130:133], v[208:211], v[94:97]
	v_mfma_f32_16x16x32_bf16 v[90:93], v[138:141], v[208:211], v[90:93]
	v_mfma_f32_16x16x32_bf16 v[78:81], v[130:133], v[216:219], v[78:81]
	v_mfma_f32_16x16x32_bf16 v[74:77], v[138:141], v[216:219], v[74:77]
	v_mfma_f32_16x16x32_bf16 v[126:129], v[134:137], v[182:185], v[126:129]
	v_mfma_f32_16x16x32_bf16 v[122:125], v[142:145], v[182:185], v[122:125]
	v_mfma_f32_16x16x32_bf16 v[110:113], v[134:137], v[204:207], v[110:113]
	v_mfma_f32_16x16x32_bf16 v[106:109], v[142:145], v[204:207], v[106:109]
	v_mfma_f32_16x16x32_bf16 v[94:97], v[134:137], v[212:215], v[94:97]
	v_mfma_f32_16x16x32_bf16 v[90:93], v[142:145], v[212:215], v[90:93]
	v_mfma_f32_16x16x32_bf16 v[78:81], v[134:137], v[220:223], v[78:81]
	v_mfma_f32_16x16x32_bf16 v[74:77], v[142:145], v[220:223], v[74:77]
	v_mfma_f32_16x16x32_bf16 v[118:121], v[146:149], v[178:181], v[118:121]
	v_mfma_f32_16x16x32_bf16 v[114:117], v[170:173], v[178:181], v[114:117]
	v_mfma_f32_16x16x32_bf16 v[102:105], v[146:149], v[200:203], v[102:105]
	v_mfma_f32_16x16x32_bf16 v[98:101], v[170:173], v[200:203], v[98:101]
	v_mfma_f32_16x16x32_bf16 v[86:89], v[146:149], v[208:211], v[86:89]
	v_mfma_f32_16x16x32_bf16 v[82:85], v[170:173], v[208:211], v[82:85]
	v_mfma_f32_16x16x32_bf16 v[70:73], v[146:149], v[216:219], v[70:73]
	v_mfma_f32_16x16x32_bf16 v[66:69], v[170:173], v[216:219], v[66:69]
	v_mfma_f32_16x16x32_bf16 v[118:121], v[150:153], v[182:185], v[118:121]
	v_mfma_f32_16x16x32_bf16 v[114:117], v[174:177], v[182:185], v[114:117]
	v_mfma_f32_16x16x32_bf16 v[102:105], v[150:153], v[204:207], v[102:105]
	v_mfma_f32_16x16x32_bf16 v[98:101], v[174:177], v[204:207], v[98:101]
	v_mfma_f32_16x16x32_bf16 v[86:89], v[150:153], v[212:215], v[86:89]
	v_mfma_f32_16x16x32_bf16 v[82:85], v[174:177], v[212:215], v[82:85]
	v_mfma_f32_16x16x32_bf16 v[70:73], v[150:153], v[220:223], v[70:73]
	v_mfma_f32_16x16x32_bf16 v[66:69], v[174:177], v[220:223], v[66:69]
	s_setprio 0
	s_barrier
	s_add_i32 s78, s67, s57
	v_lshl_add_u64 v[186:187], s[52:53], 0, v[156:157]
	s_mov_b32 m0, s78
	ds_read_b128 v[178:181], v198 offset:16384
	ds_read_b128 v[182:185], v198 offset:17408
	ds_read_b128 v[200:203], v198 offset:18432
	ds_read_b128 v[204:207], v198 offset:19456
	ds_read_b128 v[208:211], v198 offset:20480
	ds_read_b128 v[212:215], v198 offset:21504
	ds_read_b128 v[216:219], v198 offset:22528
	ds_read_b128 v[220:223], v198 offset:23552
	global_load_lds_dwordx4 v[186:187], off
	s_add_i32 m0, s78, 0x2000
	s_add_u32 s78, s52, 0xb0000
	v_lshl_add_u64 v[224:225], s[52:53], 0, v[160:161]
	s_addc_u32 s79, s53, 0
	s_add_i32 s80, s68, s57
	global_load_lds_dwordx4 v[224:225], off
	v_lshl_add_u64 v[226:227], s[78:79], 0, v[156:157]
	s_mov_b32 m0, s80
	v_lshl_add_u64 v[228:229], s[54:55], 0, v[158:159]
	global_load_lds_dwordx4 v[226:227], off
	v_lshl_add_u64 v[226:227], s[78:79], 0, v[160:161]
	s_add_i32 m0, s80, 0x2000
	s_nop 0
	global_load_lds_dwordx4 v[226:227], off
	v_lshl_add_u64 v[226:227], s[54:55], 0, v[154:155]
	s_mov_b32 m0, s58
	s_nop 0
	global_load_lds_dwordx4 v[226:227], off
	s_mov_b32 m0, s59
	s_nop 0
	global_load_lds_dwordx4 v[228:229], off
	s_waitcnt vmcnt(8)
	s_waitcnt lgkmcnt(0)
	s_barrier
	s_setprio 3
	v_mfma_f32_16x16x32_bf16 v[62:65], v[130:133], v[178:181], v[62:65]
	v_mfma_f32_16x16x32_bf16 v[58:61], v[138:141], v[178:181], v[58:61]
	v_mfma_f32_16x16x32_bf16 v[46:49], v[130:133], v[200:203], v[46:49]
	v_mfma_f32_16x16x32_bf16 v[42:45], v[138:141], v[200:203], v[42:45]
	v_mfma_f32_16x16x32_bf16 v[30:33], v[130:133], v[208:211], v[30:33]
	v_mfma_f32_16x16x32_bf16 v[26:29], v[138:141], v[208:211], v[26:29]
	v_mfma_f32_16x16x32_bf16 v[14:17], v[130:133], v[216:219], v[14:17]
	v_mfma_f32_16x16x32_bf16 v[10:13], v[138:141], v[216:219], v[10:13]
	v_mfma_f32_16x16x32_bf16 v[62:65], v[134:137], v[182:185], v[62:65]
	v_mfma_f32_16x16x32_bf16 v[58:61], v[142:145], v[182:185], v[58:61]
	v_mfma_f32_16x16x32_bf16 v[46:49], v[134:137], v[204:207], v[46:49]
	v_mfma_f32_16x16x32_bf16 v[42:45], v[142:145], v[204:207], v[42:45]
	v_mfma_f32_16x16x32_bf16 v[30:33], v[134:137], v[212:215], v[30:33]
	v_mfma_f32_16x16x32_bf16 v[26:29], v[142:145], v[212:215], v[26:29]
	v_mfma_f32_16x16x32_bf16 v[14:17], v[134:137], v[220:223], v[14:17]
	v_mfma_f32_16x16x32_bf16 v[10:13], v[142:145], v[220:223], v[10:13]
	v_mfma_f32_16x16x32_bf16 v[54:57], v[146:149], v[178:181], v[54:57]
	v_mfma_f32_16x16x32_bf16 v[50:53], v[170:173], v[178:181], v[50:53]
	v_mfma_f32_16x16x32_bf16 v[38:41], v[146:149], v[200:203], v[38:41]
	v_mfma_f32_16x16x32_bf16 v[34:37], v[170:173], v[200:203], v[34:37]
	v_mfma_f32_16x16x32_bf16 v[22:25], v[146:149], v[208:211], v[22:25]
	v_mfma_f32_16x16x32_bf16 v[18:21], v[170:173], v[208:211], v[18:21]
	v_mfma_f32_16x16x32_bf16 v[6:9], v[146:149], v[216:219], v[6:9]
	v_mfma_f32_16x16x32_bf16 v[2:5], v[170:173], v[216:219], v[2:5]
	v_mfma_f32_16x16x32_bf16 v[54:57], v[150:153], v[182:185], v[54:57]
	v_mfma_f32_16x16x32_bf16 v[50:53], v[174:177], v[182:185], v[50:53]
	v_mfma_f32_16x16x32_bf16 v[38:41], v[150:153], v[204:207], v[38:41]
	v_mfma_f32_16x16x32_bf16 v[34:37], v[174:177], v[204:207], v[34:37]
	v_mfma_f32_16x16x32_bf16 v[22:25], v[150:153], v[212:215], v[22:25]
	v_mfma_f32_16x16x32_bf16 v[18:21], v[174:177], v[212:215], v[18:21]
	v_mfma_f32_16x16x32_bf16 v[6:9], v[150:153], v[220:223], v[6:9]
	v_mfma_f32_16x16x32_bf16 v[2:5], v[174:177], v[220:223], v[2:5]
	s_setprio 0
	s_barrier
; #define PG8_STAGE(bufoff, gbase, voff) do { _Pragma("unroll") for (int _i = 0; _i < 2; ++_i) \
;         __builtin_amdgcn_global_load_lds((const unsigned*)((const char*)(gbase) + (voff)[_i]), (LAS unsigned*)(lds + (bufoff) + ldsw + _i * 8192), 16, 0, 0); } while (0)
; #define PG8_LDA(dst, b, h) do { _Pragma("unroll") for (int m = 0; m < 4; ++m) _Pragma("unroll") for (int k = 0; k < 2; ++k) dst[m][k] = *(const LAS bf16x8*)(lds + PG8_SA(b, h) + aoff + m * 2048 + k * 1024); } while (0)
; #define PG8_LDB(dst, b, h) do { _Pragma("unroll") for (int n = 0; n < 2; ++n) _Pragma("unroll") for (int k = 0; k < 2; ++k) dst[n][k] = *(const LAS bf16x8*)(lds + PG8_SB(b, h) + boff + n * 2048 + k * 1024); } while (0)
; #define PG8_MMA(ai, bj, At, Bt) do { __builtin_amdgcn_s_setprio(3); _Pragma("unroll") for (int m = 0; m < 4; ++m) _Pragma("unroll") for (int n = 0; n < 2; ++n) _Pragma("unroll") for (int k = 0; k < 2; ++k) \
;         acc[ai][bj][m][n] = __builtin_amdgcn_mfma_f32_16x16x32_bf16(Bt[n][k], At[m][k], acc[ai][bj][m][n], 0, 0, 0); __builtin_amdgcn_s_setprio(0); } while (0)
; #define PG8_WAIT_V(n) asm volatile("s_waitcnt vmcnt(" #n ")" ::: "memory")
; #define PG8_WAIT_L(n) asm volatile("s_waitcnt lgkmcnt(" #n ")" ::: "memory")
; #define PG8_BAR __builtin_amdgcn_s_barrier()
; #define PG8_SCHED __builtin_amdgcn_sched_barrier(0)
; template <class Epi, bool ALIGN_EPI>
; __device__ __forceinline__ void gemm_phase(LAS unsigned char* lds, const Gemm g, const StaticOrder& S, const Epi& E) {
;     ...
;             PG8_LDB(B0, 1, 0); PG8_LDB(B1, 1, 1); PG8_SCHED; PG8_LDA(At, 1, 0); PG8_STAGE(PG8_SA(0, 1), a2 + hstep, voffA);
;             PG8_WAIT_V(8); PG8_WAIT_L(0); PG8_BAR; PG8_MMA(0, 0, At, B0); PG8_MMA(0, 1, At, B1); PG8_BAR; PG8_SCHED;
	s_add_i32 s78, 0, 0x18000
	s_add_i32 s79, 0, 0x1c000
	v_add_u32_e32 v142, s78, v194
	v_add_u32_e32 v174, s79, v194
	ds_read_b128 v[130:133], v142
	ds_read_b128 v[134:137], v142 offset:1024
	ds_read_b128 v[138:141], v142 offset:2048
	ds_read_b128 v[142:145], v142 offset:3072
	ds_read_b128 v[146:149], v174
	ds_read_b128 v[150:153], v174 offset:1024
	ds_read_b128 v[170:173], v174 offset:2048
	ds_read_b128 v[174:177], v174 offset:3072
	s_add_u32 s54, s54, 0xb0000
	s_addc_u32 s55, s55, 0
	s_mov_b32 m0, s60
	v_lshl_add_u64 v[230:231], s[54:55], 0, v[154:155]
	ds_read_b128 v[178:181], v198 offset:32768
	ds_read_b128 v[182:185], v198 offset:33792
	ds_read_b128 v[200:203], v198 offset:34816
	ds_read_b128 v[204:207], v198 offset:35840
	ds_read_b128 v[208:211], v198 offset:36864
	ds_read_b128 v[212:215], v198 offset:37888
	ds_read_b128 v[216:219], v198 offset:38912
	ds_read_b128 v[220:223], v198 offset:39936
	global_load_lds_dwordx4 v[230:231], off
	v_lshl_add_u64 v[230:231], s[54:55], 0, v[158:159]
	s_mov_b32 m0, s61
	s_nop 0
	global_load_lds_dwordx4 v[230:231], off
	s_waitcnt vmcnt(8)
	s_waitcnt lgkmcnt(0)
	s_barrier
	s_setprio 3
	v_mfma_f32_16x16x32_bf16 v[126:129], v[130:133], v[178:181], v[126:129]
	v_mfma_f32_16x16x32_bf16 v[122:125], v[138:141], v[178:181], v[122:125]
	v_mfma_f32_16x16x32_bf16 v[110:113], v[130:133], v[200:203], v[110:113]
	v_mfma_f32_16x16x32_bf16 v[106:109], v[138:141], v[200:203], v[106:109]
	v_mfma_f32_16x16x32_bf16 v[94:97], v[130:133], v[208:211], v[94:97]
	v_mfma_f32_16x16x32_bf16 v[90:93], v[138:141], v[208:211], v[90:93]
	v_mfma_f32_16x16x32_bf16 v[78:81], v[130:133], v[216:219], v[78:81]
	v_mfma_f32_16x16x32_bf16 v[74:77], v[138:141], v[216:219], v[74:77]
	v_mfma_f32_16x16x32_bf16 v[126:129], v[134:137], v[182:185], v[126:129]
	v_mfma_f32_16x16x32_bf16 v[122:125], v[142:145], v[182:185], v[122:125]
	v_mfma_f32_16x16x32_bf16 v[110:113], v[134:137], v[204:207], v[110:113]
	v_mfma_f32_16x16x32_bf16 v[106:109], v[142:145], v[204:207], v[106:109]
	v_mfma_f32_16x16x32_bf16 v[94:97], v[134:137], v[212:215], v[94:97]
	v_mfma_f32_16x16x32_bf16 v[90:93], v[142:145], v[212:215], v[90:93]
	v_mfma_f32_16x16x32_bf16 v[78:81], v[134:137], v[220:223], v[78:81]
	v_mfma_f32_16x16x32_bf16 v[74:77], v[142:145], v[220:223], v[74:77]
	v_mfma_f32_16x16x32_bf16 v[118:121], v[146:149], v[178:181], v[118:121]
	v_mfma_f32_16x16x32_bf16 v[114:117], v[170:173], v[178:181], v[114:117]
	v_mfma_f32_16x16x32_bf16 v[102:105], v[146:149], v[200:203], v[102:105]
	v_mfma_f32_16x16x32_bf16 v[98:101], v[170:173], v[200:203], v[98:101]
	v_mfma_f32_16x16x32_bf16 v[86:89], v[146:149], v[208:211], v[86:89]
	v_mfma_f32_16x16x32_bf16 v[82:85], v[170:173], v[208:211], v[82:85]
	v_mfma_f32_16x16x32_bf16 v[70:73], v[146:149], v[216:219], v[70:73]
	v_mfma_f32_16x16x32_bf16 v[66:69], v[170:173], v[216:219], v[66:69]
	v_mfma_f32_16x16x32_bf16 v[118:121], v[150:153], v[182:185], v[118:121]
	v_mfma_f32_16x16x32_bf16 v[114:117], v[174:177], v[182:185], v[114:117]
	v_mfma_f32_16x16x32_bf16 v[102:105], v[150:153], v[204:207], v[102:105]
	v_mfma_f32_16x16x32_bf16 v[98:101], v[174:177], v[204:207], v[98:101]
	v_mfma_f32_16x16x32_bf16 v[86:89], v[150:153], v[212:215], v[86:89]
	v_mfma_f32_16x16x32_bf16 v[82:85], v[174:177], v[212:215], v[82:85]
	v_mfma_f32_16x16x32_bf16 v[70:73], v[150:153], v[220:223], v[70:73]
	v_mfma_f32_16x16x32_bf16 v[66:69], v[174:177], v[220:223], v[66:69]
	s_setprio 0
	s_barrier
; #define PG8_STAGE(bufoff, gbase, voff) do { _Pragma("unroll") for (int _i = 0; _i < 2; ++_i) \
;         __builtin_amdgcn_global_load_lds((const unsigned*)((const char*)(gbase) + (voff)[_i]), (LAS unsigned*)(lds + (bufoff) + ldsw + _i * 8192), 16, 0, 0); } while (0)
; #define PG8_LDA(dst, b, h) do { _Pragma("unroll") for (int m = 0; m < 4; ++m) _Pragma("unroll") for (int k = 0; k < 2; ++k) dst[m][k] = *(const LAS bf16x8*)(lds + PG8_SA(b, h) + aoff + m * 2048 + k * 1024); } while (0)
; #define PG8_MMA(ai, bj, At, Bt) do { __builtin_amdgcn_s_setprio(3); _Pragma("unroll") for (int m = 0; m < 4; ++m) _Pragma("unroll") for (int n = 0; n < 2; ++n) _Pragma("unroll") for (int k = 0; k < 2; ++k) \
;         acc[ai][bj][m][n] = __builtin_amdgcn_mfma_f32_16x16x32_bf16(Bt[n][k], At[m][k], acc[ai][bj][m][n], 0, 0, 0); __builtin_amdgcn_s_setprio(0); } while (0)
; #define PG8_WAIT_V(n) asm volatile("s_waitcnt vmcnt(" #n ")" ::: "memory")
; #define PG8_WAIT_L(n) asm volatile("s_waitcnt lgkmcnt(" #n ")" ::: "memory")
; #define PG8_BAR __builtin_amdgcn_s_barrier()
; #define PG8_SCHED __builtin_amdgcn_sched_barrier(0)
; template <class Epi, bool ALIGN_EPI>
; __device__ __forceinline__ void gemm_phase(LAS unsigned char* lds, const Gemm g, const StaticOrder& S, const Epi& E) {
;     ...
;             PG8_LDA(At, 1, 1); PG8_STAGE(PG8_SB(1, 0), b3, voffB); PG8_STAGE(PG8_SB(1, 1), b3 + hstep, voffB); PG8_STAGE(PG8_SA(1, 0), a3, voffA);
;             PG8_WAIT_V(8); PG8_WAIT_L(0); PG8_BAR; PG8_MMA(1, 0, At, B0); PG8_MMA(1, 1, At, B1); PG8_BAR; PG8_SCHED;
;         }
;         if constexpr (ALIGN_EPI) { if (wr == 0) PG8_BAR; }
	s_add_i32 s54, s78, s57
	v_lshl_add_u64 v[186:187], v[186:187], 0, s[14:15]
	s_mov_b32 m0, s54
	ds_read_b128 v[178:181], v198 offset:49152
	ds_read_b128 v[182:185], v198 offset:50176
	ds_read_b128 v[200:203], v198 offset:51200
	ds_read_b128 v[204:207], v198 offset:52224
	ds_read_b128 v[208:211], v198 offset:53248
	ds_read_b128 v[212:215], v198 offset:54272
	ds_read_b128 v[216:219], v198 offset:55296
	ds_read_b128 v[220:223], v198 offset:56320
	global_load_lds_dwordx4 v[186:187], off
	s_add_i32 m0, s54, 0x2000
	s_add_u32 s52, s52, 0xb0080
	v_lshl_add_u64 v[186:187], v[224:225], 0, s[14:15]
	s_addc_u32 s53, s53, 0
	s_add_i32 s54, s79, s57
	global_load_lds_dwordx4 v[186:187], off
	v_lshl_add_u64 v[186:187], s[52:53], 0, v[156:157]
	s_mov_b32 m0, s54
	s_nop 0
	global_load_lds_dwordx4 v[186:187], off
	v_lshl_add_u64 v[186:187], s[52:53], 0, v[160:161]
	s_add_i32 m0, s54, 0x2000
	s_nop 0
	global_load_lds_dwordx4 v[186:187], off
	v_lshl_add_u64 v[186:187], v[226:227], 0, s[14:15]
	s_mov_b32 m0, s63
	s_nop 0
	global_load_lds_dwordx4 v[186:187], off
	v_lshl_add_u64 v[186:187], v[228:229], 0, s[14:15]
	s_mov_b32 m0, s64
	s_nop 0
	global_load_lds_dwordx4 v[186:187], off
	s_waitcnt vmcnt(8)
	s_waitcnt lgkmcnt(0)
	s_barrier
	s_setprio 3
	v_mfma_f32_16x16x32_bf16 v[62:65], v[130:133], v[178:181], v[62:65]
	v_mfma_f32_16x16x32_bf16 v[58:61], v[138:141], v[178:181], v[58:61]
	v_mfma_f32_16x16x32_bf16 v[46:49], v[130:133], v[200:203], v[46:49]
	v_mfma_f32_16x16x32_bf16 v[42:45], v[138:141], v[200:203], v[42:45]
	v_mfma_f32_16x16x32_bf16 v[30:33], v[130:133], v[208:211], v[30:33]
	v_mfma_f32_16x16x32_bf16 v[26:29], v[138:141], v[208:211], v[26:29]
	v_mfma_f32_16x16x32_bf16 v[14:17], v[130:133], v[216:219], v[14:17]
	v_mfma_f32_16x16x32_bf16 v[10:13], v[138:141], v[216:219], v[10:13]
	v_mfma_f32_16x16x32_bf16 v[62:65], v[134:137], v[182:185], v[62:65]
	v_mfma_f32_16x16x32_bf16 v[58:61], v[142:145], v[182:185], v[58:61]
	v_mfma_f32_16x16x32_bf16 v[46:49], v[134:137], v[204:207], v[46:49]
	v_mfma_f32_16x16x32_bf16 v[42:45], v[142:145], v[204:207], v[42:45]
	v_mfma_f32_16x16x32_bf16 v[30:33], v[134:137], v[212:215], v[30:33]
	v_mfma_f32_16x16x32_bf16 v[26:29], v[142:145], v[212:215], v[26:29]
	v_mfma_f32_16x16x32_bf16 v[14:17], v[134:137], v[220:223], v[14:17]
	v_mfma_f32_16x16x32_bf16 v[10:13], v[142:145], v[220:223], v[10:13]
	v_mfma_f32_16x16x32_bf16 v[54:57], v[146:149], v[178:181], v[54:57]
	v_mfma_f32_16x16x32_bf16 v[50:53], v[170:173], v[178:181], v[50:53]
	v_mfma_f32_16x16x32_bf16 v[38:41], v[146:149], v[200:203], v[38:41]
	v_mfma_f32_16x16x32_bf16 v[34:37], v[170:173], v[200:203], v[34:37]
	v_mfma_f32_16x16x32_bf16 v[22:25], v[146:149], v[208:211], v[22:25]
	v_mfma_f32_16x16x32_bf16 v[18:21], v[170:173], v[208:211], v[18:21]
	v_mfma_f32_16x16x32_bf16 v[6:9], v[146:149], v[216:219], v[6:9]
	v_mfma_f32_16x16x32_bf16 v[2:5], v[170:173], v[216:219], v[2:5]
	v_mfma_f32_16x16x32_bf16 v[54:57], v[150:153], v[182:185], v[54:57]
	v_mfma_f32_16x16x32_bf16 v[50:53], v[174:177], v[182:185], v[50:53]
	v_mfma_f32_16x16x32_bf16 v[38:41], v[150:153], v[204:207], v[38:41]
	v_mfma_f32_16x16x32_bf16 v[34:37], v[174:177], v[204:207], v[34:37]
	v_mfma_f32_16x16x32_bf16 v[22:25], v[150:153], v[212:215], v[22:25]
	v_mfma_f32_16x16x32_bf16 v[18:21], v[174:177], v[212:215], v[18:21]
	v_mfma_f32_16x16x32_bf16 v[6:9], v[150:153], v[220:223], v[6:9]
	v_mfma_f32_16x16x32_bf16 v[2:5], v[174:177], v[220:223], v[2:5]
	s_setprio 0
	s_barrier
	s_add_i32 s77, s77, 2
	s_add_u32 s50, s50, 0x100
	s_addc_u32 s51, s51, 0
	s_add_u32 s73, s73, 0x100
	s_addc_u32 s76, s76, 0
	s_cmp_gt_u32 s77, 41
	s_cbranch_scc0 .LBB0_696
	s_and_b64 vcc, exec, s[16:17]
	s_cbranch_vccz .LBB0_699
	s_barrier

; #define PG8_STAGE(bufoff, gbase, voff) do { _Pragma("unroll") for (int _i = 0; _i < 2; ++_i) \
;         __builtin_amdgcn_global_load_lds((const unsigned*)((const char*)(gbase) + (voff)[_i]), (LAS unsigned*)(lds + (bufoff) + ldsw + _i * 8192), 16, 0, 0); } while (0)
; #define PG8_LDA(dst, b, h) do { _Pragma("unroll") for (int m = 0; m < 4; ++m) _Pragma("unroll") for (int k = 0; k < 2; ++k) dst[m][k] = *(const LAS bf16x8*)(lds + PG8_SA(b, h) + aoff + m * 2048 + k * 1024); } while (0)
; #define PG8_LDB(dst, b, h) do { _Pragma("unroll") for (int n = 0; n < 2; ++n) _Pragma("unroll") for (int k = 0; k < 2; ++k) dst[n][k] = *(const LAS bf16x8*)(lds + PG8_SB(b, h) + boff + n * 2048 + k * 1024); } while (0)
; #define PG8_MMA(ai, bj, At, Bt) do { __builtin_amdgcn_s_setprio(3); _Pragma("unroll") for (int m = 0; m < 4; ++m) _Pragma("unroll") for (int n = 0; n < 2; ++n) _Pragma("unroll") for (int k = 0; k < 2; ++k) \
;         acc[ai][bj][m][n] = __builtin_amdgcn_mfma_f32_16x16x32_bf16(Bt[n][k], At[m][k], acc[ai][bj][m][n], 0, 0, 0); __builtin_amdgcn_s_setprio(0); } while (0)
; #define PG8_WAIT_V(n) asm volatile("s_waitcnt vmcnt(" #n ")" ::: "memory")
; #define PG8_WAIT_L(n) asm volatile("s_waitcnt lgkmcnt(" #n ")" ::: "memory")
; template <class Epi, bool ALIGN_EPI>
; __device__ __forceinline__ void gemm_phase(LAS unsigned char* lds, const Gemm g, const StaticOrder& S, const Epi& E) {
;     ...
;         const bool has_next = S.next(ui + 1, nxt);
;         const char* nA = has_next ? (const char*)g.A + (size_t)nxt.pm * tstep : cA; const char* nB = has_next ? (const char*)g.Bt + (size_t)nxt.pn * tstep : cB;
;         for (int t = 0; t < nt; t += 2) {
;             const bool last = (t == nt - 2);
;             const char* a1 = cA + (size_t)(t + 1) * kstep;
;             const char* a2 = last ? nA : cA + (size_t)(t + 2) * kstep; const char* b2 = last ? nB : cB + (size_t)(t + 2) * kstep;
;             const char* a3 = a2 + kstep; const char* b3 = b2 + kstep;
;             PG8_LDB(B0, 0, 0); PG8_LDB(B1, 0, 1); PG8_SCHED; PG8_LDA(At, 0, 0); PG8_STAGE(PG8_SA(1, 1), a1 + hstep, voffA);
;             PG8_WAIT_V(8); PG8_WAIT_L(0); PG8_BAR; PG8_MMA(0, 0, At, B0); PG8_MMA(0, 1, At, B1); PG8_BAR; PG8_SCHED;
;             PG8_LDA(At, 0, 1); PG8_STAGE(PG8_SB(0, 0), b2, voffB); PG8_STAGE(PG8_SB(0, 1), b2 + hstep, voffB); PG8_STAGE(PG8_SA(0, 0), a2, voffA);
.LBB0_786:
	s_ashr_i32 s79, s78, 31
	s_lshl_b64 s[8:9], s[78:79], 19
	s_add_u32 s80, s34, s8
	s_addc_u32 s81, s35, s9
	s_and_b64 s[8:9], s[10:11], exec
	s_cselect_b32 s50, s81, s5
	s_cselect_b32 s55, s80, s4
	s_ashr_i32 s73, s72, 31
	s_lshl_b64 s[8:9], s[72:73], 19
	s_add_u32 s82, s18, s8
	s_addc_u32 s83, s19, s9
	s_and_b64 s[8:9], s[10:11], exec
	s_cselect_b32 s73, s83, s7
	s_cselect_b32 s79, s82, s6
	s_add_u32 s4, s4, 0x40080
	s_addc_u32 s5, s5, 0
	s_add_u32 s85, s6, 0x100
	s_addc_u32 s88, s7, 0
	s_mov_b32 s89, -2
	s_waitcnt lgkmcnt(0)
	ds_read_b128 v[130:133], v220
	ds_read_b128 v[134:137], v220 offset:1024
	ds_read_b128 v[138:141], v220 offset:2048
	ds_read_b128 v[142:145], v220 offset:3072
	ds_read_b128 v[166:169], v221
	ds_read_b128 v[170:173], v221 offset:1024
	ds_read_b128 v[174:177], v221 offset:2048
	ds_read_b128 v[178:181], v221 offset:3072
	s_add_u32 s6, s4, 0xfffc0080
	s_addc_u32 s7, s5, -1
	s_cmp_eq_u32 s89, 12
	s_cselect_b32 s9, s50, s7
	s_cselect_b32 s8, s55, s6
	s_cselect_b32 s7, s73, s88
	s_cselect_b32 s6, s79, s85
	v_lshl_add_u64 v[230:231], s[4:5], 0, v[158:159]
	s_add_i32 m0, s77, 0xc000
	ds_read_b128 v[182:185], v222
	ds_read_b128 v[186:189], v222 offset:1024
	ds_read_b128 v[190:193], v222 offset:2048
	ds_read_b128 v[194:197], v222 offset:3072
	ds_read_b128 v[198:201], v222 offset:4096
	ds_read_b128 v[202:205], v222 offset:5120
	ds_read_b128 v[206:209], v222 offset:6144
	ds_read_b128 v[226:229], v222 offset:7168
	global_load_lds_dwordx4 v[230:231], off
	v_lshl_add_u64 v[230:231], s[4:5], 0, v[160:161]
	s_add_i32 m0, s77, 0xe000
	s_nop 0
	global_load_lds_dwordx4 v[230:231], off
	s_waitcnt vmcnt(8)
	s_waitcnt lgkmcnt(0)
	s_barrier
	s_setprio 3
	v_mfma_f32_16x16x32_bf16 v[126:129], v[130:133], v[182:185], 0
	v_mfma_f32_16x16x32_bf16 v[122:125], v[138:141], v[182:185], 0
	v_mfma_f32_16x16x32_bf16 v[110:113], v[130:133], v[190:193], 0
	v_mfma_f32_16x16x32_bf16 v[106:109], v[138:141], v[190:193], 0
	v_mfma_f32_16x16x32_bf16 v[94:97], v[130:133], v[198:201], 0
	v_mfma_f32_16x16x32_bf16 v[90:93], v[138:141], v[198:201], 0
	v_mfma_f32_16x16x32_bf16 v[78:81], v[130:133], v[206:209], 0
	v_mfma_f32_16x16x32_bf16 v[74:77], v[138:141], v[206:209], 0
	v_mfma_f32_16x16x32_bf16 v[126:129], v[134:137], v[186:189], v[126:129]
	v_mfma_f32_16x16x32_bf16 v[122:125], v[142:145], v[186:189], v[122:125]
	v_mfma_f32_16x16x32_bf16 v[110:113], v[134:137], v[194:197], v[110:113]
	v_mfma_f32_16x16x32_bf16 v[106:109], v[142:145], v[194:197], v[106:109]
	v_mfma_f32_16x16x32_bf16 v[94:97], v[134:137], v[202:205], v[94:97]
	v_mfma_f32_16x16x32_bf16 v[90:93], v[142:145], v[202:205], v[90:93]
	v_mfma_f32_16x16x32_bf16 v[78:81], v[134:137], v[226:229], v[78:81]
	v_mfma_f32_16x16x32_bf16 v[74:77], v[142:145], v[226:229], v[74:77]
	v_mfma_f32_16x16x32_bf16 v[118:121], v[166:169], v[182:185], 0
	v_mfma_f32_16x16x32_bf16 v[114:117], v[174:177], v[182:185], 0
	v_mfma_f32_16x16x32_bf16 v[102:105], v[166:169], v[190:193], 0
	v_mfma_f32_16x16x32_bf16 v[98:101], v[174:177], v[190:193], 0
	v_mfma_f32_16x16x32_bf16 v[86:89], v[166:169], v[198:201], 0
	v_mfma_f32_16x16x32_bf16 v[82:85], v[174:177], v[198:201], 0
	v_mfma_f32_16x16x32_bf16 v[70:73], v[166:169], v[206:209], 0
	v_mfma_f32_16x16x32_bf16 v[66:69], v[174:177], v[206:209], 0
	v_mfma_f32_16x16x32_bf16 v[118:121], v[170:173], v[186:189], v[118:121]
	v_mfma_f32_16x16x32_bf16 v[114:117], v[178:181], v[186:189], v[114:117]
	v_mfma_f32_16x16x32_bf16 v[102:105], v[170:173], v[194:197], v[102:105]
	v_mfma_f32_16x16x32_bf16 v[98:101], v[178:181], v[194:197], v[98:101]
	v_mfma_f32_16x16x32_bf16 v[86:89], v[170:173], v[202:205], v[86:89]
	v_mfma_f32_16x16x32_bf16 v[82:85], v[178:181], v[202:205], v[82:85]
	v_mfma_f32_16x16x32_bf16 v[70:73], v[170:173], v[226:229], v[70:73]
	v_mfma_f32_16x16x32_bf16 v[66:69], v[178:181], v[226:229], v[66:69]
	s_setprio 0
	s_barrier
	s_add_i32 s90, s69, s76
	v_lshl_add_u64 v[230:231], s[6:7], 0, v[148:149]
	s_mov_b32 m0, s90
	ds_read_b128 v[182:185], v222 offset:16384
	ds_read_b128 v[186:189], v222 offset:17408
	ds_read_b128 v[190:193], v222 offset:18432
	ds_read_b128 v[194:197], v222 offset:19456
	ds_read_b128 v[198:201], v222 offset:20480
	ds_read_b128 v[202:205], v222 offset:21504
	ds_read_b128 v[206:209], v222 offset:22528
	ds_read_b128 v[226:229], v222 offset:23552
	global_load_lds_dwordx4 v[230:231], off
	s_add_i32 m0, s90, 0x2000
	s_add_u32 s90, s6, 0x40000
	v_lshl_add_u64 v[232:233], s[6:7], 0, v[152:153]
	s_addc_u32 s91, s7, 0
	s_add_i32 s92, s70, s76
	global_load_lds_dwordx4 v[232:233], off
	v_lshl_add_u64 v[234:235], s[90:91], 0, v[148:149]
	s_mov_b32 m0, s92
	v_lshl_add_u64 v[236:237], s[8:9], 0, v[150:151]
	global_load_lds_dwordx4 v[234:235], off
	v_lshl_add_u64 v[234:235], s[90:91], 0, v[152:153]
	s_add_i32 m0, s92, 0x2000
	s_nop 0
	global_load_lds_dwordx4 v[234:235], off
	v_lshl_add_u64 v[234:235], s[8:9], 0, v[146:147]
	s_mov_b32 m0, s77
	s_nop 0
	global_load_lds_dwordx4 v[234:235], off
	s_mov_b32 m0, s87
	s_nop 0
	global_load_lds_dwordx4 v[236:237], off
	s_waitcnt vmcnt(8)
	s_waitcnt lgkmcnt(0)
	s_barrier
; #define PG8_STAGE(bufoff, gbase, voff) do { _Pragma("unroll") for (int _i = 0; _i < 2; ++_i) \
;         __builtin_amdgcn_global_load_lds((const unsigned*)((const char*)(gbase) + (voff)[_i]), (LAS unsigned*)(lds + (bufoff) + ldsw + _i * 8192), 16, 0, 0); } while (0)
; #define PG8_LDA(dst, b, h) do { _Pragma("unroll") for (int m = 0; m < 4; ++m) _Pragma("unroll") for (int k = 0; k < 2; ++k) dst[m][k] = *(const LAS bf16x8*)(lds + PG8_SA(b, h) + aoff + m * 2048 + k * 1024); } while (0)
; #define PG8_LDB(dst, b, h) do { _Pragma("unroll") for (int n = 0; n < 2; ++n) _Pragma("unroll") for (int k = 0; k < 2; ++k) dst[n][k] = *(const LAS bf16x8*)(lds + PG8_SB(b, h) + boff + n * 2048 + k * 1024); } while (0)
; #define PG8_MMA(ai, bj, At, Bt) do { __builtin_amdgcn_s_setprio(3); _Pragma("unroll") for (int m = 0; m < 4; ++m) _Pragma("unroll") for (int n = 0; n < 2; ++n) _Pragma("unroll") for (int k = 0; k < 2; ++k) \
;         acc[ai][bj][m][n] = __builtin_amdgcn_mfma_f32_16x16x32_bf16(Bt[n][k], At[m][k], acc[ai][bj][m][n], 0, 0, 0); __builtin_amdgcn_s_setprio(0); } while (0)
; #define PG8_WAIT_V(n) asm volatile("s_waitcnt vmcnt(" #n ")" ::: "memory")
; #define PG8_WAIT_L(n) asm volatile("s_waitcnt lgkmcnt(" #n ")" ::: "memory")
; #define PG8_BAR __builtin_amdgcn_s_barrier()
; #define PG8_SCHED __builtin_amdgcn_sched_barrier(0)
; template <class Epi, bool ALIGN_EPI>
; __device__ __forceinline__ void gemm_phase(LAS unsigned char* lds, const Gemm g, const StaticOrder& S, const Epi& E) {
;     ...
;             PG8_WAIT_V(8); PG8_WAIT_L(0); PG8_BAR; PG8_MMA(1, 0, At, B0); PG8_MMA(1, 1, At, B1); PG8_BAR; PG8_SCHED;
;             PG8_LDB(B0, 1, 0); PG8_LDB(B1, 1, 1); PG8_SCHED; PG8_LDA(At, 1, 0); PG8_STAGE(PG8_SA(0, 1), a2 + hstep, voffA);
;             PG8_WAIT_V(8); PG8_WAIT_L(0); PG8_BAR; PG8_MMA(0, 0, At, B0); PG8_MMA(0, 1, At, B1); PG8_BAR; PG8_SCHED;
	s_setprio 3
	v_mfma_f32_16x16x32_bf16 v[62:65], v[130:133], v[182:185], 0
	v_mfma_f32_16x16x32_bf16 v[58:61], v[138:141], v[182:185], 0
	v_mfma_f32_16x16x32_bf16 v[46:49], v[130:133], v[190:193], 0
	v_mfma_f32_16x16x32_bf16 v[42:45], v[138:141], v[190:193], 0
	v_mfma_f32_16x16x32_bf16 v[30:33], v[130:133], v[198:201], 0
	v_mfma_f32_16x16x32_bf16 v[26:29], v[138:141], v[198:201], 0
	v_mfma_f32_16x16x32_bf16 v[14:17], v[130:133], v[206:209], 0
	v_mfma_f32_16x16x32_bf16 v[10:13], v[138:141], v[206:209], 0
	v_mfma_f32_16x16x32_bf16 v[62:65], v[134:137], v[186:189], v[62:65]
	v_mfma_f32_16x16x32_bf16 v[58:61], v[142:145], v[186:189], v[58:61]
	v_mfma_f32_16x16x32_bf16 v[46:49], v[134:137], v[194:197], v[46:49]
	v_mfma_f32_16x16x32_bf16 v[42:45], v[142:145], v[194:197], v[42:45]
	v_mfma_f32_16x16x32_bf16 v[30:33], v[134:137], v[202:205], v[30:33]
	v_mfma_f32_16x16x32_bf16 v[26:29], v[142:145], v[202:205], v[26:29]
	v_mfma_f32_16x16x32_bf16 v[14:17], v[134:137], v[226:229], v[14:17]
	v_mfma_f32_16x16x32_bf16 v[10:13], v[142:145], v[226:229], v[10:13]
	v_mfma_f32_16x16x32_bf16 v[54:57], v[166:169], v[182:185], 0
	v_mfma_f32_16x16x32_bf16 v[50:53], v[174:177], v[182:185], 0
	v_mfma_f32_16x16x32_bf16 v[38:41], v[166:169], v[190:193], 0
	v_mfma_f32_16x16x32_bf16 v[34:37], v[174:177], v[190:193], 0
	v_mfma_f32_16x16x32_bf16 v[22:25], v[166:169], v[198:201], 0
	v_mfma_f32_16x16x32_bf16 v[18:21], v[174:177], v[198:201], 0
	v_mfma_f32_16x16x32_bf16 v[6:9], v[166:169], v[206:209], 0
	v_mfma_f32_16x16x32_bf16 v[2:5], v[174:177], v[206:209], 0
	v_mfma_f32_16x16x32_bf16 v[54:57], v[170:173], v[186:189], v[54:57]
	v_mfma_f32_16x16x32_bf16 v[50:53], v[178:181], v[186:189], v[50:53]
	v_mfma_f32_16x16x32_bf16 v[38:41], v[170:173], v[194:197], v[38:41]
	v_mfma_f32_16x16x32_bf16 v[34:37], v[178:181], v[194:197], v[34:37]
	v_mfma_f32_16x16x32_bf16 v[22:25], v[170:173], v[202:205], v[22:25]
	v_mfma_f32_16x16x32_bf16 v[18:21], v[178:181], v[202:205], v[18:21]
	v_mfma_f32_16x16x32_bf16 v[6:9], v[170:173], v[226:229], v[6:9]
	v_mfma_f32_16x16x32_bf16 v[2:5], v[178:181], v[226:229], v[2:5]
	s_setprio 0
	s_barrier
	s_add_i32 s90, 0, 0x18000
	s_add_i32 s91, 0, 0x1c000
	v_add_u32_e32 v142, s90, v217
	v_add_u32_e32 v154, s91, v217
	ds_read_b128 v[130:133], v142
	ds_read_b128 v[134:137], v142 offset:1024
	ds_read_b128 v[138:141], v142 offset:2048
	ds_read_b128 v[142:145], v142 offset:3072
	ds_read_b128 v[166:169], v154
	ds_read_b128 v[170:173], v154 offset:1024
	ds_read_b128 v[174:177], v154 offset:2048
	ds_read_b128 v[178:181], v154 offset:3072
	s_add_u32 s8, s8, 0x40000
	s_addc_u32 s9, s9, 0
	s_mov_b32 m0, s33
	v_lshl_add_u64 v[238:239], s[8:9], 0, v[146:147]
	ds_read_b128 v[182:185], v222 offset:32768
	ds_read_b128 v[186:189], v222 offset:33792
	ds_read_b128 v[190:193], v222 offset:34816
	ds_read_b128 v[194:197], v222 offset:35840
	ds_read_b128 v[198:201], v222 offset:36864
	ds_read_b128 v[202:205], v222 offset:37888
	ds_read_b128 v[206:209], v222 offset:38912
	ds_read_b128 v[226:229], v222 offset:39936
	global_load_lds_dwordx4 v[238:239], off
	v_lshl_add_u64 v[238:239], s[8:9], 0, v[150:151]
	s_mov_b32 m0, s14
	s_nop 0
	global_load_lds_dwordx4 v[238:239], off
	s_waitcnt vmcnt(8)
	s_waitcnt lgkmcnt(0)
	s_barrier
	s_setprio 3
	v_mfma_f32_16x16x32_bf16 v[126:129], v[130:133], v[182:185], v[126:129]
	v_mfma_f32_16x16x32_bf16 v[122:125], v[138:141], v[182:185], v[122:125]
	v_mfma_f32_16x16x32_bf16 v[110:113], v[130:133], v[190:193], v[110:113]
	v_mfma_f32_16x16x32_bf16 v[106:109], v[138:141], v[190:193], v[106:109]
	v_mfma_f32_16x16x32_bf16 v[94:97], v[130:133], v[198:201], v[94:97]
	v_mfma_f32_16x16x32_bf16 v[90:93], v[138:141], v[198:201], v[90:93]
	v_mfma_f32_16x16x32_bf16 v[78:81], v[130:133], v[206:209], v[78:81]
	v_mfma_f32_16x16x32_bf16 v[74:77], v[138:141], v[206:209], v[74:77]
	v_mfma_f32_16x16x32_bf16 v[126:129], v[134:137], v[186:189], v[126:129]
	v_mfma_f32_16x16x32_bf16 v[122:125], v[142:145], v[186:189], v[122:125]
	v_mfma_f32_16x16x32_bf16 v[110:113], v[134:137], v[194:197], v[110:113]
	v_mfma_f32_16x16x32_bf16 v[106:109], v[142:145], v[194:197], v[106:109]
	v_mfma_f32_16x16x32_bf16 v[94:97], v[134:137], v[202:205], v[94:97]
	v_mfma_f32_16x16x32_bf16 v[90:93], v[142:145], v[202:205], v[90:93]
	v_mfma_f32_16x16x32_bf16 v[78:81], v[134:137], v[226:229], v[78:81]
	v_mfma_f32_16x16x32_bf16 v[74:77], v[142:145], v[226:229], v[74:77]
	v_mfma_f32_16x16x32_bf16 v[118:121], v[166:169], v[182:185], v[118:121]
	v_mfma_f32_16x16x32_bf16 v[114:117], v[174:177], v[182:185], v[114:117]
	v_mfma_f32_16x16x32_bf16 v[102:105], v[166:169], v[190:193], v[102:105]
	v_mfma_f32_16x16x32_bf16 v[98:101], v[174:177], v[190:193], v[98:101]
	v_mfma_f32_16x16x32_bf16 v[86:89], v[166:169], v[198:201], v[86:89]
	v_mfma_f32_16x16x32_bf16 v[82:85], v[174:177], v[198:201], v[82:85]
	v_mfma_f32_16x16x32_bf16 v[70:73], v[166:169], v[206:209], v[70:73]
	v_mfma_f32_16x16x32_bf16 v[66:69], v[174:177], v[206:209], v[66:69]
	v_mfma_f32_16x16x32_bf16 v[118:121], v[170:173], v[186:189], v[118:121]
	v_mfma_f32_16x16x32_bf16 v[114:117], v[178:181], v[186:189], v[114:117]
	v_mfma_f32_16x16x32_bf16 v[102:105], v[170:173], v[194:197], v[102:105]
	v_mfma_f32_16x16x32_bf16 v[98:101], v[178:181], v[194:197], v[98:101]
	v_mfma_f32_16x16x32_bf16 v[86:89], v[170:173], v[202:205], v[86:89]
	v_mfma_f32_16x16x32_bf16 v[82:85], v[178:181], v[202:205], v[82:85]
	v_mfma_f32_16x16x32_bf16 v[70:73], v[170:173], v[226:229], v[70:73]
	v_mfma_f32_16x16x32_bf16 v[66:69], v[178:181], v[226:229], v[66:69]
	s_setprio 0
	s_barrier
; #define PG8_STAGE(bufoff, gbase, voff) do { _Pragma("unroll") for (int _i = 0; _i < 2; ++_i) \
;         __builtin_amdgcn_global_load_lds((const unsigned*)((const char*)(gbase) + (voff)[_i]), (LAS unsigned*)(lds + (bufoff) + ldsw + _i * 8192), 16, 0, 0); } while (0)
; #define PG8_LDA(dst, b, h) do { _Pragma("unroll") for (int m = 0; m < 4; ++m) _Pragma("unroll") for (int k = 0; k < 2; ++k) dst[m][k] = *(const LAS bf16x8*)(lds + PG8_SA(b, h) + aoff + m * 2048 + k * 1024); } while (0)
; #define PG8_LDB(dst, b, h) do { _Pragma("unroll") for (int n = 0; n < 2; ++n) _Pragma("unroll") for (int k = 0; k < 2; ++k) dst[n][k] = *(const LAS bf16x8*)(lds + PG8_SB(b, h) + boff + n * 2048 + k * 1024); } while (0)
; #define PG8_MMA(ai, bj, At, Bt) do { __builtin_amdgcn_s_setprio(3); _Pragma("unroll") for (int m = 0; m < 4; ++m) _Pragma("unroll") for (int n = 0; n < 2; ++n) _Pragma("unroll") for (int k = 0; k < 2; ++k) \
;         acc[ai][bj][m][n] = __builtin_amdgcn_mfma_f32_16x16x32_bf16(Bt[n][k], At[m][k], acc[ai][bj][m][n], 0, 0, 0); __builtin_amdgcn_s_setprio(0); } while (0)
; #define PG8_WAIT_V(n) asm volatile("s_waitcnt vmcnt(" #n ")" ::: "memory")
; #define PG8_BAR __builtin_amdgcn_s_barrier()
; template <class Epi, bool ALIGN_EPI>
; __device__ __forceinline__ void gemm_phase(LAS unsigned char* lds, const Gemm g, const StaticOrder& S, const Epi& E) {
;     ...
;             PG8_LDB(B0, 0, 0); PG8_LDB(B1, 0, 1); PG8_SCHED; PG8_LDA(At, 0, 0); PG8_STAGE(PG8_SA(1, 1), a1 + hstep, voffA);
;             PG8_WAIT_V(8); PG8_WAIT_L(0); PG8_BAR; PG8_MMA(0, 0, At, B0); PG8_MMA(0, 1, At, B1); PG8_BAR; PG8_SCHED;
;             PG8_LDA(At, 0, 1); PG8_STAGE(PG8_SB(0, 0), b2, voffB); PG8_STAGE(PG8_SB(0, 1), b2 + hstep, voffB); PG8_STAGE(PG8_SA(0, 0), a2, voffA);
;             PG8_WAIT_V(8); PG8_WAIT_L(0); PG8_BAR; PG8_MMA(1, 0, At, B0); PG8_MMA(1, 1, At, B1); PG8_BAR; PG8_SCHED;
;             PG8_LDB(B0, 1, 0); PG8_LDB(B1, 1, 1); PG8_SCHED; PG8_LDA(At, 1, 0); PG8_STAGE(PG8_SA(0, 1), a2 + hstep, voffA);
;             PG8_WAIT_V(8); PG8_WAIT_L(0); PG8_BAR; PG8_MMA(0, 0, At, B0); PG8_MMA(0, 1, At, B1); PG8_BAR; PG8_SCHED;
;             PG8_LDA(At, 1, 1); PG8_STAGE(PG8_SB(1, 0), b3, voffB); PG8_STAGE(PG8_SB(1, 1), b3 + hstep, voffB); PG8_STAGE(PG8_SA(1, 0), a3, voffA);
;             PG8_WAIT_V(8); PG8_WAIT_L(0); PG8_BAR; PG8_MMA(1, 0, At, B0); PG8_MMA(1, 1, At, B1); PG8_BAR; PG8_SCHED;
	s_add_i32 s8, s90, s76
	v_lshl_add_u64 v[230:231], v[230:231], 0, s[60:61]
	s_mov_b32 m0, s8
	ds_read_b128 v[182:185], v222 offset:49152
	ds_read_b128 v[186:189], v222 offset:50176
	ds_read_b128 v[190:193], v222 offset:51200
	ds_read_b128 v[194:197], v222 offset:52224
	ds_read_b128 v[198:201], v222 offset:53248
	ds_read_b128 v[202:205], v222 offset:54272
	ds_read_b128 v[206:209], v222 offset:55296
	ds_read_b128 v[226:229], v222 offset:56320
	global_load_lds_dwordx4 v[230:231], off
	s_add_i32 m0, s8, 0x2000
	s_add_u32 s6, s6, 0x40080
	v_lshl_add_u64 v[230:231], v[232:233], 0, s[60:61]
	s_addc_u32 s7, s7, 0
	s_add_i32 s8, s91, s76
	global_load_lds_dwordx4 v[230:231], off
	v_lshl_add_u64 v[230:231], s[6:7], 0, v[148:149]
	s_mov_b32 m0, s8
	s_nop 0
	global_load_lds_dwordx4 v[230:231], off
	v_lshl_add_u64 v[230:231], s[6:7], 0, v[152:153]
	s_add_i32 m0, s8, 0x2000
	s_nop 0
	global_load_lds_dwordx4 v[230:231], off
	v_lshl_add_u64 v[230:231], v[234:235], 0, s[60:61]
	s_mov_b32 m0, s65
	s_nop 0
	global_load_lds_dwordx4 v[230:231], off
	v_lshl_add_u64 v[230:231], v[236:237], 0, s[60:61]
	s_mov_b32 m0, s66
	s_nop 0
	global_load_lds_dwordx4 v[230:231], off
	s_waitcnt vmcnt(8)
	s_waitcnt lgkmcnt(0)
	s_barrier
	s_setprio 3
	v_mfma_f32_16x16x32_bf16 v[62:65], v[130:133], v[182:185], v[62:65]
	v_mfma_f32_16x16x32_bf16 v[58:61], v[138:141], v[182:185], v[58:61]
	v_mfma_f32_16x16x32_bf16 v[46:49], v[130:133], v[190:193], v[46:49]
	v_mfma_f32_16x16x32_bf16 v[42:45], v[138:141], v[190:193], v[42:45]
	v_mfma_f32_16x16x32_bf16 v[30:33], v[130:133], v[198:201], v[30:33]
	v_mfma_f32_16x16x32_bf16 v[26:29], v[138:141], v[198:201], v[26:29]
	v_mfma_f32_16x16x32_bf16 v[14:17], v[130:133], v[206:209], v[14:17]
	v_mfma_f32_16x16x32_bf16 v[10:13], v[138:141], v[206:209], v[10:13]
	v_mfma_f32_16x16x32_bf16 v[62:65], v[134:137], v[186:189], v[62:65]
	v_mfma_f32_16x16x32_bf16 v[58:61], v[142:145], v[186:189], v[58:61]
	v_mfma_f32_16x16x32_bf16 v[46:49], v[134:137], v[194:197], v[46:49]
	v_mfma_f32_16x16x32_bf16 v[42:45], v[142:145], v[194:197], v[42:45]
	v_mfma_f32_16x16x32_bf16 v[30:33], v[134:137], v[202:205], v[30:33]
	v_mfma_f32_16x16x32_bf16 v[26:29], v[142:145], v[202:205], v[26:29]
	v_mfma_f32_16x16x32_bf16 v[14:17], v[134:137], v[226:229], v[14:17]
	v_mfma_f32_16x16x32_bf16 v[10:13], v[142:145], v[226:229], v[10:13]
	v_mfma_f32_16x16x32_bf16 v[54:57], v[166:169], v[182:185], v[54:57]
	v_mfma_f32_16x16x32_bf16 v[50:53], v[174:177], v[182:185], v[50:53]
	v_mfma_f32_16x16x32_bf16 v[38:41], v[166:169], v[190:193], v[38:41]
	v_mfma_f32_16x16x32_bf16 v[34:37], v[174:177], v[190:193], v[34:37]
	v_mfma_f32_16x16x32_bf16 v[22:25], v[166:169], v[198:201], v[22:25]
	v_mfma_f32_16x16x32_bf16 v[18:21], v[174:177], v[198:201], v[18:21]
	v_mfma_f32_16x16x32_bf16 v[6:9], v[166:169], v[206:209], v[6:9]
	v_mfma_f32_16x16x32_bf16 v[2:5], v[174:177], v[206:209], v[2:5]
	v_mfma_f32_16x16x32_bf16 v[54:57], v[170:173], v[186:189], v[54:57]
	v_mfma_f32_16x16x32_bf16 v[50:53], v[178:181], v[186:189], v[50:53]
	v_mfma_f32_16x16x32_bf16 v[38:41], v[170:173], v[194:197], v[38:41]
	v_mfma_f32_16x16x32_bf16 v[34:37], v[178:181], v[194:197], v[34:37]
	v_mfma_f32_16x16x32_bf16 v[22:25], v[170:173], v[202:205], v[22:25]
	v_mfma_f32_16x16x32_bf16 v[18:21], v[178:181], v[202:205], v[18:21]
	v_mfma_f32_16x16x32_bf16 v[6:9], v[170:173], v[226:229], v[6:9]
	v_mfma_f32_16x16x32_bf16 v[2:5], v[178:181], v[226:229], v[2:5]
	s_setprio 0
	s_barrier
	s_add_i32 s89, s89, 2
	s_add_u32 s4, s4, 0x100
	s_addc_u32 s5, s5, 0
	s_add_u32 s85, s85, 0x100
	s_addc_u32 s88, s88, 0
.LBB0_787:
	s_waitcnt lgkmcnt(0)
	ds_read_b128 v[130:133], v220
	ds_read_b128 v[134:137], v220 offset:1024
	ds_read_b128 v[138:141], v220 offset:2048
	ds_read_b128 v[142:145], v220 offset:3072
	ds_read_b128 v[166:169], v221
	ds_read_b128 v[170:173], v221 offset:1024
	ds_read_b128 v[174:177], v221 offset:2048
	ds_read_b128 v[178:181], v221 offset:3072
	s_add_u32 s6, s4, 0xfffc0080
	s_addc_u32 s7, s5, -1
	s_cmp_eq_u32 s89, 12
	s_cselect_b32 s9, s50, s7
	s_cselect_b32 s8, s55, s6
	s_cselect_b32 s7, s73, s88
	s_cselect_b32 s6, s79, s85
	v_lshl_add_u64 v[230:231], s[4:5], 0, v[158:159]
	s_add_i32 m0, s77, 0xc000
	ds_read_b128 v[182:185], v222
	ds_read_b128 v[186:189], v222 offset:1024
	ds_read_b128 v[190:193], v222 offset:2048
	ds_read_b128 v[194:197], v222 offset:3072
	ds_read_b128 v[198:201], v222 offset:4096
	ds_read_b128 v[202:205], v222 offset:5120
	ds_read_b128 v[206:209], v222 offset:6144
	ds_read_b128 v[226:229], v222 offset:7168
	global_load_lds_dwordx4 v[230:231], off
	v_lshl_add_u64 v[230:231], s[4:5], 0, v[160:161]
	s_add_i32 m0, s77, 0xe000
	s_nop 0
	global_load_lds_dwordx4 v[230:231], off
	s_waitcnt vmcnt(8)
	s_waitcnt lgkmcnt(0)
	s_barrier
; #define PG8_STAGE(bufoff, gbase, voff) do { _Pragma("unroll") for (int _i = 0; _i < 2; ++_i) \
;         __builtin_amdgcn_global_load_lds((const unsigned*)((const char*)(gbase) + (voff)[_i]), (LAS unsigned*)(lds + (bufoff) + ldsw + _i * 8192), 16, 0, 0); } while (0)
; #define PG8_LDA(dst, b, h) do { _Pragma("unroll") for (int m = 0; m < 4; ++m) _Pragma("unroll") for (int k = 0; k < 2; ++k) dst[m][k] = *(const LAS bf16x8*)(lds + PG8_SA(b, h) + aoff + m * 2048 + k * 1024); } while (0)
; #define PG8_MMA(ai, bj, At, Bt) do { __builtin_amdgcn_s_setprio(3); _Pragma("unroll") for (int m = 0; m < 4; ++m) _Pragma("unroll") for (int n = 0; n < 2; ++n) _Pragma("unroll") for (int k = 0; k < 2; ++k) \
;         acc[ai][bj][m][n] = __builtin_amdgcn_mfma_f32_16x16x32_bf16(Bt[n][k], At[m][k], acc[ai][bj][m][n], 0, 0, 0); __builtin_amdgcn_s_setprio(0); } while (0)
; #define PG8_WAIT_V(n) asm volatile("s_waitcnt vmcnt(" #n ")" ::: "memory")
; #define PG8_WAIT_L(n) asm volatile("s_waitcnt lgkmcnt(" #n ")" ::: "memory")
; #define PG8_BAR __builtin_amdgcn_s_barrier()
; #define PG8_SCHED __builtin_amdgcn_sched_barrier(0)
; template <class Epi, bool ALIGN_EPI>
; __device__ __forceinline__ void gemm_phase(LAS unsigned char* lds, const Gemm g, const StaticOrder& S, const Epi& E) {
;     ...
;             PG8_WAIT_V(8); PG8_WAIT_L(0); PG8_BAR; PG8_MMA(0, 0, At, B0); PG8_MMA(0, 1, At, B1); PG8_BAR; PG8_SCHED;
;             PG8_LDA(At, 0, 1); PG8_STAGE(PG8_SB(0, 0), b2, voffB); PG8_STAGE(PG8_SB(0, 1), b2 + hstep, voffB); PG8_STAGE(PG8_SA(0, 0), a2, voffA);
;             PG8_WAIT_V(8); PG8_WAIT_L(0); PG8_BAR; PG8_MMA(1, 0, At, B0); PG8_MMA(1, 1, At, B1); PG8_BAR; PG8_SCHED;
	s_setprio 3
	v_mfma_f32_16x16x32_bf16 v[126:129], v[130:133], v[182:185], v[126:129]
	v_mfma_f32_16x16x32_bf16 v[122:125], v[138:141], v[182:185], v[122:125]
	v_mfma_f32_16x16x32_bf16 v[110:113], v[130:133], v[190:193], v[110:113]
	v_mfma_f32_16x16x32_bf16 v[106:109], v[138:141], v[190:193], v[106:109]
	v_mfma_f32_16x16x32_bf16 v[94:97], v[130:133], v[198:201], v[94:97]
	v_mfma_f32_16x16x32_bf16 v[90:93], v[138:141], v[198:201], v[90:93]
	v_mfma_f32_16x16x32_bf16 v[78:81], v[130:133], v[206:209], v[78:81]
	v_mfma_f32_16x16x32_bf16 v[74:77], v[138:141], v[206:209], v[74:77]
	v_mfma_f32_16x16x32_bf16 v[126:129], v[134:137], v[186:189], v[126:129]
	v_mfma_f32_16x16x32_bf16 v[122:125], v[142:145], v[186:189], v[122:125]
	v_mfma_f32_16x16x32_bf16 v[110:113], v[134:137], v[194:197], v[110:113]
	v_mfma_f32_16x16x32_bf16 v[106:109], v[142:145], v[194:197], v[106:109]
	v_mfma_f32_16x16x32_bf16 v[94:97], v[134:137], v[202:205], v[94:97]
	v_mfma_f32_16x16x32_bf16 v[90:93], v[142:145], v[202:205], v[90:93]
	v_mfma_f32_16x16x32_bf16 v[78:81], v[134:137], v[226:229], v[78:81]
	v_mfma_f32_16x16x32_bf16 v[74:77], v[142:145], v[226:229], v[74:77]
	v_mfma_f32_16x16x32_bf16 v[118:121], v[166:169], v[182:185], v[118:121]
	v_mfma_f32_16x16x32_bf16 v[114:117], v[174:177], v[182:185], v[114:117]
	v_mfma_f32_16x16x32_bf16 v[102:105], v[166:169], v[190:193], v[102:105]
	v_mfma_f32_16x16x32_bf16 v[98:101], v[174:177], v[190:193], v[98:101]
	v_mfma_f32_16x16x32_bf16 v[86:89], v[166:169], v[198:201], v[86:89]
	v_mfma_f32_16x16x32_bf16 v[82:85], v[174:177], v[198:201], v[82:85]
	v_mfma_f32_16x16x32_bf16 v[70:73], v[166:169], v[206:209], v[70:73]
	v_mfma_f32_16x16x32_bf16 v[66:69], v[174:177], v[206:209], v[66:69]
	v_mfma_f32_16x16x32_bf16 v[118:121], v[170:173], v[186:189], v[118:121]
	v_mfma_f32_16x16x32_bf16 v[114:117], v[178:181], v[186:189], v[114:117]
	v_mfma_f32_16x16x32_bf16 v[102:105], v[170:173], v[194:197], v[102:105]
	v_mfma_f32_16x16x32_bf16 v[98:101], v[178:181], v[194:197], v[98:101]
	v_mfma_f32_16x16x32_bf16 v[86:89], v[170:173], v[202:205], v[86:89]
	v_mfma_f32_16x16x32_bf16 v[82:85], v[178:181], v[202:205], v[82:85]
	v_mfma_f32_16x16x32_bf16 v[70:73], v[170:173], v[226:229], v[70:73]
	v_mfma_f32_16x16x32_bf16 v[66:69], v[178:181], v[226:229], v[66:69]
	s_setprio 0
	s_barrier
	s_add_i32 s90, s69, s76
	v_lshl_add_u64 v[230:231], s[6:7], 0, v[148:149]
	s_mov_b32 m0, s90
	ds_read_b128 v[182:185], v222 offset:16384
	ds_read_b128 v[186:189], v222 offset:17408
	ds_read_b128 v[190:193], v222 offset:18432
	ds_read_b128 v[194:197], v222 offset:19456
	ds_read_b128 v[198:201], v222 offset:20480
	ds_read_b128 v[202:205], v222 offset:21504
	ds_read_b128 v[206:209], v222 offset:22528
	ds_read_b128 v[226:229], v222 offset:23552
	global_load_lds_dwordx4 v[230:231], off
	s_add_i32 m0, s90, 0x2000
	s_add_u32 s90, s6, 0x40000
	v_lshl_add_u64 v[232:233], s[6:7], 0, v[152:153]
	s_addc_u32 s91, s7, 0
	s_add_i32 s92, s70, s76
	global_load_lds_dwordx4 v[232:233], off
	v_lshl_add_u64 v[234:235], s[90:91], 0, v[148:149]
	s_mov_b32 m0, s92
	v_lshl_add_u64 v[236:237], s[8:9], 0, v[150:151]
	global_load_lds_dwordx4 v[234:235], off
	v_lshl_add_u64 v[234:235], s[90:91], 0, v[152:153]
	s_add_i32 m0, s92, 0x2000
	s_nop 0
	global_load_lds_dwordx4 v[234:235], off
	v_lshl_add_u64 v[234:235], s[8:9], 0, v[146:147]
	s_mov_b32 m0, s77
	s_nop 0
	global_load_lds_dwordx4 v[234:235], off
	s_mov_b32 m0, s87
	s_nop 0
	global_load_lds_dwordx4 v[236:237], off
	s_waitcnt vmcnt(8)
	s_waitcnt lgkmcnt(0)
	s_barrier
	s_setprio 3
	v_mfma_f32_16x16x32_bf16 v[62:65], v[130:133], v[182:185], v[62:65]
	v_mfma_f32_16x16x32_bf16 v[58:61], v[138:141], v[182:185], v[58:61]
	v_mfma_f32_16x16x32_bf16 v[46:49], v[130:133], v[190:193], v[46:49]
	v_mfma_f32_16x16x32_bf16 v[42:45], v[138:141], v[190:193], v[42:45]
	v_mfma_f32_16x16x32_bf16 v[30:33], v[130:133], v[198:201], v[30:33]
	v_mfma_f32_16x16x32_bf16 v[26:29], v[138:141], v[198:201], v[26:29]
	v_mfma_f32_16x16x32_bf16 v[14:17], v[130:133], v[206:209], v[14:17]
	v_mfma_f32_16x16x32_bf16 v[10:13], v[138:141], v[206:209], v[10:13]
	v_mfma_f32_16x16x32_bf16 v[62:65], v[134:137], v[186:189], v[62:65]
	v_mfma_f32_16x16x32_bf16 v[58:61], v[142:145], v[186:189], v[58:61]
	v_mfma_f32_16x16x32_bf16 v[46:49], v[134:137], v[194:197], v[46:49]
	v_mfma_f32_16x16x32_bf16 v[42:45], v[142:145], v[194:197], v[42:45]
	v_mfma_f32_16x16x32_bf16 v[30:33], v[134:137], v[202:205], v[30:33]
	v_mfma_f32_16x16x32_bf16 v[26:29], v[142:145], v[202:205], v[26:29]
	v_mfma_f32_16x16x32_bf16 v[14:17], v[134:137], v[226:229], v[14:17]
	v_mfma_f32_16x16x32_bf16 v[10:13], v[142:145], v[226:229], v[10:13]
	v_mfma_f32_16x16x32_bf16 v[54:57], v[166:169], v[182:185], v[54:57]
	v_mfma_f32_16x16x32_bf16 v[50:53], v[174:177], v[182:185], v[50:53]
	v_mfma_f32_16x16x32_bf16 v[38:41], v[166:169], v[190:193], v[38:41]
	v_mfma_f32_16x16x32_bf16 v[34:37], v[174:177], v[190:193], v[34:37]
	v_mfma_f32_16x16x32_bf16 v[22:25], v[166:169], v[198:201], v[22:25]
	v_mfma_f32_16x16x32_bf16 v[18:21], v[174:177], v[198:201], v[18:21]
	v_mfma_f32_16x16x32_bf16 v[6:9], v[166:169], v[206:209], v[6:9]
	v_mfma_f32_16x16x32_bf16 v[2:5], v[174:177], v[206:209], v[2:5]
	v_mfma_f32_16x16x32_bf16 v[54:57], v[170:173], v[186:189], v[54:57]
	v_mfma_f32_16x16x32_bf16 v[50:53], v[178:181], v[186:189], v[50:53]
	v_mfma_f32_16x16x32_bf16 v[38:41], v[170:173], v[194:197], v[38:41]
	v_mfma_f32_16x16x32_bf16 v[34:37], v[178:181], v[194:197], v[34:37]
	v_mfma_f32_16x16x32_bf16 v[22:25], v[170:173], v[202:205], v[22:25]
	v_mfma_f32_16x16x32_bf16 v[18:21], v[178:181], v[202:205], v[18:21]
	v_mfma_f32_16x16x32_bf16 v[6:9], v[170:173], v[226:229], v[6:9]
	v_mfma_f32_16x16x32_bf16 v[2:5], v[178:181], v[226:229], v[2:5]
	s_setprio 0
	s_barrier
; #define PG8_STAGE(bufoff, gbase, voff) do { _Pragma("unroll") for (int _i = 0; _i < 2; ++_i) \
;         __builtin_amdgcn_global_load_lds((const unsigned*)((const char*)(gbase) + (voff)[_i]), (LAS unsigned*)(lds + (bufoff) + ldsw + _i * 8192), 16, 0, 0); } while (0)
; #define PG8_LDA(dst, b, h) do { _Pragma("unroll") for (int m = 0; m < 4; ++m) _Pragma("unroll") for (int k = 0; k < 2; ++k) dst[m][k] = *(const LAS bf16x8*)(lds + PG8_SA(b, h) + aoff + m * 2048 + k * 1024); } while (0)
; #define PG8_LDB(dst, b, h) do { _Pragma("unroll") for (int n = 0; n < 2; ++n) _Pragma("unroll") for (int k = 0; k < 2; ++k) dst[n][k] = *(const LAS bf16x8*)(lds + PG8_SB(b, h) + boff + n * 2048 + k * 1024); } while (0)
; #define PG8_MMA(ai, bj, At, Bt) do { __builtin_amdgcn_s_setprio(3); _Pragma("unroll") for (int m = 0; m < 4; ++m) _Pragma("unroll") for (int n = 0; n < 2; ++n) _Pragma("unroll") for (int k = 0; k < 2; ++k) \
;         acc[ai][bj][m][n] = __builtin_amdgcn_mfma_f32_16x16x32_bf16(Bt[n][k], At[m][k], acc[ai][bj][m][n], 0, 0, 0); __builtin_amdgcn_s_setprio(0); } while (0)
; #define PG8_WAIT_V(n) asm volatile("s_waitcnt vmcnt(" #n ")" ::: "memory")
; #define PG8_WAIT_L(n) asm volatile("s_waitcnt lgkmcnt(" #n ")" ::: "memory")
; #define PG8_BAR __builtin_amdgcn_s_barrier()
; #define PG8_SCHED __builtin_amdgcn_sched_barrier(0)
; template <class Epi, bool ALIGN_EPI>
; __device__ __forceinline__ void gemm_phase(LAS unsigned char* lds, const Gemm g, const StaticOrder& S, const Epi& E) {
;     ...
;             PG8_LDB(B0, 1, 0); PG8_LDB(B1, 1, 1); PG8_SCHED; PG8_LDA(At, 1, 0); PG8_STAGE(PG8_SA(0, 1), a2 + hstep, voffA);
;             PG8_WAIT_V(8); PG8_WAIT_L(0); PG8_BAR; PG8_MMA(0, 0, At, B0); PG8_MMA(0, 1, At, B1); PG8_BAR; PG8_SCHED;
	s_add_i32 s90, 0, 0x18000
	s_add_i32 s91, 0, 0x1c000
	v_add_u32_e32 v142, s90, v217
	v_add_u32_e32 v154, s91, v217
	ds_read_b128 v[130:133], v142
	ds_read_b128 v[134:137], v142 offset:1024
	ds_read_b128 v[138:141], v142 offset:2048
	ds_read_b128 v[142:145], v142 offset:3072
	ds_read_b128 v[166:169], v154
	ds_read_b128 v[170:173], v154 offset:1024
	ds_read_b128 v[174:177], v154 offset:2048
	ds_read_b128 v[178:181], v154 offset:3072
	s_add_u32 s8, s8, 0x40000
	s_addc_u32 s9, s9, 0
	s_mov_b32 m0, s33
	v_lshl_add_u64 v[238:239], s[8:9], 0, v[146:147]
	ds_read_b128 v[182:185], v222 offset:32768
	ds_read_b128 v[186:189], v222 offset:33792
	ds_read_b128 v[190:193], v222 offset:34816
	ds_read_b128 v[194:197], v222 offset:35840
	ds_read_b128 v[198:201], v222 offset:36864
	ds_read_b128 v[202:205], v222 offset:37888
	ds_read_b128 v[206:209], v222 offset:38912
	ds_read_b128 v[226:229], v222 offset:39936
	global_load_lds_dwordx4 v[238:239], off
	v_lshl_add_u64 v[238:239], s[8:9], 0, v[150:151]
	s_mov_b32 m0, s14
	s_nop 0
	global_load_lds_dwordx4 v[238:239], off
	s_waitcnt vmcnt(8)
	s_waitcnt lgkmcnt(0)
	s_barrier
	s_setprio 3
	v_mfma_f32_16x16x32_bf16 v[126:129], v[130:133], v[182:185], v[126:129]
	v_mfma_f32_16x16x32_bf16 v[122:125], v[138:141], v[182:185], v[122:125]
	v_mfma_f32_16x16x32_bf16 v[110:113], v[130:133], v[190:193], v[110:113]
	v_mfma_f32_16x16x32_bf16 v[106:109], v[138:141], v[190:193], v[106:109]
	v_mfma_f32_16x16x32_bf16 v[94:97], v[130:133], v[198:201], v[94:97]
	v_mfma_f32_16x16x32_bf16 v[90:93], v[138:141], v[198:201], v[90:93]
	v_mfma_f32_16x16x32_bf16 v[78:81], v[130:133], v[206:209], v[78:81]
	v_mfma_f32_16x16x32_bf16 v[74:77], v[138:141], v[206:209], v[74:77]
	v_mfma_f32_16x16x32_bf16 v[126:129], v[134:137], v[186:189], v[126:129]
	v_mfma_f32_16x16x32_bf16 v[122:125], v[142:145], v[186:189], v[122:125]
	v_mfma_f32_16x16x32_bf16 v[110:113], v[134:137], v[194:197], v[110:113]
	v_mfma_f32_16x16x32_bf16 v[106:109], v[142:145], v[194:197], v[106:109]
	v_mfma_f32_16x16x32_bf16 v[94:97], v[134:137], v[202:205], v[94:97]
	v_mfma_f32_16x16x32_bf16 v[90:93], v[142:145], v[202:205], v[90:93]
	v_mfma_f32_16x16x32_bf16 v[78:81], v[134:137], v[226:229], v[78:81]
	v_mfma_f32_16x16x32_bf16 v[74:77], v[142:145], v[226:229], v[74:77]
	v_mfma_f32_16x16x32_bf16 v[118:121], v[166:169], v[182:185], v[118:121]
	v_mfma_f32_16x16x32_bf16 v[114:117], v[174:177], v[182:185], v[114:117]
	v_mfma_f32_16x16x32_bf16 v[102:105], v[166:169], v[190:193], v[102:105]
	v_mfma_f32_16x16x32_bf16 v[98:101], v[174:177], v[190:193], v[98:101]
	v_mfma_f32_16x16x32_bf16 v[86:89], v[166:169], v[198:201], v[86:89]
	v_mfma_f32_16x16x32_bf16 v[82:85], v[174:177], v[198:201], v[82:85]
	v_mfma_f32_16x16x32_bf16 v[70:73], v[166:169], v[206:209], v[70:73]
	v_mfma_f32_16x16x32_bf16 v[66:69], v[174:177], v[206:209], v[66:69]
	v_mfma_f32_16x16x32_bf16 v[118:121], v[170:173], v[186:189], v[118:121]
	v_mfma_f32_16x16x32_bf16 v[114:117], v[178:181], v[186:189], v[114:117]
	v_mfma_f32_16x16x32_bf16 v[102:105], v[170:173], v[194:197], v[102:105]
	v_mfma_f32_16x16x32_bf16 v[98:101], v[178:181], v[194:197], v[98:101]
	v_mfma_f32_16x16x32_bf16 v[86:89], v[170:173], v[202:205], v[86:89]
	v_mfma_f32_16x16x32_bf16 v[82:85], v[178:181], v[202:205], v[82:85]
	v_mfma_f32_16x16x32_bf16 v[70:73], v[170:173], v[226:229], v[70:73]
	v_mfma_f32_16x16x32_bf16 v[66:69], v[178:181], v[226:229], v[66:69]
	s_setprio 0
	s_barrier
; #define PG8_STAGE(bufoff, gbase, voff) do { _Pragma("unroll") for (int _i = 0; _i < 2; ++_i) \
;         __builtin_amdgcn_global_load_lds((const unsigned*)((const char*)(gbase) + (voff)[_i]), (LAS unsigned*)(lds + (bufoff) + ldsw + _i * 8192), 16, 0, 0); } while (0)
; #define PG8_LDA(dst, b, h) do { _Pragma("unroll") for (int m = 0; m < 4; ++m) _Pragma("unroll") for (int k = 0; k < 2; ++k) dst[m][k] = *(const LAS bf16x8*)(lds + PG8_SA(b, h) + aoff + m * 2048 + k * 1024); } while (0)
; #define PG8_MMA(ai, bj, At, Bt) do { __builtin_amdgcn_s_setprio(3); _Pragma("unroll") for (int m = 0; m < 4; ++m) _Pragma("unroll") for (int n = 0; n < 2; ++n) _Pragma("unroll") for (int k = 0; k < 2; ++k) \
;         acc[ai][bj][m][n] = __builtin_amdgcn_mfma_f32_16x16x32_bf16(Bt[n][k], At[m][k], acc[ai][bj][m][n], 0, 0, 0); __builtin_amdgcn_s_setprio(0); } while (0)
; #define PG8_WAIT_V(n) asm volatile("s_waitcnt vmcnt(" #n ")" ::: "memory")
; #define PG8_WAIT_L(n) asm volatile("s_waitcnt lgkmcnt(" #n ")" ::: "memory")
; #define PG8_BAR __builtin_amdgcn_s_barrier()
; #define PG8_SCHED __builtin_amdgcn_sched_barrier(0)
; template <class Epi, bool ALIGN_EPI>
; __device__ __forceinline__ void gemm_phase(LAS unsigned char* lds, const Gemm g, const StaticOrder& S, const Epi& E) {
;     ...
;             PG8_LDA(At, 1, 1); PG8_STAGE(PG8_SB(1, 0), b3, voffB); PG8_STAGE(PG8_SB(1, 1), b3 + hstep, voffB); PG8_STAGE(PG8_SA(1, 0), a3, voffA);
;             PG8_WAIT_V(8); PG8_WAIT_L(0); PG8_BAR; PG8_MMA(1, 0, At, B0); PG8_MMA(1, 1, At, B1); PG8_BAR; PG8_SCHED;
;         }
;         if constexpr (ALIGN_EPI) { if (wr == 0) PG8_BAR; }
	s_add_i32 s8, s90, s76
	v_lshl_add_u64 v[230:231], v[230:231], 0, s[60:61]
	s_mov_b32 m0, s8
	ds_read_b128 v[182:185], v222 offset:49152
	ds_read_b128 v[186:189], v222 offset:50176
	ds_read_b128 v[190:193], v222 offset:51200
	ds_read_b128 v[194:197], v222 offset:52224
	ds_read_b128 v[198:201], v222 offset:53248
	ds_read_b128 v[202:205], v222 offset:54272
	ds_read_b128 v[206:209], v222 offset:55296
	ds_read_b128 v[226:229], v222 offset:56320
	global_load_lds_dwordx4 v[230:231], off
	s_add_i32 m0, s8, 0x2000
	s_add_u32 s6, s6, 0x40080
	v_lshl_add_u64 v[230:231], v[232:233], 0, s[60:61]
	s_addc_u32 s7, s7, 0
	s_add_i32 s8, s91, s76
	global_load_lds_dwordx4 v[230:231], off
	v_lshl_add_u64 v[230:231], s[6:7], 0, v[148:149]
	s_mov_b32 m0, s8
	s_nop 0
	global_load_lds_dwordx4 v[230:231], off
	v_lshl_add_u64 v[230:231], s[6:7], 0, v[152:153]
	s_add_i32 m0, s8, 0x2000
	s_nop 0
	global_load_lds_dwordx4 v[230:231], off
	v_lshl_add_u64 v[230:231], v[234:235], 0, s[60:61]
	s_mov_b32 m0, s65
	s_nop 0
	global_load_lds_dwordx4 v[230:231], off
	v_lshl_add_u64 v[230:231], v[236:237], 0, s[60:61]
	s_mov_b32 m0, s66
	s_nop 0
	global_load_lds_dwordx4 v[230:231], off
	s_waitcnt vmcnt(8)
	s_waitcnt lgkmcnt(0)
	s_barrier
	s_setprio 3
	v_mfma_f32_16x16x32_bf16 v[62:65], v[130:133], v[182:185], v[62:65]
	v_mfma_f32_16x16x32_bf16 v[58:61], v[138:141], v[182:185], v[58:61]
	v_mfma_f32_16x16x32_bf16 v[46:49], v[130:133], v[190:193], v[46:49]
	v_mfma_f32_16x16x32_bf16 v[42:45], v[138:141], v[190:193], v[42:45]
	v_mfma_f32_16x16x32_bf16 v[30:33], v[130:133], v[198:201], v[30:33]
	v_mfma_f32_16x16x32_bf16 v[26:29], v[138:141], v[198:201], v[26:29]
	v_mfma_f32_16x16x32_bf16 v[14:17], v[130:133], v[206:209], v[14:17]
	v_mfma_f32_16x16x32_bf16 v[10:13], v[138:141], v[206:209], v[10:13]
	v_mfma_f32_16x16x32_bf16 v[62:65], v[134:137], v[186:189], v[62:65]
	v_mfma_f32_16x16x32_bf16 v[58:61], v[142:145], v[186:189], v[58:61]
	v_mfma_f32_16x16x32_bf16 v[46:49], v[134:137], v[194:197], v[46:49]
	v_mfma_f32_16x16x32_bf16 v[42:45], v[142:145], v[194:197], v[42:45]
	v_mfma_f32_16x16x32_bf16 v[30:33], v[134:137], v[202:205], v[30:33]
	v_mfma_f32_16x16x32_bf16 v[26:29], v[142:145], v[202:205], v[26:29]
	v_mfma_f32_16x16x32_bf16 v[14:17], v[134:137], v[226:229], v[14:17]
	v_mfma_f32_16x16x32_bf16 v[10:13], v[142:145], v[226:229], v[10:13]
	v_mfma_f32_16x16x32_bf16 v[54:57], v[166:169], v[182:185], v[54:57]
	v_mfma_f32_16x16x32_bf16 v[50:53], v[174:177], v[182:185], v[50:53]
	v_mfma_f32_16x16x32_bf16 v[38:41], v[166:169], v[190:193], v[38:41]
	v_mfma_f32_16x16x32_bf16 v[34:37], v[174:177], v[190:193], v[34:37]
	v_mfma_f32_16x16x32_bf16 v[22:25], v[166:169], v[198:201], v[22:25]
	v_mfma_f32_16x16x32_bf16 v[18:21], v[174:177], v[198:201], v[18:21]
	v_mfma_f32_16x16x32_bf16 v[6:9], v[166:169], v[206:209], v[6:9]
	v_mfma_f32_16x16x32_bf16 v[2:5], v[174:177], v[206:209], v[2:5]
	v_mfma_f32_16x16x32_bf16 v[54:57], v[170:173], v[186:189], v[54:57]
	v_mfma_f32_16x16x32_bf16 v[50:53], v[178:181], v[186:189], v[50:53]
	v_mfma_f32_16x16x32_bf16 v[38:41], v[170:173], v[194:197], v[38:41]
	v_mfma_f32_16x16x32_bf16 v[34:37], v[178:181], v[194:197], v[34:37]
	v_mfma_f32_16x16x32_bf16 v[22:25], v[170:173], v[202:205], v[22:25]
	v_mfma_f32_16x16x32_bf16 v[18:21], v[178:181], v[202:205], v[18:21]
	v_mfma_f32_16x16x32_bf16 v[6:9], v[170:173], v[226:229], v[6:9]
	v_mfma_f32_16x16x32_bf16 v[2:5], v[178:181], v[226:229], v[2:5]
	s_setprio 0
	s_barrier
	s_add_i32 s89, s89, 2
	s_add_u32 s4, s4, 0x100
	s_addc_u32 s5, s5, 0
	s_add_u32 s85, s85, 0x100
	s_addc_u32 s88, s88, 0
	s_cmp_gt_u32 s89, 13
	s_cbranch_scc0 .LBB0_787
	s_and_b64 vcc, exec, s[62:63]
	s_cbranch_vccz .LBB0_790
	s_barrier

; #define PG8_STAGE(bufoff, gbase, voff) do { _Pragma("unroll") for (int _i = 0; _i < 2; ++_i) \
;         __builtin_amdgcn_global_load_lds((const unsigned*)((const char*)(gbase) + (voff)[_i]), (LAS unsigned*)(lds + (bufoff) + ldsw + _i * 8192), 16, 0, 0); } while (0)
; #define PG8_LDA(dst, b, h) do { _Pragma("unroll") for (int m = 0; m < 4; ++m) _Pragma("unroll") for (int k = 0; k < 2; ++k) dst[m][k] = *(const LAS bf16x8*)(lds + PG8_SA(b, h) + aoff + m * 2048 + k * 1024); } while (0)
; #define PG8_LDB(dst, b, h) do { _Pragma("unroll") for (int n = 0; n < 2; ++n) _Pragma("unroll") for (int k = 0; k < 2; ++k) dst[n][k] = *(const LAS bf16x8*)(lds + PG8_SB(b, h) + boff + n * 2048 + k * 1024); } while (0)
; #define PG8_MMA(ai, bj, At, Bt) do { __builtin_amdgcn_s_setprio(3); _Pragma("unroll") for (int m = 0; m < 4; ++m) _Pragma("unroll") for (int n = 0; n < 2; ++n) _Pragma("unroll") for (int k = 0; k < 2; ++k) \
;         acc[ai][bj][m][n] = __builtin_amdgcn_mfma_f32_16x16x32_bf16(Bt[n][k], At[m][k], acc[ai][bj][m][n], 0, 0, 0); __builtin_amdgcn_s_setprio(0); } while (0)
; #define PG8_WAIT_V(n) asm volatile("s_waitcnt vmcnt(" #n ")" ::: "memory")
; #define PG8_WAIT_L(n) asm volatile("s_waitcnt lgkmcnt(" #n ")" ::: "memory")
; template <class Epi, bool ALIGN_EPI>
; __device__ __forceinline__ void gemm_phase(LAS unsigned char* lds, const Gemm g, const StaticOrder& S, const Epi& E) {
;     ...
;         const bool has_next = S.next(ui + 1, nxt);
;         const char* nA = has_next ? (const char*)g.A + (size_t)nxt.pm * tstep : cA; const char* nB = has_next ? (const char*)g.Bt + (size_t)nxt.pn * tstep : cB;
;         for (int t = 0; t < nt; t += 2) {
;             const bool last = (t == nt - 2);
;             const char* a1 = cA + (size_t)(t + 1) * kstep;
;             const char* a2 = last ? nA : cA + (size_t)(t + 2) * kstep; const char* b2 = last ? nB : cB + (size_t)(t + 2) * kstep;
;             const char* a3 = a2 + kstep; const char* b3 = b2 + kstep;
;             PG8_LDB(B0, 0, 0); PG8_LDB(B1, 0, 1); PG8_SCHED; PG8_LDA(At, 0, 0); PG8_STAGE(PG8_SA(1, 1), a1 + hstep, voffA);
;             PG8_WAIT_V(8); PG8_WAIT_L(0); PG8_BAR; PG8_MMA(0, 0, At, B0); PG8_MMA(0, 1, At, B1); PG8_BAR; PG8_SCHED;
;             PG8_LDA(At, 0, 1); PG8_STAGE(PG8_SB(0, 0), b2, voffB); PG8_STAGE(PG8_SB(0, 1), b2 + hstep, voffB); PG8_STAGE(PG8_SA(0, 0), a2, voffA);
.LBB0_1338:
	s_ashr_i32 s19, s18, 31
	s_lshl_b64 s[20:21], s[18:19], 19
	s_add_u32 s20, s26, s20
	s_addc_u32 s21, s27, s21
	s_and_b64 s[22:23], s[4:5], exec
	s_cselect_b32 s19, s21, s41
	s_cselect_b32 s37, s20, s40
	s_ashr_i32 s17, s16, 31
	s_lshl_b64 s[22:23], s[16:17], 19
	s_add_u32 s22, s33, s22
	s_addc_u32 s23, s46, s23
	s_and_b64 s[44:45], s[4:5], exec
	s_cselect_b32 s17, s23, s43
	s_cselect_b32 s58, s22, s42
	s_add_u32 s40, s40, 0x40080
	s_addc_u32 s41, s41, 0
	s_add_u32 s59, s42, 0x100
	s_addc_u32 s60, s43, 0
	s_mov_b32 s61, -2
	s_waitcnt lgkmcnt(0)
	ds_read_b128 v[130:133], v196
	ds_read_b128 v[134:137], v196 offset:1024
	ds_read_b128 v[138:141], v196 offset:2048
	ds_read_b128 v[142:145], v196 offset:3072
	ds_read_b128 v[146:149], v197
	ds_read_b128 v[150:153], v197 offset:1024
	ds_read_b128 v[170:173], v197 offset:2048
	ds_read_b128 v[174:177], v197 offset:3072
	s_add_u32 s42, s40, 0xfffc0080
	s_addc_u32 s43, s41, -1
	s_cmp_eq_u32 s61, 12
	s_cselect_b32 s45, s19, s43
	s_cselect_b32 s44, s37, s42
	s_cselect_b32 s43, s17, s60
	s_cselect_b32 s42, s58, s59
	v_lshl_add_u64 v[186:187], s[40:41], 0, v[162:163]
	s_add_i32 m0, s39, 0xc000
	ds_read_b128 v[178:181], v198
	ds_read_b128 v[182:185], v198 offset:1024
	ds_read_b128 v[200:203], v198 offset:2048
	ds_read_b128 v[204:207], v198 offset:3072
	ds_read_b128 v[208:211], v198 offset:4096
	ds_read_b128 v[212:215], v198 offset:5120
	ds_read_b128 v[216:219], v198 offset:6144
	ds_read_b128 v[220:223], v198 offset:7168
	global_load_lds_dwordx4 v[186:187], off
	v_lshl_add_u64 v[186:187], s[40:41], 0, v[164:165]
	s_add_i32 m0, s39, 0xe000
	s_nop 0
	global_load_lds_dwordx4 v[186:187], off
	s_waitcnt vmcnt(8)
	s_waitcnt lgkmcnt(0)
	s_barrier
	s_setprio 3
	v_mfma_f32_16x16x32_bf16 v[126:129], v[130:133], v[178:181], 0
	v_mfma_f32_16x16x32_bf16 v[122:125], v[138:141], v[178:181], 0
	v_mfma_f32_16x16x32_bf16 v[110:113], v[130:133], v[200:203], 0
	v_mfma_f32_16x16x32_bf16 v[106:109], v[138:141], v[200:203], 0
	v_mfma_f32_16x16x32_bf16 v[94:97], v[130:133], v[208:211], 0
	v_mfma_f32_16x16x32_bf16 v[90:93], v[138:141], v[208:211], 0
	v_mfma_f32_16x16x32_bf16 v[78:81], v[130:133], v[216:219], 0
	v_mfma_f32_16x16x32_bf16 v[74:77], v[138:141], v[216:219], 0
	v_mfma_f32_16x16x32_bf16 v[126:129], v[134:137], v[182:185], v[126:129]
	v_mfma_f32_16x16x32_bf16 v[122:125], v[142:145], v[182:185], v[122:125]
	v_mfma_f32_16x16x32_bf16 v[110:113], v[134:137], v[204:207], v[110:113]
	v_mfma_f32_16x16x32_bf16 v[106:109], v[142:145], v[204:207], v[106:109]
	v_mfma_f32_16x16x32_bf16 v[94:97], v[134:137], v[212:215], v[94:97]
	v_mfma_f32_16x16x32_bf16 v[90:93], v[142:145], v[212:215], v[90:93]
	v_mfma_f32_16x16x32_bf16 v[78:81], v[134:137], v[220:223], v[78:81]
	v_mfma_f32_16x16x32_bf16 v[74:77], v[142:145], v[220:223], v[74:77]
	v_mfma_f32_16x16x32_bf16 v[118:121], v[146:149], v[178:181], 0
	v_mfma_f32_16x16x32_bf16 v[114:117], v[170:173], v[178:181], 0
	v_mfma_f32_16x16x32_bf16 v[102:105], v[146:149], v[200:203], 0
	v_mfma_f32_16x16x32_bf16 v[98:101], v[170:173], v[200:203], 0
	v_mfma_f32_16x16x32_bf16 v[86:89], v[146:149], v[208:211], 0
	v_mfma_f32_16x16x32_bf16 v[82:85], v[170:173], v[208:211], 0
	v_mfma_f32_16x16x32_bf16 v[70:73], v[146:149], v[216:219], 0
	v_mfma_f32_16x16x32_bf16 v[66:69], v[170:173], v[216:219], 0
	v_mfma_f32_16x16x32_bf16 v[118:121], v[150:153], v[182:185], v[118:121]
	v_mfma_f32_16x16x32_bf16 v[114:117], v[174:177], v[182:185], v[114:117]
	v_mfma_f32_16x16x32_bf16 v[102:105], v[150:153], v[204:207], v[102:105]
	v_mfma_f32_16x16x32_bf16 v[98:101], v[174:177], v[204:207], v[98:101]
	v_mfma_f32_16x16x32_bf16 v[86:89], v[150:153], v[212:215], v[86:89]
	v_mfma_f32_16x16x32_bf16 v[82:85], v[174:177], v[212:215], v[82:85]
	v_mfma_f32_16x16x32_bf16 v[70:73], v[150:153], v[220:223], v[70:73]
	v_mfma_f32_16x16x32_bf16 v[66:69], v[174:177], v[220:223], v[66:69]
	s_setprio 0
	s_barrier
	s_add_i32 s62, s56, s47
	v_lshl_add_u64 v[186:187], s[42:43], 0, v[156:157]
	s_mov_b32 m0, s62
	ds_read_b128 v[178:181], v198 offset:16384
	ds_read_b128 v[182:185], v198 offset:17408
	ds_read_b128 v[200:203], v198 offset:18432
	ds_read_b128 v[204:207], v198 offset:19456
	ds_read_b128 v[208:211], v198 offset:20480
	ds_read_b128 v[212:215], v198 offset:21504
	ds_read_b128 v[216:219], v198 offset:22528
	ds_read_b128 v[220:223], v198 offset:23552
	global_load_lds_dwordx4 v[186:187], off
	s_add_i32 m0, s62, 0x2000
	s_add_u32 s62, s42, 0x40000
	v_lshl_add_u64 v[224:225], s[42:43], 0, v[160:161]
	s_addc_u32 s63, s43, 0
	s_add_i32 s64, s57, s47
	global_load_lds_dwordx4 v[224:225], off
	v_lshl_add_u64 v[226:227], s[62:63], 0, v[156:157]
	s_mov_b32 m0, s64
	v_lshl_add_u64 v[228:229], s[44:45], 0, v[158:159]
	global_load_lds_dwordx4 v[226:227], off
	v_lshl_add_u64 v[226:227], s[62:63], 0, v[160:161]
	s_add_i32 m0, s64, 0x2000
	s_nop 0
	global_load_lds_dwordx4 v[226:227], off
	v_lshl_add_u64 v[226:227], s[44:45], 0, v[154:155]
	s_mov_b32 m0, s39
	s_nop 0
	global_load_lds_dwordx4 v[226:227], off
	s_mov_b32 m0, s48
	s_nop 0
	global_load_lds_dwordx4 v[228:229], off
	s_waitcnt vmcnt(8)
	s_waitcnt lgkmcnt(0)
	s_barrier
; #define PG8_STAGE(bufoff, gbase, voff) do { _Pragma("unroll") for (int _i = 0; _i < 2; ++_i) \
;         __builtin_amdgcn_global_load_lds((const unsigned*)((const char*)(gbase) + (voff)[_i]), (LAS unsigned*)(lds + (bufoff) + ldsw + _i * 8192), 16, 0, 0); } while (0)
; #define PG8_LDA(dst, b, h) do { _Pragma("unroll") for (int m = 0; m < 4; ++m) _Pragma("unroll") for (int k = 0; k < 2; ++k) dst[m][k] = *(const LAS bf16x8*)(lds + PG8_SA(b, h) + aoff + m * 2048 + k * 1024); } while (0)
; #define PG8_LDB(dst, b, h) do { _Pragma("unroll") for (int n = 0; n < 2; ++n) _Pragma("unroll") for (int k = 0; k < 2; ++k) dst[n][k] = *(const LAS bf16x8*)(lds + PG8_SB(b, h) + boff + n * 2048 + k * 1024); } while (0)
; #define PG8_MMA(ai, bj, At, Bt) do { __builtin_amdgcn_s_setprio(3); _Pragma("unroll") for (int m = 0; m < 4; ++m) _Pragma("unroll") for (int n = 0; n < 2; ++n) _Pragma("unroll") for (int k = 0; k < 2; ++k) \
;         acc[ai][bj][m][n] = __builtin_amdgcn_mfma_f32_16x16x32_bf16(Bt[n][k], At[m][k], acc[ai][bj][m][n], 0, 0, 0); __builtin_amdgcn_s_setprio(0); } while (0)
; #define PG8_WAIT_V(n) asm volatile("s_waitcnt vmcnt(" #n ")" ::: "memory")
; #define PG8_WAIT_L(n) asm volatile("s_waitcnt lgkmcnt(" #n ")" ::: "memory")
; #define PG8_BAR __builtin_amdgcn_s_barrier()
; #define PG8_SCHED __builtin_amdgcn_sched_barrier(0)
; template <class Epi, bool ALIGN_EPI>
; __device__ __forceinline__ void gemm_phase(LAS unsigned char* lds, const Gemm g, const StaticOrder& S, const Epi& E) {
;     ...
;             PG8_WAIT_V(8); PG8_WAIT_L(0); PG8_BAR; PG8_MMA(1, 0, At, B0); PG8_MMA(1, 1, At, B1); PG8_BAR; PG8_SCHED;
;             PG8_LDB(B0, 1, 0); PG8_LDB(B1, 1, 1); PG8_SCHED; PG8_LDA(At, 1, 0); PG8_STAGE(PG8_SA(0, 1), a2 + hstep, voffA);
;             PG8_WAIT_V(8); PG8_WAIT_L(0); PG8_BAR; PG8_MMA(0, 0, At, B0); PG8_MMA(0, 1, At, B1); PG8_BAR; PG8_SCHED;
	s_setprio 3
	v_mfma_f32_16x16x32_bf16 v[62:65], v[130:133], v[178:181], 0
	v_mfma_f32_16x16x32_bf16 v[58:61], v[138:141], v[178:181], 0
	v_mfma_f32_16x16x32_bf16 v[46:49], v[130:133], v[200:203], 0
	v_mfma_f32_16x16x32_bf16 v[42:45], v[138:141], v[200:203], 0
	v_mfma_f32_16x16x32_bf16 v[30:33], v[130:133], v[208:211], 0
	v_mfma_f32_16x16x32_bf16 v[26:29], v[138:141], v[208:211], 0
	v_mfma_f32_16x16x32_bf16 v[14:17], v[130:133], v[216:219], 0
	v_mfma_f32_16x16x32_bf16 v[10:13], v[138:141], v[216:219], 0
	v_mfma_f32_16x16x32_bf16 v[62:65], v[134:137], v[182:185], v[62:65]
	v_mfma_f32_16x16x32_bf16 v[58:61], v[142:145], v[182:185], v[58:61]
	v_mfma_f32_16x16x32_bf16 v[46:49], v[134:137], v[204:207], v[46:49]
	v_mfma_f32_16x16x32_bf16 v[42:45], v[142:145], v[204:207], v[42:45]
	v_mfma_f32_16x16x32_bf16 v[30:33], v[134:137], v[212:215], v[30:33]
	v_mfma_f32_16x16x32_bf16 v[26:29], v[142:145], v[212:215], v[26:29]
	v_mfma_f32_16x16x32_bf16 v[14:17], v[134:137], v[220:223], v[14:17]
	v_mfma_f32_16x16x32_bf16 v[10:13], v[142:145], v[220:223], v[10:13]
	v_mfma_f32_16x16x32_bf16 v[54:57], v[146:149], v[178:181], 0
	v_mfma_f32_16x16x32_bf16 v[50:53], v[170:173], v[178:181], 0
	v_mfma_f32_16x16x32_bf16 v[38:41], v[146:149], v[200:203], 0
	v_mfma_f32_16x16x32_bf16 v[34:37], v[170:173], v[200:203], 0
	v_mfma_f32_16x16x32_bf16 v[22:25], v[146:149], v[208:211], 0
	v_mfma_f32_16x16x32_bf16 v[18:21], v[170:173], v[208:211], 0
	v_mfma_f32_16x16x32_bf16 v[6:9], v[146:149], v[216:219], 0
	v_mfma_f32_16x16x32_bf16 v[2:5], v[170:173], v[216:219], 0
	v_mfma_f32_16x16x32_bf16 v[54:57], v[150:153], v[182:185], v[54:57]
	v_mfma_f32_16x16x32_bf16 v[50:53], v[174:177], v[182:185], v[50:53]
	v_mfma_f32_16x16x32_bf16 v[38:41], v[150:153], v[204:207], v[38:41]
	v_mfma_f32_16x16x32_bf16 v[34:37], v[174:177], v[204:207], v[34:37]
	v_mfma_f32_16x16x32_bf16 v[22:25], v[150:153], v[212:215], v[22:25]
	v_mfma_f32_16x16x32_bf16 v[18:21], v[174:177], v[212:215], v[18:21]
	v_mfma_f32_16x16x32_bf16 v[6:9], v[150:153], v[220:223], v[6:9]
	v_mfma_f32_16x16x32_bf16 v[2:5], v[174:177], v[220:223], v[2:5]
	s_setprio 0
	s_barrier
	s_add_i32 s62, 0, 0x18000
	s_add_i32 s63, 0, 0x1c000
	v_add_u32_e32 v142, s62, v194
	v_add_u32_e32 v174, s63, v194
	ds_read_b128 v[130:133], v142
	ds_read_b128 v[134:137], v142 offset:1024
	ds_read_b128 v[138:141], v142 offset:2048
	ds_read_b128 v[142:145], v142 offset:3072
	ds_read_b128 v[146:149], v174
	ds_read_b128 v[150:153], v174 offset:1024
	ds_read_b128 v[170:173], v174 offset:2048
	ds_read_b128 v[174:177], v174 offset:3072
	s_add_u32 s44, s44, 0x40000
	s_addc_u32 s45, s45, 0
	s_mov_b32 m0, s49
	v_lshl_add_u64 v[230:231], s[44:45], 0, v[154:155]
	ds_read_b128 v[178:181], v198 offset:32768
	ds_read_b128 v[182:185], v198 offset:33792
	ds_read_b128 v[200:203], v198 offset:34816
	ds_read_b128 v[204:207], v198 offset:35840
	ds_read_b128 v[208:211], v198 offset:36864
	ds_read_b128 v[212:215], v198 offset:37888
	ds_read_b128 v[216:219], v198 offset:38912
	ds_read_b128 v[220:223], v198 offset:39936
	global_load_lds_dwordx4 v[230:231], off
	v_lshl_add_u64 v[230:231], s[44:45], 0, v[158:159]
	s_mov_b32 m0, s50
	s_nop 0
	global_load_lds_dwordx4 v[230:231], off
	s_waitcnt vmcnt(8)
	s_waitcnt lgkmcnt(0)
	s_barrier
	s_setprio 3
	v_mfma_f32_16x16x32_bf16 v[126:129], v[130:133], v[178:181], v[126:129]
	v_mfma_f32_16x16x32_bf16 v[122:125], v[138:141], v[178:181], v[122:125]
	v_mfma_f32_16x16x32_bf16 v[110:113], v[130:133], v[200:203], v[110:113]
	v_mfma_f32_16x16x32_bf16 v[106:109], v[138:141], v[200:203], v[106:109]
	v_mfma_f32_16x16x32_bf16 v[94:97], v[130:133], v[208:211], v[94:97]
	v_mfma_f32_16x16x32_bf16 v[90:93], v[138:141], v[208:211], v[90:93]
	v_mfma_f32_16x16x32_bf16 v[78:81], v[130:133], v[216:219], v[78:81]
	v_mfma_f32_16x16x32_bf16 v[74:77], v[138:141], v[216:219], v[74:77]
	v_mfma_f32_16x16x32_bf16 v[126:129], v[134:137], v[182:185], v[126:129]
	v_mfma_f32_16x16x32_bf16 v[122:125], v[142:145], v[182:185], v[122:125]
	v_mfma_f32_16x16x32_bf16 v[110:113], v[134:137], v[204:207], v[110:113]
	v_mfma_f32_16x16x32_bf16 v[106:109], v[142:145], v[204:207], v[106:109]
	v_mfma_f32_16x16x32_bf16 v[94:97], v[134:137], v[212:215], v[94:97]
	v_mfma_f32_16x16x32_bf16 v[90:93], v[142:145], v[212:215], v[90:93]
	v_mfma_f32_16x16x32_bf16 v[78:81], v[134:137], v[220:223], v[78:81]
	v_mfma_f32_16x16x32_bf16 v[74:77], v[142:145], v[220:223], v[74:77]
	v_mfma_f32_16x16x32_bf16 v[118:121], v[146:149], v[178:181], v[118:121]
	v_mfma_f32_16x16x32_bf16 v[114:117], v[170:173], v[178:181], v[114:117]
	v_mfma_f32_16x16x32_bf16 v[102:105], v[146:149], v[200:203], v[102:105]
	v_mfma_f32_16x16x32_bf16 v[98:101], v[170:173], v[200:203], v[98:101]
	v_mfma_f32_16x16x32_bf16 v[86:89], v[146:149], v[208:211], v[86:89]
	v_mfma_f32_16x16x32_bf16 v[82:85], v[170:173], v[208:211], v[82:85]
	v_mfma_f32_16x16x32_bf16 v[70:73], v[146:149], v[216:219], v[70:73]
	v_mfma_f32_16x16x32_bf16 v[66:69], v[170:173], v[216:219], v[66:69]
	v_mfma_f32_16x16x32_bf16 v[118:121], v[150:153], v[182:185], v[118:121]
	v_mfma_f32_16x16x32_bf16 v[114:117], v[174:177], v[182:185], v[114:117]
	v_mfma_f32_16x16x32_bf16 v[102:105], v[150:153], v[204:207], v[102:105]
	v_mfma_f32_16x16x32_bf16 v[98:101], v[174:177], v[204:207], v[98:101]
	v_mfma_f32_16x16x32_bf16 v[86:89], v[150:153], v[212:215], v[86:89]
	v_mfma_f32_16x16x32_bf16 v[82:85], v[174:177], v[212:215], v[82:85]
	v_mfma_f32_16x16x32_bf16 v[70:73], v[150:153], v[220:223], v[70:73]
	v_mfma_f32_16x16x32_bf16 v[66:69], v[174:177], v[220:223], v[66:69]
	s_setprio 0
	s_barrier
; #define PG8_STAGE(bufoff, gbase, voff) do { _Pragma("unroll") for (int _i = 0; _i < 2; ++_i) \
;         __builtin_amdgcn_global_load_lds((const unsigned*)((const char*)(gbase) + (voff)[_i]), (LAS unsigned*)(lds + (bufoff) + ldsw + _i * 8192), 16, 0, 0); } while (0)
; #define PG8_LDA(dst, b, h) do { _Pragma("unroll") for (int m = 0; m < 4; ++m) _Pragma("unroll") for (int k = 0; k < 2; ++k) dst[m][k] = *(const LAS bf16x8*)(lds + PG8_SA(b, h) + aoff + m * 2048 + k * 1024); } while (0)
; #define PG8_LDB(dst, b, h) do { _Pragma("unroll") for (int n = 0; n < 2; ++n) _Pragma("unroll") for (int k = 0; k < 2; ++k) dst[n][k] = *(const LAS bf16x8*)(lds + PG8_SB(b, h) + boff + n * 2048 + k * 1024); } while (0)
; #define PG8_MMA(ai, bj, At, Bt) do { __builtin_amdgcn_s_setprio(3); _Pragma("unroll") for (int m = 0; m < 4; ++m) _Pragma("unroll") for (int n = 0; n < 2; ++n) _Pragma("unroll") for (int k = 0; k < 2; ++k) \
;         acc[ai][bj][m][n] = __builtin_amdgcn_mfma_f32_16x16x32_bf16(Bt[n][k], At[m][k], acc[ai][bj][m][n], 0, 0, 0); __builtin_amdgcn_s_setprio(0); } while (0)
; #define PG8_WAIT_V(n) asm volatile("s_waitcnt vmcnt(" #n ")" ::: "memory")
; #define PG8_BAR __builtin_amdgcn_s_barrier()
; template <class Epi, bool ALIGN_EPI>
; __device__ __forceinline__ void gemm_phase(LAS unsigned char* lds, const Gemm g, const StaticOrder& S, const Epi& E) {
;     ...
;             PG8_LDB(B0, 0, 0); PG8_LDB(B1, 0, 1); PG8_SCHED; PG8_LDA(At, 0, 0); PG8_STAGE(PG8_SA(1, 1), a1 + hstep, voffA);
;             PG8_WAIT_V(8); PG8_WAIT_L(0); PG8_BAR; PG8_MMA(0, 0, At, B0); PG8_MMA(0, 1, At, B1); PG8_BAR; PG8_SCHED;
;             PG8_LDA(At, 0, 1); PG8_STAGE(PG8_SB(0, 0), b2, voffB); PG8_STAGE(PG8_SB(0, 1), b2 + hstep, voffB); PG8_STAGE(PG8_SA(0, 0), a2, voffA);
;             PG8_WAIT_V(8); PG8_WAIT_L(0); PG8_BAR; PG8_MMA(1, 0, At, B0); PG8_MMA(1, 1, At, B1); PG8_BAR; PG8_SCHED;
;             PG8_LDB(B0, 1, 0); PG8_LDB(B1, 1, 1); PG8_SCHED; PG8_LDA(At, 1, 0); PG8_STAGE(PG8_SA(0, 1), a2 + hstep, voffA);
;             PG8_WAIT_V(8); PG8_WAIT_L(0); PG8_BAR; PG8_MMA(0, 0, At, B0); PG8_MMA(0, 1, At, B1); PG8_BAR; PG8_SCHED;
;             PG8_LDA(At, 1, 1); PG8_STAGE(PG8_SB(1, 0), b3, voffB); PG8_STAGE(PG8_SB(1, 1), b3 + hstep, voffB); PG8_STAGE(PG8_SA(1, 0), a3, voffA);
;             PG8_WAIT_V(8); PG8_WAIT_L(0); PG8_BAR; PG8_MMA(1, 0, At, B0); PG8_MMA(1, 1, At, B1); PG8_BAR; PG8_SCHED;
	s_add_i32 s44, s62, s47
	v_lshl_add_u64 v[186:187], v[186:187], 0, s[12:13]
	s_mov_b32 m0, s44
	ds_read_b128 v[178:181], v198 offset:49152
	ds_read_b128 v[182:185], v198 offset:50176
	ds_read_b128 v[200:203], v198 offset:51200
	ds_read_b128 v[204:207], v198 offset:52224
	ds_read_b128 v[208:211], v198 offset:53248
	ds_read_b128 v[212:215], v198 offset:54272
	ds_read_b128 v[216:219], v198 offset:55296
	ds_read_b128 v[220:223], v198 offset:56320
	global_load_lds_dwordx4 v[186:187], off
	s_add_i32 m0, s44, 0x2000
	s_add_u32 s42, s42, 0x40080
	v_lshl_add_u64 v[186:187], v[224:225], 0, s[12:13]
	s_addc_u32 s43, s43, 0
	s_add_i32 s44, s63, s47
	global_load_lds_dwordx4 v[186:187], off
	v_lshl_add_u64 v[186:187], s[42:43], 0, v[156:157]
	s_mov_b32 m0, s44
	s_nop 0
	global_load_lds_dwordx4 v[186:187], off
	v_lshl_add_u64 v[186:187], s[42:43], 0, v[160:161]
	s_add_i32 m0, s44, 0x2000
	s_nop 0
	global_load_lds_dwordx4 v[186:187], off
	v_lshl_add_u64 v[186:187], v[226:227], 0, s[12:13]
	s_mov_b32 m0, s52
	s_nop 0
	global_load_lds_dwordx4 v[186:187], off
	v_lshl_add_u64 v[186:187], v[228:229], 0, s[12:13]
	s_mov_b32 m0, s53
	s_nop 0
	global_load_lds_dwordx4 v[186:187], off
	s_waitcnt vmcnt(8)
	s_waitcnt lgkmcnt(0)
	s_barrier
	s_setprio 3
	v_mfma_f32_16x16x32_bf16 v[62:65], v[130:133], v[178:181], v[62:65]
	v_mfma_f32_16x16x32_bf16 v[58:61], v[138:141], v[178:181], v[58:61]
	v_mfma_f32_16x16x32_bf16 v[46:49], v[130:133], v[200:203], v[46:49]
	v_mfma_f32_16x16x32_bf16 v[42:45], v[138:141], v[200:203], v[42:45]
	v_mfma_f32_16x16x32_bf16 v[30:33], v[130:133], v[208:211], v[30:33]
	v_mfma_f32_16x16x32_bf16 v[26:29], v[138:141], v[208:211], v[26:29]
	v_mfma_f32_16x16x32_bf16 v[14:17], v[130:133], v[216:219], v[14:17]
	v_mfma_f32_16x16x32_bf16 v[10:13], v[138:141], v[216:219], v[10:13]
	v_mfma_f32_16x16x32_bf16 v[62:65], v[134:137], v[182:185], v[62:65]
	v_mfma_f32_16x16x32_bf16 v[58:61], v[142:145], v[182:185], v[58:61]
	v_mfma_f32_16x16x32_bf16 v[46:49], v[134:137], v[204:207], v[46:49]
	v_mfma_f32_16x16x32_bf16 v[42:45], v[142:145], v[204:207], v[42:45]
	v_mfma_f32_16x16x32_bf16 v[30:33], v[134:137], v[212:215], v[30:33]
	v_mfma_f32_16x16x32_bf16 v[26:29], v[142:145], v[212:215], v[26:29]
	v_mfma_f32_16x16x32_bf16 v[14:17], v[134:137], v[220:223], v[14:17]
	v_mfma_f32_16x16x32_bf16 v[10:13], v[142:145], v[220:223], v[10:13]
	v_mfma_f32_16x16x32_bf16 v[54:57], v[146:149], v[178:181], v[54:57]
	v_mfma_f32_16x16x32_bf16 v[50:53], v[170:173], v[178:181], v[50:53]
	v_mfma_f32_16x16x32_bf16 v[38:41], v[146:149], v[200:203], v[38:41]
	v_mfma_f32_16x16x32_bf16 v[34:37], v[170:173], v[200:203], v[34:37]
	v_mfma_f32_16x16x32_bf16 v[22:25], v[146:149], v[208:211], v[22:25]
	v_mfma_f32_16x16x32_bf16 v[18:21], v[170:173], v[208:211], v[18:21]
	v_mfma_f32_16x16x32_bf16 v[6:9], v[146:149], v[216:219], v[6:9]
	v_mfma_f32_16x16x32_bf16 v[2:5], v[170:173], v[216:219], v[2:5]
	v_mfma_f32_16x16x32_bf16 v[54:57], v[150:153], v[182:185], v[54:57]
	v_mfma_f32_16x16x32_bf16 v[50:53], v[174:177], v[182:185], v[50:53]
	v_mfma_f32_16x16x32_bf16 v[38:41], v[150:153], v[204:207], v[38:41]
	v_mfma_f32_16x16x32_bf16 v[34:37], v[174:177], v[204:207], v[34:37]
	v_mfma_f32_16x16x32_bf16 v[22:25], v[150:153], v[212:215], v[22:25]
	v_mfma_f32_16x16x32_bf16 v[18:21], v[174:177], v[212:215], v[18:21]
	v_mfma_f32_16x16x32_bf16 v[6:9], v[150:153], v[220:223], v[6:9]
	v_mfma_f32_16x16x32_bf16 v[2:5], v[174:177], v[220:223], v[2:5]
	s_setprio 0
	s_barrier
	s_add_i32 s61, s61, 2
	s_add_u32 s40, s40, 0x100
	s_addc_u32 s41, s41, 0
	s_add_u32 s59, s59, 0x100
	s_addc_u32 s60, s60, 0
.LBB0_1339:
	ds_read_b128 v[130:133], v196
	ds_read_b128 v[134:137], v196 offset:1024
	ds_read_b128 v[138:141], v196 offset:2048
	ds_read_b128 v[142:145], v196 offset:3072
	ds_read_b128 v[146:149], v197
	ds_read_b128 v[150:153], v197 offset:1024
	ds_read_b128 v[170:173], v197 offset:2048
	ds_read_b128 v[174:177], v197 offset:3072
	s_add_u32 s42, s40, 0xfffc0080
	s_addc_u32 s43, s41, -1
	s_cmp_eq_u32 s61, 12
	s_cselect_b32 s45, s19, s43
	s_cselect_b32 s44, s37, s42
	s_cselect_b32 s43, s17, s60
	s_cselect_b32 s42, s58, s59
	v_lshl_add_u64 v[186:187], s[40:41], 0, v[162:163]
	s_add_i32 m0, s39, 0xc000
	ds_read_b128 v[178:181], v198
	ds_read_b128 v[182:185], v198 offset:1024
	ds_read_b128 v[200:203], v198 offset:2048
	ds_read_b128 v[204:207], v198 offset:3072
	ds_read_b128 v[208:211], v198 offset:4096
	ds_read_b128 v[212:215], v198 offset:5120
	ds_read_b128 v[216:219], v198 offset:6144
	ds_read_b128 v[220:223], v198 offset:7168
	global_load_lds_dwordx4 v[186:187], off
	v_lshl_add_u64 v[186:187], s[40:41], 0, v[164:165]
	s_add_i32 m0, s39, 0xe000
	s_nop 0
	global_load_lds_dwordx4 v[186:187], off
	s_waitcnt vmcnt(8)
	s_waitcnt lgkmcnt(0)
	s_barrier
; #define PG8_STAGE(bufoff, gbase, voff) do { _Pragma("unroll") for (int _i = 0; _i < 2; ++_i) \
;         __builtin_amdgcn_global_load_lds((const unsigned*)((const char*)(gbase) + (voff)[_i]), (LAS unsigned*)(lds + (bufoff) + ldsw + _i * 8192), 16, 0, 0); } while (0)
; #define PG8_LDA(dst, b, h) do { _Pragma("unroll") for (int m = 0; m < 4; ++m) _Pragma("unroll") for (int k = 0; k < 2; ++k) dst[m][k] = *(const LAS bf16x8*)(lds + PG8_SA(b, h) + aoff + m * 2048 + k * 1024); } while (0)
; #define PG8_MMA(ai, bj, At, Bt) do { __builtin_amdgcn_s_setprio(3); _Pragma("unroll") for (int m = 0; m < 4; ++m) _Pragma("unroll") for (int n = 0; n < 2; ++n) _Pragma("unroll") for (int k = 0; k < 2; ++k) \
;         acc[ai][bj][m][n] = __builtin_amdgcn_mfma_f32_16x16x32_bf16(Bt[n][k], At[m][k], acc[ai][bj][m][n], 0, 0, 0); __builtin_amdgcn_s_setprio(0); } while (0)
; #define PG8_WAIT_V(n) asm volatile("s_waitcnt vmcnt(" #n ")" ::: "memory")
; #define PG8_WAIT_L(n) asm volatile("s_waitcnt lgkmcnt(" #n ")" ::: "memory")
; #define PG8_BAR __builtin_amdgcn_s_barrier()
; #define PG8_SCHED __builtin_amdgcn_sched_barrier(0)
; template <class Epi, bool ALIGN_EPI>
; __device__ __forceinline__ void gemm_phase(LAS unsigned char* lds, const Gemm g, const StaticOrder& S, const Epi& E) {
;     ...
;             PG8_WAIT_V(8); PG8_WAIT_L(0); PG8_BAR; PG8_MMA(0, 0, At, B0); PG8_MMA(0, 1, At, B1); PG8_BAR; PG8_SCHED;
;             PG8_LDA(At, 0, 1); PG8_STAGE(PG8_SB(0, 0), b2, voffB); PG8_STAGE(PG8_SB(0, 1), b2 + hstep, voffB); PG8_STAGE(PG8_SA(0, 0), a2, voffA);
;             PG8_WAIT_V(8); PG8_WAIT_L(0); PG8_BAR; PG8_MMA(1, 0, At, B0); PG8_MMA(1, 1, At, B1); PG8_BAR; PG8_SCHED;
	s_setprio 3
	v_mfma_f32_16x16x32_bf16 v[126:129], v[130:133], v[178:181], v[126:129]
	v_mfma_f32_16x16x32_bf16 v[122:125], v[138:141], v[178:181], v[122:125]
	v_mfma_f32_16x16x32_bf16 v[110:113], v[130:133], v[200:203], v[110:113]
	v_mfma_f32_16x16x32_bf16 v[106:109], v[138:141], v[200:203], v[106:109]
	v_mfma_f32_16x16x32_bf16 v[94:97], v[130:133], v[208:211], v[94:97]
	v_mfma_f32_16x16x32_bf16 v[90:93], v[138:141], v[208:211], v[90:93]
	v_mfma_f32_16x16x32_bf16 v[78:81], v[130:133], v[216:219], v[78:81]
	v_mfma_f32_16x16x32_bf16 v[74:77], v[138:141], v[216:219], v[74:77]
	v_mfma_f32_16x16x32_bf16 v[126:129], v[134:137], v[182:185], v[126:129]
	v_mfma_f32_16x16x32_bf16 v[122:125], v[142:145], v[182:185], v[122:125]
	v_mfma_f32_16x16x32_bf16 v[110:113], v[134:137], v[204:207], v[110:113]
	v_mfma_f32_16x16x32_bf16 v[106:109], v[142:145], v[204:207], v[106:109]
	v_mfma_f32_16x16x32_bf16 v[94:97], v[134:137], v[212:215], v[94:97]
	v_mfma_f32_16x16x32_bf16 v[90:93], v[142:145], v[212:215], v[90:93]
	v_mfma_f32_16x16x32_bf16 v[78:81], v[134:137], v[220:223], v[78:81]
	v_mfma_f32_16x16x32_bf16 v[74:77], v[142:145], v[220:223], v[74:77]
	v_mfma_f32_16x16x32_bf16 v[118:121], v[146:149], v[178:181], v[118:121]
	v_mfma_f32_16x16x32_bf16 v[114:117], v[170:173], v[178:181], v[114:117]
	v_mfma_f32_16x16x32_bf16 v[102:105], v[146:149], v[200:203], v[102:105]
	v_mfma_f32_16x16x32_bf16 v[98:101], v[170:173], v[200:203], v[98:101]
	v_mfma_f32_16x16x32_bf16 v[86:89], v[146:149], v[208:211], v[86:89]
	v_mfma_f32_16x16x32_bf16 v[82:85], v[170:173], v[208:211], v[82:85]
	v_mfma_f32_16x16x32_bf16 v[70:73], v[146:149], v[216:219], v[70:73]
	v_mfma_f32_16x16x32_bf16 v[66:69], v[170:173], v[216:219], v[66:69]
	v_mfma_f32_16x16x32_bf16 v[118:121], v[150:153], v[182:185], v[118:121]
	v_mfma_f32_16x16x32_bf16 v[114:117], v[174:177], v[182:185], v[114:117]
	v_mfma_f32_16x16x32_bf16 v[102:105], v[150:153], v[204:207], v[102:105]
	v_mfma_f32_16x16x32_bf16 v[98:101], v[174:177], v[204:207], v[98:101]
	v_mfma_f32_16x16x32_bf16 v[86:89], v[150:153], v[212:215], v[86:89]
	v_mfma_f32_16x16x32_bf16 v[82:85], v[174:177], v[212:215], v[82:85]
	v_mfma_f32_16x16x32_bf16 v[70:73], v[150:153], v[220:223], v[70:73]
	v_mfma_f32_16x16x32_bf16 v[66:69], v[174:177], v[220:223], v[66:69]
	s_setprio 0
	s_barrier
	s_add_i32 s62, s56, s47
	v_lshl_add_u64 v[186:187], s[42:43], 0, v[156:157]
	s_mov_b32 m0, s62
	ds_read_b128 v[178:181], v198 offset:16384
	ds_read_b128 v[182:185], v198 offset:17408
	ds_read_b128 v[200:203], v198 offset:18432
	ds_read_b128 v[204:207], v198 offset:19456
	ds_read_b128 v[208:211], v198 offset:20480
	ds_read_b128 v[212:215], v198 offset:21504
	ds_read_b128 v[216:219], v198 offset:22528
	ds_read_b128 v[220:223], v198 offset:23552
	global_load_lds_dwordx4 v[186:187], off
	s_add_i32 m0, s62, 0x2000
	s_add_u32 s62, s42, 0x40000
	v_lshl_add_u64 v[224:225], s[42:43], 0, v[160:161]
	s_addc_u32 s63, s43, 0
	s_add_i32 s64, s57, s47
	global_load_lds_dwordx4 v[224:225], off
	v_lshl_add_u64 v[226:227], s[62:63], 0, v[156:157]
	s_mov_b32 m0, s64
	v_lshl_add_u64 v[228:229], s[44:45], 0, v[158:159]
	global_load_lds_dwordx4 v[226:227], off
	v_lshl_add_u64 v[226:227], s[62:63], 0, v[160:161]
	s_add_i32 m0, s64, 0x2000
	s_nop 0
	global_load_lds_dwordx4 v[226:227], off
	v_lshl_add_u64 v[226:227], s[44:45], 0, v[154:155]
	s_mov_b32 m0, s39
	s_nop 0
	global_load_lds_dwordx4 v[226:227], off
	s_mov_b32 m0, s48
	s_nop 0
	global_load_lds_dwordx4 v[228:229], off
	s_waitcnt vmcnt(8)
	s_waitcnt lgkmcnt(0)
	s_barrier
	s_setprio 3
	v_mfma_f32_16x16x32_bf16 v[62:65], v[130:133], v[178:181], v[62:65]
	v_mfma_f32_16x16x32_bf16 v[58:61], v[138:141], v[178:181], v[58:61]
	v_mfma_f32_16x16x32_bf16 v[46:49], v[130:133], v[200:203], v[46:49]
	v_mfma_f32_16x16x32_bf16 v[42:45], v[138:141], v[200:203], v[42:45]
	v_mfma_f32_16x16x32_bf16 v[30:33], v[130:133], v[208:211], v[30:33]
	v_mfma_f32_16x16x32_bf16 v[26:29], v[138:141], v[208:211], v[26:29]
	v_mfma_f32_16x16x32_bf16 v[14:17], v[130:133], v[216:219], v[14:17]
	v_mfma_f32_16x16x32_bf16 v[10:13], v[138:141], v[216:219], v[10:13]
	v_mfma_f32_16x16x32_bf16 v[62:65], v[134:137], v[182:185], v[62:65]
	v_mfma_f32_16x16x32_bf16 v[58:61], v[142:145], v[182:185], v[58:61]
	v_mfma_f32_16x16x32_bf16 v[46:49], v[134:137], v[204:207], v[46:49]
	v_mfma_f32_16x16x32_bf16 v[42:45], v[142:145], v[204:207], v[42:45]
	v_mfma_f32_16x16x32_bf16 v[30:33], v[134:137], v[212:215], v[30:33]
	v_mfma_f32_16x16x32_bf16 v[26:29], v[142:145], v[212:215], v[26:29]
	v_mfma_f32_16x16x32_bf16 v[14:17], v[134:137], v[220:223], v[14:17]
	v_mfma_f32_16x16x32_bf16 v[10:13], v[142:145], v[220:223], v[10:13]
	v_mfma_f32_16x16x32_bf16 v[54:57], v[146:149], v[178:181], v[54:57]
	v_mfma_f32_16x16x32_bf16 v[50:53], v[170:173], v[178:181], v[50:53]
	v_mfma_f32_16x16x32_bf16 v[38:41], v[146:149], v[200:203], v[38:41]
	v_mfma_f32_16x16x32_bf16 v[34:37], v[170:173], v[200:203], v[34:37]
	v_mfma_f32_16x16x32_bf16 v[22:25], v[146:149], v[208:211], v[22:25]
	v_mfma_f32_16x16x32_bf16 v[18:21], v[170:173], v[208:211], v[18:21]
	v_mfma_f32_16x16x32_bf16 v[6:9], v[146:149], v[216:219], v[6:9]
	v_mfma_f32_16x16x32_bf16 v[2:5], v[170:173], v[216:219], v[2:5]
	v_mfma_f32_16x16x32_bf16 v[54:57], v[150:153], v[182:185], v[54:57]
	v_mfma_f32_16x16x32_bf16 v[50:53], v[174:177], v[182:185], v[50:53]
	v_mfma_f32_16x16x32_bf16 v[38:41], v[150:153], v[204:207], v[38:41]
	v_mfma_f32_16x16x32_bf16 v[34:37], v[174:177], v[204:207], v[34:37]
	v_mfma_f32_16x16x32_bf16 v[22:25], v[150:153], v[212:215], v[22:25]
	v_mfma_f32_16x16x32_bf16 v[18:21], v[174:177], v[212:215], v[18:21]
	v_mfma_f32_16x16x32_bf16 v[6:9], v[150:153], v[220:223], v[6:9]
	v_mfma_f32_16x16x32_bf16 v[2:5], v[174:177], v[220:223], v[2:5]
	s_setprio 0
	s_barrier
; #define PG8_STAGE(bufoff, gbase, voff) do { _Pragma("unroll") for (int _i = 0; _i < 2; ++_i) \
;         __builtin_amdgcn_global_load_lds((const unsigned*)((const char*)(gbase) + (voff)[_i]), (LAS unsigned*)(lds + (bufoff) + ldsw + _i * 8192), 16, 0, 0); } while (0)
; #define PG8_LDA(dst, b, h) do { _Pragma("unroll") for (int m = 0; m < 4; ++m) _Pragma("unroll") for (int k = 0; k < 2; ++k) dst[m][k] = *(const LAS bf16x8*)(lds + PG8_SA(b, h) + aoff + m * 2048 + k * 1024); } while (0)
; #define PG8_LDB(dst, b, h) do { _Pragma("unroll") for (int n = 0; n < 2; ++n) _Pragma("unroll") for (int k = 0; k < 2; ++k) dst[n][k] = *(const LAS bf16x8*)(lds + PG8_SB(b, h) + boff + n * 2048 + k * 1024); } while (0)
; #define PG8_MMA(ai, bj, At, Bt) do { __builtin_amdgcn_s_setprio(3); _Pragma("unroll") for (int m = 0; m < 4; ++m) _Pragma("unroll") for (int n = 0; n < 2; ++n) _Pragma("unroll") for (int k = 0; k < 2; ++k) \
;         acc[ai][bj][m][n] = __builtin_amdgcn_mfma_f32_16x16x32_bf16(Bt[n][k], At[m][k], acc[ai][bj][m][n], 0, 0, 0); __builtin_amdgcn_s_setprio(0); } while (0)
; #define PG8_WAIT_V(n) asm volatile("s_waitcnt vmcnt(" #n ")" ::: "memory")
; #define PG8_WAIT_L(n) asm volatile("s_waitcnt lgkmcnt(" #n ")" ::: "memory")
; #define PG8_BAR __builtin_amdgcn_s_barrier()
; #define PG8_SCHED __builtin_amdgcn_sched_barrier(0)
; template <class Epi, bool ALIGN_EPI>
; __device__ __forceinline__ void gemm_phase(LAS unsigned char* lds, const Gemm g, const StaticOrder& S, const Epi& E) {
;     ...
;             PG8_LDB(B0, 1, 0); PG8_LDB(B1, 1, 1); PG8_SCHED; PG8_LDA(At, 1, 0); PG8_STAGE(PG8_SA(0, 1), a2 + hstep, voffA);
;             PG8_WAIT_V(8); PG8_WAIT_L(0); PG8_BAR; PG8_MMA(0, 0, At, B0); PG8_MMA(0, 1, At, B1); PG8_BAR; PG8_SCHED;
	s_add_i32 s62, 0, 0x18000
	s_add_i32 s63, 0, 0x1c000
	v_add_u32_e32 v142, s62, v194
	v_add_u32_e32 v174, s63, v194
	ds_read_b128 v[130:133], v142
	ds_read_b128 v[134:137], v142 offset:1024
	ds_read_b128 v[138:141], v142 offset:2048
	ds_read_b128 v[142:145], v142 offset:3072
	ds_read_b128 v[146:149], v174
	ds_read_b128 v[150:153], v174 offset:1024
	ds_read_b128 v[170:173], v174 offset:2048
	ds_read_b128 v[174:177], v174 offset:3072
	s_add_u32 s44, s44, 0x40000
	s_addc_u32 s45, s45, 0
	s_mov_b32 m0, s49
	v_lshl_add_u64 v[230:231], s[44:45], 0, v[154:155]
	ds_read_b128 v[178:181], v198 offset:32768
	ds_read_b128 v[182:185], v198 offset:33792
	ds_read_b128 v[200:203], v198 offset:34816
	ds_read_b128 v[204:207], v198 offset:35840
	ds_read_b128 v[208:211], v198 offset:36864
	ds_read_b128 v[212:215], v198 offset:37888
	ds_read_b128 v[216:219], v198 offset:38912
	ds_read_b128 v[220:223], v198 offset:39936
	global_load_lds_dwordx4 v[230:231], off
	v_lshl_add_u64 v[230:231], s[44:45], 0, v[158:159]
	s_mov_b32 m0, s50
	s_nop 0
	global_load_lds_dwordx4 v[230:231], off
	s_waitcnt vmcnt(8)
	s_waitcnt lgkmcnt(0)
	s_barrier
	s_setprio 3
	v_mfma_f32_16x16x32_bf16 v[126:129], v[130:133], v[178:181], v[126:129]
	v_mfma_f32_16x16x32_bf16 v[122:125], v[138:141], v[178:181], v[122:125]
	v_mfma_f32_16x16x32_bf16 v[110:113], v[130:133], v[200:203], v[110:113]
	v_mfma_f32_16x16x32_bf16 v[106:109], v[138:141], v[200:203], v[106:109]
	v_mfma_f32_16x16x32_bf16 v[94:97], v[130:133], v[208:211], v[94:97]
	v_mfma_f32_16x16x32_bf16 v[90:93], v[138:141], v[208:211], v[90:93]
	v_mfma_f32_16x16x32_bf16 v[78:81], v[130:133], v[216:219], v[78:81]
	v_mfma_f32_16x16x32_bf16 v[74:77], v[138:141], v[216:219], v[74:77]
	v_mfma_f32_16x16x32_bf16 v[126:129], v[134:137], v[182:185], v[126:129]
	v_mfma_f32_16x16x32_bf16 v[122:125], v[142:145], v[182:185], v[122:125]
	v_mfma_f32_16x16x32_bf16 v[110:113], v[134:137], v[204:207], v[110:113]
	v_mfma_f32_16x16x32_bf16 v[106:109], v[142:145], v[204:207], v[106:109]
	v_mfma_f32_16x16x32_bf16 v[94:97], v[134:137], v[212:215], v[94:97]
	v_mfma_f32_16x16x32_bf16 v[90:93], v[142:145], v[212:215], v[90:93]
	v_mfma_f32_16x16x32_bf16 v[78:81], v[134:137], v[220:223], v[78:81]
	v_mfma_f32_16x16x32_bf16 v[74:77], v[142:145], v[220:223], v[74:77]
	v_mfma_f32_16x16x32_bf16 v[118:121], v[146:149], v[178:181], v[118:121]
	v_mfma_f32_16x16x32_bf16 v[114:117], v[170:173], v[178:181], v[114:117]
	v_mfma_f32_16x16x32_bf16 v[102:105], v[146:149], v[200:203], v[102:105]
	v_mfma_f32_16x16x32_bf16 v[98:101], v[170:173], v[200:203], v[98:101]
	v_mfma_f32_16x16x32_bf16 v[86:89], v[146:149], v[208:211], v[86:89]
	v_mfma_f32_16x16x32_bf16 v[82:85], v[170:173], v[208:211], v[82:85]
	v_mfma_f32_16x16x32_bf16 v[70:73], v[146:149], v[216:219], v[70:73]
	v_mfma_f32_16x16x32_bf16 v[66:69], v[170:173], v[216:219], v[66:69]
	v_mfma_f32_16x16x32_bf16 v[118:121], v[150:153], v[182:185], v[118:121]
	v_mfma_f32_16x16x32_bf16 v[114:117], v[174:177], v[182:185], v[114:117]
	v_mfma_f32_16x16x32_bf16 v[102:105], v[150:153], v[204:207], v[102:105]
	v_mfma_f32_16x16x32_bf16 v[98:101], v[174:177], v[204:207], v[98:101]
	v_mfma_f32_16x16x32_bf16 v[86:89], v[150:153], v[212:215], v[86:89]
	v_mfma_f32_16x16x32_bf16 v[82:85], v[174:177], v[212:215], v[82:85]
	v_mfma_f32_16x16x32_bf16 v[70:73], v[150:153], v[220:223], v[70:73]
	v_mfma_f32_16x16x32_bf16 v[66:69], v[174:177], v[220:223], v[66:69]
	s_setprio 0
	s_barrier
; #define PG8_STAGE(bufoff, gbase, voff) do { _Pragma("unroll") for (int _i = 0; _i < 2; ++_i) \
;         __builtin_amdgcn_global_load_lds((const unsigned*)((const char*)(gbase) + (voff)[_i]), (LAS unsigned*)(lds + (bufoff) + ldsw + _i * 8192), 16, 0, 0); } while (0)
; #define PG8_LDA(dst, b, h) do { _Pragma("unroll") for (int m = 0; m < 4; ++m) _Pragma("unroll") for (int k = 0; k < 2; ++k) dst[m][k] = *(const LAS bf16x8*)(lds + PG8_SA(b, h) + aoff + m * 2048 + k * 1024); } while (0)
; #define PG8_MMA(ai, bj, At, Bt) do { __builtin_amdgcn_s_setprio(3); _Pragma("unroll") for (int m = 0; m < 4; ++m) _Pragma("unroll") for (int n = 0; n < 2; ++n) _Pragma("unroll") for (int k = 0; k < 2; ++k) \
;         acc[ai][bj][m][n] = __builtin_amdgcn_mfma_f32_16x16x32_bf16(Bt[n][k], At[m][k], acc[ai][bj][m][n], 0, 0, 0); __builtin_amdgcn_s_setprio(0); } while (0)
; #define PG8_WAIT_V(n) asm volatile("s_waitcnt vmcnt(" #n ")" ::: "memory")
; #define PG8_WAIT_L(n) asm volatile("s_waitcnt lgkmcnt(" #n ")" ::: "memory")
; #define PG8_BAR __builtin_amdgcn_s_barrier()
; #define PG8_SCHED __builtin_amdgcn_sched_barrier(0)
; template <class Epi, bool ALIGN_EPI>
; __device__ __forceinline__ void gemm_phase(LAS unsigned char* lds, const Gemm g, const StaticOrder& S, const Epi& E) {
;     ...
;             PG8_LDA(At, 1, 1); PG8_STAGE(PG8_SB(1, 0), b3, voffB); PG8_STAGE(PG8_SB(1, 1), b3 + hstep, voffB); PG8_STAGE(PG8_SA(1, 0), a3, voffA);
;             PG8_WAIT_V(8); PG8_WAIT_L(0); PG8_BAR; PG8_MMA(1, 0, At, B0); PG8_MMA(1, 1, At, B1); PG8_BAR; PG8_SCHED;
;         }
;         if constexpr (ALIGN_EPI) { if (wr == 0) PG8_BAR; }
	s_add_i32 s44, s62, s47
	v_lshl_add_u64 v[186:187], v[186:187], 0, s[12:13]
	s_mov_b32 m0, s44
	ds_read_b128 v[178:181], v198 offset:49152
	ds_read_b128 v[182:185], v198 offset:50176
	ds_read_b128 v[200:203], v198 offset:51200
	ds_read_b128 v[204:207], v198 offset:52224
	ds_read_b128 v[208:211], v198 offset:53248
	ds_read_b128 v[212:215], v198 offset:54272
	ds_read_b128 v[216:219], v198 offset:55296
	ds_read_b128 v[220:223], v198 offset:56320
	global_load_lds_dwordx4 v[186:187], off
	s_add_i32 m0, s44, 0x2000
	s_add_u32 s42, s42, 0x40080
	v_lshl_add_u64 v[186:187], v[224:225], 0, s[12:13]
	s_addc_u32 s43, s43, 0
	s_add_i32 s44, s63, s47
	global_load_lds_dwordx4 v[186:187], off
	v_lshl_add_u64 v[186:187], s[42:43], 0, v[156:157]
	s_mov_b32 m0, s44
	s_nop 0
	global_load_lds_dwordx4 v[186:187], off
	v_lshl_add_u64 v[186:187], s[42:43], 0, v[160:161]
	s_add_i32 m0, s44, 0x2000
	s_nop 0
	global_load_lds_dwordx4 v[186:187], off
	v_lshl_add_u64 v[186:187], v[226:227], 0, s[12:13]
	s_mov_b32 m0, s52
	s_nop 0
	global_load_lds_dwordx4 v[186:187], off
	v_lshl_add_u64 v[186:187], v[228:229], 0, s[12:13]
	s_mov_b32 m0, s53
	s_nop 0
	global_load_lds_dwordx4 v[186:187], off
	s_waitcnt vmcnt(8)
	s_waitcnt lgkmcnt(0)
	s_barrier
	s_setprio 3
	v_mfma_f32_16x16x32_bf16 v[62:65], v[130:133], v[178:181], v[62:65]
	v_mfma_f32_16x16x32_bf16 v[58:61], v[138:141], v[178:181], v[58:61]
	v_mfma_f32_16x16x32_bf16 v[46:49], v[130:133], v[200:203], v[46:49]
	v_mfma_f32_16x16x32_bf16 v[42:45], v[138:141], v[200:203], v[42:45]
	v_mfma_f32_16x16x32_bf16 v[30:33], v[130:133], v[208:211], v[30:33]
	v_mfma_f32_16x16x32_bf16 v[26:29], v[138:141], v[208:211], v[26:29]
	v_mfma_f32_16x16x32_bf16 v[14:17], v[130:133], v[216:219], v[14:17]
	v_mfma_f32_16x16x32_bf16 v[10:13], v[138:141], v[216:219], v[10:13]
	v_mfma_f32_16x16x32_bf16 v[62:65], v[134:137], v[182:185], v[62:65]
	v_mfma_f32_16x16x32_bf16 v[58:61], v[142:145], v[182:185], v[58:61]
	v_mfma_f32_16x16x32_bf16 v[46:49], v[134:137], v[204:207], v[46:49]
	v_mfma_f32_16x16x32_bf16 v[42:45], v[142:145], v[204:207], v[42:45]
	v_mfma_f32_16x16x32_bf16 v[30:33], v[134:137], v[212:215], v[30:33]
	v_mfma_f32_16x16x32_bf16 v[26:29], v[142:145], v[212:215], v[26:29]
	v_mfma_f32_16x16x32_bf16 v[14:17], v[134:137], v[220:223], v[14:17]
	v_mfma_f32_16x16x32_bf16 v[10:13], v[142:145], v[220:223], v[10:13]
	v_mfma_f32_16x16x32_bf16 v[54:57], v[146:149], v[178:181], v[54:57]
	v_mfma_f32_16x16x32_bf16 v[50:53], v[170:173], v[178:181], v[50:53]
	v_mfma_f32_16x16x32_bf16 v[38:41], v[146:149], v[200:203], v[38:41]
	v_mfma_f32_16x16x32_bf16 v[34:37], v[170:173], v[200:203], v[34:37]
	v_mfma_f32_16x16x32_bf16 v[22:25], v[146:149], v[208:211], v[22:25]
	v_mfma_f32_16x16x32_bf16 v[18:21], v[170:173], v[208:211], v[18:21]
	v_mfma_f32_16x16x32_bf16 v[6:9], v[146:149], v[216:219], v[6:9]
	v_mfma_f32_16x16x32_bf16 v[2:5], v[170:173], v[216:219], v[2:5]
	v_mfma_f32_16x16x32_bf16 v[54:57], v[150:153], v[182:185], v[54:57]
	v_mfma_f32_16x16x32_bf16 v[50:53], v[174:177], v[182:185], v[50:53]
	v_mfma_f32_16x16x32_bf16 v[38:41], v[150:153], v[204:207], v[38:41]
	v_mfma_f32_16x16x32_bf16 v[34:37], v[174:177], v[204:207], v[34:37]
	v_mfma_f32_16x16x32_bf16 v[22:25], v[150:153], v[212:215], v[22:25]
	v_mfma_f32_16x16x32_bf16 v[18:21], v[174:177], v[212:215], v[18:21]
	v_mfma_f32_16x16x32_bf16 v[6:9], v[150:153], v[220:223], v[6:9]
	v_mfma_f32_16x16x32_bf16 v[2:5], v[174:177], v[220:223], v[2:5]
	s_setprio 0
	s_barrier
	s_add_i32 s61, s61, 2
	s_add_u32 s40, s40, 0x100
	s_addc_u32 s41, s41, 0
	s_add_u32 s59, s59, 0x100
	s_addc_u32 s60, s60, 0
	s_cmp_gt_u32 s61, 13
	s_cbranch_scc0 .LBB0_1339
	s_and_b64 vcc, exec, s[14:15]
	s_cbranch_vccz .LBB0_1342
	s_barrier

; #define PG8_STAGE(bufoff, gbase, voff) do { _Pragma("unroll") for (int _i = 0; _i < 2; ++_i) \
;         __builtin_amdgcn_global_load_lds((const unsigned*)((const char*)(gbase) + (voff)[_i]), (LAS unsigned*)(lds + (bufoff) + ldsw + _i * 8192), 16, 0, 0); } while (0)
; #define PG8_LDA(dst, b, h) do { _Pragma("unroll") for (int m = 0; m < 4; ++m) _Pragma("unroll") for (int k = 0; k < 2; ++k) dst[m][k] = *(const LAS bf16x8*)(lds + PG8_SA(b, h) + aoff + m * 2048 + k * 1024); } while (0)
; #define PG8_LDB(dst, b, h) do { _Pragma("unroll") for (int n = 0; n < 2; ++n) _Pragma("unroll") for (int k = 0; k < 2; ++k) dst[n][k] = *(const LAS bf16x8*)(lds + PG8_SB(b, h) + boff + n * 2048 + k * 1024); } while (0)
; #define PG8_MMA(ai, bj, At, Bt) do { __builtin_amdgcn_s_setprio(3); _Pragma("unroll") for (int m = 0; m < 4; ++m) _Pragma("unroll") for (int n = 0; n < 2; ++n) _Pragma("unroll") for (int k = 0; k < 2; ++k) \
;         acc[ai][bj][m][n] = __builtin_amdgcn_mfma_f32_16x16x32_bf16(Bt[n][k], At[m][k], acc[ai][bj][m][n], 0, 0, 0); __builtin_amdgcn_s_setprio(0); } while (0)
; #define PG8_WAIT_V(n) asm volatile("s_waitcnt vmcnt(" #n ")" ::: "memory")
; #define PG8_WAIT_L(n) asm volatile("s_waitcnt lgkmcnt(" #n ")" ::: "memory")
; template <class Epi, bool ALIGN_EPI>
; __device__ __forceinline__ void gemm_phase(LAS unsigned char* lds, const Gemm g, const StaticOrder& S, const Epi& E) {
;     ...
;         const bool has_next = S.next(ui + 1, nxt);
;         const char* nA = has_next ? (const char*)g.A + (size_t)nxt.pm * tstep : cA; const char* nB = has_next ? (const char*)g.Bt + (size_t)nxt.pn * tstep : cB;
;         for (int t = 0; t < nt; t += 2) {
;             const bool last = (t == nt - 2);
;             const char* a1 = cA + (size_t)(t + 1) * kstep;
;             const char* a2 = last ? nA : cA + (size_t)(t + 2) * kstep; const char* b2 = last ? nB : cB + (size_t)(t + 2) * kstep;
;             const char* a3 = a2 + kstep; const char* b3 = b2 + kstep;
;             PG8_LDB(B0, 0, 0); PG8_LDB(B1, 0, 1); PG8_SCHED; PG8_LDA(At, 0, 0); PG8_STAGE(PG8_SA(1, 1), a1 + hstep, voffA);
;             PG8_WAIT_V(8); PG8_WAIT_L(0); PG8_BAR; PG8_MMA(0, 0, At, B0); PG8_MMA(0, 1, At, B1); PG8_BAR; PG8_SCHED;
;             PG8_LDA(At, 0, 1); PG8_STAGE(PG8_SB(0, 0), b2, voffB); PG8_STAGE(PG8_SB(0, 1), b2 + hstep, voffB); PG8_STAGE(PG8_SA(0, 0), a2, voffA);
.LBB0_1427:
	s_ashr_i32 s43, s42, 31
	s_lshl_b64 s[10:11], s[42:43], 19
	s_add_u32 s44, s34, s10
	s_addc_u32 s45, s35, s11
	s_and_b64 s[10:11], s[0:1], exec
	s_cselect_b32 s12, s45, s7
	s_cselect_b32 s13, s44, s6
	s_ashr_i32 s41, s40, 31
	s_lshl_b64 s[10:11], s[40:41], 19
	s_add_u32 s46, s22, s10
	s_addc_u32 s47, s23, s11
	s_and_b64 s[10:11], s[0:1], exec
	s_cselect_b32 s14, s47, s9
	s_cselect_b32 s15, s46, s8
	s_add_u32 s6, s6, 0x40080
	s_addc_u32 s7, s7, 0
	s_add_u32 s16, s8, 0x100
	s_addc_u32 s17, s9, 0
	s_mov_b32 s41, -2
	ds_read_b128 v[146:149], v168
	ds_read_b128 v[150:153], v168 offset:1024
	ds_read_b128 v[154:157], v168 offset:2048
	ds_read_b128 v[158:161], v168 offset:3072
	ds_read_b128 v[172:175], v169
	ds_read_b128 v[176:179], v169 offset:1024
	ds_read_b128 v[180:183], v169 offset:2048
	ds_read_b128 v[184:187], v169 offset:3072
	s_add_u32 s8, s6, 0xfffc0080
	s_addc_u32 s9, s7, -1
	s_cmp_eq_u32 s41, 12
	s_cselect_b32 s11, s12, s9
	s_cselect_b32 s10, s13, s8
	s_cselect_b32 s9, s14, s17
	s_cselect_b32 s8, s15, s16
	v_lshl_add_u64 v[220:221], s[6:7], 0, v[138:139]
	s_add_i32 m0, s50, 0xc000
	ds_read_b128 v[188:191], v170
	ds_read_b128 v[192:195], v170 offset:1024
	ds_read_b128 v[196:199], v170 offset:2048
	ds_read_b128 v[200:203], v170 offset:3072
	ds_read_b128 v[204:207], v170 offset:4096
	ds_read_b128 v[208:211], v170 offset:5120
	ds_read_b128 v[212:215], v170 offset:6144
	ds_read_b128 v[216:219], v170 offset:7168
	global_load_lds_dwordx4 v[220:221], off
	v_lshl_add_u64 v[220:221], s[6:7], 0, v[140:141]
	s_add_i32 m0, s50, 0xe000
	s_nop 0
	global_load_lds_dwordx4 v[220:221], off
	s_waitcnt vmcnt(8)
	s_waitcnt lgkmcnt(0)
	s_barrier
	s_setprio 3
	v_mfma_f32_16x16x32_bf16 v[126:129], v[146:149], v[188:191], 0
	v_mfma_f32_16x16x32_bf16 v[118:121], v[154:157], v[188:191], 0
	v_mfma_f32_16x16x32_bf16 v[110:113], v[146:149], v[196:199], 0
	v_mfma_f32_16x16x32_bf16 v[102:105], v[154:157], v[196:199], 0
	v_mfma_f32_16x16x32_bf16 v[94:97], v[146:149], v[204:207], 0
	v_mfma_f32_16x16x32_bf16 v[86:89], v[154:157], v[204:207], 0
	v_mfma_f32_16x16x32_bf16 v[78:81], v[146:149], v[212:215], 0
	v_mfma_f32_16x16x32_bf16 v[70:73], v[154:157], v[212:215], 0
	v_mfma_f32_16x16x32_bf16 v[126:129], v[150:153], v[192:195], v[126:129]
	v_mfma_f32_16x16x32_bf16 v[118:121], v[158:161], v[192:195], v[118:121]
	v_mfma_f32_16x16x32_bf16 v[110:113], v[150:153], v[200:203], v[110:113]
	v_mfma_f32_16x16x32_bf16 v[102:105], v[158:161], v[200:203], v[102:105]
	v_mfma_f32_16x16x32_bf16 v[94:97], v[150:153], v[208:211], v[94:97]
	v_mfma_f32_16x16x32_bf16 v[86:89], v[158:161], v[208:211], v[86:89]
	v_mfma_f32_16x16x32_bf16 v[78:81], v[150:153], v[216:219], v[78:81]
	v_mfma_f32_16x16x32_bf16 v[70:73], v[158:161], v[216:219], v[70:73]
	v_mfma_f32_16x16x32_bf16 v[122:125], v[172:175], v[188:191], 0
	v_mfma_f32_16x16x32_bf16 v[114:117], v[180:183], v[188:191], 0
	v_mfma_f32_16x16x32_bf16 v[106:109], v[172:175], v[196:199], 0
	v_mfma_f32_16x16x32_bf16 v[98:101], v[180:183], v[196:199], 0
	v_mfma_f32_16x16x32_bf16 v[90:93], v[172:175], v[204:207], 0
	v_mfma_f32_16x16x32_bf16 v[82:85], v[180:183], v[204:207], 0
	v_mfma_f32_16x16x32_bf16 v[74:77], v[172:175], v[212:215], 0
	v_mfma_f32_16x16x32_bf16 v[66:69], v[180:183], v[212:215], 0
	v_mfma_f32_16x16x32_bf16 v[122:125], v[176:179], v[192:195], v[122:125]
	v_mfma_f32_16x16x32_bf16 v[114:117], v[184:187], v[192:195], v[114:117]
	v_mfma_f32_16x16x32_bf16 v[106:109], v[176:179], v[200:203], v[106:109]
	v_mfma_f32_16x16x32_bf16 v[98:101], v[184:187], v[200:203], v[98:101]
	v_mfma_f32_16x16x32_bf16 v[90:93], v[176:179], v[208:211], v[90:93]
	v_mfma_f32_16x16x32_bf16 v[82:85], v[184:187], v[208:211], v[82:85]
	v_mfma_f32_16x16x32_bf16 v[74:77], v[176:179], v[216:219], v[74:77]
	v_mfma_f32_16x16x32_bf16 v[66:69], v[184:187], v[216:219], v[66:69]
	s_setprio 0
	s_barrier
	s_add_i32 s43, s58, s33
	v_lshl_add_u64 v[220:221], s[8:9], 0, v[132:133]
	s_mov_b32 m0, s43
	ds_read_b128 v[188:191], v170 offset:16384
	ds_read_b128 v[192:195], v170 offset:17408
	ds_read_b128 v[196:199], v170 offset:18432
	ds_read_b128 v[200:203], v170 offset:19456
	ds_read_b128 v[204:207], v170 offset:20480
	ds_read_b128 v[208:211], v170 offset:21504
	ds_read_b128 v[212:215], v170 offset:22528
	ds_read_b128 v[216:219], v170 offset:23552
	global_load_lds_dwordx4 v[220:221], off
	s_add_i32 m0, s43, 0x2000
	s_add_u32 s62, s8, 0x40000
	v_lshl_add_u64 v[222:223], s[8:9], 0, v[136:137]
	s_addc_u32 s63, s9, 0
	s_add_i32 s43, s59, s33
	global_load_lds_dwordx4 v[222:223], off
	v_lshl_add_u64 v[224:225], s[62:63], 0, v[132:133]
	s_mov_b32 m0, s43
	v_lshl_add_u64 v[226:227], s[10:11], 0, v[134:135]
	global_load_lds_dwordx4 v[224:225], off
	v_lshl_add_u64 v[224:225], s[62:63], 0, v[136:137]
	s_add_i32 m0, s43, 0x2000
	s_nop 0
	global_load_lds_dwordx4 v[224:225], off
	v_lshl_add_u64 v[224:225], s[10:11], 0, v[130:131]
	s_mov_b32 m0, s50
	s_nop 0
	global_load_lds_dwordx4 v[224:225], off
	s_mov_b32 m0, s51
	s_nop 0
	global_load_lds_dwordx4 v[226:227], off
	s_waitcnt vmcnt(8)
	s_waitcnt lgkmcnt(0)
	s_barrier
; #define PG8_STAGE(bufoff, gbase, voff) do { _Pragma("unroll") for (int _i = 0; _i < 2; ++_i) \
;         __builtin_amdgcn_global_load_lds((const unsigned*)((const char*)(gbase) + (voff)[_i]), (LAS unsigned*)(lds + (bufoff) + ldsw + _i * 8192), 16, 0, 0); } while (0)
; #define PG8_LDA(dst, b, h) do { _Pragma("unroll") for (int m = 0; m < 4; ++m) _Pragma("unroll") for (int k = 0; k < 2; ++k) dst[m][k] = *(const LAS bf16x8*)(lds + PG8_SA(b, h) + aoff + m * 2048 + k * 1024); } while (0)
; #define PG8_LDB(dst, b, h) do { _Pragma("unroll") for (int n = 0; n < 2; ++n) _Pragma("unroll") for (int k = 0; k < 2; ++k) dst[n][k] = *(const LAS bf16x8*)(lds + PG8_SB(b, h) + boff + n * 2048 + k * 1024); } while (0)
; #define PG8_MMA(ai, bj, At, Bt) do { __builtin_amdgcn_s_setprio(3); _Pragma("unroll") for (int m = 0; m < 4; ++m) _Pragma("unroll") for (int n = 0; n < 2; ++n) _Pragma("unroll") for (int k = 0; k < 2; ++k) \
;         acc[ai][bj][m][n] = __builtin_amdgcn_mfma_f32_16x16x32_bf16(Bt[n][k], At[m][k], acc[ai][bj][m][n], 0, 0, 0); __builtin_amdgcn_s_setprio(0); } while (0)
; #define PG8_WAIT_V(n) asm volatile("s_waitcnt vmcnt(" #n ")" ::: "memory")
; #define PG8_WAIT_L(n) asm volatile("s_waitcnt lgkmcnt(" #n ")" ::: "memory")
; #define PG8_BAR __builtin_amdgcn_s_barrier()
; #define PG8_SCHED __builtin_amdgcn_sched_barrier(0)
; template <class Epi, bool ALIGN_EPI>
; __device__ __forceinline__ void gemm_phase(LAS unsigned char* lds, const Gemm g, const StaticOrder& S, const Epi& E) {
;     ...
;             PG8_WAIT_V(8); PG8_WAIT_L(0); PG8_BAR; PG8_MMA(1, 0, At, B0); PG8_MMA(1, 1, At, B1); PG8_BAR; PG8_SCHED;
;             PG8_LDB(B0, 1, 0); PG8_LDB(B1, 1, 1); PG8_SCHED; PG8_LDA(At, 1, 0); PG8_STAGE(PG8_SA(0, 1), a2 + hstep, voffA);
;             PG8_WAIT_V(8); PG8_WAIT_L(0); PG8_BAR; PG8_MMA(0, 0, At, B0); PG8_MMA(0, 1, At, B1); PG8_BAR; PG8_SCHED;
	s_setprio 3
	v_mfma_f32_16x16x32_bf16 v[62:65], v[146:149], v[188:191], 0
	v_mfma_f32_16x16x32_bf16 v[54:57], v[154:157], v[188:191], 0
	v_mfma_f32_16x16x32_bf16 v[46:49], v[146:149], v[196:199], 0
	v_mfma_f32_16x16x32_bf16 v[38:41], v[154:157], v[196:199], 0
	v_mfma_f32_16x16x32_bf16 v[30:33], v[146:149], v[204:207], 0
	v_mfma_f32_16x16x32_bf16 v[22:25], v[154:157], v[204:207], 0
	v_mfma_f32_16x16x32_bf16 v[14:17], v[146:149], v[212:215], 0
	v_mfma_f32_16x16x32_bf16 v[6:9], v[154:157], v[212:215], 0
	v_mfma_f32_16x16x32_bf16 v[62:65], v[150:153], v[192:195], v[62:65]
	v_mfma_f32_16x16x32_bf16 v[54:57], v[158:161], v[192:195], v[54:57]
	v_mfma_f32_16x16x32_bf16 v[46:49], v[150:153], v[200:203], v[46:49]
	v_mfma_f32_16x16x32_bf16 v[38:41], v[158:161], v[200:203], v[38:41]
	v_mfma_f32_16x16x32_bf16 v[30:33], v[150:153], v[208:211], v[30:33]
	v_mfma_f32_16x16x32_bf16 v[22:25], v[158:161], v[208:211], v[22:25]
	v_mfma_f32_16x16x32_bf16 v[14:17], v[150:153], v[216:219], v[14:17]
	v_mfma_f32_16x16x32_bf16 v[6:9], v[158:161], v[216:219], v[6:9]
	v_mfma_f32_16x16x32_bf16 v[58:61], v[172:175], v[188:191], 0
	v_mfma_f32_16x16x32_bf16 v[50:53], v[180:183], v[188:191], 0
	v_mfma_f32_16x16x32_bf16 v[42:45], v[172:175], v[196:199], 0
	v_mfma_f32_16x16x32_bf16 v[34:37], v[180:183], v[196:199], 0
	v_mfma_f32_16x16x32_bf16 v[26:29], v[172:175], v[204:207], 0
	v_mfma_f32_16x16x32_bf16 v[18:21], v[180:183], v[204:207], 0
	v_mfma_f32_16x16x32_bf16 v[10:13], v[172:175], v[212:215], 0
	v_mfma_f32_16x16x32_bf16 v[2:5], v[180:183], v[212:215], 0
	v_mfma_f32_16x16x32_bf16 v[58:61], v[176:179], v[192:195], v[58:61]
	v_mfma_f32_16x16x32_bf16 v[50:53], v[184:187], v[192:195], v[50:53]
	v_mfma_f32_16x16x32_bf16 v[42:45], v[176:179], v[200:203], v[42:45]
	v_mfma_f32_16x16x32_bf16 v[34:37], v[184:187], v[200:203], v[34:37]
	v_mfma_f32_16x16x32_bf16 v[26:29], v[176:179], v[208:211], v[26:29]
	v_mfma_f32_16x16x32_bf16 v[18:21], v[184:187], v[208:211], v[18:21]
	v_mfma_f32_16x16x32_bf16 v[10:13], v[176:179], v[216:219], v[10:13]
	v_mfma_f32_16x16x32_bf16 v[2:5], v[184:187], v[216:219], v[2:5]
	s_setprio 0
	s_barrier
	s_add_i32 s43, 0, 0x18000
	s_add_i32 s62, 0, 0x1c000
	v_add_u32_e32 v158, s43, v166
	v_add_u32_e32 v184, s62, v166
	ds_read_b128 v[146:149], v158
	ds_read_b128 v[150:153], v158 offset:1024
	ds_read_b128 v[154:157], v158 offset:2048
	ds_read_b128 v[158:161], v158 offset:3072
	ds_read_b128 v[172:175], v184
	ds_read_b128 v[176:179], v184 offset:1024
	ds_read_b128 v[180:183], v184 offset:2048
	ds_read_b128 v[184:187], v184 offset:3072
	s_add_u32 s10, s10, 0x40000
	s_addc_u32 s11, s11, 0
	s_mov_b32 m0, s52
	v_lshl_add_u64 v[228:229], s[10:11], 0, v[130:131]
	ds_read_b128 v[188:191], v170 offset:32768
	ds_read_b128 v[192:195], v170 offset:33792
	ds_read_b128 v[196:199], v170 offset:34816
	ds_read_b128 v[200:203], v170 offset:35840
	ds_read_b128 v[204:207], v170 offset:36864
	ds_read_b128 v[208:211], v170 offset:37888
	ds_read_b128 v[212:215], v170 offset:38912
	ds_read_b128 v[216:219], v170 offset:39936
	global_load_lds_dwordx4 v[228:229], off
	v_lshl_add_u64 v[228:229], s[10:11], 0, v[134:135]
	s_mov_b32 m0, s53
	s_nop 0
	global_load_lds_dwordx4 v[228:229], off
	s_waitcnt vmcnt(8)
	s_waitcnt lgkmcnt(0)
	s_barrier
	s_setprio 3
	v_mfma_f32_16x16x32_bf16 v[126:129], v[146:149], v[188:191], v[126:129]
	v_mfma_f32_16x16x32_bf16 v[118:121], v[154:157], v[188:191], v[118:121]
	v_mfma_f32_16x16x32_bf16 v[110:113], v[146:149], v[196:199], v[110:113]
	v_mfma_f32_16x16x32_bf16 v[102:105], v[154:157], v[196:199], v[102:105]
	v_mfma_f32_16x16x32_bf16 v[94:97], v[146:149], v[204:207], v[94:97]
	v_mfma_f32_16x16x32_bf16 v[86:89], v[154:157], v[204:207], v[86:89]
	v_mfma_f32_16x16x32_bf16 v[78:81], v[146:149], v[212:215], v[78:81]
	v_mfma_f32_16x16x32_bf16 v[70:73], v[154:157], v[212:215], v[70:73]
	v_mfma_f32_16x16x32_bf16 v[126:129], v[150:153], v[192:195], v[126:129]
	v_mfma_f32_16x16x32_bf16 v[118:121], v[158:161], v[192:195], v[118:121]
	v_mfma_f32_16x16x32_bf16 v[110:113], v[150:153], v[200:203], v[110:113]
	v_mfma_f32_16x16x32_bf16 v[102:105], v[158:161], v[200:203], v[102:105]
	v_mfma_f32_16x16x32_bf16 v[94:97], v[150:153], v[208:211], v[94:97]
	v_mfma_f32_16x16x32_bf16 v[86:89], v[158:161], v[208:211], v[86:89]
	v_mfma_f32_16x16x32_bf16 v[78:81], v[150:153], v[216:219], v[78:81]
	v_mfma_f32_16x16x32_bf16 v[70:73], v[158:161], v[216:219], v[70:73]
	v_mfma_f32_16x16x32_bf16 v[122:125], v[172:175], v[188:191], v[122:125]
	v_mfma_f32_16x16x32_bf16 v[114:117], v[180:183], v[188:191], v[114:117]
	v_mfma_f32_16x16x32_bf16 v[106:109], v[172:175], v[196:199], v[106:109]
	v_mfma_f32_16x16x32_bf16 v[98:101], v[180:183], v[196:199], v[98:101]
	v_mfma_f32_16x16x32_bf16 v[90:93], v[172:175], v[204:207], v[90:93]
	v_mfma_f32_16x16x32_bf16 v[82:85], v[180:183], v[204:207], v[82:85]
	v_mfma_f32_16x16x32_bf16 v[74:77], v[172:175], v[212:215], v[74:77]
	v_mfma_f32_16x16x32_bf16 v[66:69], v[180:183], v[212:215], v[66:69]
	v_mfma_f32_16x16x32_bf16 v[122:125], v[176:179], v[192:195], v[122:125]
	v_mfma_f32_16x16x32_bf16 v[114:117], v[184:187], v[192:195], v[114:117]
	v_mfma_f32_16x16x32_bf16 v[106:109], v[176:179], v[200:203], v[106:109]
	v_mfma_f32_16x16x32_bf16 v[98:101], v[184:187], v[200:203], v[98:101]
	v_mfma_f32_16x16x32_bf16 v[90:93], v[176:179], v[208:211], v[90:93]
	v_mfma_f32_16x16x32_bf16 v[82:85], v[184:187], v[208:211], v[82:85]
	v_mfma_f32_16x16x32_bf16 v[74:77], v[176:179], v[216:219], v[74:77]
	v_mfma_f32_16x16x32_bf16 v[66:69], v[184:187], v[216:219], v[66:69]
	s_setprio 0
	s_barrier
; #define PG8_STAGE(bufoff, gbase, voff) do { _Pragma("unroll") for (int _i = 0; _i < 2; ++_i) \
;         __builtin_amdgcn_global_load_lds((const unsigned*)((const char*)(gbase) + (voff)[_i]), (LAS unsigned*)(lds + (bufoff) + ldsw + _i * 8192), 16, 0, 0); } while (0)
; #define PG8_LDA(dst, b, h) do { _Pragma("unroll") for (int m = 0; m < 4; ++m) _Pragma("unroll") for (int k = 0; k < 2; ++k) dst[m][k] = *(const LAS bf16x8*)(lds + PG8_SA(b, h) + aoff + m * 2048 + k * 1024); } while (0)
; #define PG8_LDB(dst, b, h) do { _Pragma("unroll") for (int n = 0; n < 2; ++n) _Pragma("unroll") for (int k = 0; k < 2; ++k) dst[n][k] = *(const LAS bf16x8*)(lds + PG8_SB(b, h) + boff + n * 2048 + k * 1024); } while (0)
; #define PG8_MMA(ai, bj, At, Bt) do { __builtin_amdgcn_s_setprio(3); _Pragma("unroll") for (int m = 0; m < 4; ++m) _Pragma("unroll") for (int n = 0; n < 2; ++n) _Pragma("unroll") for (int k = 0; k < 2; ++k) \
;         acc[ai][bj][m][n] = __builtin_amdgcn_mfma_f32_16x16x32_bf16(Bt[n][k], At[m][k], acc[ai][bj][m][n], 0, 0, 0); __builtin_amdgcn_s_setprio(0); } while (0)
; #define PG8_WAIT_V(n) asm volatile("s_waitcnt vmcnt(" #n ")" ::: "memory")
; #define PG8_BAR __builtin_amdgcn_s_barrier()
; template <class Epi, bool ALIGN_EPI>
; __device__ __forceinline__ void gemm_phase(LAS unsigned char* lds, const Gemm g, const StaticOrder& S, const Epi& E) {
;     ...
;             PG8_LDB(B0, 0, 0); PG8_LDB(B1, 0, 1); PG8_SCHED; PG8_LDA(At, 0, 0); PG8_STAGE(PG8_SA(1, 1), a1 + hstep, voffA);
;             PG8_WAIT_V(8); PG8_WAIT_L(0); PG8_BAR; PG8_MMA(0, 0, At, B0); PG8_MMA(0, 1, At, B1); PG8_BAR; PG8_SCHED;
;             PG8_LDA(At, 0, 1); PG8_STAGE(PG8_SB(0, 0), b2, voffB); PG8_STAGE(PG8_SB(0, 1), b2 + hstep, voffB); PG8_STAGE(PG8_SA(0, 0), a2, voffA);
;             PG8_WAIT_V(8); PG8_WAIT_L(0); PG8_BAR; PG8_MMA(1, 0, At, B0); PG8_MMA(1, 1, At, B1); PG8_BAR; PG8_SCHED;
;             PG8_LDB(B0, 1, 0); PG8_LDB(B1, 1, 1); PG8_SCHED; PG8_LDA(At, 1, 0); PG8_STAGE(PG8_SA(0, 1), a2 + hstep, voffA);
;             PG8_WAIT_V(8); PG8_WAIT_L(0); PG8_BAR; PG8_MMA(0, 0, At, B0); PG8_MMA(0, 1, At, B1); PG8_BAR; PG8_SCHED;
;             PG8_LDA(At, 1, 1); PG8_STAGE(PG8_SB(1, 0), b3, voffB); PG8_STAGE(PG8_SB(1, 1), b3 + hstep, voffB); PG8_STAGE(PG8_SA(1, 0), a3, voffA);
;             PG8_WAIT_V(8); PG8_WAIT_L(0); PG8_BAR; PG8_MMA(1, 0, At, B0); PG8_MMA(1, 1, At, B1); PG8_BAR; PG8_SCHED;
	s_add_i32 s10, s43, s33
	v_lshl_add_u64 v[220:221], v[220:221], 0, s[36:37]
	s_mov_b32 m0, s10
	ds_read_b128 v[188:191], v170 offset:49152
	ds_read_b128 v[192:195], v170 offset:50176
	ds_read_b128 v[196:199], v170 offset:51200
	ds_read_b128 v[200:203], v170 offset:52224
	ds_read_b128 v[204:207], v170 offset:53248
	ds_read_b128 v[208:211], v170 offset:54272
	ds_read_b128 v[212:215], v170 offset:55296
	ds_read_b128 v[216:219], v170 offset:56320
	global_load_lds_dwordx4 v[220:221], off
	s_add_i32 m0, s10, 0x2000
	s_add_u32 s8, s8, 0x40080
	v_lshl_add_u64 v[220:221], v[222:223], 0, s[36:37]
	s_addc_u32 s9, s9, 0
	s_add_i32 s10, s62, s33
	global_load_lds_dwordx4 v[220:221], off
	v_lshl_add_u64 v[220:221], s[8:9], 0, v[132:133]
	s_mov_b32 m0, s10
	s_nop 0
	global_load_lds_dwordx4 v[220:221], off
	v_lshl_add_u64 v[220:221], s[8:9], 0, v[136:137]
	s_add_i32 m0, s10, 0x2000
	s_nop 0
	global_load_lds_dwordx4 v[220:221], off
	v_lshl_add_u64 v[220:221], v[224:225], 0, s[36:37]
	s_mov_b32 m0, s56
	s_nop 0
	global_load_lds_dwordx4 v[220:221], off
	v_lshl_add_u64 v[220:221], v[226:227], 0, s[36:37]
	s_mov_b32 m0, s57
	s_nop 0
	global_load_lds_dwordx4 v[220:221], off
	s_waitcnt vmcnt(8)
	s_waitcnt lgkmcnt(0)
	s_barrier
	s_setprio 3
	v_mfma_f32_16x16x32_bf16 v[62:65], v[146:149], v[188:191], v[62:65]
	v_mfma_f32_16x16x32_bf16 v[54:57], v[154:157], v[188:191], v[54:57]
	v_mfma_f32_16x16x32_bf16 v[46:49], v[146:149], v[196:199], v[46:49]
	v_mfma_f32_16x16x32_bf16 v[38:41], v[154:157], v[196:199], v[38:41]
	v_mfma_f32_16x16x32_bf16 v[30:33], v[146:149], v[204:207], v[30:33]
	v_mfma_f32_16x16x32_bf16 v[22:25], v[154:157], v[204:207], v[22:25]
	v_mfma_f32_16x16x32_bf16 v[14:17], v[146:149], v[212:215], v[14:17]
	v_mfma_f32_16x16x32_bf16 v[6:9], v[154:157], v[212:215], v[6:9]
	v_mfma_f32_16x16x32_bf16 v[62:65], v[150:153], v[192:195], v[62:65]
	v_mfma_f32_16x16x32_bf16 v[54:57], v[158:161], v[192:195], v[54:57]
	v_mfma_f32_16x16x32_bf16 v[46:49], v[150:153], v[200:203], v[46:49]
	v_mfma_f32_16x16x32_bf16 v[38:41], v[158:161], v[200:203], v[38:41]
	v_mfma_f32_16x16x32_bf16 v[30:33], v[150:153], v[208:211], v[30:33]
	v_mfma_f32_16x16x32_bf16 v[22:25], v[158:161], v[208:211], v[22:25]
	v_mfma_f32_16x16x32_bf16 v[14:17], v[150:153], v[216:219], v[14:17]
	v_mfma_f32_16x16x32_bf16 v[6:9], v[158:161], v[216:219], v[6:9]
	v_mfma_f32_16x16x32_bf16 v[58:61], v[172:175], v[188:191], v[58:61]
	v_mfma_f32_16x16x32_bf16 v[50:53], v[180:183], v[188:191], v[50:53]
	v_mfma_f32_16x16x32_bf16 v[42:45], v[172:175], v[196:199], v[42:45]
	v_mfma_f32_16x16x32_bf16 v[34:37], v[180:183], v[196:199], v[34:37]
	v_mfma_f32_16x16x32_bf16 v[26:29], v[172:175], v[204:207], v[26:29]
	v_mfma_f32_16x16x32_bf16 v[18:21], v[180:183], v[204:207], v[18:21]
	v_mfma_f32_16x16x32_bf16 v[10:13], v[172:175], v[212:215], v[10:13]
	v_mfma_f32_16x16x32_bf16 v[2:5], v[180:183], v[212:215], v[2:5]
	v_mfma_f32_16x16x32_bf16 v[58:61], v[176:179], v[192:195], v[58:61]
	v_mfma_f32_16x16x32_bf16 v[50:53], v[184:187], v[192:195], v[50:53]
	v_mfma_f32_16x16x32_bf16 v[42:45], v[176:179], v[200:203], v[42:45]
	v_mfma_f32_16x16x32_bf16 v[34:37], v[184:187], v[200:203], v[34:37]
	v_mfma_f32_16x16x32_bf16 v[26:29], v[176:179], v[208:211], v[26:29]
	v_mfma_f32_16x16x32_bf16 v[18:21], v[184:187], v[208:211], v[18:21]
	v_mfma_f32_16x16x32_bf16 v[10:13], v[176:179], v[216:219], v[10:13]
	v_mfma_f32_16x16x32_bf16 v[2:5], v[184:187], v[216:219], v[2:5]
	s_setprio 0
	s_barrier
	s_add_i32 s41, s41, 2
	s_add_u32 s6, s6, 0x100
	s_addc_u32 s7, s7, 0
	s_add_u32 s16, s16, 0x100
	s_addc_u32 s17, s17, 0
.LBB0_1428:
	ds_read_b128 v[146:149], v168
	ds_read_b128 v[150:153], v168 offset:1024
	ds_read_b128 v[154:157], v168 offset:2048
	ds_read_b128 v[158:161], v168 offset:3072
	ds_read_b128 v[172:175], v169
	ds_read_b128 v[176:179], v169 offset:1024
	ds_read_b128 v[180:183], v169 offset:2048
	ds_read_b128 v[184:187], v169 offset:3072
	s_add_u32 s8, s6, 0xfffc0080
	s_addc_u32 s9, s7, -1
	s_cmp_eq_u32 s41, 12
	s_cselect_b32 s11, s12, s9
	s_cselect_b32 s10, s13, s8
	s_cselect_b32 s9, s14, s17
	s_cselect_b32 s8, s15, s16
	v_lshl_add_u64 v[220:221], s[6:7], 0, v[138:139]
	s_add_i32 m0, s50, 0xc000
	ds_read_b128 v[188:191], v170
	ds_read_b128 v[192:195], v170 offset:1024
	ds_read_b128 v[196:199], v170 offset:2048
	ds_read_b128 v[200:203], v170 offset:3072
	ds_read_b128 v[204:207], v170 offset:4096
	ds_read_b128 v[208:211], v170 offset:5120
	ds_read_b128 v[212:215], v170 offset:6144
	ds_read_b128 v[216:219], v170 offset:7168
	global_load_lds_dwordx4 v[220:221], off
	v_lshl_add_u64 v[220:221], s[6:7], 0, v[140:141]
	s_add_i32 m0, s50, 0xe000
	s_nop 0
	global_load_lds_dwordx4 v[220:221], off
	s_waitcnt vmcnt(8)
	s_waitcnt lgkmcnt(0)
	s_barrier
; #define PG8_STAGE(bufoff, gbase, voff) do { _Pragma("unroll") for (int _i = 0; _i < 2; ++_i) \
;         __builtin_amdgcn_global_load_lds((const unsigned*)((const char*)(gbase) + (voff)[_i]), (LAS unsigned*)(lds + (bufoff) + ldsw + _i * 8192), 16, 0, 0); } while (0)
; #define PG8_LDA(dst, b, h) do { _Pragma("unroll") for (int m = 0; m < 4; ++m) _Pragma("unroll") for (int k = 0; k < 2; ++k) dst[m][k] = *(const LAS bf16x8*)(lds + PG8_SA(b, h) + aoff + m * 2048 + k * 1024); } while (0)
; #define PG8_LDB(dst, b, h) do { _Pragma("unroll") for (int n = 0; n < 2; ++n) _Pragma("unroll") for (int k = 0; k < 2; ++k) dst[n][k] = *(const LAS bf16x8*)(lds + PG8_SB(b, h) + boff + n * 2048 + k * 1024); } while (0)
; #define PG8_MMA(ai, bj, At, Bt) do { __builtin_amdgcn_s_setprio(3); _Pragma("unroll") for (int m = 0; m < 4; ++m) _Pragma("unroll") for (int n = 0; n < 2; ++n) _Pragma("unroll") for (int k = 0; k < 2; ++k) \
;         acc[ai][bj][m][n] = __builtin_amdgcn_mfma_f32_16x16x32_bf16(Bt[n][k], At[m][k], acc[ai][bj][m][n], 0, 0, 0); __builtin_amdgcn_s_setprio(0); } while (0)
; #define PG8_WAIT_V(n) asm volatile("s_waitcnt vmcnt(" #n ")" ::: "memory")
; #define PG8_WAIT_L(n) asm volatile("s_waitcnt lgkmcnt(" #n ")" ::: "memory")
; #define PG8_BAR __builtin_amdgcn_s_barrier()
; #define PG8_SCHED __builtin_amdgcn_sched_barrier(0)
; template <class Epi, bool ALIGN_EPI>
; __device__ __forceinline__ void gemm_phase(LAS unsigned char* lds, const Gemm g, const StaticOrder& S, const Epi& E) {
;     ...
;             PG8_LDB(B0, 0, 0); PG8_LDB(B1, 0, 1); PG8_SCHED; PG8_LDA(At, 0, 0); PG8_STAGE(PG8_SA(1, 1), a1 + hstep, voffA);
;             PG8_WAIT_V(8); PG8_WAIT_L(0); PG8_BAR; PG8_MMA(0, 0, At, B0); PG8_MMA(0, 1, At, B1); PG8_BAR; PG8_SCHED;
;             PG8_LDA(At, 0, 1); PG8_STAGE(PG8_SB(0, 0), b2, voffB); PG8_STAGE(PG8_SB(0, 1), b2 + hstep, voffB); PG8_STAGE(PG8_SA(0, 0), a2, voffA);
;             PG8_WAIT_V(8); PG8_WAIT_L(0); PG8_BAR; PG8_MMA(1, 0, At, B0); PG8_MMA(1, 1, At, B1); PG8_BAR; PG8_SCHED;
	s_setprio 3
	v_mfma_f32_16x16x32_bf16 v[126:129], v[146:149], v[188:191], v[126:129]
	v_mfma_f32_16x16x32_bf16 v[118:121], v[154:157], v[188:191], v[118:121]
	v_mfma_f32_16x16x32_bf16 v[110:113], v[146:149], v[196:199], v[110:113]
	v_mfma_f32_16x16x32_bf16 v[102:105], v[154:157], v[196:199], v[102:105]
	v_mfma_f32_16x16x32_bf16 v[94:97], v[146:149], v[204:207], v[94:97]
	v_mfma_f32_16x16x32_bf16 v[86:89], v[154:157], v[204:207], v[86:89]
	v_mfma_f32_16x16x32_bf16 v[78:81], v[146:149], v[212:215], v[78:81]
	v_mfma_f32_16x16x32_bf16 v[70:73], v[154:157], v[212:215], v[70:73]
	v_mfma_f32_16x16x32_bf16 v[126:129], v[150:153], v[192:195], v[126:129]
	v_mfma_f32_16x16x32_bf16 v[118:121], v[158:161], v[192:195], v[118:121]
	v_mfma_f32_16x16x32_bf16 v[110:113], v[150:153], v[200:203], v[110:113]
	v_mfma_f32_16x16x32_bf16 v[102:105], v[158:161], v[200:203], v[102:105]
	v_mfma_f32_16x16x32_bf16 v[94:97], v[150:153], v[208:211], v[94:97]
	v_mfma_f32_16x16x32_bf16 v[86:89], v[158:161], v[208:211], v[86:89]
	v_mfma_f32_16x16x32_bf16 v[78:81], v[150:153], v[216:219], v[78:81]
	v_mfma_f32_16x16x32_bf16 v[70:73], v[158:161], v[216:219], v[70:73]
	v_mfma_f32_16x16x32_bf16 v[122:125], v[172:175], v[188:191], v[122:125]
	v_mfma_f32_16x16x32_bf16 v[114:117], v[180:183], v[188:191], v[114:117]
	v_mfma_f32_16x16x32_bf16 v[106:109], v[172:175], v[196:199], v[106:109]
	v_mfma_f32_16x16x32_bf16 v[98:101], v[180:183], v[196:199], v[98:101]
	v_mfma_f32_16x16x32_bf16 v[90:93], v[172:175], v[204:207], v[90:93]
	v_mfma_f32_16x16x32_bf16 v[82:85], v[180:183], v[204:207], v[82:85]
	v_mfma_f32_16x16x32_bf16 v[74:77], v[172:175], v[212:215], v[74:77]
	v_mfma_f32_16x16x32_bf16 v[66:69], v[180:183], v[212:215], v[66:69]
	v_mfma_f32_16x16x32_bf16 v[122:125], v[176:179], v[192:195], v[122:125]
	v_mfma_f32_16x16x32_bf16 v[114:117], v[184:187], v[192:195], v[114:117]
	v_mfma_f32_16x16x32_bf16 v[106:109], v[176:179], v[200:203], v[106:109]
	v_mfma_f32_16x16x32_bf16 v[98:101], v[184:187], v[200:203], v[98:101]
	v_mfma_f32_16x16x32_bf16 v[90:93], v[176:179], v[208:211], v[90:93]
	v_mfma_f32_16x16x32_bf16 v[82:85], v[184:187], v[208:211], v[82:85]
	v_mfma_f32_16x16x32_bf16 v[74:77], v[176:179], v[216:219], v[74:77]
	v_mfma_f32_16x16x32_bf16 v[66:69], v[184:187], v[216:219], v[66:69]
	s_setprio 0
	s_barrier
	s_add_i32 s43, s58, s33
	v_lshl_add_u64 v[220:221], s[8:9], 0, v[132:133]
	s_mov_b32 m0, s43
	ds_read_b128 v[188:191], v170 offset:16384
	ds_read_b128 v[192:195], v170 offset:17408
	ds_read_b128 v[196:199], v170 offset:18432
	ds_read_b128 v[200:203], v170 offset:19456
	ds_read_b128 v[204:207], v170 offset:20480
	ds_read_b128 v[208:211], v170 offset:21504
	ds_read_b128 v[212:215], v170 offset:22528
	ds_read_b128 v[216:219], v170 offset:23552
	global_load_lds_dwordx4 v[220:221], off
	s_add_i32 m0, s43, 0x2000
	s_add_u32 s62, s8, 0x40000
	v_lshl_add_u64 v[222:223], s[8:9], 0, v[136:137]
	s_addc_u32 s63, s9, 0
	s_add_i32 s43, s59, s33
	global_load_lds_dwordx4 v[222:223], off
	v_lshl_add_u64 v[224:225], s[62:63], 0, v[132:133]
	s_mov_b32 m0, s43
	v_lshl_add_u64 v[226:227], s[10:11], 0, v[134:135]
	global_load_lds_dwordx4 v[224:225], off
	v_lshl_add_u64 v[224:225], s[62:63], 0, v[136:137]
	s_add_i32 m0, s43, 0x2000
	s_nop 0
	global_load_lds_dwordx4 v[224:225], off
	v_lshl_add_u64 v[224:225], s[10:11], 0, v[130:131]
	s_mov_b32 m0, s50
	s_nop 0
	global_load_lds_dwordx4 v[224:225], off
	s_mov_b32 m0, s51
	s_nop 0
	global_load_lds_dwordx4 v[226:227], off
	s_waitcnt vmcnt(8)
	s_waitcnt lgkmcnt(0)
	s_barrier
	s_setprio 3
	v_mfma_f32_16x16x32_bf16 v[62:65], v[146:149], v[188:191], v[62:65]
	v_mfma_f32_16x16x32_bf16 v[54:57], v[154:157], v[188:191], v[54:57]
	v_mfma_f32_16x16x32_bf16 v[46:49], v[146:149], v[196:199], v[46:49]
	v_mfma_f32_16x16x32_bf16 v[38:41], v[154:157], v[196:199], v[38:41]
	v_mfma_f32_16x16x32_bf16 v[30:33], v[146:149], v[204:207], v[30:33]
	v_mfma_f32_16x16x32_bf16 v[22:25], v[154:157], v[204:207], v[22:25]
	v_mfma_f32_16x16x32_bf16 v[14:17], v[146:149], v[212:215], v[14:17]
	v_mfma_f32_16x16x32_bf16 v[6:9], v[154:157], v[212:215], v[6:9]
	v_mfma_f32_16x16x32_bf16 v[62:65], v[150:153], v[192:195], v[62:65]
	v_mfma_f32_16x16x32_bf16 v[54:57], v[158:161], v[192:195], v[54:57]
	v_mfma_f32_16x16x32_bf16 v[46:49], v[150:153], v[200:203], v[46:49]
	v_mfma_f32_16x16x32_bf16 v[38:41], v[158:161], v[200:203], v[38:41]
	v_mfma_f32_16x16x32_bf16 v[30:33], v[150:153], v[208:211], v[30:33]
	v_mfma_f32_16x16x32_bf16 v[22:25], v[158:161], v[208:211], v[22:25]
	v_mfma_f32_16x16x32_bf16 v[14:17], v[150:153], v[216:219], v[14:17]
	v_mfma_f32_16x16x32_bf16 v[6:9], v[158:161], v[216:219], v[6:9]
	v_mfma_f32_16x16x32_bf16 v[58:61], v[172:175], v[188:191], v[58:61]
	v_mfma_f32_16x16x32_bf16 v[50:53], v[180:183], v[188:191], v[50:53]
	v_mfma_f32_16x16x32_bf16 v[42:45], v[172:175], v[196:199], v[42:45]
	v_mfma_f32_16x16x32_bf16 v[34:37], v[180:183], v[196:199], v[34:37]
	v_mfma_f32_16x16x32_bf16 v[26:29], v[172:175], v[204:207], v[26:29]
	v_mfma_f32_16x16x32_bf16 v[18:21], v[180:183], v[204:207], v[18:21]
	v_mfma_f32_16x16x32_bf16 v[10:13], v[172:175], v[212:215], v[10:13]
	v_mfma_f32_16x16x32_bf16 v[2:5], v[180:183], v[212:215], v[2:5]
	v_mfma_f32_16x16x32_bf16 v[58:61], v[176:179], v[192:195], v[58:61]
	v_mfma_f32_16x16x32_bf16 v[50:53], v[184:187], v[192:195], v[50:53]
	v_mfma_f32_16x16x32_bf16 v[42:45], v[176:179], v[200:203], v[42:45]
	v_mfma_f32_16x16x32_bf16 v[34:37], v[184:187], v[200:203], v[34:37]
	v_mfma_f32_16x16x32_bf16 v[26:29], v[176:179], v[208:211], v[26:29]
	v_mfma_f32_16x16x32_bf16 v[18:21], v[184:187], v[208:211], v[18:21]
	v_mfma_f32_16x16x32_bf16 v[10:13], v[176:179], v[216:219], v[10:13]
	v_mfma_f32_16x16x32_bf16 v[2:5], v[184:187], v[216:219], v[2:5]
	s_setprio 0
	s_barrier
; #define PG8_STAGE(bufoff, gbase, voff) do { _Pragma("unroll") for (int _i = 0; _i < 2; ++_i) \
;         __builtin_amdgcn_global_load_lds((const unsigned*)((const char*)(gbase) + (voff)[_i]), (LAS unsigned*)(lds + (bufoff) + ldsw + _i * 8192), 16, 0, 0); } while (0)
; #define PG8_LDA(dst, b, h) do { _Pragma("unroll") for (int m = 0; m < 4; ++m) _Pragma("unroll") for (int k = 0; k < 2; ++k) dst[m][k] = *(const LAS bf16x8*)(lds + PG8_SA(b, h) + aoff + m * 2048 + k * 1024); } while (0)
; #define PG8_LDB(dst, b, h) do { _Pragma("unroll") for (int n = 0; n < 2; ++n) _Pragma("unroll") for (int k = 0; k < 2; ++k) dst[n][k] = *(const LAS bf16x8*)(lds + PG8_SB(b, h) + boff + n * 2048 + k * 1024); } while (0)
; #define PG8_MMA(ai, bj, At, Bt) do { __builtin_amdgcn_s_setprio(3); _Pragma("unroll") for (int m = 0; m < 4; ++m) _Pragma("unroll") for (int n = 0; n < 2; ++n) _Pragma("unroll") for (int k = 0; k < 2; ++k) \
;         acc[ai][bj][m][n] = __builtin_amdgcn_mfma_f32_16x16x32_bf16(Bt[n][k], At[m][k], acc[ai][bj][m][n], 0, 0, 0); __builtin_amdgcn_s_setprio(0); } while (0)
; #define PG8_WAIT_V(n) asm volatile("s_waitcnt vmcnt(" #n ")" ::: "memory")
; #define PG8_WAIT_L(n) asm volatile("s_waitcnt lgkmcnt(" #n ")" ::: "memory")
; #define PG8_BAR __builtin_amdgcn_s_barrier()
; #define PG8_SCHED __builtin_amdgcn_sched_barrier(0)
; template <class Epi, bool ALIGN_EPI>
; __device__ __forceinline__ void gemm_phase(LAS unsigned char* lds, const Gemm g, const StaticOrder& S, const Epi& E) {
;     ...
;             PG8_LDB(B0, 1, 0); PG8_LDB(B1, 1, 1); PG8_SCHED; PG8_LDA(At, 1, 0); PG8_STAGE(PG8_SA(0, 1), a2 + hstep, voffA);
;             PG8_WAIT_V(8); PG8_WAIT_L(0); PG8_BAR; PG8_MMA(0, 0, At, B0); PG8_MMA(0, 1, At, B1); PG8_BAR; PG8_SCHED;
	s_add_i32 s43, 0, 0x18000
	s_add_i32 s62, 0, 0x1c000
	v_add_u32_e32 v158, s43, v166
	v_add_u32_e32 v184, s62, v166
	ds_read_b128 v[146:149], v158
	ds_read_b128 v[150:153], v158 offset:1024
	ds_read_b128 v[154:157], v158 offset:2048
	ds_read_b128 v[158:161], v158 offset:3072
	ds_read_b128 v[172:175], v184
	ds_read_b128 v[176:179], v184 offset:1024
	ds_read_b128 v[180:183], v184 offset:2048
	ds_read_b128 v[184:187], v184 offset:3072
	s_add_u32 s10, s10, 0x40000
	s_addc_u32 s11, s11, 0
	s_mov_b32 m0, s52
	v_lshl_add_u64 v[228:229], s[10:11], 0, v[130:131]
	ds_read_b128 v[188:191], v170 offset:32768
	ds_read_b128 v[192:195], v170 offset:33792
	ds_read_b128 v[196:199], v170 offset:34816
	ds_read_b128 v[200:203], v170 offset:35840
	ds_read_b128 v[204:207], v170 offset:36864
	ds_read_b128 v[208:211], v170 offset:37888
	ds_read_b128 v[212:215], v170 offset:38912
	ds_read_b128 v[216:219], v170 offset:39936
	global_load_lds_dwordx4 v[228:229], off
	v_lshl_add_u64 v[228:229], s[10:11], 0, v[134:135]
	s_mov_b32 m0, s53
	s_nop 0
	global_load_lds_dwordx4 v[228:229], off
	s_waitcnt vmcnt(8)
	s_waitcnt lgkmcnt(0)
	s_barrier
	s_setprio 3
	v_mfma_f32_16x16x32_bf16 v[126:129], v[146:149], v[188:191], v[126:129]
	v_mfma_f32_16x16x32_bf16 v[118:121], v[154:157], v[188:191], v[118:121]
	v_mfma_f32_16x16x32_bf16 v[110:113], v[146:149], v[196:199], v[110:113]
	v_mfma_f32_16x16x32_bf16 v[102:105], v[154:157], v[196:199], v[102:105]
	v_mfma_f32_16x16x32_bf16 v[94:97], v[146:149], v[204:207], v[94:97]
	v_mfma_f32_16x16x32_bf16 v[86:89], v[154:157], v[204:207], v[86:89]
	v_mfma_f32_16x16x32_bf16 v[78:81], v[146:149], v[212:215], v[78:81]
	v_mfma_f32_16x16x32_bf16 v[70:73], v[154:157], v[212:215], v[70:73]
	v_mfma_f32_16x16x32_bf16 v[126:129], v[150:153], v[192:195], v[126:129]
	v_mfma_f32_16x16x32_bf16 v[118:121], v[158:161], v[192:195], v[118:121]
	v_mfma_f32_16x16x32_bf16 v[110:113], v[150:153], v[200:203], v[110:113]
	v_mfma_f32_16x16x32_bf16 v[102:105], v[158:161], v[200:203], v[102:105]
	v_mfma_f32_16x16x32_bf16 v[94:97], v[150:153], v[208:211], v[94:97]
	v_mfma_f32_16x16x32_bf16 v[86:89], v[158:161], v[208:211], v[86:89]
	v_mfma_f32_16x16x32_bf16 v[78:81], v[150:153], v[216:219], v[78:81]
	v_mfma_f32_16x16x32_bf16 v[70:73], v[158:161], v[216:219], v[70:73]
	v_mfma_f32_16x16x32_bf16 v[122:125], v[172:175], v[188:191], v[122:125]
	v_mfma_f32_16x16x32_bf16 v[114:117], v[180:183], v[188:191], v[114:117]
	v_mfma_f32_16x16x32_bf16 v[106:109], v[172:175], v[196:199], v[106:109]
	v_mfma_f32_16x16x32_bf16 v[98:101], v[180:183], v[196:199], v[98:101]
	v_mfma_f32_16x16x32_bf16 v[90:93], v[172:175], v[204:207], v[90:93]
	v_mfma_f32_16x16x32_bf16 v[82:85], v[180:183], v[204:207], v[82:85]
	v_mfma_f32_16x16x32_bf16 v[74:77], v[172:175], v[212:215], v[74:77]
	v_mfma_f32_16x16x32_bf16 v[66:69], v[180:183], v[212:215], v[66:69]
	v_mfma_f32_16x16x32_bf16 v[122:125], v[176:179], v[192:195], v[122:125]
	v_mfma_f32_16x16x32_bf16 v[114:117], v[184:187], v[192:195], v[114:117]
	v_mfma_f32_16x16x32_bf16 v[106:109], v[176:179], v[200:203], v[106:109]
	v_mfma_f32_16x16x32_bf16 v[98:101], v[184:187], v[200:203], v[98:101]
	v_mfma_f32_16x16x32_bf16 v[90:93], v[176:179], v[208:211], v[90:93]
	v_mfma_f32_16x16x32_bf16 v[82:85], v[184:187], v[208:211], v[82:85]
	v_mfma_f32_16x16x32_bf16 v[74:77], v[176:179], v[216:219], v[74:77]
	v_mfma_f32_16x16x32_bf16 v[66:69], v[184:187], v[216:219], v[66:69]
	s_setprio 0
	s_barrier
; #define PG8_STAGE(bufoff, gbase, voff) do { _Pragma("unroll") for (int _i = 0; _i < 2; ++_i) \
;         __builtin_amdgcn_global_load_lds((const unsigned*)((const char*)(gbase) + (voff)[_i]), (LAS unsigned*)(lds + (bufoff) + ldsw + _i * 8192), 16, 0, 0); } while (0)
; #define PG8_LDA(dst, b, h) do { _Pragma("unroll") for (int m = 0; m < 4; ++m) _Pragma("unroll") for (int k = 0; k < 2; ++k) dst[m][k] = *(const LAS bf16x8*)(lds + PG8_SA(b, h) + aoff + m * 2048 + k * 1024); } while (0)
; #define PG8_MMA(ai, bj, At, Bt) do { __builtin_amdgcn_s_setprio(3); _Pragma("unroll") for (int m = 0; m < 4; ++m) _Pragma("unroll") for (int n = 0; n < 2; ++n) _Pragma("unroll") for (int k = 0; k < 2; ++k) \
;         acc[ai][bj][m][n] = __builtin_amdgcn_mfma_f32_16x16x32_bf16(Bt[n][k], At[m][k], acc[ai][bj][m][n], 0, 0, 0); __builtin_amdgcn_s_setprio(0); } while (0)
; #define PG8_WAIT_V(n) asm volatile("s_waitcnt vmcnt(" #n ")" ::: "memory")
; #define PG8_WAIT_L(n) asm volatile("s_waitcnt lgkmcnt(" #n ")" ::: "memory")
; #define PG8_BAR __builtin_amdgcn_s_barrier()
; #define PG8_SCHED __builtin_amdgcn_sched_barrier(0)
; template <class Epi, bool ALIGN_EPI>
; __device__ __forceinline__ void gemm_phase(LAS unsigned char* lds, const Gemm g, const StaticOrder& S, const Epi& E) {
;     ...
;             PG8_LDA(At, 1, 1); PG8_STAGE(PG8_SB(1, 0), b3, voffB); PG8_STAGE(PG8_SB(1, 1), b3 + hstep, voffB); PG8_STAGE(PG8_SA(1, 0), a3, voffA);
;             PG8_WAIT_V(8); PG8_WAIT_L(0); PG8_BAR; PG8_MMA(1, 0, At, B0); PG8_MMA(1, 1, At, B1); PG8_BAR; PG8_SCHED;
;         }
	s_add_i32 s10, s43, s33
	v_lshl_add_u64 v[220:221], v[220:221], 0, s[36:37]
	s_mov_b32 m0, s10
	ds_read_b128 v[188:191], v170 offset:49152
	ds_read_b128 v[192:195], v170 offset:50176
	ds_read_b128 v[196:199], v170 offset:51200
	ds_read_b128 v[200:203], v170 offset:52224
	ds_read_b128 v[204:207], v170 offset:53248
	ds_read_b128 v[208:211], v170 offset:54272
	ds_read_b128 v[212:215], v170 offset:55296
	ds_read_b128 v[216:219], v170 offset:56320
	global_load_lds_dwordx4 v[220:221], off
	s_add_i32 m0, s10, 0x2000
	s_add_u32 s8, s8, 0x40080
	v_lshl_add_u64 v[220:221], v[222:223], 0, s[36:37]
	s_addc_u32 s9, s9, 0
	s_add_i32 s10, s62, s33
	global_load_lds_dwordx4 v[220:221], off
	v_lshl_add_u64 v[220:221], s[8:9], 0, v[132:133]
	s_mov_b32 m0, s10
	s_nop 0
	global_load_lds_dwordx4 v[220:221], off
	v_lshl_add_u64 v[220:221], s[8:9], 0, v[136:137]
	s_add_i32 m0, s10, 0x2000
	s_nop 0
	global_load_lds_dwordx4 v[220:221], off
	v_lshl_add_u64 v[220:221], v[224:225], 0, s[36:37]
	s_mov_b32 m0, s56
	s_nop 0
	global_load_lds_dwordx4 v[220:221], off
	v_lshl_add_u64 v[220:221], v[226:227], 0, s[36:37]
	s_mov_b32 m0, s57
	s_nop 0
	global_load_lds_dwordx4 v[220:221], off
	s_waitcnt vmcnt(8)
	s_waitcnt lgkmcnt(0)
	s_barrier
	s_setprio 3
	v_mfma_f32_16x16x32_bf16 v[62:65], v[146:149], v[188:191], v[62:65]
	v_mfma_f32_16x16x32_bf16 v[54:57], v[154:157], v[188:191], v[54:57]
	v_mfma_f32_16x16x32_bf16 v[46:49], v[146:149], v[196:199], v[46:49]
	v_mfma_f32_16x16x32_bf16 v[38:41], v[154:157], v[196:199], v[38:41]
	v_mfma_f32_16x16x32_bf16 v[30:33], v[146:149], v[204:207], v[30:33]
	v_mfma_f32_16x16x32_bf16 v[22:25], v[154:157], v[204:207], v[22:25]
	v_mfma_f32_16x16x32_bf16 v[14:17], v[146:149], v[212:215], v[14:17]
	v_mfma_f32_16x16x32_bf16 v[6:9], v[154:157], v[212:215], v[6:9]
	v_mfma_f32_16x16x32_bf16 v[62:65], v[150:153], v[192:195], v[62:65]
	v_mfma_f32_16x16x32_bf16 v[54:57], v[158:161], v[192:195], v[54:57]
	v_mfma_f32_16x16x32_bf16 v[46:49], v[150:153], v[200:203], v[46:49]
	v_mfma_f32_16x16x32_bf16 v[38:41], v[158:161], v[200:203], v[38:41]
	v_mfma_f32_16x16x32_bf16 v[30:33], v[150:153], v[208:211], v[30:33]
	v_mfma_f32_16x16x32_bf16 v[22:25], v[158:161], v[208:211], v[22:25]
	v_mfma_f32_16x16x32_bf16 v[14:17], v[150:153], v[216:219], v[14:17]
	v_mfma_f32_16x16x32_bf16 v[6:9], v[158:161], v[216:219], v[6:9]
	v_mfma_f32_16x16x32_bf16 v[58:61], v[172:175], v[188:191], v[58:61]
	v_mfma_f32_16x16x32_bf16 v[50:53], v[180:183], v[188:191], v[50:53]
	v_mfma_f32_16x16x32_bf16 v[42:45], v[172:175], v[196:199], v[42:45]
	v_mfma_f32_16x16x32_bf16 v[34:37], v[180:183], v[196:199], v[34:37]
	v_mfma_f32_16x16x32_bf16 v[26:29], v[172:175], v[204:207], v[26:29]
	v_mfma_f32_16x16x32_bf16 v[18:21], v[180:183], v[204:207], v[18:21]
	v_mfma_f32_16x16x32_bf16 v[10:13], v[172:175], v[212:215], v[10:13]
	v_mfma_f32_16x16x32_bf16 v[2:5], v[180:183], v[212:215], v[2:5]
	v_mfma_f32_16x16x32_bf16 v[58:61], v[176:179], v[192:195], v[58:61]
	v_mfma_f32_16x16x32_bf16 v[50:53], v[184:187], v[192:195], v[50:53]
	v_mfma_f32_16x16x32_bf16 v[42:45], v[176:179], v[200:203], v[42:45]
	v_mfma_f32_16x16x32_bf16 v[34:37], v[184:187], v[200:203], v[34:37]
	v_mfma_f32_16x16x32_bf16 v[26:29], v[176:179], v[208:211], v[26:29]
	v_mfma_f32_16x16x32_bf16 v[18:21], v[184:187], v[208:211], v[18:21]
	v_mfma_f32_16x16x32_bf16 v[10:13], v[176:179], v[216:219], v[10:13]
	v_mfma_f32_16x16x32_bf16 v[2:5], v[184:187], v[216:219], v[2:5]
	s_setprio 0
	s_barrier
	s_add_i32 s41, s41, 2
	s_add_u32 s6, s6, 0x100
	s_addc_u32 s7, s7, 0
	s_add_u32 s16, s16, 0x100
	s_addc_u32 s17, s17, 0
	s_cmp_gt_u32 s41, 13
	s_cbranch_scc0 .LBB0_1428
	s_and_b64 vcc, exec, s[38:39]
	s_cbranch_vccz .LBB0_1431
	s_barrier

; #define PG8_STAGE(bufoff, gbase, voff) do { _Pragma("unroll") for (int _i = 0; _i < 2; ++_i) \
;         __builtin_amdgcn_global_load_lds((const unsigned*)((const char*)(gbase) + (voff)[_i]), (LAS unsigned*)(lds + (bufoff) + ldsw + _i * 8192), 16, 0, 0); } while (0)
; #define PG8_LDA(dst, b, h) do { _Pragma("unroll") for (int m = 0; m < 4; ++m) _Pragma("unroll") for (int k = 0; k < 2; ++k) dst[m][k] = *(const LAS bf16x8*)(lds + PG8_SA(b, h) + aoff + m * 2048 + k * 1024); } while (0)
; #define PG8_LDB(dst, b, h) do { _Pragma("unroll") for (int n = 0; n < 2; ++n) _Pragma("unroll") for (int k = 0; k < 2; ++k) dst[n][k] = *(const LAS bf16x8*)(lds + PG8_SB(b, h) + boff + n * 2048 + k * 1024); } while (0)
; #define PG8_MMA(ai, bj, At, Bt) do { __builtin_amdgcn_s_setprio(3); _Pragma("unroll") for (int m = 0; m < 4; ++m) _Pragma("unroll") for (int n = 0; n < 2; ++n) _Pragma("unroll") for (int k = 0; k < 2; ++k) \
;         acc[ai][bj][m][n] = __builtin_amdgcn_mfma_f32_16x16x32_bf16(Bt[n][k], At[m][k], acc[ai][bj][m][n], 0, 0, 0); __builtin_amdgcn_s_setprio(0); } while (0)
; #define PG8_WAIT_V(n) asm volatile("s_waitcnt vmcnt(" #n ")" ::: "memory")
; #define PG8_BAR __builtin_amdgcn_s_barrier()
; template <class Epi, bool ALIGN_EPI>
; __device__ __forceinline__ void gemm_phase(LAS unsigned char* lds, const Gemm g, const StaticOrder& S, const Epi& E) {
;     ...
;         const char* nA = has_next ? (const char*)g.A + (size_t)nxt.pm * tstep : cA; const char* nB = has_next ? (const char*)g.Bt + (size_t)nxt.pn * tstep : cB;
;         for (int t = 0; t < nt; t += 2) {
;             const bool last = (t == nt - 2);
;             const char* a1 = cA + (size_t)(t + 1) * kstep;
;             const char* a2 = last ? nA : cA + (size_t)(t + 2) * kstep; const char* b2 = last ? nB : cB + (size_t)(t + 2) * kstep;
;             const char* a3 = a2 + kstep; const char* b3 = b2 + kstep;
;             PG8_LDB(B0, 0, 0); PG8_LDB(B1, 0, 1); PG8_SCHED; PG8_LDA(At, 0, 0); PG8_STAGE(PG8_SA(1, 1), a1 + hstep, voffA);
;             PG8_WAIT_V(8); PG8_WAIT_L(0); PG8_BAR; PG8_MMA(0, 0, At, B0); PG8_MMA(0, 1, At, B1); PG8_BAR; PG8_SCHED;
;             PG8_LDA(At, 0, 1); PG8_STAGE(PG8_SB(0, 0), b2, voffB); PG8_STAGE(PG8_SB(0, 1), b2 + hstep, voffB); PG8_STAGE(PG8_SA(0, 0), a2, voffA);
;             PG8_WAIT_V(8); PG8_WAIT_L(0); PG8_BAR; PG8_MMA(1, 0, At, B0); PG8_MMA(1, 1, At, B1); PG8_BAR; PG8_SCHED;
.LBB0_1512:
	s_add_u32 s14, s14, 0xb0080
	s_addc_u32 s15, s15, 0
	s_add_u32 s43, s16, 0x100
	s_addc_u32 s44, s17, 0
	s_mov_b32 s45, -2
	ds_read_b128 v[144:147], v158
	ds_read_b128 v[148:151], v158 offset:1024
	ds_read_b128 v[162:165], v158 offset:2048
	ds_read_b128 v[166:169], v158 offset:3072
	ds_read_b128 v[170:173], v159
	ds_read_b128 v[174:177], v159 offset:1024
	ds_read_b128 v[178:181], v159 offset:2048
	ds_read_b128 v[182:185], v159 offset:3072
	s_add_u32 s16, s14, 0xfff50080
	s_addc_u32 s17, s15, -1
	s_cmp_eq_u32 s45, 40
	s_cselect_b32 s19, s5, s17
	s_cselect_b32 s18, s4, s16
	s_cselect_b32 s17, s13, s44
	s_cselect_b32 s16, s12, s43
	v_lshl_add_u64 v[218:219], s[14:15], 0, v[136:137]
	s_add_i32 m0, s26, 0xc000
	ds_read_b128 v[186:189], v160
	ds_read_b128 v[190:193], v160 offset:1024
	ds_read_b128 v[194:197], v160 offset:2048
	ds_read_b128 v[198:201], v160 offset:3072
	ds_read_b128 v[202:205], v160 offset:4096
	ds_read_b128 v[206:209], v160 offset:5120
	ds_read_b128 v[210:213], v160 offset:6144
	ds_read_b128 v[214:217], v160 offset:7168
	global_load_lds_dwordx4 v[218:219], off
	v_lshl_add_u64 v[218:219], s[14:15], 0, v[138:139]
	s_add_i32 m0, s26, 0xe000
	s_nop 0
	global_load_lds_dwordx4 v[218:219], off
	s_waitcnt vmcnt(8)
	s_waitcnt lgkmcnt(0)
	s_barrier
	s_setprio 3
	v_mfma_f32_16x16x32_bf16 v[124:127], v[144:147], v[186:189], 0
	v_mfma_f32_16x16x32_bf16 v[120:123], v[162:165], v[186:189], 0
	v_mfma_f32_16x16x32_bf16 v[108:111], v[144:147], v[194:197], 0
	v_mfma_f32_16x16x32_bf16 v[104:107], v[162:165], v[194:197], 0
	v_mfma_f32_16x16x32_bf16 v[96:99], v[144:147], v[202:205], 0
	v_mfma_f32_16x16x32_bf16 v[88:91], v[162:165], v[202:205], 0
	v_mfma_f32_16x16x32_bf16 v[80:83], v[144:147], v[210:213], 0
	v_mfma_f32_16x16x32_bf16 v[72:75], v[162:165], v[210:213], 0
	v_mfma_f32_16x16x32_bf16 v[124:127], v[148:151], v[190:193], v[124:127]
	v_mfma_f32_16x16x32_bf16 v[120:123], v[166:169], v[190:193], v[120:123]
	v_mfma_f32_16x16x32_bf16 v[108:111], v[148:151], v[198:201], v[108:111]
	v_mfma_f32_16x16x32_bf16 v[104:107], v[166:169], v[198:201], v[104:107]
	v_mfma_f32_16x16x32_bf16 v[96:99], v[148:151], v[206:209], v[96:99]
	v_mfma_f32_16x16x32_bf16 v[88:91], v[166:169], v[206:209], v[88:91]
	v_mfma_f32_16x16x32_bf16 v[80:83], v[148:151], v[214:217], v[80:83]
	v_mfma_f32_16x16x32_bf16 v[72:75], v[166:169], v[214:217], v[72:75]
	v_mfma_f32_16x16x32_bf16 v[116:119], v[170:173], v[186:189], 0
	v_mfma_f32_16x16x32_bf16 v[112:115], v[178:181], v[186:189], 0
	v_mfma_f32_16x16x32_bf16 v[100:103], v[170:173], v[194:197], 0
	v_mfma_f32_16x16x32_bf16 v[92:95], v[178:181], v[194:197], 0
	v_mfma_f32_16x16x32_bf16 v[84:87], v[170:173], v[202:205], 0
	v_mfma_f32_16x16x32_bf16 v[76:79], v[178:181], v[202:205], 0
	v_mfma_f32_16x16x32_bf16 v[68:71], v[170:173], v[210:213], 0
	v_mfma_f32_16x16x32_bf16 v[64:67], v[178:181], v[210:213], 0
	v_mfma_f32_16x16x32_bf16 v[116:119], v[174:177], v[190:193], v[116:119]
	v_mfma_f32_16x16x32_bf16 v[112:115], v[182:185], v[190:193], v[112:115]
	v_mfma_f32_16x16x32_bf16 v[100:103], v[174:177], v[198:201], v[100:103]
	v_mfma_f32_16x16x32_bf16 v[92:95], v[182:185], v[198:201], v[92:95]
	v_mfma_f32_16x16x32_bf16 v[84:87], v[174:177], v[206:209], v[84:87]
	v_mfma_f32_16x16x32_bf16 v[76:79], v[182:185], v[206:209], v[76:79]
	v_mfma_f32_16x16x32_bf16 v[68:71], v[174:177], v[214:217], v[68:71]
	v_mfma_f32_16x16x32_bf16 v[64:67], v[182:185], v[214:217], v[64:67]
	s_setprio 0
	s_barrier
	s_add_i32 s46, s37, s23
	v_lshl_add_u64 v[218:219], s[16:17], 0, v[130:131]
	s_mov_b32 m0, s46
	ds_read_b128 v[186:189], v160 offset:16384
	ds_read_b128 v[190:193], v160 offset:17408
	ds_read_b128 v[194:197], v160 offset:18432
	ds_read_b128 v[198:201], v160 offset:19456
	ds_read_b128 v[202:205], v160 offset:20480
	ds_read_b128 v[206:209], v160 offset:21504
	ds_read_b128 v[210:213], v160 offset:22528
	ds_read_b128 v[214:217], v160 offset:23552
	global_load_lds_dwordx4 v[218:219], off
	s_add_i32 m0, s46, 0x2000
	s_add_u32 s46, s16, 0xb0000
	v_lshl_add_u64 v[220:221], s[16:17], 0, v[134:135]
	s_addc_u32 s47, s17, 0
	s_add_i32 s48, s38, s23
	global_load_lds_dwordx4 v[220:221], off
	v_lshl_add_u64 v[222:223], s[46:47], 0, v[130:131]
	s_mov_b32 m0, s48
	v_lshl_add_u64 v[224:225], s[18:19], 0, v[132:133]
	global_load_lds_dwordx4 v[222:223], off
	v_lshl_add_u64 v[222:223], s[46:47], 0, v[134:135]
	s_add_i32 m0, s48, 0x2000
	s_nop 0
	global_load_lds_dwordx4 v[222:223], off
	v_lshl_add_u64 v[222:223], s[18:19], 0, v[128:129]
	s_mov_b32 m0, s26
	s_nop 0
	global_load_lds_dwordx4 v[222:223], off
	s_mov_b32 m0, s27
	s_nop 0
	global_load_lds_dwordx4 v[224:225], off
	s_waitcnt vmcnt(8)
	s_waitcnt lgkmcnt(0)
	s_barrier
; #define PG8_STAGE(bufoff, gbase, voff) do { _Pragma("unroll") for (int _i = 0; _i < 2; ++_i) \
;         __builtin_amdgcn_global_load_lds((const unsigned*)((const char*)(gbase) + (voff)[_i]), (LAS unsigned*)(lds + (bufoff) + ldsw + _i * 8192), 16, 0, 0); } while (0)
; #define PG8_LDA(dst, b, h) do { _Pragma("unroll") for (int m = 0; m < 4; ++m) _Pragma("unroll") for (int k = 0; k < 2; ++k) dst[m][k] = *(const LAS bf16x8*)(lds + PG8_SA(b, h) + aoff + m * 2048 + k * 1024); } while (0)
; #define PG8_LDB(dst, b, h) do { _Pragma("unroll") for (int n = 0; n < 2; ++n) _Pragma("unroll") for (int k = 0; k < 2; ++k) dst[n][k] = *(const LAS bf16x8*)(lds + PG8_SB(b, h) + boff + n * 2048 + k * 1024); } while (0)
; #define PG8_MMA(ai, bj, At, Bt) do { __builtin_amdgcn_s_setprio(3); _Pragma("unroll") for (int m = 0; m < 4; ++m) _Pragma("unroll") for (int n = 0; n < 2; ++n) _Pragma("unroll") for (int k = 0; k < 2; ++k) \
;         acc[ai][bj][m][n] = __builtin_amdgcn_mfma_f32_16x16x32_bf16(Bt[n][k], At[m][k], acc[ai][bj][m][n], 0, 0, 0); __builtin_amdgcn_s_setprio(0); } while (0)
; #define PG8_WAIT_V(n) asm volatile("s_waitcnt vmcnt(" #n ")" ::: "memory")
; #define PG8_WAIT_L(n) asm volatile("s_waitcnt lgkmcnt(" #n ")" ::: "memory")
; #define PG8_BAR __builtin_amdgcn_s_barrier()
; #define PG8_SCHED __builtin_amdgcn_sched_barrier(0)
; template <class Epi, bool ALIGN_EPI>
; __device__ __forceinline__ void gemm_phase(LAS unsigned char* lds, const Gemm g, const StaticOrder& S, const Epi& E) {
;     ...
;             PG8_WAIT_V(8); PG8_WAIT_L(0); PG8_BAR; PG8_MMA(0, 0, At, B0); PG8_MMA(0, 1, At, B1); PG8_BAR; PG8_SCHED;
;             PG8_LDA(At, 0, 1); PG8_STAGE(PG8_SB(0, 0), b2, voffB); PG8_STAGE(PG8_SB(0, 1), b2 + hstep, voffB); PG8_STAGE(PG8_SA(0, 0), a2, voffA);
;             PG8_WAIT_V(8); PG8_WAIT_L(0); PG8_BAR; PG8_MMA(1, 0, At, B0); PG8_MMA(1, 1, At, B1); PG8_BAR; PG8_SCHED;
;             PG8_LDB(B0, 1, 0); PG8_LDB(B1, 1, 1); PG8_SCHED; PG8_LDA(At, 1, 0); PG8_STAGE(PG8_SA(0, 1), a2 + hstep, voffA);
;             PG8_WAIT_V(8); PG8_WAIT_L(0); PG8_BAR; PG8_MMA(0, 0, At, B0); PG8_MMA(0, 1, At, B1); PG8_BAR; PG8_SCHED;
	s_setprio 3
	v_mfma_f32_16x16x32_bf16 v[60:63], v[144:147], v[186:189], 0
	v_mfma_f32_16x16x32_bf16 v[56:59], v[162:165], v[186:189], 0
	v_mfma_f32_16x16x32_bf16 v[48:51], v[144:147], v[194:197], 0
	v_mfma_f32_16x16x32_bf16 v[40:43], v[162:165], v[194:197], 0
	v_mfma_f32_16x16x32_bf16 v[32:35], v[144:147], v[202:205], 0
	v_mfma_f32_16x16x32_bf16 v[24:27], v[162:165], v[202:205], 0
	v_mfma_f32_16x16x32_bf16 v[16:19], v[144:147], v[210:213], 0
	v_mfma_f32_16x16x32_bf16 v[8:11], v[162:165], v[210:213], 0
	v_mfma_f32_16x16x32_bf16 v[60:63], v[148:151], v[190:193], v[60:63]
	v_mfma_f32_16x16x32_bf16 v[56:59], v[166:169], v[190:193], v[56:59]
	v_mfma_f32_16x16x32_bf16 v[48:51], v[148:151], v[198:201], v[48:51]
	v_mfma_f32_16x16x32_bf16 v[40:43], v[166:169], v[198:201], v[40:43]
	v_mfma_f32_16x16x32_bf16 v[32:35], v[148:151], v[206:209], v[32:35]
	v_mfma_f32_16x16x32_bf16 v[24:27], v[166:169], v[206:209], v[24:27]
	v_mfma_f32_16x16x32_bf16 v[16:19], v[148:151], v[214:217], v[16:19]
	v_mfma_f32_16x16x32_bf16 v[8:11], v[166:169], v[214:217], v[8:11]
	v_mfma_f32_16x16x32_bf16 v[52:55], v[170:173], v[186:189], 0
	v_mfma_f32_16x16x32_bf16 v[44:47], v[178:181], v[186:189], 0
	v_mfma_f32_16x16x32_bf16 v[36:39], v[170:173], v[194:197], 0
	v_mfma_f32_16x16x32_bf16 v[28:31], v[178:181], v[194:197], 0
	v_mfma_f32_16x16x32_bf16 v[20:23], v[170:173], v[202:205], 0
	v_mfma_f32_16x16x32_bf16 v[12:15], v[178:181], v[202:205], 0
	v_mfma_f32_16x16x32_bf16 v[4:7], v[170:173], v[210:213], 0
	v_mfma_f32_16x16x32_bf16 v[0:3], v[178:181], v[210:213], 0
	v_mfma_f32_16x16x32_bf16 v[52:55], v[174:177], v[190:193], v[52:55]
	v_mfma_f32_16x16x32_bf16 v[44:47], v[182:185], v[190:193], v[44:47]
	v_mfma_f32_16x16x32_bf16 v[36:39], v[174:177], v[198:201], v[36:39]
	v_mfma_f32_16x16x32_bf16 v[28:31], v[182:185], v[198:201], v[28:31]
	v_mfma_f32_16x16x32_bf16 v[20:23], v[174:177], v[206:209], v[20:23]
	v_mfma_f32_16x16x32_bf16 v[12:15], v[182:185], v[206:209], v[12:15]
	v_mfma_f32_16x16x32_bf16 v[4:7], v[174:177], v[214:217], v[4:7]
	v_mfma_f32_16x16x32_bf16 v[0:3], v[182:185], v[214:217], v[0:3]
	s_setprio 0
	s_barrier
	s_add_i32 s46, 0, 0x18000
	v_add_u32_e32 v161, s46, v156
	s_add_i32 s47, 0, 0x1c000
	ds_read_b128 v[144:147], v161
	ds_read_b128 v[148:151], v161 offset:1024
	ds_read_b128 v[162:165], v161 offset:2048
	ds_read_b128 v[166:169], v161 offset:3072
	v_add_u32_e32 v161, s47, v156
	ds_read_b128 v[170:173], v161
	ds_read_b128 v[174:177], v161 offset:1024
	ds_read_b128 v[178:181], v161 offset:2048
	ds_read_b128 v[182:185], v161 offset:3072
	s_add_u32 s18, s18, 0xb0000
	s_addc_u32 s19, s19, 0
	s_mov_b32 m0, s28
	v_lshl_add_u64 v[226:227], s[18:19], 0, v[128:129]
	ds_read_b128 v[186:189], v160 offset:32768
	ds_read_b128 v[190:193], v160 offset:33792
	ds_read_b128 v[194:197], v160 offset:34816
	ds_read_b128 v[198:201], v160 offset:35840
	ds_read_b128 v[202:205], v160 offset:36864
	ds_read_b128 v[206:209], v160 offset:37888
	ds_read_b128 v[210:213], v160 offset:38912
	ds_read_b128 v[214:217], v160 offset:39936
	global_load_lds_dwordx4 v[226:227], off
	v_lshl_add_u64 v[226:227], s[18:19], 0, v[132:133]
	s_mov_b32 m0, s29
	s_nop 0
	global_load_lds_dwordx4 v[226:227], off
	s_waitcnt vmcnt(8)
	s_waitcnt lgkmcnt(0)
	s_barrier
	s_setprio 3
	v_mfma_f32_16x16x32_bf16 v[124:127], v[144:147], v[186:189], v[124:127]
	v_mfma_f32_16x16x32_bf16 v[120:123], v[162:165], v[186:189], v[120:123]
	v_mfma_f32_16x16x32_bf16 v[108:111], v[144:147], v[194:197], v[108:111]
	v_mfma_f32_16x16x32_bf16 v[104:107], v[162:165], v[194:197], v[104:107]
	v_mfma_f32_16x16x32_bf16 v[96:99], v[144:147], v[202:205], v[96:99]
	v_mfma_f32_16x16x32_bf16 v[88:91], v[162:165], v[202:205], v[88:91]
	v_mfma_f32_16x16x32_bf16 v[80:83], v[144:147], v[210:213], v[80:83]
	v_mfma_f32_16x16x32_bf16 v[72:75], v[162:165], v[210:213], v[72:75]
	v_mfma_f32_16x16x32_bf16 v[124:127], v[148:151], v[190:193], v[124:127]
	v_mfma_f32_16x16x32_bf16 v[120:123], v[166:169], v[190:193], v[120:123]
	v_mfma_f32_16x16x32_bf16 v[108:111], v[148:151], v[198:201], v[108:111]
	v_mfma_f32_16x16x32_bf16 v[104:107], v[166:169], v[198:201], v[104:107]
	v_mfma_f32_16x16x32_bf16 v[96:99], v[148:151], v[206:209], v[96:99]
	v_mfma_f32_16x16x32_bf16 v[88:91], v[166:169], v[206:209], v[88:91]
	v_mfma_f32_16x16x32_bf16 v[80:83], v[148:151], v[214:217], v[80:83]
	v_mfma_f32_16x16x32_bf16 v[72:75], v[166:169], v[214:217], v[72:75]
	v_mfma_f32_16x16x32_bf16 v[116:119], v[170:173], v[186:189], v[116:119]
	v_mfma_f32_16x16x32_bf16 v[112:115], v[178:181], v[186:189], v[112:115]
	v_mfma_f32_16x16x32_bf16 v[100:103], v[170:173], v[194:197], v[100:103]
	v_mfma_f32_16x16x32_bf16 v[92:95], v[178:181], v[194:197], v[92:95]
	v_mfma_f32_16x16x32_bf16 v[84:87], v[170:173], v[202:205], v[84:87]
	v_mfma_f32_16x16x32_bf16 v[76:79], v[178:181], v[202:205], v[76:79]
	v_mfma_f32_16x16x32_bf16 v[68:71], v[170:173], v[210:213], v[68:71]
	v_mfma_f32_16x16x32_bf16 v[64:67], v[178:181], v[210:213], v[64:67]
	v_mfma_f32_16x16x32_bf16 v[116:119], v[174:177], v[190:193], v[116:119]
	v_mfma_f32_16x16x32_bf16 v[112:115], v[182:185], v[190:193], v[112:115]
	v_mfma_f32_16x16x32_bf16 v[100:103], v[174:177], v[198:201], v[100:103]
	v_mfma_f32_16x16x32_bf16 v[92:95], v[182:185], v[198:201], v[92:95]
	v_mfma_f32_16x16x32_bf16 v[84:87], v[174:177], v[206:209], v[84:87]
	v_mfma_f32_16x16x32_bf16 v[76:79], v[182:185], v[206:209], v[76:79]
	v_mfma_f32_16x16x32_bf16 v[68:71], v[174:177], v[214:217], v[68:71]
	v_mfma_f32_16x16x32_bf16 v[64:67], v[182:185], v[214:217], v[64:67]
	s_setprio 0
	s_barrier
; #define PG8_STAGE(bufoff, gbase, voff) do { _Pragma("unroll") for (int _i = 0; _i < 2; ++_i) \
;         __builtin_amdgcn_global_load_lds((const unsigned*)((const char*)(gbase) + (voff)[_i]), (LAS unsigned*)(lds + (bufoff) + ldsw + _i * 8192), 16, 0, 0); } while (0)
; #define PG8_LDA(dst, b, h) do { _Pragma("unroll") for (int m = 0; m < 4; ++m) _Pragma("unroll") for (int k = 0; k < 2; ++k) dst[m][k] = *(const LAS bf16x8*)(lds + PG8_SA(b, h) + aoff + m * 2048 + k * 1024); } while (0)
; #define PG8_LDB(dst, b, h) do { _Pragma("unroll") for (int n = 0; n < 2; ++n) _Pragma("unroll") for (int k = 0; k < 2; ++k) dst[n][k] = *(const LAS bf16x8*)(lds + PG8_SB(b, h) + boff + n * 2048 + k * 1024); } while (0)
; #define PG8_MMA(ai, bj, At, Bt) do { __builtin_amdgcn_s_setprio(3); _Pragma("unroll") for (int m = 0; m < 4; ++m) _Pragma("unroll") for (int n = 0; n < 2; ++n) _Pragma("unroll") for (int k = 0; k < 2; ++k) \
;         acc[ai][bj][m][n] = __builtin_amdgcn_mfma_f32_16x16x32_bf16(Bt[n][k], At[m][k], acc[ai][bj][m][n], 0, 0, 0); __builtin_amdgcn_s_setprio(0); } while (0)
; #define PG8_WAIT_V(n) asm volatile("s_waitcnt vmcnt(" #n ")" ::: "memory")
; #define PG8_WAIT_L(n) asm volatile("s_waitcnt lgkmcnt(" #n ")" ::: "memory")
; #define PG8_BAR __builtin_amdgcn_s_barrier()
; #define PG8_SCHED __builtin_amdgcn_sched_barrier(0)
; template <class Epi, bool ALIGN_EPI>
; __device__ __forceinline__ void gemm_phase(LAS unsigned char* lds, const Gemm g, const StaticOrder& S, const Epi& E) {
;     ...
;             PG8_LDB(B0, 0, 0); PG8_LDB(B1, 0, 1); PG8_SCHED; PG8_LDA(At, 0, 0); PG8_STAGE(PG8_SA(1, 1), a1 + hstep, voffA);
;             PG8_WAIT_V(8); PG8_WAIT_L(0); PG8_BAR; PG8_MMA(0, 0, At, B0); PG8_MMA(0, 1, At, B1); PG8_BAR; PG8_SCHED;
;     ...
;             PG8_LDA(At, 1, 1); PG8_STAGE(PG8_SB(1, 0), b3, voffB); PG8_STAGE(PG8_SB(1, 1), b3 + hstep, voffB); PG8_STAGE(PG8_SA(1, 0), a3, voffA);
;             PG8_WAIT_V(8); PG8_WAIT_L(0); PG8_BAR; PG8_MMA(1, 0, At, B0); PG8_MMA(1, 1, At, B1); PG8_BAR; PG8_SCHED;
	s_add_i32 s18, s46, s23
	v_lshl_add_u64 v[218:219], v[218:219], 0, s[8:9]
	s_mov_b32 m0, s18
	ds_read_b128 v[186:189], v160 offset:49152
	ds_read_b128 v[190:193], v160 offset:50176
	ds_read_b128 v[194:197], v160 offset:51200
	ds_read_b128 v[198:201], v160 offset:52224
	ds_read_b128 v[202:205], v160 offset:53248
	ds_read_b128 v[206:209], v160 offset:54272
	ds_read_b128 v[210:213], v160 offset:55296
	ds_read_b128 v[214:217], v160 offset:56320
	global_load_lds_dwordx4 v[218:219], off
	s_add_i32 m0, s18, 0x2000
	s_add_u32 s16, s16, 0xb0080
	v_lshl_add_u64 v[218:219], v[220:221], 0, s[8:9]
	s_addc_u32 s17, s17, 0
	s_add_i32 s18, s47, s23
	global_load_lds_dwordx4 v[218:219], off
	v_lshl_add_u64 v[218:219], s[16:17], 0, v[130:131]
	s_mov_b32 m0, s18
	s_nop 0
	global_load_lds_dwordx4 v[218:219], off
	v_lshl_add_u64 v[218:219], s[16:17], 0, v[134:135]
	s_add_i32 m0, s18, 0x2000
	s_nop 0
	global_load_lds_dwordx4 v[218:219], off
	v_lshl_add_u64 v[218:219], v[222:223], 0, s[8:9]
	s_mov_b32 m0, s31
	s_nop 0
	global_load_lds_dwordx4 v[218:219], off
	v_lshl_add_u64 v[218:219], v[224:225], 0, s[8:9]
	s_mov_b32 m0, s33
	s_nop 0
	global_load_lds_dwordx4 v[218:219], off
	s_waitcnt vmcnt(8)
	s_waitcnt lgkmcnt(0)
	s_barrier
	s_setprio 3
	v_mfma_f32_16x16x32_bf16 v[60:63], v[144:147], v[186:189], v[60:63]
	v_mfma_f32_16x16x32_bf16 v[56:59], v[162:165], v[186:189], v[56:59]
	v_mfma_f32_16x16x32_bf16 v[48:51], v[144:147], v[194:197], v[48:51]
	v_mfma_f32_16x16x32_bf16 v[40:43], v[162:165], v[194:197], v[40:43]
	v_mfma_f32_16x16x32_bf16 v[32:35], v[144:147], v[202:205], v[32:35]
	v_mfma_f32_16x16x32_bf16 v[24:27], v[162:165], v[202:205], v[24:27]
	v_mfma_f32_16x16x32_bf16 v[16:19], v[144:147], v[210:213], v[16:19]
	v_mfma_f32_16x16x32_bf16 v[8:11], v[162:165], v[210:213], v[8:11]
	v_mfma_f32_16x16x32_bf16 v[60:63], v[148:151], v[190:193], v[60:63]
	v_mfma_f32_16x16x32_bf16 v[56:59], v[166:169], v[190:193], v[56:59]
	v_mfma_f32_16x16x32_bf16 v[48:51], v[148:151], v[198:201], v[48:51]
	v_mfma_f32_16x16x32_bf16 v[40:43], v[166:169], v[198:201], v[40:43]
	v_mfma_f32_16x16x32_bf16 v[32:35], v[148:151], v[206:209], v[32:35]
	v_mfma_f32_16x16x32_bf16 v[24:27], v[166:169], v[206:209], v[24:27]
	v_mfma_f32_16x16x32_bf16 v[16:19], v[148:151], v[214:217], v[16:19]
	v_mfma_f32_16x16x32_bf16 v[8:11], v[166:169], v[214:217], v[8:11]
	v_mfma_f32_16x16x32_bf16 v[52:55], v[170:173], v[186:189], v[52:55]
	v_mfma_f32_16x16x32_bf16 v[44:47], v[178:181], v[186:189], v[44:47]
	v_mfma_f32_16x16x32_bf16 v[36:39], v[170:173], v[194:197], v[36:39]
	v_mfma_f32_16x16x32_bf16 v[28:31], v[178:181], v[194:197], v[28:31]
	v_mfma_f32_16x16x32_bf16 v[20:23], v[170:173], v[202:205], v[20:23]
	v_mfma_f32_16x16x32_bf16 v[12:15], v[178:181], v[202:205], v[12:15]
	v_mfma_f32_16x16x32_bf16 v[4:7], v[170:173], v[210:213], v[4:7]
	v_mfma_f32_16x16x32_bf16 v[0:3], v[178:181], v[210:213], v[0:3]
	v_mfma_f32_16x16x32_bf16 v[52:55], v[174:177], v[190:193], v[52:55]
	v_mfma_f32_16x16x32_bf16 v[44:47], v[182:185], v[190:193], v[44:47]
	v_mfma_f32_16x16x32_bf16 v[36:39], v[174:177], v[198:201], v[36:39]
	v_mfma_f32_16x16x32_bf16 v[28:31], v[182:185], v[198:201], v[28:31]
	v_mfma_f32_16x16x32_bf16 v[20:23], v[174:177], v[206:209], v[20:23]
	v_mfma_f32_16x16x32_bf16 v[12:15], v[182:185], v[206:209], v[12:15]
	v_mfma_f32_16x16x32_bf16 v[4:7], v[174:177], v[214:217], v[4:7]
	v_mfma_f32_16x16x32_bf16 v[0:3], v[182:185], v[214:217], v[0:3]
	s_setprio 0
	s_barrier
	s_add_i32 s45, s45, 2
	s_add_u32 s14, s14, 0x100
	s_addc_u32 s15, s15, 0
	s_add_u32 s43, s43, 0x100
	s_addc_u32 s44, s44, 0
.LBB0_1513:
	ds_read_b128 v[144:147], v158
	ds_read_b128 v[148:151], v158 offset:1024
	ds_read_b128 v[162:165], v158 offset:2048
	ds_read_b128 v[166:169], v158 offset:3072
	ds_read_b128 v[170:173], v159
	ds_read_b128 v[174:177], v159 offset:1024
	ds_read_b128 v[178:181], v159 offset:2048
	ds_read_b128 v[182:185], v159 offset:3072
	s_add_u32 s16, s14, 0xfff50080
	s_addc_u32 s17, s15, -1
	s_cmp_eq_u32 s45, 40
	s_cselect_b32 s19, s5, s17
	s_cselect_b32 s18, s4, s16
	s_cselect_b32 s17, s13, s44
	s_cselect_b32 s16, s12, s43
	v_lshl_add_u64 v[218:219], s[14:15], 0, v[136:137]
	s_add_i32 m0, s26, 0xc000
	ds_read_b128 v[186:189], v160
	ds_read_b128 v[190:193], v160 offset:1024
	ds_read_b128 v[194:197], v160 offset:2048
	ds_read_b128 v[198:201], v160 offset:3072
	ds_read_b128 v[202:205], v160 offset:4096
	ds_read_b128 v[206:209], v160 offset:5120
	ds_read_b128 v[210:213], v160 offset:6144
	ds_read_b128 v[214:217], v160 offset:7168
	global_load_lds_dwordx4 v[218:219], off
	v_lshl_add_u64 v[218:219], s[14:15], 0, v[138:139]
	s_add_i32 m0, s26, 0xe000
	s_nop 0
	global_load_lds_dwordx4 v[218:219], off
	s_waitcnt vmcnt(8)
	s_waitcnt lgkmcnt(0)
	s_barrier
; #define PG8_STAGE(bufoff, gbase, voff) do { _Pragma("unroll") for (int _i = 0; _i < 2; ++_i) \
;         __builtin_amdgcn_global_load_lds((const unsigned*)((const char*)(gbase) + (voff)[_i]), (LAS unsigned*)(lds + (bufoff) + ldsw + _i * 8192), 16, 0, 0); } while (0)
; #define PG8_LDA(dst, b, h) do { _Pragma("unroll") for (int m = 0; m < 4; ++m) _Pragma("unroll") for (int k = 0; k < 2; ++k) dst[m][k] = *(const LAS bf16x8*)(lds + PG8_SA(b, h) + aoff + m * 2048 + k * 1024); } while (0)
; #define PG8_MMA(ai, bj, At, Bt) do { __builtin_amdgcn_s_setprio(3); _Pragma("unroll") for (int m = 0; m < 4; ++m) _Pragma("unroll") for (int n = 0; n < 2; ++n) _Pragma("unroll") for (int k = 0; k < 2; ++k) \
;         acc[ai][bj][m][n] = __builtin_amdgcn_mfma_f32_16x16x32_bf16(Bt[n][k], At[m][k], acc[ai][bj][m][n], 0, 0, 0); __builtin_amdgcn_s_setprio(0); } while (0)
; #define PG8_WAIT_V(n) asm volatile("s_waitcnt vmcnt(" #n ")" ::: "memory")
; #define PG8_WAIT_L(n) asm volatile("s_waitcnt lgkmcnt(" #n ")" ::: "memory")
; #define PG8_BAR __builtin_amdgcn_s_barrier()
; #define PG8_SCHED __builtin_amdgcn_sched_barrier(0)
; template <class Epi, bool ALIGN_EPI>
; __device__ __forceinline__ void gemm_phase(LAS unsigned char* lds, const Gemm g, const StaticOrder& S, const Epi& E) {
;     ...
;             PG8_WAIT_V(8); PG8_WAIT_L(0); PG8_BAR; PG8_MMA(0, 0, At, B0); PG8_MMA(0, 1, At, B1); PG8_BAR; PG8_SCHED;
;             PG8_LDA(At, 0, 1); PG8_STAGE(PG8_SB(0, 0), b2, voffB); PG8_STAGE(PG8_SB(0, 1), b2 + hstep, voffB); PG8_STAGE(PG8_SA(0, 0), a2, voffA);
;             PG8_WAIT_V(8); PG8_WAIT_L(0); PG8_BAR; PG8_MMA(1, 0, At, B0); PG8_MMA(1, 1, At, B1); PG8_BAR; PG8_SCHED;
	s_setprio 3
	v_mfma_f32_16x16x32_bf16 v[124:127], v[144:147], v[186:189], v[124:127]
	v_mfma_f32_16x16x32_bf16 v[120:123], v[162:165], v[186:189], v[120:123]
	v_mfma_f32_16x16x32_bf16 v[108:111], v[144:147], v[194:197], v[108:111]
	v_mfma_f32_16x16x32_bf16 v[104:107], v[162:165], v[194:197], v[104:107]
	v_mfma_f32_16x16x32_bf16 v[96:99], v[144:147], v[202:205], v[96:99]
	v_mfma_f32_16x16x32_bf16 v[88:91], v[162:165], v[202:205], v[88:91]
	v_mfma_f32_16x16x32_bf16 v[80:83], v[144:147], v[210:213], v[80:83]
	v_mfma_f32_16x16x32_bf16 v[72:75], v[162:165], v[210:213], v[72:75]
	v_mfma_f32_16x16x32_bf16 v[124:127], v[148:151], v[190:193], v[124:127]
	v_mfma_f32_16x16x32_bf16 v[120:123], v[166:169], v[190:193], v[120:123]
	v_mfma_f32_16x16x32_bf16 v[108:111], v[148:151], v[198:201], v[108:111]
	v_mfma_f32_16x16x32_bf16 v[104:107], v[166:169], v[198:201], v[104:107]
	v_mfma_f32_16x16x32_bf16 v[96:99], v[148:151], v[206:209], v[96:99]
	v_mfma_f32_16x16x32_bf16 v[88:91], v[166:169], v[206:209], v[88:91]
	v_mfma_f32_16x16x32_bf16 v[80:83], v[148:151], v[214:217], v[80:83]
	v_mfma_f32_16x16x32_bf16 v[72:75], v[166:169], v[214:217], v[72:75]
	v_mfma_f32_16x16x32_bf16 v[116:119], v[170:173], v[186:189], v[116:119]
	v_mfma_f32_16x16x32_bf16 v[112:115], v[178:181], v[186:189], v[112:115]
	v_mfma_f32_16x16x32_bf16 v[100:103], v[170:173], v[194:197], v[100:103]
	v_mfma_f32_16x16x32_bf16 v[92:95], v[178:181], v[194:197], v[92:95]
	v_mfma_f32_16x16x32_bf16 v[84:87], v[170:173], v[202:205], v[84:87]
	v_mfma_f32_16x16x32_bf16 v[76:79], v[178:181], v[202:205], v[76:79]
	v_mfma_f32_16x16x32_bf16 v[68:71], v[170:173], v[210:213], v[68:71]
	v_mfma_f32_16x16x32_bf16 v[64:67], v[178:181], v[210:213], v[64:67]
	v_mfma_f32_16x16x32_bf16 v[116:119], v[174:177], v[190:193], v[116:119]
	v_mfma_f32_16x16x32_bf16 v[112:115], v[182:185], v[190:193], v[112:115]
	v_mfma_f32_16x16x32_bf16 v[100:103], v[174:177], v[198:201], v[100:103]
	v_mfma_f32_16x16x32_bf16 v[92:95], v[182:185], v[198:201], v[92:95]
	v_mfma_f32_16x16x32_bf16 v[84:87], v[174:177], v[206:209], v[84:87]
	v_mfma_f32_16x16x32_bf16 v[76:79], v[182:185], v[206:209], v[76:79]
	v_mfma_f32_16x16x32_bf16 v[68:71], v[174:177], v[214:217], v[68:71]
	v_mfma_f32_16x16x32_bf16 v[64:67], v[182:185], v[214:217], v[64:67]
	s_setprio 0
	s_barrier
	s_add_i32 s46, s37, s23
	v_lshl_add_u64 v[218:219], s[16:17], 0, v[130:131]
	s_mov_b32 m0, s46
	ds_read_b128 v[186:189], v160 offset:16384
	ds_read_b128 v[190:193], v160 offset:17408
	ds_read_b128 v[194:197], v160 offset:18432
	ds_read_b128 v[198:201], v160 offset:19456
	ds_read_b128 v[202:205], v160 offset:20480
	ds_read_b128 v[206:209], v160 offset:21504
	ds_read_b128 v[210:213], v160 offset:22528
	ds_read_b128 v[214:217], v160 offset:23552
	global_load_lds_dwordx4 v[218:219], off
	s_add_i32 m0, s46, 0x2000
	s_add_u32 s46, s16, 0xb0000
	v_lshl_add_u64 v[220:221], s[16:17], 0, v[134:135]
	s_addc_u32 s47, s17, 0
	s_add_i32 s48, s38, s23
	global_load_lds_dwordx4 v[220:221], off
	v_lshl_add_u64 v[222:223], s[46:47], 0, v[130:131]
	s_mov_b32 m0, s48
	v_lshl_add_u64 v[224:225], s[18:19], 0, v[132:133]
	global_load_lds_dwordx4 v[222:223], off
	v_lshl_add_u64 v[222:223], s[46:47], 0, v[134:135]
	s_add_i32 m0, s48, 0x2000
	s_nop 0
	global_load_lds_dwordx4 v[222:223], off
	v_lshl_add_u64 v[222:223], s[18:19], 0, v[128:129]
	s_mov_b32 m0, s26
	s_nop 0
	global_load_lds_dwordx4 v[222:223], off
	s_mov_b32 m0, s27
	s_nop 0
	global_load_lds_dwordx4 v[224:225], off
	s_waitcnt vmcnt(8)
	s_waitcnt lgkmcnt(0)
	s_barrier
	s_setprio 3
	v_mfma_f32_16x16x32_bf16 v[60:63], v[144:147], v[186:189], v[60:63]
	v_mfma_f32_16x16x32_bf16 v[56:59], v[162:165], v[186:189], v[56:59]
	v_mfma_f32_16x16x32_bf16 v[48:51], v[144:147], v[194:197], v[48:51]
	v_mfma_f32_16x16x32_bf16 v[40:43], v[162:165], v[194:197], v[40:43]
	v_mfma_f32_16x16x32_bf16 v[32:35], v[144:147], v[202:205], v[32:35]
	v_mfma_f32_16x16x32_bf16 v[24:27], v[162:165], v[202:205], v[24:27]
	v_mfma_f32_16x16x32_bf16 v[16:19], v[144:147], v[210:213], v[16:19]
	v_mfma_f32_16x16x32_bf16 v[8:11], v[162:165], v[210:213], v[8:11]
	v_mfma_f32_16x16x32_bf16 v[60:63], v[148:151], v[190:193], v[60:63]
	v_mfma_f32_16x16x32_bf16 v[56:59], v[166:169], v[190:193], v[56:59]
	v_mfma_f32_16x16x32_bf16 v[48:51], v[148:151], v[198:201], v[48:51]
	v_mfma_f32_16x16x32_bf16 v[40:43], v[166:169], v[198:201], v[40:43]
	v_mfma_f32_16x16x32_bf16 v[32:35], v[148:151], v[206:209], v[32:35]
	v_mfma_f32_16x16x32_bf16 v[24:27], v[166:169], v[206:209], v[24:27]
	v_mfma_f32_16x16x32_bf16 v[16:19], v[148:151], v[214:217], v[16:19]
	v_mfma_f32_16x16x32_bf16 v[8:11], v[166:169], v[214:217], v[8:11]
	v_mfma_f32_16x16x32_bf16 v[52:55], v[170:173], v[186:189], v[52:55]
	v_mfma_f32_16x16x32_bf16 v[44:47], v[178:181], v[186:189], v[44:47]
	v_mfma_f32_16x16x32_bf16 v[36:39], v[170:173], v[194:197], v[36:39]
	v_mfma_f32_16x16x32_bf16 v[28:31], v[178:181], v[194:197], v[28:31]
	v_mfma_f32_16x16x32_bf16 v[20:23], v[170:173], v[202:205], v[20:23]
	v_mfma_f32_16x16x32_bf16 v[12:15], v[178:181], v[202:205], v[12:15]
	v_mfma_f32_16x16x32_bf16 v[4:7], v[170:173], v[210:213], v[4:7]
	v_mfma_f32_16x16x32_bf16 v[0:3], v[178:181], v[210:213], v[0:3]
	v_mfma_f32_16x16x32_bf16 v[52:55], v[174:177], v[190:193], v[52:55]
	v_mfma_f32_16x16x32_bf16 v[44:47], v[182:185], v[190:193], v[44:47]
	v_mfma_f32_16x16x32_bf16 v[36:39], v[174:177], v[198:201], v[36:39]
	v_mfma_f32_16x16x32_bf16 v[28:31], v[182:185], v[198:201], v[28:31]
	v_mfma_f32_16x16x32_bf16 v[20:23], v[174:177], v[206:209], v[20:23]
	v_mfma_f32_16x16x32_bf16 v[12:15], v[182:185], v[206:209], v[12:15]
	v_mfma_f32_16x16x32_bf16 v[4:7], v[174:177], v[214:217], v[4:7]
	v_mfma_f32_16x16x32_bf16 v[0:3], v[182:185], v[214:217], v[0:3]
	s_setprio 0
	s_barrier
; #define PG8_STAGE(bufoff, gbase, voff) do { _Pragma("unroll") for (int _i = 0; _i < 2; ++_i) \
;         __builtin_amdgcn_global_load_lds((const unsigned*)((const char*)(gbase) + (voff)[_i]), (LAS unsigned*)(lds + (bufoff) + ldsw + _i * 8192), 16, 0, 0); } while (0)
; #define PG8_LDA(dst, b, h) do { _Pragma("unroll") for (int m = 0; m < 4; ++m) _Pragma("unroll") for (int k = 0; k < 2; ++k) dst[m][k] = *(const LAS bf16x8*)(lds + PG8_SA(b, h) + aoff + m * 2048 + k * 1024); } while (0)
; #define PG8_LDB(dst, b, h) do { _Pragma("unroll") for (int n = 0; n < 2; ++n) _Pragma("unroll") for (int k = 0; k < 2; ++k) dst[n][k] = *(const LAS bf16x8*)(lds + PG8_SB(b, h) + boff + n * 2048 + k * 1024); } while (0)
; #define PG8_MMA(ai, bj, At, Bt) do { __builtin_amdgcn_s_setprio(3); _Pragma("unroll") for (int m = 0; m < 4; ++m) _Pragma("unroll") for (int n = 0; n < 2; ++n) _Pragma("unroll") for (int k = 0; k < 2; ++k) \
;         acc[ai][bj][m][n] = __builtin_amdgcn_mfma_f32_16x16x32_bf16(Bt[n][k], At[m][k], acc[ai][bj][m][n], 0, 0, 0); __builtin_amdgcn_s_setprio(0); } while (0)
; #define PG8_WAIT_V(n) asm volatile("s_waitcnt vmcnt(" #n ")" ::: "memory")
; #define PG8_WAIT_L(n) asm volatile("s_waitcnt lgkmcnt(" #n ")" ::: "memory")
; #define PG8_BAR __builtin_amdgcn_s_barrier()
; #define PG8_SCHED __builtin_amdgcn_sched_barrier(0)
; template <class Epi, bool ALIGN_EPI>
; __device__ __forceinline__ void gemm_phase(LAS unsigned char* lds, const Gemm g, const StaticOrder& S, const Epi& E) {
;     ...
;             PG8_LDB(B0, 1, 0); PG8_LDB(B1, 1, 1); PG8_SCHED; PG8_LDA(At, 1, 0); PG8_STAGE(PG8_SA(0, 1), a2 + hstep, voffA);
;             PG8_WAIT_V(8); PG8_WAIT_L(0); PG8_BAR; PG8_MMA(0, 0, At, B0); PG8_MMA(0, 1, At, B1); PG8_BAR; PG8_SCHED;
	s_add_i32 s46, 0, 0x18000
	v_add_u32_e32 v161, s46, v156
	s_add_i32 s47, 0, 0x1c000
	ds_read_b128 v[144:147], v161
	ds_read_b128 v[148:151], v161 offset:1024
	ds_read_b128 v[162:165], v161 offset:2048
	ds_read_b128 v[166:169], v161 offset:3072
	v_add_u32_e32 v161, s47, v156
	ds_read_b128 v[170:173], v161
	ds_read_b128 v[174:177], v161 offset:1024
	ds_read_b128 v[178:181], v161 offset:2048
	ds_read_b128 v[182:185], v161 offset:3072
	s_add_u32 s18, s18, 0xb0000
	s_addc_u32 s19, s19, 0
	s_mov_b32 m0, s28
	v_lshl_add_u64 v[226:227], s[18:19], 0, v[128:129]
	ds_read_b128 v[186:189], v160 offset:32768
	ds_read_b128 v[190:193], v160 offset:33792
	ds_read_b128 v[194:197], v160 offset:34816
	ds_read_b128 v[198:201], v160 offset:35840
	ds_read_b128 v[202:205], v160 offset:36864
	ds_read_b128 v[206:209], v160 offset:37888
	ds_read_b128 v[210:213], v160 offset:38912
	ds_read_b128 v[214:217], v160 offset:39936
	global_load_lds_dwordx4 v[226:227], off
	v_lshl_add_u64 v[226:227], s[18:19], 0, v[132:133]
	s_mov_b32 m0, s29
	s_nop 0
	global_load_lds_dwordx4 v[226:227], off
	s_waitcnt vmcnt(8)
	s_waitcnt lgkmcnt(0)
	s_barrier
	s_setprio 3
	v_mfma_f32_16x16x32_bf16 v[124:127], v[144:147], v[186:189], v[124:127]
	v_mfma_f32_16x16x32_bf16 v[120:123], v[162:165], v[186:189], v[120:123]
	v_mfma_f32_16x16x32_bf16 v[108:111], v[144:147], v[194:197], v[108:111]
	v_mfma_f32_16x16x32_bf16 v[104:107], v[162:165], v[194:197], v[104:107]
	v_mfma_f32_16x16x32_bf16 v[96:99], v[144:147], v[202:205], v[96:99]
	v_mfma_f32_16x16x32_bf16 v[88:91], v[162:165], v[202:205], v[88:91]
	v_mfma_f32_16x16x32_bf16 v[80:83], v[144:147], v[210:213], v[80:83]
	v_mfma_f32_16x16x32_bf16 v[72:75], v[162:165], v[210:213], v[72:75]
	v_mfma_f32_16x16x32_bf16 v[124:127], v[148:151], v[190:193], v[124:127]
	v_mfma_f32_16x16x32_bf16 v[120:123], v[166:169], v[190:193], v[120:123]
	v_mfma_f32_16x16x32_bf16 v[108:111], v[148:151], v[198:201], v[108:111]
	v_mfma_f32_16x16x32_bf16 v[104:107], v[166:169], v[198:201], v[104:107]
	v_mfma_f32_16x16x32_bf16 v[96:99], v[148:151], v[206:209], v[96:99]
	v_mfma_f32_16x16x32_bf16 v[88:91], v[166:169], v[206:209], v[88:91]
	v_mfma_f32_16x16x32_bf16 v[80:83], v[148:151], v[214:217], v[80:83]
	v_mfma_f32_16x16x32_bf16 v[72:75], v[166:169], v[214:217], v[72:75]
	v_mfma_f32_16x16x32_bf16 v[116:119], v[170:173], v[186:189], v[116:119]
	v_mfma_f32_16x16x32_bf16 v[112:115], v[178:181], v[186:189], v[112:115]
	v_mfma_f32_16x16x32_bf16 v[100:103], v[170:173], v[194:197], v[100:103]
	v_mfma_f32_16x16x32_bf16 v[92:95], v[178:181], v[194:197], v[92:95]
	v_mfma_f32_16x16x32_bf16 v[84:87], v[170:173], v[202:205], v[84:87]
	v_mfma_f32_16x16x32_bf16 v[76:79], v[178:181], v[202:205], v[76:79]
	v_mfma_f32_16x16x32_bf16 v[68:71], v[170:173], v[210:213], v[68:71]
	v_mfma_f32_16x16x32_bf16 v[64:67], v[178:181], v[210:213], v[64:67]
	v_mfma_f32_16x16x32_bf16 v[116:119], v[174:177], v[190:193], v[116:119]
	v_mfma_f32_16x16x32_bf16 v[112:115], v[182:185], v[190:193], v[112:115]
	v_mfma_f32_16x16x32_bf16 v[100:103], v[174:177], v[198:201], v[100:103]
	v_mfma_f32_16x16x32_bf16 v[92:95], v[182:185], v[198:201], v[92:95]
	v_mfma_f32_16x16x32_bf16 v[84:87], v[174:177], v[206:209], v[84:87]
	v_mfma_f32_16x16x32_bf16 v[76:79], v[182:185], v[206:209], v[76:79]
	v_mfma_f32_16x16x32_bf16 v[68:71], v[174:177], v[214:217], v[68:71]
	v_mfma_f32_16x16x32_bf16 v[64:67], v[182:185], v[214:217], v[64:67]
	s_setprio 0
	s_barrier
; #define PG8_STAGE(bufoff, gbase, voff) do { _Pragma("unroll") for (int _i = 0; _i < 2; ++_i) \
;         __builtin_amdgcn_global_load_lds((const unsigned*)((const char*)(gbase) + (voff)[_i]), (LAS unsigned*)(lds + (bufoff) + ldsw + _i * 8192), 16, 0, 0); } while (0)
; #define PG8_LDA(dst, b, h) do { _Pragma("unroll") for (int m = 0; m < 4; ++m) _Pragma("unroll") for (int k = 0; k < 2; ++k) dst[m][k] = *(const LAS bf16x8*)(lds + PG8_SA(b, h) + aoff + m * 2048 + k * 1024); } while (0)
; #define PG8_MMA(ai, bj, At, Bt) do { __builtin_amdgcn_s_setprio(3); _Pragma("unroll") for (int m = 0; m < 4; ++m) _Pragma("unroll") for (int n = 0; n < 2; ++n) _Pragma("unroll") for (int k = 0; k < 2; ++k) \
;         acc[ai][bj][m][n] = __builtin_amdgcn_mfma_f32_16x16x32_bf16(Bt[n][k], At[m][k], acc[ai][bj][m][n], 0, 0, 0); __builtin_amdgcn_s_setprio(0); } while (0)
; #define PG8_WAIT_V(n) asm volatile("s_waitcnt vmcnt(" #n ")" ::: "memory")
; #define PG8_WAIT_L(n) asm volatile("s_waitcnt lgkmcnt(" #n ")" ::: "memory")
; #define PG8_BAR __builtin_amdgcn_s_barrier()
; #define PG8_SCHED __builtin_amdgcn_sched_barrier(0)
; template <class Epi, bool ALIGN_EPI>
; __device__ __forceinline__ void gemm_phase(LAS unsigned char* lds, const Gemm g, const StaticOrder& S, const Epi& E) {
;     ...
;             PG8_LDA(At, 1, 1); PG8_STAGE(PG8_SB(1, 0), b3, voffB); PG8_STAGE(PG8_SB(1, 1), b3 + hstep, voffB); PG8_STAGE(PG8_SA(1, 0), a3, voffA);
;             PG8_WAIT_V(8); PG8_WAIT_L(0); PG8_BAR; PG8_MMA(1, 0, At, B0); PG8_MMA(1, 1, At, B1); PG8_BAR; PG8_SCHED;
;         }
;         if constexpr (ALIGN_EPI) { if (wr == 0) PG8_BAR; }
	s_add_i32 s18, s46, s23
	v_lshl_add_u64 v[218:219], v[218:219], 0, s[8:9]
	s_mov_b32 m0, s18
	ds_read_b128 v[186:189], v160 offset:49152
	ds_read_b128 v[190:193], v160 offset:50176
	ds_read_b128 v[194:197], v160 offset:51200
	ds_read_b128 v[198:201], v160 offset:52224
	ds_read_b128 v[202:205], v160 offset:53248
	ds_read_b128 v[206:209], v160 offset:54272
	ds_read_b128 v[210:213], v160 offset:55296
	ds_read_b128 v[214:217], v160 offset:56320
	global_load_lds_dwordx4 v[218:219], off
	s_add_i32 m0, s18, 0x2000
	s_add_u32 s16, s16, 0xb0080
	v_lshl_add_u64 v[218:219], v[220:221], 0, s[8:9]
	s_addc_u32 s17, s17, 0
	s_add_i32 s18, s47, s23
	global_load_lds_dwordx4 v[218:219], off
	v_lshl_add_u64 v[218:219], s[16:17], 0, v[130:131]
	s_mov_b32 m0, s18
	s_nop 0
	global_load_lds_dwordx4 v[218:219], off
	v_lshl_add_u64 v[218:219], s[16:17], 0, v[134:135]
	s_add_i32 m0, s18, 0x2000
	s_nop 0
	global_load_lds_dwordx4 v[218:219], off
	v_lshl_add_u64 v[218:219], v[222:223], 0, s[8:9]
	s_mov_b32 m0, s31
	s_nop 0
	global_load_lds_dwordx4 v[218:219], off
	v_lshl_add_u64 v[218:219], v[224:225], 0, s[8:9]
	s_mov_b32 m0, s33
	s_nop 0
	global_load_lds_dwordx4 v[218:219], off
	s_waitcnt vmcnt(8)
	s_waitcnt lgkmcnt(0)
	s_barrier
	s_setprio 3
	v_mfma_f32_16x16x32_bf16 v[60:63], v[144:147], v[186:189], v[60:63]
	v_mfma_f32_16x16x32_bf16 v[56:59], v[162:165], v[186:189], v[56:59]
	v_mfma_f32_16x16x32_bf16 v[48:51], v[144:147], v[194:197], v[48:51]
	v_mfma_f32_16x16x32_bf16 v[40:43], v[162:165], v[194:197], v[40:43]
	v_mfma_f32_16x16x32_bf16 v[32:35], v[144:147], v[202:205], v[32:35]
	v_mfma_f32_16x16x32_bf16 v[24:27], v[162:165], v[202:205], v[24:27]
	v_mfma_f32_16x16x32_bf16 v[16:19], v[144:147], v[210:213], v[16:19]
	v_mfma_f32_16x16x32_bf16 v[8:11], v[162:165], v[210:213], v[8:11]
	v_mfma_f32_16x16x32_bf16 v[60:63], v[148:151], v[190:193], v[60:63]
	v_mfma_f32_16x16x32_bf16 v[56:59], v[166:169], v[190:193], v[56:59]
	v_mfma_f32_16x16x32_bf16 v[48:51], v[148:151], v[198:201], v[48:51]
	v_mfma_f32_16x16x32_bf16 v[40:43], v[166:169], v[198:201], v[40:43]
	v_mfma_f32_16x16x32_bf16 v[32:35], v[148:151], v[206:209], v[32:35]
	v_mfma_f32_16x16x32_bf16 v[24:27], v[166:169], v[206:209], v[24:27]
	v_mfma_f32_16x16x32_bf16 v[16:19], v[148:151], v[214:217], v[16:19]
	v_mfma_f32_16x16x32_bf16 v[8:11], v[166:169], v[214:217], v[8:11]
	v_mfma_f32_16x16x32_bf16 v[52:55], v[170:173], v[186:189], v[52:55]
	v_mfma_f32_16x16x32_bf16 v[44:47], v[178:181], v[186:189], v[44:47]
	v_mfma_f32_16x16x32_bf16 v[36:39], v[170:173], v[194:197], v[36:39]
	v_mfma_f32_16x16x32_bf16 v[28:31], v[178:181], v[194:197], v[28:31]
	v_mfma_f32_16x16x32_bf16 v[20:23], v[170:173], v[202:205], v[20:23]
	v_mfma_f32_16x16x32_bf16 v[12:15], v[178:181], v[202:205], v[12:15]
	v_mfma_f32_16x16x32_bf16 v[4:7], v[170:173], v[210:213], v[4:7]
	v_mfma_f32_16x16x32_bf16 v[0:3], v[178:181], v[210:213], v[0:3]
	v_mfma_f32_16x16x32_bf16 v[52:55], v[174:177], v[190:193], v[52:55]
	v_mfma_f32_16x16x32_bf16 v[44:47], v[182:185], v[190:193], v[44:47]
	v_mfma_f32_16x16x32_bf16 v[36:39], v[174:177], v[198:201], v[36:39]
	v_mfma_f32_16x16x32_bf16 v[28:31], v[182:185], v[198:201], v[28:31]
	v_mfma_f32_16x16x32_bf16 v[20:23], v[174:177], v[206:209], v[20:23]
	v_mfma_f32_16x16x32_bf16 v[12:15], v[182:185], v[206:209], v[12:15]
	v_mfma_f32_16x16x32_bf16 v[4:7], v[174:177], v[214:217], v[4:7]
	v_mfma_f32_16x16x32_bf16 v[0:3], v[182:185], v[214:217], v[0:3]
	s_setprio 0
	s_barrier
	s_add_i32 s45, s45, 2
	s_add_u32 s14, s14, 0x100
	s_addc_u32 s15, s15, 0
	s_add_u32 s43, s43, 0x100
	s_addc_u32 s44, s44, 0
	s_cmp_gt_u32 s45, 41
	s_cbranch_scc0 .LBB0_1513
	s_and_b64 vcc, exec, s[10:11]
	s_cbranch_vccz .LBB0_1516
	s_barrier
